# GEMM tile loops: first two counted waits of every non-first tile allow 16 outstanding VMEM ops (epilogue stores need not drain)
# baseline (speedup 1.0000x reference)
; #define G_STAGE(bufoff, gbase, voff) do { _Pragma("unroll") for (int _i = 0; _i < 2; ++_i) \
;         __builtin_amdgcn_global_load_lds((const unsigned*)((const char*)(gbase) + voff[_i]), (LAS unsigned*)(lds + (bufoff) + ldsw + _i * 8192), 16, 0, 0); } while (0)
; #define WAIT_V(n) asm volatile("s_waitcnt vmcnt(" #n ")" ::: "memory")
; #define BAR __builtin_amdgcn_s_barrier()
; template <class Get, class Epi>
; DI void gemm_loop(int ntiles, int ld, char* shm, const Get& get, const Epi& epi) {
;     ...
;     for (int i = 0; i < 2; ++i) { int R, C; stage_rc(tid * 16 + i * 8192, R, C); const int rho = R & 31, Rb = (R & ~31) + 8 * ((rho & 15) >> 2) + 4 * (rho >> 4) + (rho & 3);
;         voffA[i] = (unsigned)(R * ld + C) * 2u; voffB[i] = (unsigned)(Rb * ld + C) * 2u; }
;     const size_t kstep = (size_t)(BK * 2), hstep = (size_t)HALF * ld * 2;
;     const unsigned ldsw = (unsigned)wid * 1024u;
;     const int aoff = lds_byte(wr * 64 + fr, fq * 8), boff = lds_byte(wc * 32 + fr, fq * 8);
;     ...
;     int L = bx; if (L >= ntiles) return;
;     Tile cur = get(L), nxt = cur;
;     AccT acc;
;     ...
;     G_ZERO;
;     bf16x8 At[4][2], B0[2][2], B1[2][2];
;     const char* cA = (const char*)cur.A + (size_t)cur.brow * ld * 2; const char* cB = (const char*)cur.Bt + (size_t)cur.bcol * ld * 2;
;     G_STAGE(G_SB(0, 0), cB, voffB); G_STAGE(G_SB(0, 1), cB + hstep, voffB); G_STAGE(G_SA(0, 0), cA, voffA); G_STAGE(G_SA(0, 1), cA + hstep, voffA);
;     if (wr == 1) BAR;
;     WAIT_V(2); BAR;
;     G_STAGE(G_SB(1, 0), cB + kstep, voffB); G_STAGE(G_SA(1, 0), cA + kstep, voffA); G_STAGE(G_SB(1, 1), cB + hstep + kstep, voffB);
;     WAIT_V(6); BAR;
.LBB0_425:
	v_and_b32_e32 v15, 15, v14
	v_and_b32_e32 v16, 48, v14
	v_lshlrev_b32_e32 v14, 2, v14
	v_lshlrev_b32_e32 v15, 6, v15
	v_and_b32_e32 v14, 32, v14
	s_lshl_b32 s8, s8, 12
	v_or_b32_e32 v17, v15, v16
	s_lshl_b32 s9, s9, 13
	v_bitop3_b32 v15, v15, v14, v16 bitop3:0x36
	s_and_b32 s8, s8, 0x3000
	v_bitop3_b32 v14, v17, s9, v14 bitop3:0xde
	v_or_b32_e32 v140, s8, v15
	s_mov_b64 s[8:9], 0x80
	s_add_i32 m0, s43, 0x18000
	v_lshl_add_u64 v[6:7], v[6:7], 0, s[8:9]
	s_waitcnt vmcnt(2)
	s_barrier
	global_load_lds_dwordx4 v[6:7], off
	v_lshl_add_u64 v[4:5], v[4:5], 0, s[8:9]
	s_add_i32 m0, s43, 0x1a000
	s_add_i32 s47, s43, 0x8000
	s_add_i32 s50, s43, 0xa000
	global_load_lds_dwordx4 v[4:5], off
	v_lshl_add_u64 v[0:1], v[0:1], 0, s[8:9]
	s_mov_b32 m0, s47
	s_add_u32 s12, s14, 0x100080
	global_load_lds_dwordx4 v[0:1], off
	v_lshl_add_u64 v[0:1], v[2:3], 0, s[8:9]
	s_mov_b32 m0, s50
	s_addc_u32 s13, s15, 0
	global_load_lds_dwordx4 v[0:1], off
	s_add_i32 m0, s43, 0x1c000
	v_lshl_add_u64 v[0:1], s[12:13], 0, v[132:133]
	global_load_lds_dwordx4 v[0:1], off
	v_lshl_add_u64 v[0:1], s[12:13], 0, v[128:129]
	s_add_i32 m0, s43, 0x1e000
	s_cmpk_lt_u32 s10, 0x100
	global_load_lds_dwordx4 v[0:1], off
	v_lshlrev_b32_e32 v0, 16, v12
	v_and_b32_e32 v0, 0xfffe0000, v0
	v_lshl_add_u32 v0, v11, 13, v0
	v_and_b32_e32 v1, 1, v12
	v_lshl_or_b32 v0, v1, 6, v0
	v_lshl_add_u32 v136, v13, 1, v0
	v_lshlrev_b32_e32 v0, 16, v8
	v_and_b32_e32 v0, 0xfffe0000, v0
	s_waitcnt vmcnt(6)
	s_mov_b32 s100, 0
	v_lshl_add_u32 v0, v9, 13, v0
	v_and_b32_e32 v1, 1, v8
	s_cselect_b64 s[10:11], -1, 0
	v_lshl_or_b32 v0, v1, 6, v0
	s_add_i32 s54, 0, 0x10000
	s_add_i32 s55, 0, 0x14000
	v_mov_b32_e32 v137, v133
	v_lshl_add_u32 v138, v10, 1, v0
	v_mov_b32_e32 v139, v133
	v_add_u32_e32 v141, s54, v140
	v_add_u32_e32 v142, s55, v140
	v_add_u32_e32 v143, 0, v14
	s_add_i32 s56, s43, 0xc000
	v_mov_b32_e32 v144, 0x480000
	s_mov_b32 s57, s73
	s_mov_b32 s58, s59
	s_barrier
	s_branch .LBB0_428

; #define G_STAGE(bufoff, gbase, voff) do { _Pragma("unroll") for (int _i = 0; _i < 2; ++_i) \
;         __builtin_amdgcn_global_load_lds((const unsigned*)((const char*)(gbase) + voff[_i]), (LAS unsigned*)(lds + (bufoff) + ldsw + _i * 8192), 16, 0, 0); } while (0)
; #define G_LDA(dst, b, h) do { _Pragma("unroll") for (int m = 0; m < 4; ++m) _Pragma("unroll") for (int k = 0; k < 2; ++k) dst[m][k] = *(const LAS bf16x8*)(lds + G_SA(b, h) + aoff + m * 2048 + k * 1024); } while (0)
; #define G_LDB(dst, b, h) do { _Pragma("unroll") for (int n = 0; n < 2; ++n) _Pragma("unroll") for (int k = 0; k < 2; ++k) dst[n][k] = *(const LAS bf16x8*)(lds + G_SB(b, h) + boff + n * 2048 + k * 1024); } while (0)
; #define G_MMA(ai, bj, At_, Bt_) do { __builtin_amdgcn_s_setprio(1); _Pragma("unroll") for (int m = 0; m < 4; ++m) _Pragma("unroll") for (int n = 0; n < 2; ++n) _Pragma("unroll") for (int k = 0; k < 2; ++k) \
;         acc[ai][bj][m][n] = __builtin_amdgcn_mfma_f32_16x16x32_bf16(Bt_[n][k], At_[m][k], acc[ai][bj][m][n], 0, 0, 0); __builtin_amdgcn_s_setprio(0); } while (0)
; #define WAIT_V(n) asm volatile("s_waitcnt vmcnt(" #n ")" ::: "memory")
; #define WAIT_L(n) asm volatile("s_waitcnt lgkmcnt(" #n ")" ::: "memory")
; #define BAR __builtin_amdgcn_s_barrier()
; #define SCHED __builtin_amdgcn_sched_barrier(0)
; template <class Get, class Epi>
; DI void gemm_loop(int ntiles, int ld, char* shm, const Get& get, const Epi& epi) {
;     ...
;             const bool last = (t == nt - 2);
;             const char* a1 = cA + (size_t)(t + 1) * kstep;
;             const char* a2 = last ? nA : cA + (size_t)(t + 2) * kstep; const char* b2 = last ? nB : cB + (size_t)(t + 2) * kstep;
;             const char* a3 = a2 + kstep; const char* b3 = b2 + kstep;
;             G_LDB(B0, 0, 0); G_LDB(B1, 0, 1); SCHED; G_LDA(At, 0, 0); G_STAGE(G_SA(1, 1), a1 + hstep, voffA);
;             WAIT_V(8); WAIT_L(0); BAR; G_MMA(0, 0, At, B0); G_MMA(0, 1, At, B1); BAR; SCHED;
.Lpeel_431:
	ds_read_b128 v[146:149], v141
	ds_read_b128 v[150:153], v141 offset:1024
	ds_read_b128 v[154:157], v141 offset:2048
	ds_read_b128 v[158:161], v141 offset:3072
	ds_read_b128 v[162:165], v142
	ds_read_b128 v[166:169], v142 offset:1024
	ds_read_b128 v[170:173], v142 offset:2048
	ds_read_b128 v[174:177], v142 offset:3072
	s_add_u32 s14, s34, 0xfff00080
	s_addc_u32 s15, s35, -1
	s_cmp_eq_u32 s81, 60
	s_cselect_b32 s37, s74, s15
	s_cselect_b32 s36, s75, s14
	s_cselect_b32 s15, s76, s80
	s_cselect_b32 s14, s78, s79
	s_mov_b32 m0, s56
	v_lshl_add_u64 v[182:183], s[34:35], 0, v[136:137]
	ds_read_b128 v[178:181], v143
	ds_read_b128 v[188:191], v143 offset:1024
	ds_read_b128 v[192:195], v143 offset:2048
	ds_read_b128 v[196:199], v143 offset:3072
	ds_read_b128 v[200:203], v143 offset:4096
	ds_read_b128 v[204:207], v143 offset:5120
	ds_read_b128 v[208:211], v143 offset:6144
	ds_read_b128 v[212:215], v143 offset:7168
	global_load_lds_dwordx4 v[182:183], off
	v_lshl_add_u64 v[182:183], s[34:35], 0, v[138:139]
	s_add_i32 m0, s43, 0xe000
	s_nop 0
	global_load_lds_dwordx4 v[182:183], off
	s_cmp_lg_u32 s100, 0
	s_cbranch_scc0 .Lrf_431_0
	s_waitcnt vmcnt(16)
	s_branch .Lrj_431_0

; #define G_STAGE(bufoff, gbase, voff) do { _Pragma("unroll") for (int _i = 0; _i < 2; ++_i) \
;         __builtin_amdgcn_global_load_lds((const unsigned*)((const char*)(gbase) + voff[_i]), (LAS unsigned*)(lds + (bufoff) + ldsw + _i * 8192), 16, 0, 0); } while (0)
; #define G_LDA(dst, b, h) do { _Pragma("unroll") for (int m = 0; m < 4; ++m) _Pragma("unroll") for (int k = 0; k < 2; ++k) dst[m][k] = *(const LAS bf16x8*)(lds + G_SA(b, h) + aoff + m * 2048 + k * 1024); } while (0)
; #define G_MMA(ai, bj, At_, Bt_) do { __builtin_amdgcn_s_setprio(1); _Pragma("unroll") for (int m = 0; m < 4; ++m) _Pragma("unroll") for (int n = 0; n < 2; ++n) _Pragma("unroll") for (int k = 0; k < 2; ++k) \
;         acc[ai][bj][m][n] = __builtin_amdgcn_mfma_f32_16x16x32_bf16(Bt_[n][k], At_[m][k], acc[ai][bj][m][n], 0, 0, 0); __builtin_amdgcn_s_setprio(0); } while (0)
; #define WAIT_V(n) asm volatile("s_waitcnt vmcnt(" #n ")" ::: "memory")
; #define WAIT_L(n) asm volatile("s_waitcnt lgkmcnt(" #n ")" ::: "memory")
; #define BAR __builtin_amdgcn_s_barrier()
; #define SCHED __builtin_amdgcn_sched_barrier(0)
; template <class Get, class Epi>
; DI void gemm_loop(int ntiles, int ld, char* shm, const Get& get, const Epi& epi) {
;     ...
;             WAIT_V(8); WAIT_L(0); BAR; G_MMA(0, 0, At, B0); G_MMA(0, 1, At, B1); BAR; SCHED;
;             G_LDA(At, 0, 1); G_STAGE(G_SB(0, 0), b2, voffB); G_STAGE(G_SB(0, 1), b2 + hstep, voffB); G_STAGE(G_SA(0, 0), a2, voffA);
;             WAIT_V(8); WAIT_L(0); BAR; G_MMA(1, 0, At, B0); G_MMA(1, 1, At, B1); BAR; SCHED;
.Lrj_431_0:
	s_waitcnt lgkmcnt(0)
	s_barrier
	s_setprio 1
	s_waitcnt lgkmcnt(0)
	v_mfma_f32_16x16x32_bf16 v[124:127], v[146:149], v[178:181], 0
	v_mfma_f32_16x16x32_bf16 v[120:123], v[154:157], v[178:181], 0
	v_mfma_f32_16x16x32_bf16 v[116:119], v[146:149], v[192:195], 0
	v_mfma_f32_16x16x32_bf16 v[112:115], v[154:157], v[192:195], 0
	v_mfma_f32_16x16x32_bf16 v[100:103], v[146:149], v[200:203], 0
	v_mfma_f32_16x16x32_bf16 v[96:99], v[154:157], v[200:203], 0
	v_mfma_f32_16x16x32_bf16 v[84:87], v[146:149], v[208:211], 0
	v_mfma_f32_16x16x32_bf16 v[80:83], v[154:157], v[208:211], 0
	v_mfma_f32_16x16x32_bf16 v[124:127], v[150:153], v[188:191], v[124:127]
	v_mfma_f32_16x16x32_bf16 v[120:123], v[158:161], v[188:191], v[120:123]
	v_mfma_f32_16x16x32_bf16 v[116:119], v[150:153], v[196:199], v[116:119]
	v_mfma_f32_16x16x32_bf16 v[112:115], v[158:161], v[196:199], v[112:115]
	v_mfma_f32_16x16x32_bf16 v[100:103], v[150:153], v[204:207], v[100:103]
	v_mfma_f32_16x16x32_bf16 v[96:99], v[158:161], v[204:207], v[96:99]
	v_mfma_f32_16x16x32_bf16 v[84:87], v[150:153], v[212:215], v[84:87]
	v_mfma_f32_16x16x32_bf16 v[80:83], v[158:161], v[212:215], v[80:83]
	s_setprio 0
	s_setprio 1
	v_mfma_f32_16x16x32_bf16 v[108:111], v[162:165], v[178:181], 0
	v_mfma_f32_16x16x32_bf16 v[104:107], v[170:173], v[178:181], 0
	v_mfma_f32_16x16x32_bf16 v[92:95], v[162:165], v[192:195], 0
	v_mfma_f32_16x16x32_bf16 v[88:91], v[170:173], v[192:195], 0
	v_mfma_f32_16x16x32_bf16 v[76:79], v[162:165], v[200:203], 0
	v_mfma_f32_16x16x32_bf16 v[72:75], v[170:173], v[200:203], 0
	v_mfma_f32_16x16x32_bf16 v[68:71], v[162:165], v[208:211], 0
	v_mfma_f32_16x16x32_bf16 v[64:67], v[170:173], v[208:211], 0
	v_mfma_f32_16x16x32_bf16 v[108:111], v[166:169], v[188:191], v[108:111]
	v_mfma_f32_16x16x32_bf16 v[104:107], v[174:177], v[188:191], v[104:107]
	v_mfma_f32_16x16x32_bf16 v[92:95], v[166:169], v[196:199], v[92:95]
	v_mfma_f32_16x16x32_bf16 v[88:91], v[174:177], v[196:199], v[88:91]
	v_mfma_f32_16x16x32_bf16 v[76:79], v[166:169], v[204:207], v[76:79]
	v_mfma_f32_16x16x32_bf16 v[72:75], v[174:177], v[204:207], v[72:75]
	v_mfma_f32_16x16x32_bf16 v[68:71], v[166:169], v[212:215], v[68:71]
	v_mfma_f32_16x16x32_bf16 v[64:67], v[174:177], v[212:215], v[64:67]
	s_setprio 0
	s_barrier
	s_add_i32 s82, s54, s38
	v_lshl_add_u64 v[182:183], s[14:15], 0, v[132:133]
	s_mov_b32 m0, s82
	ds_read_b128 v[178:181], v143 offset:16384
	ds_read_b128 v[188:191], v143 offset:17408
	ds_read_b128 v[192:195], v143 offset:18432
	ds_read_b128 v[196:199], v143 offset:19456
	ds_read_b128 v[200:203], v143 offset:20480
	ds_read_b128 v[204:207], v143 offset:21504
	ds_read_b128 v[208:211], v143 offset:22528
	ds_read_b128 v[212:215], v143 offset:23552
	global_load_lds_dwordx4 v[182:183], off
	s_add_i32 m0, s82, 0x2000
	s_add_u32 s82, s14, 0x100000
	v_lshl_add_u64 v[184:185], s[14:15], 0, v[128:129]
	s_addc_u32 s83, s15, 0
	s_add_i32 s84, s55, s38
	global_load_lds_dwordx4 v[184:185], off
	v_lshl_add_u64 v[186:187], s[82:83], 0, v[132:133]
	s_mov_b32 m0, s84
	v_lshl_add_u64 v[216:217], s[36:37], 0, v[130:131]
	global_load_lds_dwordx4 v[186:187], off
	v_lshl_add_u64 v[186:187], s[82:83], 0, v[128:129]
	s_add_i32 m0, s84, 0x2000
	s_nop 0
	global_load_lds_dwordx4 v[186:187], off
	v_lshl_add_u64 v[186:187], s[36:37], 0, v[134:135]
	s_mov_b32 m0, s43
	s_nop 0
	global_load_lds_dwordx4 v[186:187], off
	s_mov_b32 m0, s44
	s_nop 0
	global_load_lds_dwordx4 v[216:217], off
	s_cmp_lg_u32 s100, 0
	s_cbranch_scc0 .Lrf_431_1
	s_waitcnt vmcnt(16)
	s_branch .Lrj_431_1

; #define G_STAGE(bufoff, gbase, voff) do { _Pragma("unroll") for (int _i = 0; _i < 2; ++_i) \
;         __builtin_amdgcn_global_load_lds((const unsigned*)((const char*)(gbase) + voff[_i]), (LAS unsigned*)(lds + (bufoff) + ldsw + _i * 8192), 16, 0, 0); } while (0)
; #define G_LDA(dst, b, h) do { _Pragma("unroll") for (int m = 0; m < 4; ++m) _Pragma("unroll") for (int k = 0; k < 2; ++k) dst[m][k] = *(const LAS bf16x8*)(lds + G_SA(b, h) + aoff + m * 2048 + k * 1024); } while (0)
; #define G_LDB(dst, b, h) do { _Pragma("unroll") for (int n = 0; n < 2; ++n) _Pragma("unroll") for (int k = 0; k < 2; ++k) dst[n][k] = *(const LAS bf16x8*)(lds + G_SB(b, h) + boff + n * 2048 + k * 1024); } while (0)
; #define G_MMA(ai, bj, At_, Bt_) do { __builtin_amdgcn_s_setprio(1); _Pragma("unroll") for (int m = 0; m < 4; ++m) _Pragma("unroll") for (int n = 0; n < 2; ++n) _Pragma("unroll") for (int k = 0; k < 2; ++k) \
;         acc[ai][bj][m][n] = __builtin_amdgcn_mfma_f32_16x16x32_bf16(Bt_[n][k], At_[m][k], acc[ai][bj][m][n], 0, 0, 0); __builtin_amdgcn_s_setprio(0); } while (0)
; #define WAIT_V(n) asm volatile("s_waitcnt vmcnt(" #n ")" ::: "memory")
; #define WAIT_L(n) asm volatile("s_waitcnt lgkmcnt(" #n ")" ::: "memory")
; #define BAR __builtin_amdgcn_s_barrier()
; #define SCHED __builtin_amdgcn_sched_barrier(0)
; template <class Get, class Epi>
; DI void gemm_loop(int ntiles, int ld, char* shm, const Get& get, const Epi& epi) {
;     ...
;             WAIT_V(8); WAIT_L(0); BAR; G_MMA(1, 0, At, B0); G_MMA(1, 1, At, B1); BAR; SCHED;
;             G_LDB(B0, 1, 0); G_LDB(B1, 1, 1); SCHED; G_LDA(At, 1, 0); G_STAGE(G_SA(0, 1), a2 + hstep, voffA);
;             WAIT_V(8); WAIT_L(0); BAR; G_MMA(0, 0, At, B0); G_MMA(0, 1, At, B1); BAR; SCHED;
.Lrj_431_1:
	s_waitcnt lgkmcnt(0)
	s_barrier
	s_setprio 1
	s_waitcnt lgkmcnt(0)
	v_mfma_f32_16x16x32_bf16 v[60:63], v[146:149], v[178:181], 0
	v_mfma_f32_16x16x32_bf16 v[56:59], v[154:157], v[178:181], 0
	v_mfma_f32_16x16x32_bf16 v[52:55], v[146:149], v[192:195], 0
	v_mfma_f32_16x16x32_bf16 v[48:51], v[154:157], v[192:195], 0
	v_mfma_f32_16x16x32_bf16 v[36:39], v[146:149], v[200:203], 0
	v_mfma_f32_16x16x32_bf16 v[32:35], v[154:157], v[200:203], 0
	v_mfma_f32_16x16x32_bf16 v[20:23], v[146:149], v[208:211], 0
	v_mfma_f32_16x16x32_bf16 v[16:19], v[154:157], v[208:211], 0
	v_mfma_f32_16x16x32_bf16 v[60:63], v[150:153], v[188:191], v[60:63]
	v_mfma_f32_16x16x32_bf16 v[56:59], v[158:161], v[188:191], v[56:59]
	v_mfma_f32_16x16x32_bf16 v[52:55], v[150:153], v[196:199], v[52:55]
	v_mfma_f32_16x16x32_bf16 v[48:51], v[158:161], v[196:199], v[48:51]
	v_mfma_f32_16x16x32_bf16 v[36:39], v[150:153], v[204:207], v[36:39]
	v_mfma_f32_16x16x32_bf16 v[32:35], v[158:161], v[204:207], v[32:35]
	v_mfma_f32_16x16x32_bf16 v[20:23], v[150:153], v[212:215], v[20:23]
	v_mfma_f32_16x16x32_bf16 v[16:19], v[158:161], v[212:215], v[16:19]
	s_setprio 0
	s_setprio 1
	v_mfma_f32_16x16x32_bf16 v[44:47], v[162:165], v[178:181], 0
	v_mfma_f32_16x16x32_bf16 v[40:43], v[170:173], v[178:181], 0
	v_mfma_f32_16x16x32_bf16 v[28:31], v[162:165], v[192:195], 0
	v_mfma_f32_16x16x32_bf16 v[24:27], v[170:173], v[192:195], 0
	v_mfma_f32_16x16x32_bf16 v[12:15], v[162:165], v[200:203], 0
	v_mfma_f32_16x16x32_bf16 v[8:11], v[170:173], v[200:203], 0
	v_mfma_f32_16x16x32_bf16 v[4:7], v[162:165], v[208:211], 0
	v_mfma_f32_16x16x32_bf16 v[0:3], v[170:173], v[208:211], 0
	v_mfma_f32_16x16x32_bf16 v[44:47], v[166:169], v[188:191], v[44:47]
	v_mfma_f32_16x16x32_bf16 v[40:43], v[174:177], v[188:191], v[40:43]
	v_mfma_f32_16x16x32_bf16 v[28:31], v[166:169], v[196:199], v[28:31]
	v_mfma_f32_16x16x32_bf16 v[24:27], v[174:177], v[196:199], v[24:27]
	v_mfma_f32_16x16x32_bf16 v[12:15], v[166:169], v[204:207], v[12:15]
	v_mfma_f32_16x16x32_bf16 v[8:11], v[174:177], v[204:207], v[8:11]
	v_mfma_f32_16x16x32_bf16 v[4:7], v[166:169], v[212:215], v[4:7]
	v_mfma_f32_16x16x32_bf16 v[0:3], v[174:177], v[212:215], v[0:3]
	s_setprio 0
	s_barrier
	s_add_i32 s82, 0, 0x18000
	v_add_u32_e32 v145, s82, v140
	s_add_i32 s83, 0, 0x1c000
	ds_read_b128 v[146:149], v145
	ds_read_b128 v[150:153], v145 offset:1024
	ds_read_b128 v[154:157], v145 offset:2048
	ds_read_b128 v[158:161], v145 offset:3072
	v_add_u32_e32 v145, s83, v140
	ds_read_b128 v[162:165], v145
	ds_read_b128 v[166:169], v145 offset:1024
	ds_read_b128 v[170:173], v145 offset:2048
	ds_read_b128 v[174:177], v145 offset:3072
	s_add_u32 s36, s36, 0x100000
	s_addc_u32 s37, s37, 0
	s_mov_b32 m0, s45
	v_lshl_add_u64 v[218:219], s[36:37], 0, v[134:135]
	ds_read_b128 v[178:181], v143 offset:32768
	ds_read_b128 v[188:191], v143 offset:33792
	ds_read_b128 v[192:195], v143 offset:34816
	ds_read_b128 v[196:199], v143 offset:35840
	ds_read_b128 v[200:203], v143 offset:36864
	ds_read_b128 v[204:207], v143 offset:37888
	ds_read_b128 v[208:211], v143 offset:38912
	ds_read_b128 v[212:215], v143 offset:39936
	global_load_lds_dwordx4 v[218:219], off
	v_lshl_add_u64 v[218:219], s[36:37], 0, v[130:131]
	s_mov_b32 m0, s46
	s_nop 0
	global_load_lds_dwordx4 v[218:219], off
	s_waitcnt vmcnt(8)
	s_waitcnt lgkmcnt(0)
	s_barrier
	s_setprio 1
	s_waitcnt lgkmcnt(0)
	v_mfma_f32_16x16x32_bf16 v[124:127], v[146:149], v[178:181], v[124:127]
	v_mfma_f32_16x16x32_bf16 v[120:123], v[154:157], v[178:181], v[120:123]
	v_mfma_f32_16x16x32_bf16 v[116:119], v[146:149], v[192:195], v[116:119]
	v_mfma_f32_16x16x32_bf16 v[112:115], v[154:157], v[192:195], v[112:115]
	v_mfma_f32_16x16x32_bf16 v[100:103], v[146:149], v[200:203], v[100:103]
	v_mfma_f32_16x16x32_bf16 v[96:99], v[154:157], v[200:203], v[96:99]
	v_mfma_f32_16x16x32_bf16 v[84:87], v[146:149], v[208:211], v[84:87]
	v_mfma_f32_16x16x32_bf16 v[80:83], v[154:157], v[208:211], v[80:83]
	v_mfma_f32_16x16x32_bf16 v[124:127], v[150:153], v[188:191], v[124:127]
	v_mfma_f32_16x16x32_bf16 v[120:123], v[158:161], v[188:191], v[120:123]
	v_mfma_f32_16x16x32_bf16 v[116:119], v[150:153], v[196:199], v[116:119]
	v_mfma_f32_16x16x32_bf16 v[112:115], v[158:161], v[196:199], v[112:115]
	v_mfma_f32_16x16x32_bf16 v[100:103], v[150:153], v[204:207], v[100:103]
	v_mfma_f32_16x16x32_bf16 v[96:99], v[158:161], v[204:207], v[96:99]
	v_mfma_f32_16x16x32_bf16 v[84:87], v[150:153], v[212:215], v[84:87]
	v_mfma_f32_16x16x32_bf16 v[80:83], v[158:161], v[212:215], v[80:83]
	s_setprio 0
	s_setprio 1
	v_mfma_f32_16x16x32_bf16 v[108:111], v[162:165], v[178:181], v[108:111]
	v_mfma_f32_16x16x32_bf16 v[104:107], v[170:173], v[178:181], v[104:107]
	v_mfma_f32_16x16x32_bf16 v[92:95], v[162:165], v[192:195], v[92:95]
	v_mfma_f32_16x16x32_bf16 v[88:91], v[170:173], v[192:195], v[88:91]
	v_mfma_f32_16x16x32_bf16 v[76:79], v[162:165], v[200:203], v[76:79]
	v_mfma_f32_16x16x32_bf16 v[72:75], v[170:173], v[200:203], v[72:75]
	v_mfma_f32_16x16x32_bf16 v[68:71], v[162:165], v[208:211], v[68:71]
	v_mfma_f32_16x16x32_bf16 v[64:67], v[170:173], v[208:211], v[64:67]
	v_mfma_f32_16x16x32_bf16 v[108:111], v[166:169], v[188:191], v[108:111]
	v_mfma_f32_16x16x32_bf16 v[104:107], v[174:177], v[188:191], v[104:107]
	v_mfma_f32_16x16x32_bf16 v[92:95], v[166:169], v[196:199], v[92:95]
	v_mfma_f32_16x16x32_bf16 v[88:91], v[174:177], v[196:199], v[88:91]
	v_mfma_f32_16x16x32_bf16 v[76:79], v[166:169], v[204:207], v[76:79]
	v_mfma_f32_16x16x32_bf16 v[72:75], v[174:177], v[204:207], v[72:75]
	v_mfma_f32_16x16x32_bf16 v[68:71], v[166:169], v[212:215], v[68:71]
	v_mfma_f32_16x16x32_bf16 v[64:67], v[174:177], v[212:215], v[64:67]
	s_setprio 0
	s_barrier
; #define G_STAGE(bufoff, gbase, voff) do { _Pragma("unroll") for (int _i = 0; _i < 2; ++_i) \
;         __builtin_amdgcn_global_load_lds((const unsigned*)((const char*)(gbase) + voff[_i]), (LAS unsigned*)(lds + (bufoff) + ldsw + _i * 8192), 16, 0, 0); } while (0)
; #define G_LDA(dst, b, h) do { _Pragma("unroll") for (int m = 0; m < 4; ++m) _Pragma("unroll") for (int k = 0; k < 2; ++k) dst[m][k] = *(const LAS bf16x8*)(lds + G_SA(b, h) + aoff + m * 2048 + k * 1024); } while (0)
; #define G_MMA(ai, bj, At_, Bt_) do { __builtin_amdgcn_s_setprio(1); _Pragma("unroll") for (int m = 0; m < 4; ++m) _Pragma("unroll") for (int n = 0; n < 2; ++n) _Pragma("unroll") for (int k = 0; k < 2; ++k) \
;         acc[ai][bj][m][n] = __builtin_amdgcn_mfma_f32_16x16x32_bf16(Bt_[n][k], At_[m][k], acc[ai][bj][m][n], 0, 0, 0); __builtin_amdgcn_s_setprio(0); } while (0)
; #define WAIT_V(n) asm volatile("s_waitcnt vmcnt(" #n ")" ::: "memory")
; #define WAIT_L(n) asm volatile("s_waitcnt lgkmcnt(" #n ")" ::: "memory")
; #define BAR __builtin_amdgcn_s_barrier()
; #define SCHED __builtin_amdgcn_sched_barrier(0)
; template <class Get, class Epi>
; DI void gemm_loop(int ntiles, int ld, char* shm, const Get& get, const Epi& epi) {
;     ...
;             G_LDA(At, 1, 1); G_STAGE(G_SB(1, 0), b3, voffB); G_STAGE(G_SB(1, 1), b3 + hstep, voffB); G_STAGE(G_SA(1, 0), a3, voffA);
;             WAIT_V(8); WAIT_L(0); BAR; G_MMA(1, 0, At, B0); G_MMA(1, 1, At, B1); BAR; SCHED;
;         }
	s_add_i32 s36, s82, s38
	v_lshl_add_u64 v[182:183], v[182:183], 0, s[8:9]
	s_mov_b32 m0, s36
	ds_read_b128 v[178:181], v143 offset:49152
	ds_read_b128 v[188:191], v143 offset:50176
	ds_read_b128 v[192:195], v143 offset:51200
	ds_read_b128 v[196:199], v143 offset:52224
	ds_read_b128 v[200:203], v143 offset:53248
	ds_read_b128 v[204:207], v143 offset:54272
	ds_read_b128 v[208:211], v143 offset:55296
	ds_read_b128 v[212:215], v143 offset:56320
	global_load_lds_dwordx4 v[182:183], off
	s_add_i32 m0, s36, 0x2000
	s_add_u32 s14, s14, 0x100080
	v_lshl_add_u64 v[182:183], v[184:185], 0, s[8:9]
	s_addc_u32 s15, s15, 0
	s_add_i32 s36, s83, s38
	global_load_lds_dwordx4 v[182:183], off
	v_lshl_add_u64 v[182:183], s[14:15], 0, v[132:133]
	s_mov_b32 m0, s36
	s_nop 0
	global_load_lds_dwordx4 v[182:183], off
	v_lshl_add_u64 v[182:183], s[14:15], 0, v[128:129]
	s_add_i32 m0, s36, 0x2000
	s_nop 0
	global_load_lds_dwordx4 v[182:183], off
	v_lshl_add_u64 v[182:183], v[186:187], 0, s[8:9]
	s_mov_b32 m0, s47
	s_nop 0
	global_load_lds_dwordx4 v[182:183], off
	v_lshl_add_u64 v[182:183], v[216:217], 0, s[8:9]
	s_mov_b32 m0, s50
	s_nop 0
	global_load_lds_dwordx4 v[182:183], off
	s_waitcnt vmcnt(8)
	s_waitcnt lgkmcnt(0)
	s_barrier
	s_setprio 1
	s_waitcnt lgkmcnt(0)
	v_mfma_f32_16x16x32_bf16 v[60:63], v[146:149], v[178:181], v[60:63]
	v_mfma_f32_16x16x32_bf16 v[56:59], v[154:157], v[178:181], v[56:59]
	v_mfma_f32_16x16x32_bf16 v[52:55], v[146:149], v[192:195], v[52:55]
	v_mfma_f32_16x16x32_bf16 v[48:51], v[154:157], v[192:195], v[48:51]
	v_mfma_f32_16x16x32_bf16 v[36:39], v[146:149], v[200:203], v[36:39]
	v_mfma_f32_16x16x32_bf16 v[32:35], v[154:157], v[200:203], v[32:35]
	v_mfma_f32_16x16x32_bf16 v[20:23], v[146:149], v[208:211], v[20:23]
	v_mfma_f32_16x16x32_bf16 v[16:19], v[154:157], v[208:211], v[16:19]
	v_mfma_f32_16x16x32_bf16 v[60:63], v[150:153], v[188:191], v[60:63]
	v_mfma_f32_16x16x32_bf16 v[56:59], v[158:161], v[188:191], v[56:59]
	v_mfma_f32_16x16x32_bf16 v[52:55], v[150:153], v[196:199], v[52:55]
	v_mfma_f32_16x16x32_bf16 v[48:51], v[158:161], v[196:199], v[48:51]
	v_mfma_f32_16x16x32_bf16 v[36:39], v[150:153], v[204:207], v[36:39]
	v_mfma_f32_16x16x32_bf16 v[32:35], v[158:161], v[204:207], v[32:35]
	v_mfma_f32_16x16x32_bf16 v[20:23], v[150:153], v[212:215], v[20:23]
	v_mfma_f32_16x16x32_bf16 v[16:19], v[158:161], v[212:215], v[16:19]
	s_setprio 0
	s_setprio 1
	v_mfma_f32_16x16x32_bf16 v[44:47], v[162:165], v[178:181], v[44:47]
	v_mfma_f32_16x16x32_bf16 v[40:43], v[170:173], v[178:181], v[40:43]
	v_mfma_f32_16x16x32_bf16 v[28:31], v[162:165], v[192:195], v[28:31]
	v_mfma_f32_16x16x32_bf16 v[24:27], v[170:173], v[192:195], v[24:27]
	v_mfma_f32_16x16x32_bf16 v[12:15], v[162:165], v[200:203], v[12:15]
	v_mfma_f32_16x16x32_bf16 v[8:11], v[170:173], v[200:203], v[8:11]
	v_mfma_f32_16x16x32_bf16 v[4:7], v[162:165], v[208:211], v[4:7]
	v_mfma_f32_16x16x32_bf16 v[0:3], v[170:173], v[208:211], v[0:3]
	v_mfma_f32_16x16x32_bf16 v[44:47], v[166:169], v[188:191], v[44:47]
	v_mfma_f32_16x16x32_bf16 v[40:43], v[174:177], v[188:191], v[40:43]
	v_mfma_f32_16x16x32_bf16 v[28:31], v[166:169], v[196:199], v[28:31]
	v_mfma_f32_16x16x32_bf16 v[24:27], v[174:177], v[196:199], v[24:27]
	v_mfma_f32_16x16x32_bf16 v[12:15], v[166:169], v[204:207], v[12:15]
	v_mfma_f32_16x16x32_bf16 v[8:11], v[174:177], v[204:207], v[8:11]
	v_mfma_f32_16x16x32_bf16 v[4:7], v[166:169], v[212:215], v[4:7]
	v_mfma_f32_16x16x32_bf16 v[0:3], v[174:177], v[212:215], v[0:3]
	s_setprio 0
	s_barrier
	s_add_i32 s81, s81, 2
	s_add_u32 s34, s34, 0x100
	s_addc_u32 s35, s35, 0
	s_add_u32 s79, s79, 0x100
	s_addc_u32 s80, s80, 0
	s_cmp_gt_u32 s81, 61
	s_cbranch_scc0 .LBB0_431
	s_branch .Lpost_431

; #define BAR __builtin_amdgcn_s_barrier()
; template <class Get, class Epi>
; DI void gemm_loop(int ntiles, int ld, char* shm, const Get& get, const Epi& epi) {
;     ...
;         }
;         if (wr == 0) BAR;
.Lpost_431:
	s_mov_b32 s100, 1
	s_and_b64 vcc, exec, s[10:11]
	s_cbranch_vccz .LBB0_434
	s_barrier

; #define G_STAGE(bufoff, gbase, voff) do { _Pragma("unroll") for (int _i = 0; _i < 2; ++_i) \
;         __builtin_amdgcn_global_load_lds((const unsigned*)((const char*)(gbase) + voff[_i]), (LAS unsigned*)(lds + (bufoff) + ldsw + _i * 8192), 16, 0, 0); } while (0)
; #define WAIT_V(n) asm volatile("s_waitcnt vmcnt(" #n ")" ::: "memory")
; #define BAR __builtin_amdgcn_s_barrier()
; template <class Get, class Epi>
; DI void gemm_loop(int ntiles, int ld, char* shm, const Get& get, const Epi& epi) {
;     ...
;     for (int i = 0; i < 2; ++i) { int R, C; stage_rc(tid * 16 + i * 8192, R, C); const int rho = R & 31, Rb = (R & ~31) + 8 * ((rho & 15) >> 2) + 4 * (rho >> 4) + (rho & 3);
;         voffA[i] = (unsigned)(R * ld + C) * 2u; voffB[i] = (unsigned)(Rb * ld + C) * 2u; }
;     const size_t kstep = (size_t)(BK * 2), hstep = (size_t)HALF * ld * 2;
;     const unsigned ldsw = (unsigned)wid * 1024u;
;     const int aoff = lds_byte(wr * 64 + fr, fq * 8), boff = lds_byte(wc * 32 + fr, fq * 8);
;     ...
;     int L = bx; if (L >= ntiles) return;
;     Tile cur = get(L), nxt = cur;
;     AccT acc;
;     ...
;     G_ZERO;
;     bf16x8 At[4][2], B0[2][2], B1[2][2];
;     const char* cA = (const char*)cur.A + (size_t)cur.brow * ld * 2; const char* cB = (const char*)cur.Bt + (size_t)cur.bcol * ld * 2;
;     G_STAGE(G_SB(0, 0), cB, voffB); G_STAGE(G_SB(0, 1), cB + hstep, voffB); G_STAGE(G_SA(0, 0), cA, voffA); G_STAGE(G_SA(0, 1), cA + hstep, voffA);
;     if (wr == 1) BAR;
;     WAIT_V(2); BAR;
;     G_STAGE(G_SB(1, 0), cB + kstep, voffB); G_STAGE(G_SA(1, 0), cA + kstep, voffA); G_STAGE(G_SB(1, 1), cB + hstep + kstep, voffB);
;     WAIT_V(6); BAR;
.LBB0_441:
	v_and_b32_e32 v11, 15, v10
	v_and_b32_e32 v12, 48, v10
	v_lshlrev_b32_e32 v10, 2, v10
	v_lshlrev_b32_e32 v11, 6, v11
	v_and_b32_e32 v10, 32, v10
	s_lshl_b32 s12, s12, 12
	v_or_b32_e32 v13, v11, v12
	s_lshl_b32 s13, s13, 13
	v_bitop3_b32 v11, v11, v10, v12 bitop3:0x36
	s_and_b32 s12, s12, 0x3000
	v_bitop3_b32 v10, v13, s13, v10 bitop3:0xde
	v_or_b32_e32 v11, s12, v11
	s_mov_b64 s[12:13], 0x80
	s_add_i32 m0, s41, 0x18000
	v_lshl_add_u64 v[2:3], v[2:3], 0, s[12:13]
	s_waitcnt vmcnt(2)
	s_barrier
	global_load_lds_dwordx4 v[2:3], off
	s_add_i32 m0, s41, 0x1a000
	s_add_u32 s28, s68, 0x6c5a080
	v_lshl_add_u64 v[0:1], v[0:1], 0, s[12:13]
	s_addc_u32 s29, s69, 0
	s_add_i32 s46, s41, 0x8000
	global_load_lds_dwordx4 v[0:1], off
	v_lshl_add_u64 v[0:1], s[28:29], 0, v[134:135]
	s_mov_b32 m0, s46
	s_add_i32 s47, s41, 0xa000
	global_load_lds_dwordx4 v[0:1], off
	v_lshl_add_u64 v[0:1], s[28:29], 0, v[130:131]
	s_add_u32 s28, s8, 0x20080
	s_mov_b32 m0, s47
	s_addc_u32 s29, s9, 0
	global_load_lds_dwordx4 v[0:1], off
	s_add_i32 m0, s41, 0x1c000
	v_lshl_add_u64 v[0:1], s[28:29], 0, v[132:133]
	global_load_lds_dwordx4 v[0:1], off
	v_lshl_add_u64 v[0:1], s[28:29], 0, v[128:129]
	s_add_i32 m0, s41, 0x1e000
	s_cmpk_lt_u32 s15, 0x100
	global_load_lds_dwordx4 v[0:1], off
	v_lshlrev_b32_e32 v0, 13, v8
	v_and_b32_e32 v0, 0xffffc000, v0
	v_lshl_add_u32 v0, v7, 10, v0
	v_and_b32_e32 v1, 1, v8
	v_lshl_or_b32 v0, v1, 6, v0
	v_lshl_add_u32 v136, v9, 1, v0
	v_lshlrev_b32_e32 v0, 13, v4
	s_cselect_b64 s[28:29], -1, 0
	s_add_u32 s30, s68, 0x6c7a080
	v_and_b32_e32 v0, 0xffffc000, v0
	s_waitcnt vmcnt(6)
	s_mov_b32 s100, 0
	s_addc_u32 s31, s69, 0
	v_lshl_add_u32 v0, v5, 10, v0
	v_and_b32_e32 v1, 1, v4
	s_add_i32 s54, 0, 0x10000
	s_add_i32 s56, 0, 0x14000
	s_add_i32 s58, 0, 0x18000
	s_add_i32 s72, 0, 0x1c000
	v_lshl_or_b32 v0, v1, 6, v0
	v_add_u32_e32 v140, s54, v11
	v_add_u32_e32 v141, s56, v11
	s_add_i32 s54, s54, s14
	s_add_i32 s56, s56, s14
	v_add_u32_e32 v143, s58, v11
	v_add_u32_e32 v144, s72, v11
	s_add_i32 s58, s58, s14
	s_add_i32 s72, s72, s14
	v_mov_b32_e32 v137, v133
	v_lshl_add_u32 v138, v6, 1, v0
	v_mov_b32_e32 v139, v133
	v_add_u32_e32 v142, 0, v10
	s_add_i32 s50, s41, 0xc000
	s_add_i32 s51, s41, 0xe000
	s_add_i32 s55, s54, 0x2000
	s_add_i32 s57, s56, 0x2000
	s_add_i32 s59, s58, 0x2000
	s_add_i32 s73, s72, 0x2000
	v_mov_b32_e32 v145, 0x480000
	s_barrier
	s_branch .LBB0_444

; #define G_STAGE(bufoff, gbase, voff) do { _Pragma("unroll") for (int _i = 0; _i < 2; ++_i) \
;         __builtin_amdgcn_global_load_lds((const unsigned*)((const char*)(gbase) + voff[_i]), (LAS unsigned*)(lds + (bufoff) + ldsw + _i * 8192), 16, 0, 0); } while (0)
; #define G_LDA(dst, b, h) do { _Pragma("unroll") for (int m = 0; m < 4; ++m) _Pragma("unroll") for (int k = 0; k < 2; ++k) dst[m][k] = *(const LAS bf16x8*)(lds + G_SA(b, h) + aoff + m * 2048 + k * 1024); } while (0)
; #define G_LDB(dst, b, h) do { _Pragma("unroll") for (int n = 0; n < 2; ++n) _Pragma("unroll") for (int k = 0; k < 2; ++k) dst[n][k] = *(const LAS bf16x8*)(lds + G_SB(b, h) + boff + n * 2048 + k * 1024); } while (0)
; #define G_MMA(ai, bj, At_, Bt_) do { __builtin_amdgcn_s_setprio(1); _Pragma("unroll") for (int m = 0; m < 4; ++m) _Pragma("unroll") for (int n = 0; n < 2; ++n) _Pragma("unroll") for (int k = 0; k < 2; ++k) \
;         acc[ai][bj][m][n] = __builtin_amdgcn_mfma_f32_16x16x32_bf16(Bt_[n][k], At_[m][k], acc[ai][bj][m][n], 0, 0, 0); __builtin_amdgcn_s_setprio(0); } while (0)
; #define WAIT_V(n) asm volatile("s_waitcnt vmcnt(" #n ")" ::: "memory")
; #define WAIT_L(n) asm volatile("s_waitcnt lgkmcnt(" #n ")" ::: "memory")
; #define BAR __builtin_amdgcn_s_barrier()
; #define SCHED __builtin_amdgcn_sched_barrier(0)
; template <class Get, class Epi>
; DI void gemm_loop(int ntiles, int ld, char* shm, const Get& get, const Epi& epi) {
;     ...
;             const bool last = (t == nt - 2);
;             const char* a1 = cA + (size_t)(t + 1) * kstep;
;             const char* a2 = last ? nA : cA + (size_t)(t + 2) * kstep; const char* b2 = last ? nB : cB + (size_t)(t + 2) * kstep;
;             const char* a3 = a2 + kstep; const char* b3 = b2 + kstep;
;             G_LDB(B0, 0, 0); G_LDB(B1, 0, 1); SCHED; G_LDA(At, 0, 0); G_STAGE(G_SA(1, 1), a1 + hstep, voffA);
;             WAIT_V(8); WAIT_L(0); BAR; G_MMA(0, 0, At, B0); G_MMA(0, 1, At, B1); BAR; SCHED;
.Lpeel_445:
	ds_read_b128 v[146:149], v140
	ds_read_b128 v[150:153], v140 offset:1024
	ds_read_b128 v[154:157], v140 offset:2048
	ds_read_b128 v[158:161], v140 offset:3072
	ds_read_b128 v[162:165], v141
	ds_read_b128 v[166:169], v141 offset:1024
	ds_read_b128 v[170:173], v141 offset:2048
	ds_read_b128 v[174:177], v141 offset:3072
	s_add_u32 s14, s36, 0xfffe0080
	s_addc_u32 s15, s37, -1
	s_cmp_eq_u32 s81, 4
	s_cselect_b32 s39, s3, s15
	s_cselect_b32 s38, s2, s14
	s_cselect_b32 s15, s76, s80
	s_cselect_b32 s14, s78, s79
	s_mov_b32 m0, s50
	v_lshl_add_u64 v[182:183], s[36:37], 0, v[136:137]
	ds_read_b128 v[178:181], v142
	ds_read_b128 v[188:191], v142 offset:1024
	ds_read_b128 v[192:195], v142 offset:2048
	ds_read_b128 v[196:199], v142 offset:3072
	ds_read_b128 v[200:203], v142 offset:4096
	ds_read_b128 v[204:207], v142 offset:5120
	ds_read_b128 v[208:211], v142 offset:6144
	ds_read_b128 v[212:215], v142 offset:7168
	global_load_lds_dwordx4 v[182:183], off
	v_lshl_add_u64 v[182:183], s[36:37], 0, v[138:139]
	s_mov_b32 m0, s51
	s_nop 0
	global_load_lds_dwordx4 v[182:183], off
	s_cmp_lg_u32 s100, 0
	s_cbranch_scc0 .Lrf_445_0
	s_waitcnt vmcnt(16)
	s_branch .Lrj_445_0

; #define G_STAGE(bufoff, gbase, voff) do { _Pragma("unroll") for (int _i = 0; _i < 2; ++_i) \
;         __builtin_amdgcn_global_load_lds((const unsigned*)((const char*)(gbase) + voff[_i]), (LAS unsigned*)(lds + (bufoff) + ldsw + _i * 8192), 16, 0, 0); } while (0)
; #define G_LDA(dst, b, h) do { _Pragma("unroll") for (int m = 0; m < 4; ++m) _Pragma("unroll") for (int k = 0; k < 2; ++k) dst[m][k] = *(const LAS bf16x8*)(lds + G_SA(b, h) + aoff + m * 2048 + k * 1024); } while (0)
; #define G_MMA(ai, bj, At_, Bt_) do { __builtin_amdgcn_s_setprio(1); _Pragma("unroll") for (int m = 0; m < 4; ++m) _Pragma("unroll") for (int n = 0; n < 2; ++n) _Pragma("unroll") for (int k = 0; k < 2; ++k) \
;         acc[ai][bj][m][n] = __builtin_amdgcn_mfma_f32_16x16x32_bf16(Bt_[n][k], At_[m][k], acc[ai][bj][m][n], 0, 0, 0); __builtin_amdgcn_s_setprio(0); } while (0)
; #define WAIT_V(n) asm volatile("s_waitcnt vmcnt(" #n ")" ::: "memory")
; #define WAIT_L(n) asm volatile("s_waitcnt lgkmcnt(" #n ")" ::: "memory")
; #define BAR __builtin_amdgcn_s_barrier()
; #define SCHED __builtin_amdgcn_sched_barrier(0)
; template <class Get, class Epi>
; DI void gemm_loop(int ntiles, int ld, char* shm, const Get& get, const Epi& epi) {
;     ...
;             WAIT_V(8); WAIT_L(0); BAR; G_MMA(0, 0, At, B0); G_MMA(0, 1, At, B1); BAR; SCHED;
;             G_LDA(At, 0, 1); G_STAGE(G_SB(0, 0), b2, voffB); G_STAGE(G_SB(0, 1), b2 + hstep, voffB); G_STAGE(G_SA(0, 0), a2, voffA);
;             WAIT_V(8); WAIT_L(0); BAR; G_MMA(1, 0, At, B0); G_MMA(1, 1, At, B1); BAR; SCHED;
.Lrj_445_0:
	s_waitcnt lgkmcnt(0)
	s_barrier
	s_setprio 1
	s_waitcnt lgkmcnt(0)
	v_mfma_f32_16x16x32_bf16 v[124:127], v[146:149], v[178:181], 0
	v_mfma_f32_16x16x32_bf16 v[120:123], v[154:157], v[178:181], 0
	v_mfma_f32_16x16x32_bf16 v[116:119], v[146:149], v[192:195], 0
	v_mfma_f32_16x16x32_bf16 v[112:115], v[154:157], v[192:195], 0
	v_mfma_f32_16x16x32_bf16 v[100:103], v[146:149], v[200:203], 0
	v_mfma_f32_16x16x32_bf16 v[96:99], v[154:157], v[200:203], 0
	v_mfma_f32_16x16x32_bf16 v[84:87], v[146:149], v[208:211], 0
	v_mfma_f32_16x16x32_bf16 v[80:83], v[154:157], v[208:211], 0
	v_mfma_f32_16x16x32_bf16 v[124:127], v[150:153], v[188:191], v[124:127]
	v_mfma_f32_16x16x32_bf16 v[120:123], v[158:161], v[188:191], v[120:123]
	v_mfma_f32_16x16x32_bf16 v[116:119], v[150:153], v[196:199], v[116:119]
	v_mfma_f32_16x16x32_bf16 v[112:115], v[158:161], v[196:199], v[112:115]
	v_mfma_f32_16x16x32_bf16 v[100:103], v[150:153], v[204:207], v[100:103]
	v_mfma_f32_16x16x32_bf16 v[96:99], v[158:161], v[204:207], v[96:99]
	v_mfma_f32_16x16x32_bf16 v[84:87], v[150:153], v[212:215], v[84:87]
	v_mfma_f32_16x16x32_bf16 v[80:83], v[158:161], v[212:215], v[80:83]
	s_setprio 0
	s_setprio 1
	v_mfma_f32_16x16x32_bf16 v[108:111], v[162:165], v[178:181], 0
	v_mfma_f32_16x16x32_bf16 v[104:107], v[170:173], v[178:181], 0
	v_mfma_f32_16x16x32_bf16 v[92:95], v[162:165], v[192:195], 0
	v_mfma_f32_16x16x32_bf16 v[88:91], v[170:173], v[192:195], 0
	v_mfma_f32_16x16x32_bf16 v[76:79], v[162:165], v[200:203], 0
	v_mfma_f32_16x16x32_bf16 v[72:75], v[170:173], v[200:203], 0
	v_mfma_f32_16x16x32_bf16 v[68:71], v[162:165], v[208:211], 0
	v_mfma_f32_16x16x32_bf16 v[64:67], v[170:173], v[208:211], 0
	v_mfma_f32_16x16x32_bf16 v[108:111], v[166:169], v[188:191], v[108:111]
	v_mfma_f32_16x16x32_bf16 v[104:107], v[174:177], v[188:191], v[104:107]
	v_mfma_f32_16x16x32_bf16 v[92:95], v[166:169], v[196:199], v[92:95]
	v_mfma_f32_16x16x32_bf16 v[88:91], v[174:177], v[196:199], v[88:91]
	v_mfma_f32_16x16x32_bf16 v[76:79], v[166:169], v[204:207], v[76:79]
	v_mfma_f32_16x16x32_bf16 v[72:75], v[174:177], v[204:207], v[72:75]
	v_mfma_f32_16x16x32_bf16 v[68:71], v[166:169], v[212:215], v[68:71]
	v_mfma_f32_16x16x32_bf16 v[64:67], v[174:177], v[212:215], v[64:67]
	s_setprio 0
	s_barrier
	s_mov_b32 m0, s54
	v_lshl_add_u64 v[182:183], s[14:15], 0, v[132:133]
	s_add_u32 s82, s14, 0x20000
	ds_read_b128 v[178:181], v142 offset:16384
	ds_read_b128 v[188:191], v142 offset:17408
	ds_read_b128 v[192:195], v142 offset:18432
	ds_read_b128 v[196:199], v142 offset:19456
	ds_read_b128 v[200:203], v142 offset:20480
	ds_read_b128 v[204:207], v142 offset:21504
	ds_read_b128 v[208:211], v142 offset:22528
	ds_read_b128 v[212:215], v142 offset:23552
	global_load_lds_dwordx4 v[182:183], off
	v_lshl_add_u64 v[184:185], s[14:15], 0, v[128:129]
	s_mov_b32 m0, s55
	s_addc_u32 s83, s15, 0
	global_load_lds_dwordx4 v[184:185], off
	v_lshl_add_u64 v[186:187], s[82:83], 0, v[132:133]
	s_mov_b32 m0, s56
	v_lshl_add_u64 v[216:217], s[38:39], 0, v[130:131]
	global_load_lds_dwordx4 v[186:187], off
	v_lshl_add_u64 v[186:187], s[82:83], 0, v[128:129]
	s_mov_b32 m0, s57
	s_nop 0
	global_load_lds_dwordx4 v[186:187], off
	v_lshl_add_u64 v[186:187], s[38:39], 0, v[134:135]
	s_mov_b32 m0, s41
	s_nop 0
	global_load_lds_dwordx4 v[186:187], off
	s_mov_b32 m0, s43
	s_nop 0
	global_load_lds_dwordx4 v[216:217], off
	s_cmp_lg_u32 s100, 0
	s_cbranch_scc0 .Lrf_445_1
	s_waitcnt vmcnt(16)
	s_branch .Lrj_445_1

; #define G_STAGE(bufoff, gbase, voff) do { _Pragma("unroll") for (int _i = 0; _i < 2; ++_i) \
;         __builtin_amdgcn_global_load_lds((const unsigned*)((const char*)(gbase) + voff[_i]), (LAS unsigned*)(lds + (bufoff) + ldsw + _i * 8192), 16, 0, 0); } while (0)
; #define G_LDA(dst, b, h) do { _Pragma("unroll") for (int m = 0; m < 4; ++m) _Pragma("unroll") for (int k = 0; k < 2; ++k) dst[m][k] = *(const LAS bf16x8*)(lds + G_SA(b, h) + aoff + m * 2048 + k * 1024); } while (0)
; #define G_LDB(dst, b, h) do { _Pragma("unroll") for (int n = 0; n < 2; ++n) _Pragma("unroll") for (int k = 0; k < 2; ++k) dst[n][k] = *(const LAS bf16x8*)(lds + G_SB(b, h) + boff + n * 2048 + k * 1024); } while (0)
; #define G_MMA(ai, bj, At_, Bt_) do { __builtin_amdgcn_s_setprio(1); _Pragma("unroll") for (int m = 0; m < 4; ++m) _Pragma("unroll") for (int n = 0; n < 2; ++n) _Pragma("unroll") for (int k = 0; k < 2; ++k) \
;         acc[ai][bj][m][n] = __builtin_amdgcn_mfma_f32_16x16x32_bf16(Bt_[n][k], At_[m][k], acc[ai][bj][m][n], 0, 0, 0); __builtin_amdgcn_s_setprio(0); } while (0)
; #define WAIT_V(n) asm volatile("s_waitcnt vmcnt(" #n ")" ::: "memory")
; #define WAIT_L(n) asm volatile("s_waitcnt lgkmcnt(" #n ")" ::: "memory")
; #define BAR __builtin_amdgcn_s_barrier()
; #define SCHED __builtin_amdgcn_sched_barrier(0)
; template <class Get, class Epi>
; DI void gemm_loop(int ntiles, int ld, char* shm, const Get& get, const Epi& epi) {
;     ...
;             WAIT_V(8); WAIT_L(0); BAR; G_MMA(1, 0, At, B0); G_MMA(1, 1, At, B1); BAR; SCHED;
;             G_LDB(B0, 1, 0); G_LDB(B1, 1, 1); SCHED; G_LDA(At, 1, 0); G_STAGE(G_SA(0, 1), a2 + hstep, voffA);
;             WAIT_V(8); WAIT_L(0); BAR; G_MMA(0, 0, At, B0); G_MMA(0, 1, At, B1); BAR; SCHED;
.Lrj_445_1:
	s_waitcnt lgkmcnt(0)
	s_barrier
	s_setprio 1
	s_waitcnt lgkmcnt(0)
	v_mfma_f32_16x16x32_bf16 v[60:63], v[146:149], v[178:181], 0
	v_mfma_f32_16x16x32_bf16 v[56:59], v[154:157], v[178:181], 0
	v_mfma_f32_16x16x32_bf16 v[52:55], v[146:149], v[192:195], 0
	v_mfma_f32_16x16x32_bf16 v[48:51], v[154:157], v[192:195], 0
	v_mfma_f32_16x16x32_bf16 v[36:39], v[146:149], v[200:203], 0
	v_mfma_f32_16x16x32_bf16 v[32:35], v[154:157], v[200:203], 0
	v_mfma_f32_16x16x32_bf16 v[20:23], v[146:149], v[208:211], 0
	v_mfma_f32_16x16x32_bf16 v[16:19], v[154:157], v[208:211], 0
	v_mfma_f32_16x16x32_bf16 v[60:63], v[150:153], v[188:191], v[60:63]
	v_mfma_f32_16x16x32_bf16 v[56:59], v[158:161], v[188:191], v[56:59]
	v_mfma_f32_16x16x32_bf16 v[52:55], v[150:153], v[196:199], v[52:55]
	v_mfma_f32_16x16x32_bf16 v[48:51], v[158:161], v[196:199], v[48:51]
	v_mfma_f32_16x16x32_bf16 v[36:39], v[150:153], v[204:207], v[36:39]
	v_mfma_f32_16x16x32_bf16 v[32:35], v[158:161], v[204:207], v[32:35]
	v_mfma_f32_16x16x32_bf16 v[20:23], v[150:153], v[212:215], v[20:23]
	v_mfma_f32_16x16x32_bf16 v[16:19], v[158:161], v[212:215], v[16:19]
	s_setprio 0
	s_setprio 1
	v_mfma_f32_16x16x32_bf16 v[44:47], v[162:165], v[178:181], 0
	v_mfma_f32_16x16x32_bf16 v[40:43], v[170:173], v[178:181], 0
	v_mfma_f32_16x16x32_bf16 v[28:31], v[162:165], v[192:195], 0
	v_mfma_f32_16x16x32_bf16 v[24:27], v[170:173], v[192:195], 0
	v_mfma_f32_16x16x32_bf16 v[12:15], v[162:165], v[200:203], 0
	v_mfma_f32_16x16x32_bf16 v[8:11], v[170:173], v[200:203], 0
	v_mfma_f32_16x16x32_bf16 v[4:7], v[162:165], v[208:211], 0
	v_mfma_f32_16x16x32_bf16 v[0:3], v[170:173], v[208:211], 0
	v_mfma_f32_16x16x32_bf16 v[44:47], v[166:169], v[188:191], v[44:47]
	v_mfma_f32_16x16x32_bf16 v[40:43], v[174:177], v[188:191], v[40:43]
	v_mfma_f32_16x16x32_bf16 v[28:31], v[166:169], v[196:199], v[28:31]
	v_mfma_f32_16x16x32_bf16 v[24:27], v[174:177], v[196:199], v[24:27]
	v_mfma_f32_16x16x32_bf16 v[12:15], v[166:169], v[204:207], v[12:15]
	v_mfma_f32_16x16x32_bf16 v[8:11], v[174:177], v[204:207], v[8:11]
	v_mfma_f32_16x16x32_bf16 v[4:7], v[166:169], v[212:215], v[4:7]
	v_mfma_f32_16x16x32_bf16 v[0:3], v[174:177], v[212:215], v[0:3]
	s_setprio 0
	s_barrier
	ds_read_b128 v[146:149], v143
	ds_read_b128 v[150:153], v143 offset:1024
	ds_read_b128 v[154:157], v143 offset:2048
	ds_read_b128 v[158:161], v143 offset:3072
	ds_read_b128 v[162:165], v144
	ds_read_b128 v[166:169], v144 offset:1024
	ds_read_b128 v[170:173], v144 offset:2048
	ds_read_b128 v[174:177], v144 offset:3072
	s_add_u32 s38, s38, 0x20000
	s_addc_u32 s39, s39, 0
	s_mov_b32 m0, s44
	v_lshl_add_u64 v[218:219], s[38:39], 0, v[134:135]
	ds_read_b128 v[178:181], v142 offset:32768
	ds_read_b128 v[188:191], v142 offset:33792
	ds_read_b128 v[192:195], v142 offset:34816
	ds_read_b128 v[196:199], v142 offset:35840
	ds_read_b128 v[200:203], v142 offset:36864
	ds_read_b128 v[204:207], v142 offset:37888
	ds_read_b128 v[208:211], v142 offset:38912
	ds_read_b128 v[212:215], v142 offset:39936
	global_load_lds_dwordx4 v[218:219], off
	v_lshl_add_u64 v[218:219], s[38:39], 0, v[130:131]
	s_mov_b32 m0, s45
	s_nop 0
	global_load_lds_dwordx4 v[218:219], off
	s_waitcnt vmcnt(8)
	s_waitcnt lgkmcnt(0)
	s_barrier
	s_setprio 1
	s_waitcnt lgkmcnt(0)
	v_mfma_f32_16x16x32_bf16 v[124:127], v[146:149], v[178:181], v[124:127]
	v_mfma_f32_16x16x32_bf16 v[120:123], v[154:157], v[178:181], v[120:123]
	v_mfma_f32_16x16x32_bf16 v[116:119], v[146:149], v[192:195], v[116:119]
	v_mfma_f32_16x16x32_bf16 v[112:115], v[154:157], v[192:195], v[112:115]
	v_mfma_f32_16x16x32_bf16 v[100:103], v[146:149], v[200:203], v[100:103]
	v_mfma_f32_16x16x32_bf16 v[96:99], v[154:157], v[200:203], v[96:99]
	v_mfma_f32_16x16x32_bf16 v[84:87], v[146:149], v[208:211], v[84:87]
	v_mfma_f32_16x16x32_bf16 v[80:83], v[154:157], v[208:211], v[80:83]
	v_mfma_f32_16x16x32_bf16 v[124:127], v[150:153], v[188:191], v[124:127]
	v_mfma_f32_16x16x32_bf16 v[120:123], v[158:161], v[188:191], v[120:123]
	v_mfma_f32_16x16x32_bf16 v[116:119], v[150:153], v[196:199], v[116:119]
	v_mfma_f32_16x16x32_bf16 v[112:115], v[158:161], v[196:199], v[112:115]
	v_mfma_f32_16x16x32_bf16 v[100:103], v[150:153], v[204:207], v[100:103]
	v_mfma_f32_16x16x32_bf16 v[96:99], v[158:161], v[204:207], v[96:99]
	v_mfma_f32_16x16x32_bf16 v[84:87], v[150:153], v[212:215], v[84:87]
	v_mfma_f32_16x16x32_bf16 v[80:83], v[158:161], v[212:215], v[80:83]
	s_setprio 0
	s_setprio 1
	v_mfma_f32_16x16x32_bf16 v[108:111], v[162:165], v[178:181], v[108:111]
	v_mfma_f32_16x16x32_bf16 v[104:107], v[170:173], v[178:181], v[104:107]
	v_mfma_f32_16x16x32_bf16 v[92:95], v[162:165], v[192:195], v[92:95]
	v_mfma_f32_16x16x32_bf16 v[88:91], v[170:173], v[192:195], v[88:91]
	v_mfma_f32_16x16x32_bf16 v[76:79], v[162:165], v[200:203], v[76:79]
	v_mfma_f32_16x16x32_bf16 v[72:75], v[170:173], v[200:203], v[72:75]
	v_mfma_f32_16x16x32_bf16 v[68:71], v[162:165], v[208:211], v[68:71]
	v_mfma_f32_16x16x32_bf16 v[64:67], v[170:173], v[208:211], v[64:67]
	v_mfma_f32_16x16x32_bf16 v[108:111], v[166:169], v[188:191], v[108:111]
	v_mfma_f32_16x16x32_bf16 v[104:107], v[174:177], v[188:191], v[104:107]
	v_mfma_f32_16x16x32_bf16 v[92:95], v[166:169], v[196:199], v[92:95]
	v_mfma_f32_16x16x32_bf16 v[88:91], v[174:177], v[196:199], v[88:91]
	v_mfma_f32_16x16x32_bf16 v[76:79], v[166:169], v[204:207], v[76:79]
	v_mfma_f32_16x16x32_bf16 v[72:75], v[174:177], v[204:207], v[72:75]
	v_mfma_f32_16x16x32_bf16 v[68:71], v[166:169], v[212:215], v[68:71]
	v_mfma_f32_16x16x32_bf16 v[64:67], v[174:177], v[212:215], v[64:67]
	s_setprio 0
	s_barrier
; #define G_STAGE(bufoff, gbase, voff) do { _Pragma("unroll") for (int _i = 0; _i < 2; ++_i) \
;         __builtin_amdgcn_global_load_lds((const unsigned*)((const char*)(gbase) + voff[_i]), (LAS unsigned*)(lds + (bufoff) + ldsw + _i * 8192), 16, 0, 0); } while (0)
; #define G_LDA(dst, b, h) do { _Pragma("unroll") for (int m = 0; m < 4; ++m) _Pragma("unroll") for (int k = 0; k < 2; ++k) dst[m][k] = *(const LAS bf16x8*)(lds + G_SA(b, h) + aoff + m * 2048 + k * 1024); } while (0)
; #define G_MMA(ai, bj, At_, Bt_) do { __builtin_amdgcn_s_setprio(1); _Pragma("unroll") for (int m = 0; m < 4; ++m) _Pragma("unroll") for (int n = 0; n < 2; ++n) _Pragma("unroll") for (int k = 0; k < 2; ++k) \
;         acc[ai][bj][m][n] = __builtin_amdgcn_mfma_f32_16x16x32_bf16(Bt_[n][k], At_[m][k], acc[ai][bj][m][n], 0, 0, 0); __builtin_amdgcn_s_setprio(0); } while (0)
; #define WAIT_V(n) asm volatile("s_waitcnt vmcnt(" #n ")" ::: "memory")
; #define WAIT_L(n) asm volatile("s_waitcnt lgkmcnt(" #n ")" ::: "memory")
; #define BAR __builtin_amdgcn_s_barrier()
; #define SCHED __builtin_amdgcn_sched_barrier(0)
; template <class Get, class Epi>
; DI void gemm_loop(int ntiles, int ld, char* shm, const Get& get, const Epi& epi) {
;     ...
;             G_LDA(At, 1, 1); G_STAGE(G_SB(1, 0), b3, voffB); G_STAGE(G_SB(1, 1), b3 + hstep, voffB); G_STAGE(G_SA(1, 0), a3, voffA);
;             WAIT_V(8); WAIT_L(0); BAR; G_MMA(1, 0, At, B0); G_MMA(1, 1, At, B1); BAR; SCHED;
;         }
	s_mov_b32 m0, s58
	v_lshl_add_u64 v[182:183], v[182:183], 0, s[12:13]
	s_add_u32 s14, s14, 0x20080
	ds_read_b128 v[178:181], v142 offset:49152
	ds_read_b128 v[188:191], v142 offset:50176
	ds_read_b128 v[192:195], v142 offset:51200
	ds_read_b128 v[196:199], v142 offset:52224
	ds_read_b128 v[200:203], v142 offset:53248
	ds_read_b128 v[204:207], v142 offset:54272
	ds_read_b128 v[208:211], v142 offset:55296
	ds_read_b128 v[212:215], v142 offset:56320
	global_load_lds_dwordx4 v[182:183], off
	v_lshl_add_u64 v[182:183], v[184:185], 0, s[12:13]
	s_mov_b32 m0, s59
	s_addc_u32 s15, s15, 0
	global_load_lds_dwordx4 v[182:183], off
	v_lshl_add_u64 v[182:183], s[14:15], 0, v[132:133]
	s_mov_b32 m0, s72
	s_nop 0
	global_load_lds_dwordx4 v[182:183], off
	v_lshl_add_u64 v[182:183], s[14:15], 0, v[128:129]
	s_mov_b32 m0, s73
	s_nop 0
	global_load_lds_dwordx4 v[182:183], off
	v_lshl_add_u64 v[182:183], v[186:187], 0, s[12:13]
	s_mov_b32 m0, s46
	s_nop 0
	global_load_lds_dwordx4 v[182:183], off
	v_lshl_add_u64 v[182:183], v[216:217], 0, s[12:13]
	s_mov_b32 m0, s47
	s_nop 0
	global_load_lds_dwordx4 v[182:183], off
	s_waitcnt vmcnt(8)
	s_waitcnt lgkmcnt(0)
	s_barrier
	s_setprio 1
	s_waitcnt lgkmcnt(0)
	v_mfma_f32_16x16x32_bf16 v[60:63], v[146:149], v[178:181], v[60:63]
	v_mfma_f32_16x16x32_bf16 v[56:59], v[154:157], v[178:181], v[56:59]
	v_mfma_f32_16x16x32_bf16 v[52:55], v[146:149], v[192:195], v[52:55]
	v_mfma_f32_16x16x32_bf16 v[48:51], v[154:157], v[192:195], v[48:51]
	v_mfma_f32_16x16x32_bf16 v[36:39], v[146:149], v[200:203], v[36:39]
	v_mfma_f32_16x16x32_bf16 v[32:35], v[154:157], v[200:203], v[32:35]
	v_mfma_f32_16x16x32_bf16 v[20:23], v[146:149], v[208:211], v[20:23]
	v_mfma_f32_16x16x32_bf16 v[16:19], v[154:157], v[208:211], v[16:19]
	v_mfma_f32_16x16x32_bf16 v[60:63], v[150:153], v[188:191], v[60:63]
	v_mfma_f32_16x16x32_bf16 v[56:59], v[158:161], v[188:191], v[56:59]
	v_mfma_f32_16x16x32_bf16 v[52:55], v[150:153], v[196:199], v[52:55]
	v_mfma_f32_16x16x32_bf16 v[48:51], v[158:161], v[196:199], v[48:51]
	v_mfma_f32_16x16x32_bf16 v[36:39], v[150:153], v[204:207], v[36:39]
	v_mfma_f32_16x16x32_bf16 v[32:35], v[158:161], v[204:207], v[32:35]
	v_mfma_f32_16x16x32_bf16 v[20:23], v[150:153], v[212:215], v[20:23]
	v_mfma_f32_16x16x32_bf16 v[16:19], v[158:161], v[212:215], v[16:19]
	s_setprio 0
	s_setprio 1
	v_mfma_f32_16x16x32_bf16 v[44:47], v[162:165], v[178:181], v[44:47]
	v_mfma_f32_16x16x32_bf16 v[40:43], v[170:173], v[178:181], v[40:43]
	v_mfma_f32_16x16x32_bf16 v[28:31], v[162:165], v[192:195], v[28:31]
	v_mfma_f32_16x16x32_bf16 v[24:27], v[170:173], v[192:195], v[24:27]
	v_mfma_f32_16x16x32_bf16 v[12:15], v[162:165], v[200:203], v[12:15]
	v_mfma_f32_16x16x32_bf16 v[8:11], v[170:173], v[200:203], v[8:11]
	v_mfma_f32_16x16x32_bf16 v[4:7], v[162:165], v[208:211], v[4:7]
	v_mfma_f32_16x16x32_bf16 v[0:3], v[170:173], v[208:211], v[0:3]
	v_mfma_f32_16x16x32_bf16 v[44:47], v[166:169], v[188:191], v[44:47]
	v_mfma_f32_16x16x32_bf16 v[40:43], v[174:177], v[188:191], v[40:43]
	v_mfma_f32_16x16x32_bf16 v[28:31], v[166:169], v[196:199], v[28:31]
	v_mfma_f32_16x16x32_bf16 v[24:27], v[174:177], v[196:199], v[24:27]
	v_mfma_f32_16x16x32_bf16 v[12:15], v[166:169], v[204:207], v[12:15]
	v_mfma_f32_16x16x32_bf16 v[8:11], v[174:177], v[204:207], v[8:11]
	v_mfma_f32_16x16x32_bf16 v[4:7], v[166:169], v[212:215], v[4:7]
	v_mfma_f32_16x16x32_bf16 v[0:3], v[174:177], v[212:215], v[0:3]
	s_setprio 0
	s_barrier
	s_add_i32 s81, s81, 2
	s_add_u32 s36, s36, 0x100
	s_addc_u32 s37, s37, 0
	s_add_u32 s79, s79, 0x100
	s_addc_u32 s80, s80, 0
	s_cmp_gt_u32 s81, 5
	s_cbranch_scc0 .LBB0_445
	s_branch .Lpost_445

; #define BAR __builtin_amdgcn_s_barrier()
; template <class Get, class Epi>
; DI void gemm_loop(int ntiles, int ld, char* shm, const Get& get, const Epi& epi) {
;     ...
;         }
;         if (wr == 0) BAR;
.Lpost_445:
	s_mov_b32 s100, 1
	s_and_b64 vcc, exec, s[28:29]
	s_cbranch_vccz .LBB0_448
	s_barrier

; #define G_STAGE(bufoff, gbase, voff) do { _Pragma("unroll") for (int _i = 0; _i < 2; ++_i) \
;         __builtin_amdgcn_global_load_lds((const unsigned*)((const char*)(gbase) + voff[_i]), (LAS unsigned*)(lds + (bufoff) + ldsw + _i * 8192), 16, 0, 0); } while (0)
; #define WAIT_V(n) asm volatile("s_waitcnt vmcnt(" #n ")" ::: "memory")
; #define BAR __builtin_amdgcn_s_barrier()
; template <class Get, class Epi>
; DI void gemm_loop(int ntiles, int ld, char* shm, const Get& get, const Epi& epi) {
;     ...
;     for (int i = 0; i < 2; ++i) { int R, C; stage_rc(tid * 16 + i * 8192, R, C); const int rho = R & 31, Rb = (R & ~31) + 8 * ((rho & 15) >> 2) + 4 * (rho >> 4) + (rho & 3);
;         voffA[i] = (unsigned)(R * ld + C) * 2u; voffB[i] = (unsigned)(Rb * ld + C) * 2u; }
;     const size_t kstep = (size_t)(BK * 2), hstep = (size_t)HALF * ld * 2;
;     const unsigned ldsw = (unsigned)wid * 1024u;
;     const int aoff = lds_byte(wr * 64 + fr, fq * 8), boff = lds_byte(wc * 32 + fr, fq * 8);
;     ...
;     int L = bx; if (L >= ntiles) return;
;     Tile cur = get(L), nxt = cur;
;     AccT acc;
;     ...
;     G_ZERO;
;     bf16x8 At[4][2], B0[2][2], B1[2][2];
;     const char* cA = (const char*)cur.A + (size_t)cur.brow * ld * 2; const char* cB = (const char*)cur.Bt + (size_t)cur.bcol * ld * 2;
;     G_STAGE(G_SB(0, 0), cB, voffB); G_STAGE(G_SB(0, 1), cB + hstep, voffB); G_STAGE(G_SA(0, 0), cA, voffA); G_STAGE(G_SA(0, 1), cA + hstep, voffA);
;     if (wr == 1) BAR;
;     WAIT_V(2); BAR;
;     G_STAGE(G_SB(1, 0), cB + kstep, voffB); G_STAGE(G_SA(1, 0), cA + kstep, voffA); G_STAGE(G_SB(1, 1), cB + hstep + kstep, voffB);
;     WAIT_V(6); BAR;
.LBB0_515:
	v_and_b32_e32 v15, 15, v8
	s_add_u32 s73, s68, 0x802000
	v_and_b32_e32 v16, 48, v8
	v_lshlrev_b32_e32 v15, 6, v15
	v_lshlrev_b32_e32 v8, 2, v8
	s_addc_u32 s74, s69, 0
	v_or_b32_e32 v17, v15, v16
	s_lshl_b32 s3, s10, 13
	v_and_b32_e32 v8, 32, v8
	v_bitop3_b32 v15, v15, v8, v16 bitop3:0x36
	v_bitop3_b32 v8, v17, s3, v8 bitop3:0xde
	s_lshl_b32 s3, s11, 12
	s_mov_b64 s[10:11], 0x80
	s_add_i32 m0, s57, 0x18000
	v_lshl_add_u64 v[6:7], v[6:7], 0, s[10:11]
	s_and_b32 s3, s3, 0x3000
	s_waitcnt vmcnt(2)
	s_barrier
	global_load_lds_dwordx4 v[6:7], off
	v_lshl_add_u64 v[4:5], v[4:5], 0, s[10:11]
	s_add_i32 m0, s57, 0x1a000
	s_add_i32 s75, s57, 0x8000
	s_add_i32 s76, s57, 0xa000
	global_load_lds_dwordx4 v[4:5], off
	v_lshl_add_u64 v[0:1], v[0:1], 0, s[10:11]
	s_mov_b32 m0, s75
	s_add_u32 s28, s14, 0x40080
	global_load_lds_dwordx4 v[0:1], off
	v_lshl_add_u64 v[0:1], v[2:3], 0, s[10:11]
	s_mov_b32 m0, s76
	s_addc_u32 s29, s15, 0
	global_load_lds_dwordx4 v[0:1], off
	s_add_i32 m0, s57, 0x1c000
	v_lshl_add_u64 v[0:1], s[28:29], 0, v[154:155]
	global_load_lds_dwordx4 v[0:1], off
	v_lshl_add_u64 v[0:1], s[28:29], 0, v[158:159]
	s_add_i32 m0, s57, 0x1e000
	s_cmpk_lt_u32 s12, 0x100
	global_load_lds_dwordx4 v[0:1], off
	v_lshlrev_b32_e32 v0, 14, v9
	v_and_b32_e32 v0, 0xffff8000, v0
	v_lshl_add_u32 v0, v10, 11, v0
	v_and_b32_e32 v1, 1, v9
	v_lshl_or_b32 v0, v1, 6, v0
	v_lshl_add_u32 v160, v11, 1, v0
	v_lshlrev_b32_e32 v0, 14, v12
	v_and_b32_e32 v0, 0xffff8000, v0
	s_waitcnt vmcnt(6)
	s_mov_b32 s100, 0
	s_cselect_b64 s[12:13], -1, 0
	s_add_u32 s88, s68, 0x832000
	v_lshl_add_u32 v0, v13, 11, v0
	v_and_b32_e32 v1, 1, v12
	v_or_b32_e32 v176, s3, v15
	s_addc_u32 s89, s69, 0
	v_lshl_or_b32 v0, v1, 6, v0
	s_add_i32 s78, 0, 0x10000
	s_add_i32 s79, 0, 0x14000
	v_mov_b32_e32 v161, v155
	v_lshl_add_u32 v162, v14, 1, v0
	v_mov_b32_e32 v163, v155
	v_add_u32_e32 v177, s78, v176
	v_add_u32_e32 v178, s79, v176
	v_add_u32_e32 v179, 0, v8
	s_mov_b32 s81, s46
	s_barrier
	s_branch .LBB0_518

; #define G_STAGE(bufoff, gbase, voff) do { _Pragma("unroll") for (int _i = 0; _i < 2; ++_i) \
;         __builtin_amdgcn_global_load_lds((const unsigned*)((const char*)(gbase) + voff[_i]), (LAS unsigned*)(lds + (bufoff) + ldsw + _i * 8192), 16, 0, 0); } while (0)
; #define G_LDA(dst, b, h) do { _Pragma("unroll") for (int m = 0; m < 4; ++m) _Pragma("unroll") for (int k = 0; k < 2; ++k) dst[m][k] = *(const LAS bf16x8*)(lds + G_SA(b, h) + aoff + m * 2048 + k * 1024); } while (0)
; #define G_LDB(dst, b, h) do { _Pragma("unroll") for (int n = 0; n < 2; ++n) _Pragma("unroll") for (int k = 0; k < 2; ++k) dst[n][k] = *(const LAS bf16x8*)(lds + G_SB(b, h) + boff + n * 2048 + k * 1024); } while (0)
; #define G_MMA(ai, bj, At_, Bt_) do { __builtin_amdgcn_s_setprio(1); _Pragma("unroll") for (int m = 0; m < 4; ++m) _Pragma("unroll") for (int n = 0; n < 2; ++n) _Pragma("unroll") for (int k = 0; k < 2; ++k) \
;         acc[ai][bj][m][n] = __builtin_amdgcn_mfma_f32_16x16x32_bf16(Bt_[n][k], At_[m][k], acc[ai][bj][m][n], 0, 0, 0); __builtin_amdgcn_s_setprio(0); } while (0)
; #define WAIT_V(n) asm volatile("s_waitcnt vmcnt(" #n ")" ::: "memory")
; #define WAIT_L(n) asm volatile("s_waitcnt lgkmcnt(" #n ")" ::: "memory")
; #define BAR __builtin_amdgcn_s_barrier()
; #define SCHED __builtin_amdgcn_sched_barrier(0)
; template <class Get, class Epi>
; DI void gemm_loop(int ntiles, int ld, char* shm, const Get& get, const Epi& epi) {
;     ...
;             const bool last = (t == nt - 2);
;             const char* a1 = cA + (size_t)(t + 1) * kstep;
;             const char* a2 = last ? nA : cA + (size_t)(t + 2) * kstep; const char* b2 = last ? nB : cB + (size_t)(t + 2) * kstep;
;             const char* a3 = a2 + kstep; const char* b3 = b2 + kstep;
;             G_LDB(B0, 0, 0); G_LDB(B1, 0, 1); SCHED; G_LDA(At, 0, 0); G_STAGE(G_SA(1, 1), a1 + hstep, voffA);
;             WAIT_V(8); WAIT_L(0); BAR; G_MMA(0, 0, At, B0); G_MMA(0, 1, At, B1); BAR; SCHED;
.Lpeel_528:
	ds_read_b128 v[128:131], v177
	ds_read_b128 v[132:135], v177 offset:1024
	ds_read_b128 v[136:139], v177 offset:2048
	ds_read_b128 v[140:143], v177 offset:3072
	ds_read_b128 v[144:147], v178
	ds_read_b128 v[148:151], v178 offset:1024
	ds_read_b128 v[164:167], v178 offset:2048
	ds_read_b128 v[168:171], v178 offset:3072
	s_add_i32 s83, s14, 2
	s_add_u32 s15, s44, 0xfffc0080
	s_addc_u32 s46, s45, -1
	s_cmp_eq_u32 s54, s14
	s_cselect_b32 s14, s43, s55
	s_cselect_b32 s47, s3, s46
	s_cselect_b32 s46, s35, s15
	s_cselect_b32 s15, s37, s82
	v_lshl_add_u64 v[184:185], s[44:45], 0, v[160:161]
	s_add_i32 m0, s57, 0xc000
	ds_read_b128 v[172:175], v179
	ds_read_b128 v[180:183], v179 offset:1024
	ds_read_b128 v[188:191], v179 offset:2048
	ds_read_b128 v[192:195], v179 offset:3072
	ds_read_b128 v[196:199], v179 offset:4096
	ds_read_b128 v[200:203], v179 offset:5120
	ds_read_b128 v[204:207], v179 offset:6144
	ds_read_b128 v[208:211], v179 offset:7168
	global_load_lds_dwordx4 v[184:185], off
	v_lshl_add_u64 v[184:185], s[44:45], 0, v[162:163]
	s_add_i32 m0, s57, 0xe000
	s_nop 0
	global_load_lds_dwordx4 v[184:185], off
	s_cmp_lg_u32 s100, 0
	s_cbranch_scc0 .Lrf_528_0
	s_waitcnt vmcnt(16)
	s_branch .Lrj_528_0

; #define G_STAGE(bufoff, gbase, voff) do { _Pragma("unroll") for (int _i = 0; _i < 2; ++_i) \
;         __builtin_amdgcn_global_load_lds((const unsigned*)((const char*)(gbase) + voff[_i]), (LAS unsigned*)(lds + (bufoff) + ldsw + _i * 8192), 16, 0, 0); } while (0)
; #define G_LDA(dst, b, h) do { _Pragma("unroll") for (int m = 0; m < 4; ++m) _Pragma("unroll") for (int k = 0; k < 2; ++k) dst[m][k] = *(const LAS bf16x8*)(lds + G_SA(b, h) + aoff + m * 2048 + k * 1024); } while (0)
; #define G_MMA(ai, bj, At_, Bt_) do { __builtin_amdgcn_s_setprio(1); _Pragma("unroll") for (int m = 0; m < 4; ++m) _Pragma("unroll") for (int n = 0; n < 2; ++n) _Pragma("unroll") for (int k = 0; k < 2; ++k) \
;         acc[ai][bj][m][n] = __builtin_amdgcn_mfma_f32_16x16x32_bf16(Bt_[n][k], At_[m][k], acc[ai][bj][m][n], 0, 0, 0); __builtin_amdgcn_s_setprio(0); } while (0)
; #define WAIT_V(n) asm volatile("s_waitcnt vmcnt(" #n ")" ::: "memory")
; #define WAIT_L(n) asm volatile("s_waitcnt lgkmcnt(" #n ")" ::: "memory")
; #define BAR __builtin_amdgcn_s_barrier()
; #define SCHED __builtin_amdgcn_sched_barrier(0)
; template <class Get, class Epi>
; DI void gemm_loop(int ntiles, int ld, char* shm, const Get& get, const Epi& epi) {
;     ...
;             WAIT_V(8); WAIT_L(0); BAR; G_MMA(0, 0, At, B0); G_MMA(0, 1, At, B1); BAR; SCHED;
;             G_LDA(At, 0, 1); G_STAGE(G_SB(0, 0), b2, voffB); G_STAGE(G_SB(0, 1), b2 + hstep, voffB); G_STAGE(G_SA(0, 0), a2, voffA);
;             WAIT_V(8); WAIT_L(0); BAR; G_MMA(1, 0, At, B0); G_MMA(1, 1, At, B1); BAR; SCHED;
.Lrj_528_0:
	s_waitcnt lgkmcnt(0)
	s_barrier
	s_setprio 1
	s_waitcnt lgkmcnt(0)
	v_mfma_f32_16x16x32_bf16 v[124:127], v[128:131], v[172:175], 0
	v_mfma_f32_16x16x32_bf16 v[120:123], v[136:139], v[172:175], 0
	v_mfma_f32_16x16x32_bf16 v[116:119], v[128:131], v[188:191], 0
	v_mfma_f32_16x16x32_bf16 v[112:115], v[136:139], v[188:191], 0
	v_mfma_f32_16x16x32_bf16 v[108:111], v[128:131], v[196:199], 0
	v_mfma_f32_16x16x32_bf16 v[104:107], v[136:139], v[196:199], 0
	v_mfma_f32_16x16x32_bf16 v[100:103], v[128:131], v[204:207], 0
	v_mfma_f32_16x16x32_bf16 v[96:99], v[136:139], v[204:207], 0
	v_mfma_f32_16x16x32_bf16 v[124:127], v[132:135], v[180:183], v[124:127]
	v_mfma_f32_16x16x32_bf16 v[120:123], v[140:143], v[180:183], v[120:123]
	v_mfma_f32_16x16x32_bf16 v[116:119], v[132:135], v[192:195], v[116:119]
	v_mfma_f32_16x16x32_bf16 v[112:115], v[140:143], v[192:195], v[112:115]
	v_mfma_f32_16x16x32_bf16 v[108:111], v[132:135], v[200:203], v[108:111]
	v_mfma_f32_16x16x32_bf16 v[104:107], v[140:143], v[200:203], v[104:107]
	v_mfma_f32_16x16x32_bf16 v[100:103], v[132:135], v[208:211], v[100:103]
	v_mfma_f32_16x16x32_bf16 v[96:99], v[140:143], v[208:211], v[96:99]
	s_setprio 0
	s_setprio 1
	v_mfma_f32_16x16x32_bf16 v[60:63], v[144:147], v[172:175], 0
	v_mfma_f32_16x16x32_bf16 v[56:59], v[164:167], v[172:175], 0
	v_mfma_f32_16x16x32_bf16 v[52:55], v[144:147], v[188:191], 0
	v_mfma_f32_16x16x32_bf16 v[48:51], v[164:167], v[188:191], 0
	v_mfma_f32_16x16x32_bf16 v[44:47], v[144:147], v[196:199], 0
	v_mfma_f32_16x16x32_bf16 v[40:43], v[164:167], v[196:199], 0
	v_mfma_f32_16x16x32_bf16 v[36:39], v[144:147], v[204:207], 0
	v_mfma_f32_16x16x32_bf16 v[32:35], v[164:167], v[204:207], 0
	v_mfma_f32_16x16x32_bf16 v[60:63], v[148:151], v[180:183], v[60:63]
	v_mfma_f32_16x16x32_bf16 v[56:59], v[168:171], v[180:183], v[56:59]
	v_mfma_f32_16x16x32_bf16 v[52:55], v[148:151], v[192:195], v[52:55]
	v_mfma_f32_16x16x32_bf16 v[48:51], v[168:171], v[192:195], v[48:51]
	v_mfma_f32_16x16x32_bf16 v[44:47], v[148:151], v[200:203], v[44:47]
	v_mfma_f32_16x16x32_bf16 v[40:43], v[168:171], v[200:203], v[40:43]
	v_mfma_f32_16x16x32_bf16 v[36:39], v[148:151], v[208:211], v[36:39]
	v_mfma_f32_16x16x32_bf16 v[32:35], v[168:171], v[208:211], v[32:35]
	s_setprio 0
	s_barrier
	s_add_i32 s84, s78, s56
	v_lshl_add_u64 v[184:185], s[14:15], 0, v[154:155]
	s_mov_b32 m0, s84
	ds_read_b128 v[172:175], v179 offset:16384
	ds_read_b128 v[180:183], v179 offset:17408
	ds_read_b128 v[188:191], v179 offset:18432
	ds_read_b128 v[192:195], v179 offset:19456
	ds_read_b128 v[196:199], v179 offset:20480
	ds_read_b128 v[200:203], v179 offset:21504
	ds_read_b128 v[204:207], v179 offset:22528
	ds_read_b128 v[208:211], v179 offset:23552
	global_load_lds_dwordx4 v[184:185], off
	s_add_i32 m0, s84, 0x2000
	s_add_u32 s84, s14, 0x40000
	v_lshl_add_u64 v[186:187], s[14:15], 0, v[158:159]
	s_addc_u32 s85, s15, 0
	s_add_i32 s86, s79, s56
	global_load_lds_dwordx4 v[186:187], off
	v_lshl_add_u64 v[212:213], s[84:85], 0, v[154:155]
	s_mov_b32 m0, s86
	v_lshl_add_u64 v[214:215], s[46:47], 0, v[156:157]
	global_load_lds_dwordx4 v[212:213], off
	v_lshl_add_u64 v[212:213], s[84:85], 0, v[158:159]
	s_add_i32 m0, s86, 0x2000
	s_nop 0
	global_load_lds_dwordx4 v[212:213], off
	v_lshl_add_u64 v[212:213], s[46:47], 0, v[152:153]
	s_mov_b32 m0, s57
	s_nop 0
	global_load_lds_dwordx4 v[212:213], off
	s_mov_b32 m0, s58
	s_nop 0
	global_load_lds_dwordx4 v[214:215], off
	s_cmp_lg_u32 s100, 0
	s_cbranch_scc0 .Lrf_528_1
	s_waitcnt vmcnt(16)
	s_branch .Lrj_528_1

; #define G_STAGE(bufoff, gbase, voff) do { _Pragma("unroll") for (int _i = 0; _i < 2; ++_i) \
;         __builtin_amdgcn_global_load_lds((const unsigned*)((const char*)(gbase) + voff[_i]), (LAS unsigned*)(lds + (bufoff) + ldsw + _i * 8192), 16, 0, 0); } while (0)
; #define G_LDA(dst, b, h) do { _Pragma("unroll") for (int m = 0; m < 4; ++m) _Pragma("unroll") for (int k = 0; k < 2; ++k) dst[m][k] = *(const LAS bf16x8*)(lds + G_SA(b, h) + aoff + m * 2048 + k * 1024); } while (0)
; #define G_LDB(dst, b, h) do { _Pragma("unroll") for (int n = 0; n < 2; ++n) _Pragma("unroll") for (int k = 0; k < 2; ++k) dst[n][k] = *(const LAS bf16x8*)(lds + G_SB(b, h) + boff + n * 2048 + k * 1024); } while (0)
; #define G_MMA(ai, bj, At_, Bt_) do { __builtin_amdgcn_s_setprio(1); _Pragma("unroll") for (int m = 0; m < 4; ++m) _Pragma("unroll") for (int n = 0; n < 2; ++n) _Pragma("unroll") for (int k = 0; k < 2; ++k) \
;         acc[ai][bj][m][n] = __builtin_amdgcn_mfma_f32_16x16x32_bf16(Bt_[n][k], At_[m][k], acc[ai][bj][m][n], 0, 0, 0); __builtin_amdgcn_s_setprio(0); } while (0)
; #define WAIT_V(n) asm volatile("s_waitcnt vmcnt(" #n ")" ::: "memory")
; #define WAIT_L(n) asm volatile("s_waitcnt lgkmcnt(" #n ")" ::: "memory")
; #define BAR __builtin_amdgcn_s_barrier()
; #define SCHED __builtin_amdgcn_sched_barrier(0)
; template <class Get, class Epi>
; DI void gemm_loop(int ntiles, int ld, char* shm, const Get& get, const Epi& epi) {
;     ...
;             WAIT_V(8); WAIT_L(0); BAR; G_MMA(1, 0, At, B0); G_MMA(1, 1, At, B1); BAR; SCHED;
;             G_LDB(B0, 1, 0); G_LDB(B1, 1, 1); SCHED; G_LDA(At, 1, 0); G_STAGE(G_SA(0, 1), a2 + hstep, voffA);
;             WAIT_V(8); WAIT_L(0); BAR; G_MMA(0, 0, At, B0); G_MMA(0, 1, At, B1); BAR; SCHED;
.Lrj_528_1:
	s_waitcnt lgkmcnt(0)
	s_barrier
	s_setprio 1
	s_waitcnt lgkmcnt(0)
	v_mfma_f32_16x16x32_bf16 v[92:95], v[128:131], v[172:175], 0
	v_mfma_f32_16x16x32_bf16 v[88:91], v[136:139], v[172:175], 0
	v_mfma_f32_16x16x32_bf16 v[84:87], v[128:131], v[188:191], 0
	v_mfma_f32_16x16x32_bf16 v[80:83], v[136:139], v[188:191], 0
	v_mfma_f32_16x16x32_bf16 v[76:79], v[128:131], v[196:199], 0
	v_mfma_f32_16x16x32_bf16 v[72:75], v[136:139], v[196:199], 0
	v_mfma_f32_16x16x32_bf16 v[68:71], v[128:131], v[204:207], 0
	v_mfma_f32_16x16x32_bf16 v[64:67], v[136:139], v[204:207], 0
	v_mfma_f32_16x16x32_bf16 v[92:95], v[132:135], v[180:183], v[92:95]
	v_mfma_f32_16x16x32_bf16 v[88:91], v[140:143], v[180:183], v[88:91]
	v_mfma_f32_16x16x32_bf16 v[84:87], v[132:135], v[192:195], v[84:87]
	v_mfma_f32_16x16x32_bf16 v[80:83], v[140:143], v[192:195], v[80:83]
	v_mfma_f32_16x16x32_bf16 v[76:79], v[132:135], v[200:203], v[76:79]
	v_mfma_f32_16x16x32_bf16 v[72:75], v[140:143], v[200:203], v[72:75]
	v_mfma_f32_16x16x32_bf16 v[68:71], v[132:135], v[208:211], v[68:71]
	v_mfma_f32_16x16x32_bf16 v[64:67], v[140:143], v[208:211], v[64:67]
	s_setprio 0
	s_setprio 1
	v_mfma_f32_16x16x32_bf16 v[28:31], v[144:147], v[172:175], 0
	v_mfma_f32_16x16x32_bf16 v[24:27], v[164:167], v[172:175], 0
	v_mfma_f32_16x16x32_bf16 v[20:23], v[144:147], v[188:191], 0
	v_mfma_f32_16x16x32_bf16 v[16:19], v[164:167], v[188:191], 0
	v_mfma_f32_16x16x32_bf16 v[12:15], v[144:147], v[196:199], 0
	v_mfma_f32_16x16x32_bf16 v[8:11], v[164:167], v[196:199], 0
	v_mfma_f32_16x16x32_bf16 v[4:7], v[144:147], v[204:207], 0
	v_mfma_f32_16x16x32_bf16 v[0:3], v[164:167], v[204:207], 0
	v_mfma_f32_16x16x32_bf16 v[28:31], v[148:151], v[180:183], v[28:31]
	v_mfma_f32_16x16x32_bf16 v[24:27], v[168:171], v[180:183], v[24:27]
	v_mfma_f32_16x16x32_bf16 v[20:23], v[148:151], v[192:195], v[20:23]
	v_mfma_f32_16x16x32_bf16 v[16:19], v[168:171], v[192:195], v[16:19]
	v_mfma_f32_16x16x32_bf16 v[12:15], v[148:151], v[200:203], v[12:15]
	v_mfma_f32_16x16x32_bf16 v[8:11], v[168:171], v[200:203], v[8:11]
	v_mfma_f32_16x16x32_bf16 v[4:7], v[148:151], v[208:211], v[4:7]
	v_mfma_f32_16x16x32_bf16 v[0:3], v[168:171], v[208:211], v[0:3]
	s_setprio 0
	s_barrier
	s_add_i32 s84, 0, 0x18000
	s_add_i32 s85, 0, 0x1c000
	v_add_u32_e32 v140, s84, v176
	v_add_u32_e32 v168, s85, v176
	ds_read_b128 v[128:131], v140
	ds_read_b128 v[132:135], v140 offset:1024
	ds_read_b128 v[136:139], v140 offset:2048
	ds_read_b128 v[140:143], v140 offset:3072
	ds_read_b128 v[144:147], v168
	ds_read_b128 v[148:151], v168 offset:1024
	ds_read_b128 v[164:167], v168 offset:2048
	ds_read_b128 v[168:171], v168 offset:3072
	s_add_u32 s46, s46, 0x40000
	s_addc_u32 s47, s47, 0
	s_mov_b32 m0, s59
	v_lshl_add_u64 v[216:217], s[46:47], 0, v[152:153]
	ds_read_b128 v[172:175], v179 offset:32768
	ds_read_b128 v[180:183], v179 offset:33792
	ds_read_b128 v[188:191], v179 offset:34816
	ds_read_b128 v[192:195], v179 offset:35840
	ds_read_b128 v[196:199], v179 offset:36864
	ds_read_b128 v[200:203], v179 offset:37888
	ds_read_b128 v[204:207], v179 offset:38912
	ds_read_b128 v[208:211], v179 offset:39936
	global_load_lds_dwordx4 v[216:217], off
	v_lshl_add_u64 v[216:217], s[46:47], 0, v[156:157]
	s_mov_b32 m0, s72
	s_nop 0
	global_load_lds_dwordx4 v[216:217], off
	s_waitcnt vmcnt(8)
	s_waitcnt lgkmcnt(0)
	s_barrier
	s_setprio 1
	s_waitcnt lgkmcnt(0)
	v_mfma_f32_16x16x32_bf16 v[124:127], v[128:131], v[172:175], v[124:127]
	v_mfma_f32_16x16x32_bf16 v[120:123], v[136:139], v[172:175], v[120:123]
	v_mfma_f32_16x16x32_bf16 v[116:119], v[128:131], v[188:191], v[116:119]
	v_mfma_f32_16x16x32_bf16 v[112:115], v[136:139], v[188:191], v[112:115]
	v_mfma_f32_16x16x32_bf16 v[108:111], v[128:131], v[196:199], v[108:111]
	v_mfma_f32_16x16x32_bf16 v[104:107], v[136:139], v[196:199], v[104:107]
	v_mfma_f32_16x16x32_bf16 v[100:103], v[128:131], v[204:207], v[100:103]
	v_mfma_f32_16x16x32_bf16 v[96:99], v[136:139], v[204:207], v[96:99]
	v_mfma_f32_16x16x32_bf16 v[124:127], v[132:135], v[180:183], v[124:127]
	v_mfma_f32_16x16x32_bf16 v[120:123], v[140:143], v[180:183], v[120:123]
	v_mfma_f32_16x16x32_bf16 v[116:119], v[132:135], v[192:195], v[116:119]
	v_mfma_f32_16x16x32_bf16 v[112:115], v[140:143], v[192:195], v[112:115]
	v_mfma_f32_16x16x32_bf16 v[108:111], v[132:135], v[200:203], v[108:111]
	v_mfma_f32_16x16x32_bf16 v[104:107], v[140:143], v[200:203], v[104:107]
	v_mfma_f32_16x16x32_bf16 v[100:103], v[132:135], v[208:211], v[100:103]
	v_mfma_f32_16x16x32_bf16 v[96:99], v[140:143], v[208:211], v[96:99]
	s_setprio 0
	s_setprio 1
	v_mfma_f32_16x16x32_bf16 v[60:63], v[144:147], v[172:175], v[60:63]
	v_mfma_f32_16x16x32_bf16 v[56:59], v[164:167], v[172:175], v[56:59]
	v_mfma_f32_16x16x32_bf16 v[52:55], v[144:147], v[188:191], v[52:55]
	v_mfma_f32_16x16x32_bf16 v[48:51], v[164:167], v[188:191], v[48:51]
	v_mfma_f32_16x16x32_bf16 v[44:47], v[144:147], v[196:199], v[44:47]
	v_mfma_f32_16x16x32_bf16 v[40:43], v[164:167], v[196:199], v[40:43]
	v_mfma_f32_16x16x32_bf16 v[36:39], v[144:147], v[204:207], v[36:39]
	v_mfma_f32_16x16x32_bf16 v[32:35], v[164:167], v[204:207], v[32:35]
	v_mfma_f32_16x16x32_bf16 v[60:63], v[148:151], v[180:183], v[60:63]
	v_mfma_f32_16x16x32_bf16 v[56:59], v[168:171], v[180:183], v[56:59]
	v_mfma_f32_16x16x32_bf16 v[52:55], v[148:151], v[192:195], v[52:55]
	v_mfma_f32_16x16x32_bf16 v[48:51], v[168:171], v[192:195], v[48:51]
	v_mfma_f32_16x16x32_bf16 v[44:47], v[148:151], v[200:203], v[44:47]
	v_mfma_f32_16x16x32_bf16 v[40:43], v[168:171], v[200:203], v[40:43]
	v_mfma_f32_16x16x32_bf16 v[36:39], v[148:151], v[208:211], v[36:39]
	v_mfma_f32_16x16x32_bf16 v[32:35], v[168:171], v[208:211], v[32:35]
	s_setprio 0
	s_barrier
; #define G_STAGE(bufoff, gbase, voff) do { _Pragma("unroll") for (int _i = 0; _i < 2; ++_i) \
;         __builtin_amdgcn_global_load_lds((const unsigned*)((const char*)(gbase) + voff[_i]), (LAS unsigned*)(lds + (bufoff) + ldsw + _i * 8192), 16, 0, 0); } while (0)
; #define G_LDA(dst, b, h) do { _Pragma("unroll") for (int m = 0; m < 4; ++m) _Pragma("unroll") for (int k = 0; k < 2; ++k) dst[m][k] = *(const LAS bf16x8*)(lds + G_SA(b, h) + aoff + m * 2048 + k * 1024); } while (0)
; #define G_MMA(ai, bj, At_, Bt_) do { __builtin_amdgcn_s_setprio(1); _Pragma("unroll") for (int m = 0; m < 4; ++m) _Pragma("unroll") for (int n = 0; n < 2; ++n) _Pragma("unroll") for (int k = 0; k < 2; ++k) \
;         acc[ai][bj][m][n] = __builtin_amdgcn_mfma_f32_16x16x32_bf16(Bt_[n][k], At_[m][k], acc[ai][bj][m][n], 0, 0, 0); __builtin_amdgcn_s_setprio(0); } while (0)
; #define WAIT_V(n) asm volatile("s_waitcnt vmcnt(" #n ")" ::: "memory")
; #define WAIT_L(n) asm volatile("s_waitcnt lgkmcnt(" #n ")" ::: "memory")
; #define BAR __builtin_amdgcn_s_barrier()
; #define SCHED __builtin_amdgcn_sched_barrier(0)
; template <class Get, class Epi>
; DI void gemm_loop(int ntiles, int ld, char* shm, const Get& get, const Epi& epi) {
;     ...
;             G_LDA(At, 1, 1); G_STAGE(G_SB(1, 0), b3, voffB); G_STAGE(G_SB(1, 1), b3 + hstep, voffB); G_STAGE(G_SA(1, 0), a3, voffA);
;             WAIT_V(8); WAIT_L(0); BAR; G_MMA(1, 0, At, B0); G_MMA(1, 1, At, B1); BAR; SCHED;
;         }
	s_add_i32 s46, s84, s56
	v_lshl_add_u64 v[184:185], v[184:185], 0, s[10:11]
	s_mov_b32 m0, s46
	ds_read_b128 v[172:175], v179 offset:49152
	ds_read_b128 v[180:183], v179 offset:50176
	ds_read_b128 v[188:191], v179 offset:51200
	ds_read_b128 v[192:195], v179 offset:52224
	ds_read_b128 v[196:199], v179 offset:53248
	ds_read_b128 v[200:203], v179 offset:54272
	ds_read_b128 v[204:207], v179 offset:55296
	ds_read_b128 v[208:211], v179 offset:56320
	global_load_lds_dwordx4 v[184:185], off
	s_add_i32 m0, s46, 0x2000
	s_add_u32 s14, s14, 0x40080
	v_lshl_add_u64 v[184:185], v[186:187], 0, s[10:11]
	s_addc_u32 s15, s15, 0
	s_add_i32 s46, s85, s56
	global_load_lds_dwordx4 v[184:185], off
	v_lshl_add_u64 v[184:185], s[14:15], 0, v[154:155]
	s_mov_b32 m0, s46
	s_nop 0
	global_load_lds_dwordx4 v[184:185], off
	v_lshl_add_u64 v[184:185], s[14:15], 0, v[158:159]
	s_add_i32 m0, s46, 0x2000
	s_nop 0
	global_load_lds_dwordx4 v[184:185], off
	v_lshl_add_u64 v[184:185], v[212:213], 0, s[10:11]
	s_mov_b32 m0, s75
	s_nop 0
	global_load_lds_dwordx4 v[184:185], off
	v_lshl_add_u64 v[184:185], v[214:215], 0, s[10:11]
	s_mov_b32 m0, s76
	s_nop 0
	global_load_lds_dwordx4 v[184:185], off
	s_waitcnt vmcnt(8)
	s_waitcnt lgkmcnt(0)
	s_barrier
	s_setprio 1
	s_waitcnt lgkmcnt(0)
	v_mfma_f32_16x16x32_bf16 v[92:95], v[128:131], v[172:175], v[92:95]
	v_mfma_f32_16x16x32_bf16 v[88:91], v[136:139], v[172:175], v[88:91]
	v_mfma_f32_16x16x32_bf16 v[84:87], v[128:131], v[188:191], v[84:87]
	v_mfma_f32_16x16x32_bf16 v[80:83], v[136:139], v[188:191], v[80:83]
	v_mfma_f32_16x16x32_bf16 v[76:79], v[128:131], v[196:199], v[76:79]
	v_mfma_f32_16x16x32_bf16 v[72:75], v[136:139], v[196:199], v[72:75]
	v_mfma_f32_16x16x32_bf16 v[68:71], v[128:131], v[204:207], v[68:71]
	v_mfma_f32_16x16x32_bf16 v[64:67], v[136:139], v[204:207], v[64:67]
	v_mfma_f32_16x16x32_bf16 v[92:95], v[132:135], v[180:183], v[92:95]
	v_mfma_f32_16x16x32_bf16 v[88:91], v[140:143], v[180:183], v[88:91]
	v_mfma_f32_16x16x32_bf16 v[84:87], v[132:135], v[192:195], v[84:87]
	v_mfma_f32_16x16x32_bf16 v[80:83], v[140:143], v[192:195], v[80:83]
	v_mfma_f32_16x16x32_bf16 v[76:79], v[132:135], v[200:203], v[76:79]
	v_mfma_f32_16x16x32_bf16 v[72:75], v[140:143], v[200:203], v[72:75]
	v_mfma_f32_16x16x32_bf16 v[68:71], v[132:135], v[208:211], v[68:71]
	v_mfma_f32_16x16x32_bf16 v[64:67], v[140:143], v[208:211], v[64:67]
	s_setprio 0
	s_setprio 1
	v_mfma_f32_16x16x32_bf16 v[28:31], v[144:147], v[172:175], v[28:31]
	v_mfma_f32_16x16x32_bf16 v[24:27], v[164:167], v[172:175], v[24:27]
	v_mfma_f32_16x16x32_bf16 v[20:23], v[144:147], v[188:191], v[20:23]
	v_mfma_f32_16x16x32_bf16 v[16:19], v[164:167], v[188:191], v[16:19]
	v_mfma_f32_16x16x32_bf16 v[12:15], v[144:147], v[196:199], v[12:15]
	v_mfma_f32_16x16x32_bf16 v[8:11], v[164:167], v[196:199], v[8:11]
	v_mfma_f32_16x16x32_bf16 v[4:7], v[144:147], v[204:207], v[4:7]
	v_mfma_f32_16x16x32_bf16 v[0:3], v[164:167], v[204:207], v[0:3]
	v_mfma_f32_16x16x32_bf16 v[28:31], v[148:151], v[180:183], v[28:31]
	v_mfma_f32_16x16x32_bf16 v[24:27], v[168:171], v[180:183], v[24:27]
	v_mfma_f32_16x16x32_bf16 v[20:23], v[148:151], v[192:195], v[20:23]
	v_mfma_f32_16x16x32_bf16 v[16:19], v[168:171], v[192:195], v[16:19]
	v_mfma_f32_16x16x32_bf16 v[12:15], v[148:151], v[200:203], v[12:15]
	v_mfma_f32_16x16x32_bf16 v[8:11], v[168:171], v[200:203], v[8:11]
	v_mfma_f32_16x16x32_bf16 v[4:7], v[148:151], v[208:211], v[4:7]
	v_mfma_f32_16x16x32_bf16 v[0:3], v[168:171], v[208:211], v[0:3]
	s_setprio 0
	s_barrier
	s_add_u32 s44, s44, 0x100
	s_addc_u32 s45, s45, 0
	s_add_u32 s55, s55, 0x100
	s_addc_u32 s82, s82, 0
	s_cmp_ge_u32 s83, s51
	s_mov_b32 s14, s83
	s_cbranch_scc0 .LBB0_528
	s_branch .Lpost_528

; #define BAR __builtin_amdgcn_s_barrier()
; template <class Get, class Epi>
; DI void gemm_loop(int ntiles, int ld, char* shm, const Get& get, const Epi& epi) {
;     ...
;         }
;         if (wr == 0) BAR;
.Lpost_528:
	s_mov_b32 s100, 1
	s_and_b64 vcc, exec, s[12:13]
	s_cbranch_vccz .LBB0_531
	s_barrier

; #define G_STAGE(bufoff, gbase, voff) do { _Pragma("unroll") for (int _i = 0; _i < 2; ++_i) \
;         __builtin_amdgcn_global_load_lds((const unsigned*)((const char*)(gbase) + voff[_i]), (LAS unsigned*)(lds + (bufoff) + ldsw + _i * 8192), 16, 0, 0); } while (0)
; #define WAIT_V(n) asm volatile("s_waitcnt vmcnt(" #n ")" ::: "memory")
; #define BAR __builtin_amdgcn_s_barrier()
; template <class Get, class Epi>
; DI void gemm_loop(int ntiles, int ld, char* shm, const Get& get, const Epi& epi) {
;     ...
;     for (int i = 0; i < 2; ++i) { int R, C; stage_rc(tid * 16 + i * 8192, R, C); const int rho = R & 31, Rb = (R & ~31) + 8 * ((rho & 15) >> 2) + 4 * (rho >> 4) + (rho & 3);
;         voffA[i] = (unsigned)(R * ld + C) * 2u; voffB[i] = (unsigned)(Rb * ld + C) * 2u; }
;     const size_t kstep = (size_t)(BK * 2), hstep = (size_t)HALF * ld * 2;
;     const unsigned ldsw = (unsigned)wid * 1024u;
;     const int aoff = lds_byte(wr * 64 + fr, fq * 8), boff = lds_byte(wc * 32 + fr, fq * 8);
;     ...
;     int L = bx; if (L >= ntiles) return;
;     Tile cur = get(L), nxt = cur;
;     AccT acc;
;     ...
;     G_ZERO;
;     bf16x8 At[4][2], B0[2][2], B1[2][2];
;     const char* cA = (const char*)cur.A + (size_t)cur.brow * ld * 2; const char* cB = (const char*)cur.Bt + (size_t)cur.bcol * ld * 2;
;     G_STAGE(G_SB(0, 0), cB, voffB); G_STAGE(G_SB(0, 1), cB + hstep, voffB); G_STAGE(G_SA(0, 0), cA, voffA); G_STAGE(G_SA(0, 1), cA + hstep, voffA);
;     if (wr == 1) BAR;
;     WAIT_V(2); BAR;
;     G_STAGE(G_SB(1, 0), cB + kstep, voffB); G_STAGE(G_SA(1, 0), cA + kstep, voffA); G_STAGE(G_SB(1, 1), cB + hstep + kstep, voffB);
;     WAIT_V(6); BAR;
.LBB0_757:
	s_lshl_b32 s2, s2, 12
	s_lshl_b32 s5, s3, 13
	s_and_b32 s8, s2, 0x3000
	s_mov_b64 s[2:3], 0x80
	s_add_i32 m0, s31, 0x18000
	v_lshl_add_u64 v[6:7], v[6:7], 0, s[2:3]
	s_waitcnt vmcnt(2)
	s_barrier
	global_load_lds_dwordx4 v[6:7], off
	v_lshl_add_u64 v[4:5], v[4:5], 0, s[2:3]
	s_add_i32 m0, s31, 0x1a000
	s_add_i32 s43, s31, 0x8000
	s_add_i32 s44, s31, 0xa000
	global_load_lds_dwordx4 v[4:5], off
	v_lshl_add_u64 v[0:1], v[0:1], 0, s[2:3]
	s_mov_b32 m0, s43
	s_add_u32 s6, s14, 0x40080
	global_load_lds_dwordx4 v[0:1], off
	v_lshl_add_u64 v[0:1], v[2:3], 0, s[2:3]
	s_mov_b32 m0, s44
	s_addc_u32 s7, s15, 0
	global_load_lds_dwordx4 v[0:1], off
	s_add_i32 m0, s31, 0x1c000
	v_lshl_add_u64 v[0:1], s[6:7], 0, v[132:133]
	global_load_lds_dwordx4 v[0:1], off
	v_lshl_add_u64 v[0:1], s[6:7], 0, v[128:129]
	s_add_i32 m0, s31, 0x1e000
	v_lshlrev_b32_e32 v3, 2, v9
	global_load_lds_dwordx4 v[0:1], off
	v_and_b32_e32 v0, 15, v9
	v_and_b32_e32 v1, 48, v9
	v_lshlrev_b32_e32 v0, 6, v0
	v_and_b32_e32 v3, 32, v3
	v_or_b32_e32 v2, v0, v1
	v_bitop3_b32 v0, v0, v3, v1 bitop3:0x36
	v_or_b32_e32 v140, s8, v0
	v_lshlrev_b32_e32 v0, 14, v13
	v_and_b32_e32 v0, 0xffff8000, v0
	v_bitop3_b32 v1, v2, s5, v3 bitop3:0xde
	v_lshl_add_u32 v0, v12, 11, v0
	v_and_b32_e32 v2, 1, v13
	v_lshl_or_b32 v0, v2, 6, v0
	v_lshl_add_u32 v136, v14, 1, v0
	v_lshlrev_b32_e32 v0, 14, v8
	v_and_b32_e32 v0, 0xffff8000, v0
	s_waitcnt vmcnt(6)
	s_mov_b32 s100, 0
	s_cmpk_lt_u32 s4, 0x100
	v_lshl_add_u32 v0, v10, 11, v0
	v_and_b32_e32 v2, 1, v8
	s_cselect_b64 s[4:5], -1, 0
	v_lshl_or_b32 v0, v2, 6, v0
	s_add_i32 s45, 0, 0x10000
	s_add_i32 s46, 0, 0x14000
	v_mov_b32_e32 v137, v133
	v_lshl_add_u32 v138, v11, 1, v0
	v_mov_b32_e32 v139, v133
	v_add_u32_e32 v141, s45, v140
	v_add_u32_e32 v142, s46, v140
	v_add_u32_e32 v143, 0, v1
	s_movk_i32 s47, 0x1600
	s_barrier
	s_branch .LBB0_760

; #define G_STAGE(bufoff, gbase, voff) do { _Pragma("unroll") for (int _i = 0; _i < 2; ++_i) \
;         __builtin_amdgcn_global_load_lds((const unsigned*)((const char*)(gbase) + voff[_i]), (LAS unsigned*)(lds + (bufoff) + ldsw + _i * 8192), 16, 0, 0); } while (0)
; #define G_LDA(dst, b, h) do { _Pragma("unroll") for (int m = 0; m < 4; ++m) _Pragma("unroll") for (int k = 0; k < 2; ++k) dst[m][k] = *(const LAS bf16x8*)(lds + G_SA(b, h) + aoff + m * 2048 + k * 1024); } while (0)
; #define G_LDB(dst, b, h) do { _Pragma("unroll") for (int n = 0; n < 2; ++n) _Pragma("unroll") for (int k = 0; k < 2; ++k) dst[n][k] = *(const LAS bf16x8*)(lds + G_SB(b, h) + boff + n * 2048 + k * 1024); } while (0)
; #define G_MMA(ai, bj, At_, Bt_) do { __builtin_amdgcn_s_setprio(1); _Pragma("unroll") for (int m = 0; m < 4; ++m) _Pragma("unroll") for (int n = 0; n < 2; ++n) _Pragma("unroll") for (int k = 0; k < 2; ++k) \
;         acc[ai][bj][m][n] = __builtin_amdgcn_mfma_f32_16x16x32_bf16(Bt_[n][k], At_[m][k], acc[ai][bj][m][n], 0, 0, 0); __builtin_amdgcn_s_setprio(0); } while (0)
; #define WAIT_V(n) asm volatile("s_waitcnt vmcnt(" #n ")" ::: "memory")
; #define WAIT_L(n) asm volatile("s_waitcnt lgkmcnt(" #n ")" ::: "memory")
; #define BAR __builtin_amdgcn_s_barrier()
; #define SCHED __builtin_amdgcn_sched_barrier(0)
; template <class Get, class Epi>
; DI void gemm_loop(int ntiles, int ld, char* shm, const Get& get, const Epi& epi) {
;     ...
;             const bool last = (t == nt - 2);
;             const char* a1 = cA + (size_t)(t + 1) * kstep;
;             const char* a2 = last ? nA : cA + (size_t)(t + 2) * kstep; const char* b2 = last ? nB : cB + (size_t)(t + 2) * kstep;
;             const char* a3 = a2 + kstep; const char* b3 = b2 + kstep;
;             G_LDB(B0, 0, 0); G_LDB(B1, 0, 1); SCHED; G_LDA(At, 0, 0); G_STAGE(G_SA(1, 1), a1 + hstep, voffA);
;             WAIT_V(8); WAIT_L(0); BAR; G_MMA(0, 0, At, B0); G_MMA(0, 1, At, B1); BAR; SCHED;
.Lpeel_763:
	ds_read_b128 v[144:147], v141
	ds_read_b128 v[148:151], v141 offset:1024
	ds_read_b128 v[152:155], v141 offset:2048
	ds_read_b128 v[156:159], v141 offset:3072
	ds_read_b128 v[160:163], v142
	ds_read_b128 v[164:167], v142 offset:1024
	ds_read_b128 v[168:171], v142 offset:2048
	ds_read_b128 v[172:175], v142 offset:3072
	s_add_u32 s14, s36, 0xfffc0080
	s_addc_u32 s15, s37, -1
	s_cmp_eq_u32 s54, 12
	s_cselect_b32 s39, s9, s15
	s_cselect_b32 s38, s50, s14
	s_cselect_b32 s15, s11, s53
	s_cselect_b32 s14, s51, s52
	v_lshl_add_u64 v[184:185], s[36:37], 0, v[136:137]
	s_add_i32 m0, s31, 0xc000
	ds_read_b128 v[176:179], v143
	ds_read_b128 v[180:183], v143 offset:1024
	ds_read_b128 v[188:191], v143 offset:2048
	ds_read_b128 v[192:195], v143 offset:3072
	ds_read_b128 v[196:199], v143 offset:4096
	ds_read_b128 v[200:203], v143 offset:5120
	ds_read_b128 v[204:207], v143 offset:6144
	ds_read_b128 v[208:211], v143 offset:7168
	global_load_lds_dwordx4 v[184:185], off
	v_lshl_add_u64 v[184:185], s[36:37], 0, v[138:139]
	s_add_i32 m0, s31, 0xe000
	s_nop 0
	global_load_lds_dwordx4 v[184:185], off
	s_cmp_lg_u32 s100, 0
	s_cbranch_scc0 .Lrf_763_0
	s_waitcnt vmcnt(16)
	s_branch .Lrj_763_0

; #define G_STAGE(bufoff, gbase, voff) do { _Pragma("unroll") for (int _i = 0; _i < 2; ++_i) \
;         __builtin_amdgcn_global_load_lds((const unsigned*)((const char*)(gbase) + voff[_i]), (LAS unsigned*)(lds + (bufoff) + ldsw + _i * 8192), 16, 0, 0); } while (0)
; #define G_LDA(dst, b, h) do { _Pragma("unroll") for (int m = 0; m < 4; ++m) _Pragma("unroll") for (int k = 0; k < 2; ++k) dst[m][k] = *(const LAS bf16x8*)(lds + G_SA(b, h) + aoff + m * 2048 + k * 1024); } while (0)
; #define G_MMA(ai, bj, At_, Bt_) do { __builtin_amdgcn_s_setprio(1); _Pragma("unroll") for (int m = 0; m < 4; ++m) _Pragma("unroll") for (int n = 0; n < 2; ++n) _Pragma("unroll") for (int k = 0; k < 2; ++k) \
;         acc[ai][bj][m][n] = __builtin_amdgcn_mfma_f32_16x16x32_bf16(Bt_[n][k], At_[m][k], acc[ai][bj][m][n], 0, 0, 0); __builtin_amdgcn_s_setprio(0); } while (0)
; #define WAIT_V(n) asm volatile("s_waitcnt vmcnt(" #n ")" ::: "memory")
; #define WAIT_L(n) asm volatile("s_waitcnt lgkmcnt(" #n ")" ::: "memory")
; #define BAR __builtin_amdgcn_s_barrier()
; #define SCHED __builtin_amdgcn_sched_barrier(0)
; template <class Get, class Epi>
; DI void gemm_loop(int ntiles, int ld, char* shm, const Get& get, const Epi& epi) {
;     ...
;             WAIT_V(8); WAIT_L(0); BAR; G_MMA(0, 0, At, B0); G_MMA(0, 1, At, B1); BAR; SCHED;
;             G_LDA(At, 0, 1); G_STAGE(G_SB(0, 0), b2, voffB); G_STAGE(G_SB(0, 1), b2 + hstep, voffB); G_STAGE(G_SA(0, 0), a2, voffA);
;             WAIT_V(8); WAIT_L(0); BAR; G_MMA(1, 0, At, B0); G_MMA(1, 1, At, B1); BAR; SCHED;
.Lrj_763_0:
	s_waitcnt lgkmcnt(0)
	s_barrier
	s_setprio 1
	s_waitcnt lgkmcnt(0)
	v_mfma_f32_16x16x32_bf16 v[124:127], v[144:147], v[176:179], 0
	v_mfma_f32_16x16x32_bf16 v[120:123], v[152:155], v[176:179], 0
	v_mfma_f32_16x16x32_bf16 v[108:111], v[144:147], v[188:191], 0
	v_mfma_f32_16x16x32_bf16 v[104:107], v[152:155], v[188:191], 0
	v_mfma_f32_16x16x32_bf16 v[92:95], v[144:147], v[196:199], 0
	v_mfma_f32_16x16x32_bf16 v[88:91], v[152:155], v[196:199], 0
	v_mfma_f32_16x16x32_bf16 v[76:79], v[144:147], v[204:207], 0
	v_mfma_f32_16x16x32_bf16 v[72:75], v[152:155], v[204:207], 0
	v_mfma_f32_16x16x32_bf16 v[124:127], v[148:151], v[180:183], v[124:127]
	v_mfma_f32_16x16x32_bf16 v[120:123], v[156:159], v[180:183], v[120:123]
	v_mfma_f32_16x16x32_bf16 v[108:111], v[148:151], v[192:195], v[108:111]
	v_mfma_f32_16x16x32_bf16 v[104:107], v[156:159], v[192:195], v[104:107]
	v_mfma_f32_16x16x32_bf16 v[92:95], v[148:151], v[200:203], v[92:95]
	v_mfma_f32_16x16x32_bf16 v[88:91], v[156:159], v[200:203], v[88:91]
	v_mfma_f32_16x16x32_bf16 v[76:79], v[148:151], v[208:211], v[76:79]
	v_mfma_f32_16x16x32_bf16 v[72:75], v[156:159], v[208:211], v[72:75]
	s_setprio 0
	s_setprio 1
	v_mfma_f32_16x16x32_bf16 v[116:119], v[160:163], v[176:179], 0
	v_mfma_f32_16x16x32_bf16 v[112:115], v[168:171], v[176:179], 0
	v_mfma_f32_16x16x32_bf16 v[100:103], v[160:163], v[188:191], 0
	v_mfma_f32_16x16x32_bf16 v[96:99], v[168:171], v[188:191], 0
	v_mfma_f32_16x16x32_bf16 v[84:87], v[160:163], v[196:199], 0
	v_mfma_f32_16x16x32_bf16 v[80:83], v[168:171], v[196:199], 0
	v_mfma_f32_16x16x32_bf16 v[68:71], v[160:163], v[204:207], 0
	v_mfma_f32_16x16x32_bf16 v[64:67], v[168:171], v[204:207], 0
	v_mfma_f32_16x16x32_bf16 v[116:119], v[164:167], v[180:183], v[116:119]
	v_mfma_f32_16x16x32_bf16 v[112:115], v[172:175], v[180:183], v[112:115]
	v_mfma_f32_16x16x32_bf16 v[100:103], v[164:167], v[192:195], v[100:103]
	v_mfma_f32_16x16x32_bf16 v[96:99], v[172:175], v[192:195], v[96:99]
	v_mfma_f32_16x16x32_bf16 v[84:87], v[164:167], v[200:203], v[84:87]
	v_mfma_f32_16x16x32_bf16 v[80:83], v[172:175], v[200:203], v[80:83]
	v_mfma_f32_16x16x32_bf16 v[68:71], v[164:167], v[208:211], v[68:71]
	v_mfma_f32_16x16x32_bf16 v[64:67], v[172:175], v[208:211], v[64:67]
	s_setprio 0
	s_barrier
	s_add_i32 s55, s45, s26
	v_lshl_add_u64 v[184:185], s[14:15], 0, v[132:133]
	s_mov_b32 m0, s55
	ds_read_b128 v[176:179], v143 offset:16384
	ds_read_b128 v[180:183], v143 offset:17408
	ds_read_b128 v[188:191], v143 offset:18432
	ds_read_b128 v[192:195], v143 offset:19456
	ds_read_b128 v[196:199], v143 offset:20480
	ds_read_b128 v[200:203], v143 offset:21504
	ds_read_b128 v[204:207], v143 offset:22528
	ds_read_b128 v[208:211], v143 offset:23552
	global_load_lds_dwordx4 v[184:185], off
	s_add_i32 m0, s55, 0x2000
	s_add_u32 s56, s14, 0x40000
	v_lshl_add_u64 v[186:187], s[14:15], 0, v[128:129]
	s_addc_u32 s57, s15, 0
	s_add_i32 s55, s46, s26
	global_load_lds_dwordx4 v[186:187], off
	v_lshl_add_u64 v[212:213], s[56:57], 0, v[132:133]
	s_mov_b32 m0, s55
	v_lshl_add_u64 v[214:215], s[38:39], 0, v[130:131]
	global_load_lds_dwordx4 v[212:213], off
	v_lshl_add_u64 v[212:213], s[56:57], 0, v[128:129]
	s_add_i32 m0, s55, 0x2000
	s_nop 0
	global_load_lds_dwordx4 v[212:213], off
	v_lshl_add_u64 v[212:213], s[38:39], 0, v[134:135]
	s_mov_b32 m0, s31
	s_nop 0
	global_load_lds_dwordx4 v[212:213], off
	s_mov_b32 m0, s35
	s_nop 0
	global_load_lds_dwordx4 v[214:215], off
	s_cmp_lg_u32 s100, 0
	s_cbranch_scc0 .Lrf_763_1
	s_waitcnt vmcnt(16)
	s_branch .Lrj_763_1

; #define G_STAGE(bufoff, gbase, voff) do { _Pragma("unroll") for (int _i = 0; _i < 2; ++_i) \
;         __builtin_amdgcn_global_load_lds((const unsigned*)((const char*)(gbase) + voff[_i]), (LAS unsigned*)(lds + (bufoff) + ldsw + _i * 8192), 16, 0, 0); } while (0)
; #define G_LDA(dst, b, h) do { _Pragma("unroll") for (int m = 0; m < 4; ++m) _Pragma("unroll") for (int k = 0; k < 2; ++k) dst[m][k] = *(const LAS bf16x8*)(lds + G_SA(b, h) + aoff + m * 2048 + k * 1024); } while (0)
; #define G_LDB(dst, b, h) do { _Pragma("unroll") for (int n = 0; n < 2; ++n) _Pragma("unroll") for (int k = 0; k < 2; ++k) dst[n][k] = *(const LAS bf16x8*)(lds + G_SB(b, h) + boff + n * 2048 + k * 1024); } while (0)
; #define G_MMA(ai, bj, At_, Bt_) do { __builtin_amdgcn_s_setprio(1); _Pragma("unroll") for (int m = 0; m < 4; ++m) _Pragma("unroll") for (int n = 0; n < 2; ++n) _Pragma("unroll") for (int k = 0; k < 2; ++k) \
;         acc[ai][bj][m][n] = __builtin_amdgcn_mfma_f32_16x16x32_bf16(Bt_[n][k], At_[m][k], acc[ai][bj][m][n], 0, 0, 0); __builtin_amdgcn_s_setprio(0); } while (0)
; #define WAIT_V(n) asm volatile("s_waitcnt vmcnt(" #n ")" ::: "memory")
; #define WAIT_L(n) asm volatile("s_waitcnt lgkmcnt(" #n ")" ::: "memory")
; #define BAR __builtin_amdgcn_s_barrier()
; #define SCHED __builtin_amdgcn_sched_barrier(0)
; template <class Get, class Epi>
; DI void gemm_loop(int ntiles, int ld, char* shm, const Get& get, const Epi& epi) {
;     ...
;             WAIT_V(8); WAIT_L(0); BAR; G_MMA(1, 0, At, B0); G_MMA(1, 1, At, B1); BAR; SCHED;
;             G_LDB(B0, 1, 0); G_LDB(B1, 1, 1); SCHED; G_LDA(At, 1, 0); G_STAGE(G_SA(0, 1), a2 + hstep, voffA);
;             WAIT_V(8); WAIT_L(0); BAR; G_MMA(0, 0, At, B0); G_MMA(0, 1, At, B1); BAR; SCHED;
.Lrj_763_1:
	s_waitcnt lgkmcnt(0)
	s_barrier
	s_setprio 1
	s_waitcnt lgkmcnt(0)
	v_mfma_f32_16x16x32_bf16 v[60:63], v[144:147], v[176:179], 0
	v_mfma_f32_16x16x32_bf16 v[56:59], v[152:155], v[176:179], 0
	v_mfma_f32_16x16x32_bf16 v[44:47], v[144:147], v[188:191], 0
	v_mfma_f32_16x16x32_bf16 v[40:43], v[152:155], v[188:191], 0
	v_mfma_f32_16x16x32_bf16 v[28:31], v[144:147], v[196:199], 0
	v_mfma_f32_16x16x32_bf16 v[24:27], v[152:155], v[196:199], 0
	v_mfma_f32_16x16x32_bf16 v[12:15], v[144:147], v[204:207], 0
	v_mfma_f32_16x16x32_bf16 v[8:11], v[152:155], v[204:207], 0
	v_mfma_f32_16x16x32_bf16 v[60:63], v[148:151], v[180:183], v[60:63]
	v_mfma_f32_16x16x32_bf16 v[56:59], v[156:159], v[180:183], v[56:59]
	v_mfma_f32_16x16x32_bf16 v[44:47], v[148:151], v[192:195], v[44:47]
	v_mfma_f32_16x16x32_bf16 v[40:43], v[156:159], v[192:195], v[40:43]
	v_mfma_f32_16x16x32_bf16 v[28:31], v[148:151], v[200:203], v[28:31]
	v_mfma_f32_16x16x32_bf16 v[24:27], v[156:159], v[200:203], v[24:27]
	v_mfma_f32_16x16x32_bf16 v[12:15], v[148:151], v[208:211], v[12:15]
	v_mfma_f32_16x16x32_bf16 v[8:11], v[156:159], v[208:211], v[8:11]
	s_setprio 0
	s_setprio 1
	v_mfma_f32_16x16x32_bf16 v[52:55], v[160:163], v[176:179], 0
	v_mfma_f32_16x16x32_bf16 v[48:51], v[168:171], v[176:179], 0
	v_mfma_f32_16x16x32_bf16 v[36:39], v[160:163], v[188:191], 0
	v_mfma_f32_16x16x32_bf16 v[32:35], v[168:171], v[188:191], 0
	v_mfma_f32_16x16x32_bf16 v[20:23], v[160:163], v[196:199], 0
	v_mfma_f32_16x16x32_bf16 v[16:19], v[168:171], v[196:199], 0
	v_mfma_f32_16x16x32_bf16 v[4:7], v[160:163], v[204:207], 0
	v_mfma_f32_16x16x32_bf16 v[0:3], v[168:171], v[204:207], 0
	v_mfma_f32_16x16x32_bf16 v[52:55], v[164:167], v[180:183], v[52:55]
	v_mfma_f32_16x16x32_bf16 v[48:51], v[172:175], v[180:183], v[48:51]
	v_mfma_f32_16x16x32_bf16 v[36:39], v[164:167], v[192:195], v[36:39]
	v_mfma_f32_16x16x32_bf16 v[32:35], v[172:175], v[192:195], v[32:35]
	v_mfma_f32_16x16x32_bf16 v[20:23], v[164:167], v[200:203], v[20:23]
	v_mfma_f32_16x16x32_bf16 v[16:19], v[172:175], v[200:203], v[16:19]
	v_mfma_f32_16x16x32_bf16 v[4:7], v[164:167], v[208:211], v[4:7]
	v_mfma_f32_16x16x32_bf16 v[0:3], v[172:175], v[208:211], v[0:3]
	s_setprio 0
	s_barrier
	s_add_i32 s55, 0, 0x18000
	s_add_i32 s56, 0, 0x1c000
	v_add_u32_e32 v156, s55, v140
	v_add_u32_e32 v172, s56, v140
	ds_read_b128 v[144:147], v156
	ds_read_b128 v[148:151], v156 offset:1024
	ds_read_b128 v[152:155], v156 offset:2048
	ds_read_b128 v[156:159], v156 offset:3072
	ds_read_b128 v[160:163], v172
	ds_read_b128 v[164:167], v172 offset:1024
	ds_read_b128 v[168:171], v172 offset:2048
	ds_read_b128 v[172:175], v172 offset:3072
	s_add_u32 s38, s38, 0x40000
	s_addc_u32 s39, s39, 0
	s_mov_b32 m0, s41
	v_lshl_add_u64 v[216:217], s[38:39], 0, v[134:135]
	ds_read_b128 v[176:179], v143 offset:32768
	ds_read_b128 v[180:183], v143 offset:33792
	ds_read_b128 v[188:191], v143 offset:34816
	ds_read_b128 v[192:195], v143 offset:35840
	ds_read_b128 v[196:199], v143 offset:36864
	ds_read_b128 v[200:203], v143 offset:37888
	ds_read_b128 v[204:207], v143 offset:38912
	ds_read_b128 v[208:211], v143 offset:39936
	global_load_lds_dwordx4 v[216:217], off
	v_lshl_add_u64 v[216:217], s[38:39], 0, v[130:131]
	s_mov_b32 m0, s42
	s_nop 0
	global_load_lds_dwordx4 v[216:217], off
	s_waitcnt vmcnt(8)
	s_waitcnt lgkmcnt(0)
	s_barrier
	s_setprio 1
	s_waitcnt lgkmcnt(0)
	v_mfma_f32_16x16x32_bf16 v[124:127], v[144:147], v[176:179], v[124:127]
	v_mfma_f32_16x16x32_bf16 v[120:123], v[152:155], v[176:179], v[120:123]
	v_mfma_f32_16x16x32_bf16 v[108:111], v[144:147], v[188:191], v[108:111]
	v_mfma_f32_16x16x32_bf16 v[104:107], v[152:155], v[188:191], v[104:107]
	v_mfma_f32_16x16x32_bf16 v[92:95], v[144:147], v[196:199], v[92:95]
	v_mfma_f32_16x16x32_bf16 v[88:91], v[152:155], v[196:199], v[88:91]
	v_mfma_f32_16x16x32_bf16 v[76:79], v[144:147], v[204:207], v[76:79]
	v_mfma_f32_16x16x32_bf16 v[72:75], v[152:155], v[204:207], v[72:75]
	v_mfma_f32_16x16x32_bf16 v[124:127], v[148:151], v[180:183], v[124:127]
	v_mfma_f32_16x16x32_bf16 v[120:123], v[156:159], v[180:183], v[120:123]
	v_mfma_f32_16x16x32_bf16 v[108:111], v[148:151], v[192:195], v[108:111]
	v_mfma_f32_16x16x32_bf16 v[104:107], v[156:159], v[192:195], v[104:107]
	v_mfma_f32_16x16x32_bf16 v[92:95], v[148:151], v[200:203], v[92:95]
	v_mfma_f32_16x16x32_bf16 v[88:91], v[156:159], v[200:203], v[88:91]
	v_mfma_f32_16x16x32_bf16 v[76:79], v[148:151], v[208:211], v[76:79]
	v_mfma_f32_16x16x32_bf16 v[72:75], v[156:159], v[208:211], v[72:75]
	s_setprio 0
	s_setprio 1
	v_mfma_f32_16x16x32_bf16 v[116:119], v[160:163], v[176:179], v[116:119]
	v_mfma_f32_16x16x32_bf16 v[112:115], v[168:171], v[176:179], v[112:115]
	v_mfma_f32_16x16x32_bf16 v[100:103], v[160:163], v[188:191], v[100:103]
	v_mfma_f32_16x16x32_bf16 v[96:99], v[168:171], v[188:191], v[96:99]
	v_mfma_f32_16x16x32_bf16 v[84:87], v[160:163], v[196:199], v[84:87]
	v_mfma_f32_16x16x32_bf16 v[80:83], v[168:171], v[196:199], v[80:83]
	v_mfma_f32_16x16x32_bf16 v[68:71], v[160:163], v[204:207], v[68:71]
	v_mfma_f32_16x16x32_bf16 v[64:67], v[168:171], v[204:207], v[64:67]
	v_mfma_f32_16x16x32_bf16 v[116:119], v[164:167], v[180:183], v[116:119]
	v_mfma_f32_16x16x32_bf16 v[112:115], v[172:175], v[180:183], v[112:115]
	v_mfma_f32_16x16x32_bf16 v[100:103], v[164:167], v[192:195], v[100:103]
	v_mfma_f32_16x16x32_bf16 v[96:99], v[172:175], v[192:195], v[96:99]
	v_mfma_f32_16x16x32_bf16 v[84:87], v[164:167], v[200:203], v[84:87]
	v_mfma_f32_16x16x32_bf16 v[80:83], v[172:175], v[200:203], v[80:83]
	v_mfma_f32_16x16x32_bf16 v[68:71], v[164:167], v[208:211], v[68:71]
	v_mfma_f32_16x16x32_bf16 v[64:67], v[172:175], v[208:211], v[64:67]
	s_setprio 0
	s_barrier
; #define G_STAGE(bufoff, gbase, voff) do { _Pragma("unroll") for (int _i = 0; _i < 2; ++_i) \
;         __builtin_amdgcn_global_load_lds((const unsigned*)((const char*)(gbase) + voff[_i]), (LAS unsigned*)(lds + (bufoff) + ldsw + _i * 8192), 16, 0, 0); } while (0)
; #define G_LDA(dst, b, h) do { _Pragma("unroll") for (int m = 0; m < 4; ++m) _Pragma("unroll") for (int k = 0; k < 2; ++k) dst[m][k] = *(const LAS bf16x8*)(lds + G_SA(b, h) + aoff + m * 2048 + k * 1024); } while (0)
; #define G_MMA(ai, bj, At_, Bt_) do { __builtin_amdgcn_s_setprio(1); _Pragma("unroll") for (int m = 0; m < 4; ++m) _Pragma("unroll") for (int n = 0; n < 2; ++n) _Pragma("unroll") for (int k = 0; k < 2; ++k) \
;         acc[ai][bj][m][n] = __builtin_amdgcn_mfma_f32_16x16x32_bf16(Bt_[n][k], At_[m][k], acc[ai][bj][m][n], 0, 0, 0); __builtin_amdgcn_s_setprio(0); } while (0)
; #define WAIT_V(n) asm volatile("s_waitcnt vmcnt(" #n ")" ::: "memory")
; #define WAIT_L(n) asm volatile("s_waitcnt lgkmcnt(" #n ")" ::: "memory")
; #define BAR __builtin_amdgcn_s_barrier()
; #define SCHED __builtin_amdgcn_sched_barrier(0)
; template <class Get, class Epi>
; DI void gemm_loop(int ntiles, int ld, char* shm, const Get& get, const Epi& epi) {
;     ...
;             G_LDA(At, 1, 1); G_STAGE(G_SB(1, 0), b3, voffB); G_STAGE(G_SB(1, 1), b3 + hstep, voffB); G_STAGE(G_SA(1, 0), a3, voffA);
;             WAIT_V(8); WAIT_L(0); BAR; G_MMA(1, 0, At, B0); G_MMA(1, 1, At, B1); BAR; SCHED;
;         }
	s_add_i32 s38, s55, s26
	v_lshl_add_u64 v[184:185], v[184:185], 0, s[2:3]
	s_mov_b32 m0, s38
	ds_read_b128 v[176:179], v143 offset:49152
	ds_read_b128 v[180:183], v143 offset:50176
	ds_read_b128 v[188:191], v143 offset:51200
	ds_read_b128 v[192:195], v143 offset:52224
	ds_read_b128 v[196:199], v143 offset:53248
	ds_read_b128 v[200:203], v143 offset:54272
	ds_read_b128 v[204:207], v143 offset:55296
	ds_read_b128 v[208:211], v143 offset:56320
	global_load_lds_dwordx4 v[184:185], off
	s_add_i32 m0, s38, 0x2000
	s_add_u32 s14, s14, 0x40080
	v_lshl_add_u64 v[184:185], v[186:187], 0, s[2:3]
	s_addc_u32 s15, s15, 0
	s_add_i32 s38, s56, s26
	global_load_lds_dwordx4 v[184:185], off
	v_lshl_add_u64 v[184:185], s[14:15], 0, v[132:133]
	s_mov_b32 m0, s38
	s_nop 0
	global_load_lds_dwordx4 v[184:185], off
	v_lshl_add_u64 v[184:185], s[14:15], 0, v[128:129]
	s_add_i32 m0, s38, 0x2000
	s_nop 0
	global_load_lds_dwordx4 v[184:185], off
	v_lshl_add_u64 v[184:185], v[212:213], 0, s[2:3]
	s_mov_b32 m0, s43
	s_nop 0
	global_load_lds_dwordx4 v[184:185], off
	v_lshl_add_u64 v[184:185], v[214:215], 0, s[2:3]
	s_mov_b32 m0, s44
	s_nop 0
	global_load_lds_dwordx4 v[184:185], off
	s_waitcnt vmcnt(8)
	s_waitcnt lgkmcnt(0)
	s_barrier
	s_setprio 1
	s_waitcnt lgkmcnt(0)
	v_mfma_f32_16x16x32_bf16 v[60:63], v[144:147], v[176:179], v[60:63]
	v_mfma_f32_16x16x32_bf16 v[56:59], v[152:155], v[176:179], v[56:59]
	v_mfma_f32_16x16x32_bf16 v[44:47], v[144:147], v[188:191], v[44:47]
	v_mfma_f32_16x16x32_bf16 v[40:43], v[152:155], v[188:191], v[40:43]
	v_mfma_f32_16x16x32_bf16 v[28:31], v[144:147], v[196:199], v[28:31]
	v_mfma_f32_16x16x32_bf16 v[24:27], v[152:155], v[196:199], v[24:27]
	v_mfma_f32_16x16x32_bf16 v[12:15], v[144:147], v[204:207], v[12:15]
	v_mfma_f32_16x16x32_bf16 v[8:11], v[152:155], v[204:207], v[8:11]
	v_mfma_f32_16x16x32_bf16 v[60:63], v[148:151], v[180:183], v[60:63]
	v_mfma_f32_16x16x32_bf16 v[56:59], v[156:159], v[180:183], v[56:59]
	v_mfma_f32_16x16x32_bf16 v[44:47], v[148:151], v[192:195], v[44:47]
	v_mfma_f32_16x16x32_bf16 v[40:43], v[156:159], v[192:195], v[40:43]
	v_mfma_f32_16x16x32_bf16 v[28:31], v[148:151], v[200:203], v[28:31]
	v_mfma_f32_16x16x32_bf16 v[24:27], v[156:159], v[200:203], v[24:27]
	v_mfma_f32_16x16x32_bf16 v[12:15], v[148:151], v[208:211], v[12:15]
	v_mfma_f32_16x16x32_bf16 v[8:11], v[156:159], v[208:211], v[8:11]
	s_setprio 0
	s_setprio 1
	v_mfma_f32_16x16x32_bf16 v[52:55], v[160:163], v[176:179], v[52:55]
	v_mfma_f32_16x16x32_bf16 v[48:51], v[168:171], v[176:179], v[48:51]
	v_mfma_f32_16x16x32_bf16 v[36:39], v[160:163], v[188:191], v[36:39]
	v_mfma_f32_16x16x32_bf16 v[32:35], v[168:171], v[188:191], v[32:35]
	v_mfma_f32_16x16x32_bf16 v[20:23], v[160:163], v[196:199], v[20:23]
	v_mfma_f32_16x16x32_bf16 v[16:19], v[168:171], v[196:199], v[16:19]
	v_mfma_f32_16x16x32_bf16 v[4:7], v[160:163], v[204:207], v[4:7]
	v_mfma_f32_16x16x32_bf16 v[0:3], v[168:171], v[204:207], v[0:3]
	v_mfma_f32_16x16x32_bf16 v[52:55], v[164:167], v[180:183], v[52:55]
	v_mfma_f32_16x16x32_bf16 v[48:51], v[172:175], v[180:183], v[48:51]
	v_mfma_f32_16x16x32_bf16 v[36:39], v[164:167], v[192:195], v[36:39]
	v_mfma_f32_16x16x32_bf16 v[32:35], v[172:175], v[192:195], v[32:35]
	v_mfma_f32_16x16x32_bf16 v[20:23], v[164:167], v[200:203], v[20:23]
	v_mfma_f32_16x16x32_bf16 v[16:19], v[172:175], v[200:203], v[16:19]
	v_mfma_f32_16x16x32_bf16 v[4:7], v[164:167], v[208:211], v[4:7]
	v_mfma_f32_16x16x32_bf16 v[0:3], v[172:175], v[208:211], v[0:3]
	s_setprio 0
	s_barrier
	s_add_i32 s54, s54, 2
	s_add_u32 s36, s36, 0x100
	s_addc_u32 s37, s37, 0
	s_add_u32 s52, s52, 0x100
	s_addc_u32 s53, s53, 0
	s_cmp_gt_u32 s54, 13
	s_cbranch_scc0 .LBB0_763
	s_branch .Lpost_763

; #define BAR __builtin_amdgcn_s_barrier()
; template <class Get, class Epi>
; DI void gemm_loop(int ntiles, int ld, char* shm, const Get& get, const Epi& epi) {
;     ...
;         }
;         if (wr == 0) BAR;
.Lpost_763:
	s_mov_b32 s100, 1
	s_and_b64 vcc, exec, s[4:5]
	s_cbranch_vccz .LBB0_766
	s_barrier

; #define G_STAGE(bufoff, gbase, voff) do { _Pragma("unroll") for (int _i = 0; _i < 2; ++_i) \
;         __builtin_amdgcn_global_load_lds((const unsigned*)((const char*)(gbase) + voff[_i]), (LAS unsigned*)(lds + (bufoff) + ldsw + _i * 8192), 16, 0, 0); } while (0)
; #define WAIT_V(n) asm volatile("s_waitcnt vmcnt(" #n ")" ::: "memory")
; #define BAR __builtin_amdgcn_s_barrier()
; template <class Get, class Epi>
; DI void gemm_loop(int ntiles, int ld, char* shm, const Get& get, const Epi& epi) {
;     ...
;     for (int i = 0; i < 2; ++i) { int R, C; stage_rc(tid * 16 + i * 8192, R, C); const int rho = R & 31, Rb = (R & ~31) + 8 * ((rho & 15) >> 2) + 4 * (rho >> 4) + (rho & 3);
;         voffA[i] = (unsigned)(R * ld + C) * 2u; voffB[i] = (unsigned)(Rb * ld + C) * 2u; }
;     const size_t kstep = (size_t)(BK * 2), hstep = (size_t)HALF * ld * 2;
;     const unsigned ldsw = (unsigned)wid * 1024u;
;     const int aoff = lds_byte(wr * 64 + fr, fq * 8), boff = lds_byte(wc * 32 + fr, fq * 8);
;     ...
;     int L = bx; if (L >= ntiles) return;
;     Tile cur = get(L), nxt = cur;
;     AccT acc;
;     ...
;     G_ZERO;
;     bf16x8 At[4][2], B0[2][2], B1[2][2];
;     const char* cA = (const char*)cur.A + (size_t)cur.brow * ld * 2; const char* cB = (const char*)cur.Bt + (size_t)cur.bcol * ld * 2;
;     G_STAGE(G_SB(0, 0), cB, voffB); G_STAGE(G_SB(0, 1), cB + hstep, voffB); G_STAGE(G_SA(0, 0), cA, voffA); G_STAGE(G_SA(0, 1), cA + hstep, voffA);
;     if (wr == 1) BAR;
;     WAIT_V(2); BAR;
;     G_STAGE(G_SB(1, 0), cB + kstep, voffB); G_STAGE(G_SA(1, 0), cA + kstep, voffA); G_STAGE(G_SB(1, 1), cB + hstep + kstep, voffB);
;     WAIT_V(6); BAR;
.LBB0_833:
	s_add_u32 s46, s68, 0x805000
	s_addc_u32 s47, s69, 0
	s_lshl_b32 s10, s10, 12
	s_and_b32 s13, s10, 0x3000
	s_mov_b64 s[10:11], 0x80
	s_add_i32 m0, s42, 0x18000
	v_lshl_add_u64 v[6:7], v[6:7], 0, s[10:11]
	s_lshl_b32 s3, s3, 13
	s_waitcnt vmcnt(2)
	s_barrier
	global_load_lds_dwordx4 v[6:7], off
	v_lshl_add_u64 v[4:5], v[4:5], 0, s[10:11]
	s_add_i32 m0, s42, 0x1a000
	s_add_i32 s48, s42, 0x8000
	s_add_i32 s49, s42, 0xa000
	global_load_lds_dwordx4 v[4:5], off
	v_lshl_add_u64 v[0:1], v[0:1], 0, s[10:11]
	s_mov_b32 m0, s48
	s_add_u32 s30, s14, 0xb0080
	global_load_lds_dwordx4 v[0:1], off
	v_lshl_add_u64 v[0:1], v[2:3], 0, s[10:11]
	s_mov_b32 m0, s49
	s_addc_u32 s31, s15, 0
	global_load_lds_dwordx4 v[0:1], off
	s_add_i32 m0, s42, 0x1c000
	v_lshl_add_u64 v[0:1], s[30:31], 0, v[148:149]
	global_load_lds_dwordx4 v[0:1], off
	v_lshl_add_u64 v[0:1], s[30:31], 0, v[152:153]
	s_add_i32 m0, s42, 0x1e000
	v_lshlrev_b32_e32 v3, 2, v8
	global_load_lds_dwordx4 v[0:1], off
	v_and_b32_e32 v0, 15, v8
	v_and_b32_e32 v1, 48, v8
	v_lshlrev_b32_e32 v0, 6, v0
	v_and_b32_e32 v3, 32, v3
	v_or_b32_e32 v2, v0, v1
	v_bitop3_b32 v0, v0, v3, v1 bitop3:0x36
	v_bitop3_b32 v2, v2, s3, v3 bitop3:0xde
	v_or_b32_e32 v168, s13, v0
	v_lshrrev_b32_e32 v1, 1, v9
	v_mul_lo_u32 v0, v11, s2
	s_mov_b32 s3, 0xb000
	v_mad_u64_u32 v[0:1], s[36:37], v1, s3, v[0:1]
	v_or_b32_e32 v0, v0, v10
	s_mov_b64 s[34:35], 0xb0080
	v_add_lshl_u32 v0, v0, v12, 1
	v_mov_b32_e32 v1, v149
	v_lshl_add_u64 v[154:155], v[0:1], 0, s[34:35]
	v_lshrrev_b32_e32 v1, 1, v13
	v_mul_lo_u32 v0, v14, s2
	s_cmpk_lt_u32 s12, 0x100
	v_mad_u64_u32 v[0:1], s[2:3], v1, s3, v[0:1]
	s_waitcnt vmcnt(6)
	s_mov_b32 s100, 0
	s_cselect_b64 s[12:13], -1, 0
	s_add_u32 s30, s68, 0x835000
	v_or_b32_e32 v0, v0, v15
	s_addc_u32 s31, s69, 0
	v_add_lshl_u32 v0, v0, v16, 1
	v_mov_b32_e32 v1, v149
	s_add_i32 s50, 0, 0x10000
	s_add_i32 s51, 0, 0x14000
	v_lshl_add_u64 v[156:157], v[0:1], 0, s[34:35]
	v_add_u32_e32 v169, s50, v168
	v_add_u32_e32 v170, s51, v168
	v_add_u32_e32 v171, 0, v2
	s_mov_b32 s53, s38
	s_mov_b32 s54, s58
	s_mov_b32 s55, s57
	s_barrier
	s_branch .LBB0_836

; #define G_STAGE(bufoff, gbase, voff) do { _Pragma("unroll") for (int _i = 0; _i < 2; ++_i) \
;         __builtin_amdgcn_global_load_lds((const unsigned*)((const char*)(gbase) + voff[_i]), (LAS unsigned*)(lds + (bufoff) + ldsw + _i * 8192), 16, 0, 0); } while (0)
; #define G_LDA(dst, b, h) do { _Pragma("unroll") for (int m = 0; m < 4; ++m) _Pragma("unroll") for (int k = 0; k < 2; ++k) dst[m][k] = *(const LAS bf16x8*)(lds + G_SA(b, h) + aoff + m * 2048 + k * 1024); } while (0)
; #define G_LDB(dst, b, h) do { _Pragma("unroll") for (int n = 0; n < 2; ++n) _Pragma("unroll") for (int k = 0; k < 2; ++k) dst[n][k] = *(const LAS bf16x8*)(lds + G_SB(b, h) + boff + n * 2048 + k * 1024); } while (0)
; #define G_MMA(ai, bj, At_, Bt_) do { __builtin_amdgcn_s_setprio(1); _Pragma("unroll") for (int m = 0; m < 4; ++m) _Pragma("unroll") for (int n = 0; n < 2; ++n) _Pragma("unroll") for (int k = 0; k < 2; ++k) \
;         acc[ai][bj][m][n] = __builtin_amdgcn_mfma_f32_16x16x32_bf16(Bt_[n][k], At_[m][k], acc[ai][bj][m][n], 0, 0, 0); __builtin_amdgcn_s_setprio(0); } while (0)
; #define WAIT_V(n) asm volatile("s_waitcnt vmcnt(" #n ")" ::: "memory")
; #define WAIT_L(n) asm volatile("s_waitcnt lgkmcnt(" #n ")" ::: "memory")
; #define BAR __builtin_amdgcn_s_barrier()
; #define SCHED __builtin_amdgcn_sched_barrier(0)
; template <class Get, class Epi>
; DI void gemm_loop(int ntiles, int ld, char* shm, const Get& get, const Epi& epi) {
;     ...
;             const bool last = (t == nt - 2);
;             const char* a1 = cA + (size_t)(t + 1) * kstep;
;             const char* a2 = last ? nA : cA + (size_t)(t + 2) * kstep; const char* b2 = last ? nB : cB + (size_t)(t + 2) * kstep;
;             const char* a3 = a2 + kstep; const char* b3 = b2 + kstep;
;             G_LDB(B0, 0, 0); G_LDB(B1, 0, 1); SCHED; G_LDA(At, 0, 0); G_STAGE(G_SA(1, 1), a1 + hstep, voffA);
;             WAIT_V(8); WAIT_L(0); BAR; G_MMA(0, 0, At, B0); G_MMA(0, 1, At, B1); BAR; SCHED;
.Lpeel_850:
	ds_read_b128 v[128:131], v169
	ds_read_b128 v[132:135], v169 offset:1024
	ds_read_b128 v[136:139], v169 offset:2048
	ds_read_b128 v[140:143], v169 offset:3072
	ds_read_b128 v[158:161], v170
	ds_read_b128 v[162:165], v170 offset:1024
	ds_read_b128 v[172:175], v170 offset:2048
	ds_read_b128 v[176:179], v170 offset:3072
	s_add_i32 s75, s38, 2
	s_add_u32 s14, s4, 0x100
	s_addc_u32 s15, s5, 0
	s_cmp_eq_u32 s72, s38
	s_cselect_b32 s38, s36, s73
	s_cselect_b32 s41, s35, s15
	s_cselect_b32 s40, s34, s14
	s_cselect_b32 s39, s37, s74
	v_lshl_add_u64 v[144:145], s[4:5], 0, v[154:155]
	s_add_i32 m0, s42, 0xc000
	ds_read_b128 v[180:183], v171
	ds_read_b128 v[188:191], v171 offset:1024
	ds_read_b128 v[192:195], v171 offset:2048
	ds_read_b128 v[196:199], v171 offset:3072
	ds_read_b128 v[200:203], v171 offset:4096
	ds_read_b128 v[204:207], v171 offset:5120
	ds_read_b128 v[208:211], v171 offset:6144
	ds_read_b128 v[212:215], v171 offset:7168
	global_load_lds_dwordx4 v[144:145], off
	v_lshl_add_u64 v[144:145], s[4:5], 0, v[156:157]
	s_add_i32 m0, s42, 0xe000
	s_nop 0
	global_load_lds_dwordx4 v[144:145], off
	s_cmp_lg_u32 s100, 0
	s_cbranch_scc0 .Lrf_850_0
	s_waitcnt vmcnt(16)
	s_branch .Lrj_850_0

; #define G_STAGE(bufoff, gbase, voff) do { _Pragma("unroll") for (int _i = 0; _i < 2; ++_i) \
;         __builtin_amdgcn_global_load_lds((const unsigned*)((const char*)(gbase) + voff[_i]), (LAS unsigned*)(lds + (bufoff) + ldsw + _i * 8192), 16, 0, 0); } while (0)
; #define G_LDA(dst, b, h) do { _Pragma("unroll") for (int m = 0; m < 4; ++m) _Pragma("unroll") for (int k = 0; k < 2; ++k) dst[m][k] = *(const LAS bf16x8*)(lds + G_SA(b, h) + aoff + m * 2048 + k * 1024); } while (0)
; #define G_MMA(ai, bj, At_, Bt_) do { __builtin_amdgcn_s_setprio(1); _Pragma("unroll") for (int m = 0; m < 4; ++m) _Pragma("unroll") for (int n = 0; n < 2; ++n) _Pragma("unroll") for (int k = 0; k < 2; ++k) \
;         acc[ai][bj][m][n] = __builtin_amdgcn_mfma_f32_16x16x32_bf16(Bt_[n][k], At_[m][k], acc[ai][bj][m][n], 0, 0, 0); __builtin_amdgcn_s_setprio(0); } while (0)
; #define WAIT_V(n) asm volatile("s_waitcnt vmcnt(" #n ")" ::: "memory")
; #define WAIT_L(n) asm volatile("s_waitcnt lgkmcnt(" #n ")" ::: "memory")
; #define BAR __builtin_amdgcn_s_barrier()
; #define SCHED __builtin_amdgcn_sched_barrier(0)
; template <class Get, class Epi>
; DI void gemm_loop(int ntiles, int ld, char* shm, const Get& get, const Epi& epi) {
;     ...
;             WAIT_V(8); WAIT_L(0); BAR; G_MMA(0, 0, At, B0); G_MMA(0, 1, At, B1); BAR; SCHED;
;             G_LDA(At, 0, 1); G_STAGE(G_SB(0, 0), b2, voffB); G_STAGE(G_SB(0, 1), b2 + hstep, voffB); G_STAGE(G_SA(0, 0), a2, voffA);
;             WAIT_V(8); WAIT_L(0); BAR; G_MMA(1, 0, At, B0); G_MMA(1, 1, At, B1); BAR; SCHED;
.Lrj_850_0:
	s_waitcnt lgkmcnt(0)
	s_barrier
	s_setprio 1
	s_waitcnt lgkmcnt(0)
	v_mfma_f32_16x16x32_bf16 v[124:127], v[128:131], v[180:183], 0
	v_mfma_f32_16x16x32_bf16 v[120:123], v[136:139], v[180:183], 0
	v_mfma_f32_16x16x32_bf16 v[116:119], v[128:131], v[192:195], 0
	v_mfma_f32_16x16x32_bf16 v[112:115], v[136:139], v[192:195], 0
	v_mfma_f32_16x16x32_bf16 v[108:111], v[128:131], v[200:203], 0
	v_mfma_f32_16x16x32_bf16 v[104:107], v[136:139], v[200:203], 0
	v_mfma_f32_16x16x32_bf16 v[100:103], v[128:131], v[208:211], 0
	v_mfma_f32_16x16x32_bf16 v[96:99], v[136:139], v[208:211], 0
	v_mfma_f32_16x16x32_bf16 v[124:127], v[132:135], v[188:191], v[124:127]
	v_mfma_f32_16x16x32_bf16 v[120:123], v[140:143], v[188:191], v[120:123]
	v_mfma_f32_16x16x32_bf16 v[116:119], v[132:135], v[196:199], v[116:119]
	v_mfma_f32_16x16x32_bf16 v[112:115], v[140:143], v[196:199], v[112:115]
	v_mfma_f32_16x16x32_bf16 v[108:111], v[132:135], v[204:207], v[108:111]
	v_mfma_f32_16x16x32_bf16 v[104:107], v[140:143], v[204:207], v[104:107]
	v_mfma_f32_16x16x32_bf16 v[100:103], v[132:135], v[212:215], v[100:103]
	v_mfma_f32_16x16x32_bf16 v[96:99], v[140:143], v[212:215], v[96:99]
	s_setprio 0
	s_setprio 1
	v_mfma_f32_16x16x32_bf16 v[60:63], v[158:161], v[180:183], 0
	v_mfma_f32_16x16x32_bf16 v[56:59], v[172:175], v[180:183], 0
	v_mfma_f32_16x16x32_bf16 v[52:55], v[158:161], v[192:195], 0
	v_mfma_f32_16x16x32_bf16 v[48:51], v[172:175], v[192:195], 0
	v_mfma_f32_16x16x32_bf16 v[44:47], v[158:161], v[200:203], 0
	v_mfma_f32_16x16x32_bf16 v[40:43], v[172:175], v[200:203], 0
	v_mfma_f32_16x16x32_bf16 v[36:39], v[158:161], v[208:211], 0
	v_mfma_f32_16x16x32_bf16 v[32:35], v[172:175], v[208:211], 0
	v_mfma_f32_16x16x32_bf16 v[60:63], v[162:165], v[188:191], v[60:63]
	v_mfma_f32_16x16x32_bf16 v[56:59], v[176:179], v[188:191], v[56:59]
	v_mfma_f32_16x16x32_bf16 v[52:55], v[162:165], v[196:199], v[52:55]
	v_mfma_f32_16x16x32_bf16 v[48:51], v[176:179], v[196:199], v[48:51]
	v_mfma_f32_16x16x32_bf16 v[44:47], v[162:165], v[204:207], v[44:47]
	v_mfma_f32_16x16x32_bf16 v[40:43], v[176:179], v[204:207], v[40:43]
	v_mfma_f32_16x16x32_bf16 v[36:39], v[162:165], v[212:215], v[36:39]
	v_mfma_f32_16x16x32_bf16 v[32:35], v[176:179], v[212:215], v[32:35]
	s_setprio 0
	s_barrier
	s_add_i32 s4, s50, s26
	v_lshl_add_u64 v[144:145], s[38:39], 0, v[148:149]
	s_mov_b32 m0, s4
	ds_read_b128 v[180:183], v171 offset:16384
	ds_read_b128 v[188:191], v171 offset:17408
	ds_read_b128 v[192:195], v171 offset:18432
	ds_read_b128 v[196:199], v171 offset:19456
	ds_read_b128 v[200:203], v171 offset:20480
	ds_read_b128 v[204:207], v171 offset:21504
	ds_read_b128 v[208:211], v171 offset:22528
	ds_read_b128 v[212:215], v171 offset:23552
	global_load_lds_dwordx4 v[144:145], off
	s_add_i32 m0, s4, 0x2000
	s_add_u32 s4, s38, 0xb0000
	v_lshl_add_u64 v[166:167], s[38:39], 0, v[152:153]
	s_addc_u32 s5, s39, 0
	s_add_i32 s76, s51, s26
	global_load_lds_dwordx4 v[166:167], off
	v_lshl_add_u64 v[184:185], s[4:5], 0, v[148:149]
	s_mov_b32 m0, s76
	v_lshl_add_u64 v[186:187], s[40:41], 0, v[150:151]
	global_load_lds_dwordx4 v[184:185], off
	v_lshl_add_u64 v[184:185], s[4:5], 0, v[152:153]
	s_add_i32 m0, s76, 0x2000
	s_nop 0
	global_load_lds_dwordx4 v[184:185], off
	v_lshl_add_u64 v[184:185], s[40:41], 0, v[146:147]
	s_mov_b32 m0, s42
	s_nop 0
	global_load_lds_dwordx4 v[184:185], off
	s_mov_b32 m0, s43
	s_nop 0
	global_load_lds_dwordx4 v[186:187], off
	s_cmp_lg_u32 s100, 0
	s_cbranch_scc0 .Lrf_850_1
	s_waitcnt vmcnt(16)
	s_branch .Lrj_850_1

; #define G_STAGE(bufoff, gbase, voff) do { _Pragma("unroll") for (int _i = 0; _i < 2; ++_i) \
;         __builtin_amdgcn_global_load_lds((const unsigned*)((const char*)(gbase) + voff[_i]), (LAS unsigned*)(lds + (bufoff) + ldsw + _i * 8192), 16, 0, 0); } while (0)
; #define G_LDA(dst, b, h) do { _Pragma("unroll") for (int m = 0; m < 4; ++m) _Pragma("unroll") for (int k = 0; k < 2; ++k) dst[m][k] = *(const LAS bf16x8*)(lds + G_SA(b, h) + aoff + m * 2048 + k * 1024); } while (0)
; #define G_LDB(dst, b, h) do { _Pragma("unroll") for (int n = 0; n < 2; ++n) _Pragma("unroll") for (int k = 0; k < 2; ++k) dst[n][k] = *(const LAS bf16x8*)(lds + G_SB(b, h) + boff + n * 2048 + k * 1024); } while (0)
; #define G_MMA(ai, bj, At_, Bt_) do { __builtin_amdgcn_s_setprio(1); _Pragma("unroll") for (int m = 0; m < 4; ++m) _Pragma("unroll") for (int n = 0; n < 2; ++n) _Pragma("unroll") for (int k = 0; k < 2; ++k) \
;         acc[ai][bj][m][n] = __builtin_amdgcn_mfma_f32_16x16x32_bf16(Bt_[n][k], At_[m][k], acc[ai][bj][m][n], 0, 0, 0); __builtin_amdgcn_s_setprio(0); } while (0)
; #define WAIT_V(n) asm volatile("s_waitcnt vmcnt(" #n ")" ::: "memory")
; #define WAIT_L(n) asm volatile("s_waitcnt lgkmcnt(" #n ")" ::: "memory")
; #define BAR __builtin_amdgcn_s_barrier()
; #define SCHED __builtin_amdgcn_sched_barrier(0)
; template <class Get, class Epi>
; DI void gemm_loop(int ntiles, int ld, char* shm, const Get& get, const Epi& epi) {
;     ...
;             WAIT_V(8); WAIT_L(0); BAR; G_MMA(1, 0, At, B0); G_MMA(1, 1, At, B1); BAR; SCHED;
;             G_LDB(B0, 1, 0); G_LDB(B1, 1, 1); SCHED; G_LDA(At, 1, 0); G_STAGE(G_SA(0, 1), a2 + hstep, voffA);
;             WAIT_V(8); WAIT_L(0); BAR; G_MMA(0, 0, At, B0); G_MMA(0, 1, At, B1); BAR; SCHED;
.Lrj_850_1:
	s_waitcnt lgkmcnt(0)
	s_barrier
	s_setprio 1
	s_waitcnt lgkmcnt(0)
	v_mfma_f32_16x16x32_bf16 v[92:95], v[128:131], v[180:183], 0
	v_mfma_f32_16x16x32_bf16 v[88:91], v[136:139], v[180:183], 0
	v_mfma_f32_16x16x32_bf16 v[84:87], v[128:131], v[192:195], 0
	v_mfma_f32_16x16x32_bf16 v[80:83], v[136:139], v[192:195], 0
	v_mfma_f32_16x16x32_bf16 v[76:79], v[128:131], v[200:203], 0
	v_mfma_f32_16x16x32_bf16 v[72:75], v[136:139], v[200:203], 0
	v_mfma_f32_16x16x32_bf16 v[68:71], v[128:131], v[208:211], 0
	v_mfma_f32_16x16x32_bf16 v[64:67], v[136:139], v[208:211], 0
	v_mfma_f32_16x16x32_bf16 v[92:95], v[132:135], v[188:191], v[92:95]
	v_mfma_f32_16x16x32_bf16 v[88:91], v[140:143], v[188:191], v[88:91]
	v_mfma_f32_16x16x32_bf16 v[84:87], v[132:135], v[196:199], v[84:87]
	v_mfma_f32_16x16x32_bf16 v[80:83], v[140:143], v[196:199], v[80:83]
	v_mfma_f32_16x16x32_bf16 v[76:79], v[132:135], v[204:207], v[76:79]
	v_mfma_f32_16x16x32_bf16 v[72:75], v[140:143], v[204:207], v[72:75]
	v_mfma_f32_16x16x32_bf16 v[68:71], v[132:135], v[212:215], v[68:71]
	v_mfma_f32_16x16x32_bf16 v[64:67], v[140:143], v[212:215], v[64:67]
	s_setprio 0
	s_setprio 1
	v_mfma_f32_16x16x32_bf16 v[28:31], v[158:161], v[180:183], 0
	v_mfma_f32_16x16x32_bf16 v[24:27], v[172:175], v[180:183], 0
	v_mfma_f32_16x16x32_bf16 v[20:23], v[158:161], v[192:195], 0
	v_mfma_f32_16x16x32_bf16 v[16:19], v[172:175], v[192:195], 0
	v_mfma_f32_16x16x32_bf16 v[12:15], v[158:161], v[200:203], 0
	v_mfma_f32_16x16x32_bf16 v[8:11], v[172:175], v[200:203], 0
	v_mfma_f32_16x16x32_bf16 v[4:7], v[158:161], v[208:211], 0
	v_mfma_f32_16x16x32_bf16 v[0:3], v[172:175], v[208:211], 0
	v_mfma_f32_16x16x32_bf16 v[28:31], v[162:165], v[188:191], v[28:31]
	v_mfma_f32_16x16x32_bf16 v[24:27], v[176:179], v[188:191], v[24:27]
	v_mfma_f32_16x16x32_bf16 v[20:23], v[162:165], v[196:199], v[20:23]
	v_mfma_f32_16x16x32_bf16 v[16:19], v[176:179], v[196:199], v[16:19]
	v_mfma_f32_16x16x32_bf16 v[12:15], v[162:165], v[204:207], v[12:15]
	v_mfma_f32_16x16x32_bf16 v[8:11], v[176:179], v[204:207], v[8:11]
	v_mfma_f32_16x16x32_bf16 v[4:7], v[162:165], v[212:215], v[4:7]
	v_mfma_f32_16x16x32_bf16 v[0:3], v[176:179], v[212:215], v[0:3]
	s_setprio 0
	s_barrier
	s_add_i32 s76, 0, 0x18000
	s_add_i32 s78, 0, 0x1c000
	v_add_u32_e32 v140, s76, v168
	v_add_u32_e32 v176, s78, v168
	ds_read_b128 v[128:131], v140
	ds_read_b128 v[132:135], v140 offset:1024
	ds_read_b128 v[136:139], v140 offset:2048
	ds_read_b128 v[140:143], v140 offset:3072
	ds_read_b128 v[158:161], v176
	ds_read_b128 v[162:165], v176 offset:1024
	ds_read_b128 v[172:175], v176 offset:2048
	ds_read_b128 v[176:179], v176 offset:3072
	s_add_u32 s4, s40, 0xb0000
	s_addc_u32 s5, s41, 0
	s_mov_b32 m0, s44
	v_lshl_add_u64 v[216:217], s[4:5], 0, v[146:147]
	ds_read_b128 v[180:183], v171 offset:32768
	ds_read_b128 v[188:191], v171 offset:33792
	ds_read_b128 v[192:195], v171 offset:34816
	ds_read_b128 v[196:199], v171 offset:35840
	ds_read_b128 v[200:203], v171 offset:36864
	ds_read_b128 v[204:207], v171 offset:37888
	ds_read_b128 v[208:211], v171 offset:38912
	ds_read_b128 v[212:215], v171 offset:39936
	global_load_lds_dwordx4 v[216:217], off
	v_lshl_add_u64 v[216:217], s[4:5], 0, v[150:151]
	s_mov_b32 m0, s45
	s_nop 0
	global_load_lds_dwordx4 v[216:217], off
	s_waitcnt vmcnt(8)
	s_waitcnt lgkmcnt(0)
	s_barrier
	s_setprio 1
	s_waitcnt lgkmcnt(0)
	v_mfma_f32_16x16x32_bf16 v[124:127], v[128:131], v[180:183], v[124:127]
	v_mfma_f32_16x16x32_bf16 v[120:123], v[136:139], v[180:183], v[120:123]
	v_mfma_f32_16x16x32_bf16 v[116:119], v[128:131], v[192:195], v[116:119]
	v_mfma_f32_16x16x32_bf16 v[112:115], v[136:139], v[192:195], v[112:115]
	v_mfma_f32_16x16x32_bf16 v[108:111], v[128:131], v[200:203], v[108:111]
	v_mfma_f32_16x16x32_bf16 v[104:107], v[136:139], v[200:203], v[104:107]
	v_mfma_f32_16x16x32_bf16 v[100:103], v[128:131], v[208:211], v[100:103]
	v_mfma_f32_16x16x32_bf16 v[96:99], v[136:139], v[208:211], v[96:99]
	v_mfma_f32_16x16x32_bf16 v[124:127], v[132:135], v[188:191], v[124:127]
	v_mfma_f32_16x16x32_bf16 v[120:123], v[140:143], v[188:191], v[120:123]
	v_mfma_f32_16x16x32_bf16 v[116:119], v[132:135], v[196:199], v[116:119]
	v_mfma_f32_16x16x32_bf16 v[112:115], v[140:143], v[196:199], v[112:115]
	v_mfma_f32_16x16x32_bf16 v[108:111], v[132:135], v[204:207], v[108:111]
	v_mfma_f32_16x16x32_bf16 v[104:107], v[140:143], v[204:207], v[104:107]
	v_mfma_f32_16x16x32_bf16 v[100:103], v[132:135], v[212:215], v[100:103]
	v_mfma_f32_16x16x32_bf16 v[96:99], v[140:143], v[212:215], v[96:99]
	s_setprio 0
	s_setprio 1
	v_mfma_f32_16x16x32_bf16 v[60:63], v[158:161], v[180:183], v[60:63]
	v_mfma_f32_16x16x32_bf16 v[56:59], v[172:175], v[180:183], v[56:59]
	v_mfma_f32_16x16x32_bf16 v[52:55], v[158:161], v[192:195], v[52:55]
	v_mfma_f32_16x16x32_bf16 v[48:51], v[172:175], v[192:195], v[48:51]
	v_mfma_f32_16x16x32_bf16 v[44:47], v[158:161], v[200:203], v[44:47]
	v_mfma_f32_16x16x32_bf16 v[40:43], v[172:175], v[200:203], v[40:43]
	v_mfma_f32_16x16x32_bf16 v[36:39], v[158:161], v[208:211], v[36:39]
	v_mfma_f32_16x16x32_bf16 v[32:35], v[172:175], v[208:211], v[32:35]
	v_mfma_f32_16x16x32_bf16 v[60:63], v[162:165], v[188:191], v[60:63]
	v_mfma_f32_16x16x32_bf16 v[56:59], v[176:179], v[188:191], v[56:59]
	v_mfma_f32_16x16x32_bf16 v[52:55], v[162:165], v[196:199], v[52:55]
	v_mfma_f32_16x16x32_bf16 v[48:51], v[176:179], v[196:199], v[48:51]
	v_mfma_f32_16x16x32_bf16 v[44:47], v[162:165], v[204:207], v[44:47]
	v_mfma_f32_16x16x32_bf16 v[40:43], v[176:179], v[204:207], v[40:43]
	v_mfma_f32_16x16x32_bf16 v[36:39], v[162:165], v[212:215], v[36:39]
	v_mfma_f32_16x16x32_bf16 v[32:35], v[176:179], v[212:215], v[32:35]
	s_setprio 0
	s_barrier
; #define G_STAGE(bufoff, gbase, voff) do { _Pragma("unroll") for (int _i = 0; _i < 2; ++_i) \
;         __builtin_amdgcn_global_load_lds((const unsigned*)((const char*)(gbase) + voff[_i]), (LAS unsigned*)(lds + (bufoff) + ldsw + _i * 8192), 16, 0, 0); } while (0)
; #define G_LDA(dst, b, h) do { _Pragma("unroll") for (int m = 0; m < 4; ++m) _Pragma("unroll") for (int k = 0; k < 2; ++k) dst[m][k] = *(const LAS bf16x8*)(lds + G_SA(b, h) + aoff + m * 2048 + k * 1024); } while (0)
; #define G_MMA(ai, bj, At_, Bt_) do { __builtin_amdgcn_s_setprio(1); _Pragma("unroll") for (int m = 0; m < 4; ++m) _Pragma("unroll") for (int n = 0; n < 2; ++n) _Pragma("unroll") for (int k = 0; k < 2; ++k) \
;         acc[ai][bj][m][n] = __builtin_amdgcn_mfma_f32_16x16x32_bf16(Bt_[n][k], At_[m][k], acc[ai][bj][m][n], 0, 0, 0); __builtin_amdgcn_s_setprio(0); } while (0)
; #define WAIT_V(n) asm volatile("s_waitcnt vmcnt(" #n ")" ::: "memory")
; #define WAIT_L(n) asm volatile("s_waitcnt lgkmcnt(" #n ")" ::: "memory")
; #define BAR __builtin_amdgcn_s_barrier()
; #define SCHED __builtin_amdgcn_sched_barrier(0)
; template <class Get, class Epi>
; DI void gemm_loop(int ntiles, int ld, char* shm, const Get& get, const Epi& epi) {
;     ...
;             G_LDA(At, 1, 1); G_STAGE(G_SB(1, 0), b3, voffB); G_STAGE(G_SB(1, 1), b3 + hstep, voffB); G_STAGE(G_SA(1, 0), a3, voffA);
;             WAIT_V(8); WAIT_L(0); BAR; G_MMA(1, 0, At, B0); G_MMA(1, 1, At, B1); BAR; SCHED;
;         }
	s_add_i32 s4, s76, s26
	v_lshl_add_u64 v[144:145], v[144:145], 0, s[10:11]
	s_mov_b32 m0, s4
	ds_read_b128 v[180:183], v171 offset:49152
	ds_read_b128 v[188:191], v171 offset:50176
	ds_read_b128 v[192:195], v171 offset:51200
	ds_read_b128 v[196:199], v171 offset:52224
	ds_read_b128 v[200:203], v171 offset:53248
	ds_read_b128 v[204:207], v171 offset:54272
	ds_read_b128 v[208:211], v171 offset:55296
	ds_read_b128 v[212:215], v171 offset:56320
	global_load_lds_dwordx4 v[144:145], off
	s_add_i32 m0, s4, 0x2000
	s_add_u32 s4, s38, 0xb0080
	v_lshl_add_u64 v[144:145], v[166:167], 0, s[10:11]
	s_addc_u32 s5, s39, 0
	s_add_i32 s38, s78, s26
	global_load_lds_dwordx4 v[144:145], off
	v_lshl_add_u64 v[144:145], s[4:5], 0, v[148:149]
	s_mov_b32 m0, s38
	s_nop 0
	global_load_lds_dwordx4 v[144:145], off
	v_lshl_add_u64 v[144:145], s[4:5], 0, v[152:153]
	s_add_i32 m0, s38, 0x2000
	s_nop 0
	global_load_lds_dwordx4 v[144:145], off
	v_lshl_add_u64 v[144:145], v[184:185], 0, s[10:11]
	s_mov_b32 m0, s48
	s_nop 0
	global_load_lds_dwordx4 v[144:145], off
	v_lshl_add_u64 v[144:145], v[186:187], 0, s[10:11]
	s_mov_b32 m0, s49
	s_nop 0
	global_load_lds_dwordx4 v[144:145], off
	s_waitcnt vmcnt(8)
	s_waitcnt lgkmcnt(0)
	s_barrier
	s_setprio 1
	s_waitcnt lgkmcnt(0)
	v_mfma_f32_16x16x32_bf16 v[92:95], v[128:131], v[180:183], v[92:95]
	v_mfma_f32_16x16x32_bf16 v[88:91], v[136:139], v[180:183], v[88:91]
	v_mfma_f32_16x16x32_bf16 v[84:87], v[128:131], v[192:195], v[84:87]
	v_mfma_f32_16x16x32_bf16 v[80:83], v[136:139], v[192:195], v[80:83]
	v_mfma_f32_16x16x32_bf16 v[76:79], v[128:131], v[200:203], v[76:79]
	v_mfma_f32_16x16x32_bf16 v[72:75], v[136:139], v[200:203], v[72:75]
	v_mfma_f32_16x16x32_bf16 v[68:71], v[128:131], v[208:211], v[68:71]
	v_mfma_f32_16x16x32_bf16 v[64:67], v[136:139], v[208:211], v[64:67]
	v_mfma_f32_16x16x32_bf16 v[92:95], v[132:135], v[188:191], v[92:95]
	v_mfma_f32_16x16x32_bf16 v[88:91], v[140:143], v[188:191], v[88:91]
	v_mfma_f32_16x16x32_bf16 v[84:87], v[132:135], v[196:199], v[84:87]
	v_mfma_f32_16x16x32_bf16 v[80:83], v[140:143], v[196:199], v[80:83]
	v_mfma_f32_16x16x32_bf16 v[76:79], v[132:135], v[204:207], v[76:79]
	v_mfma_f32_16x16x32_bf16 v[72:75], v[140:143], v[204:207], v[72:75]
	v_mfma_f32_16x16x32_bf16 v[68:71], v[132:135], v[212:215], v[68:71]
	v_mfma_f32_16x16x32_bf16 v[64:67], v[140:143], v[212:215], v[64:67]
	s_setprio 0
	s_setprio 1
	v_mfma_f32_16x16x32_bf16 v[28:31], v[158:161], v[180:183], v[28:31]
	v_mfma_f32_16x16x32_bf16 v[24:27], v[172:175], v[180:183], v[24:27]
	v_mfma_f32_16x16x32_bf16 v[20:23], v[158:161], v[192:195], v[20:23]
	v_mfma_f32_16x16x32_bf16 v[16:19], v[172:175], v[192:195], v[16:19]
	v_mfma_f32_16x16x32_bf16 v[12:15], v[158:161], v[200:203], v[12:15]
	v_mfma_f32_16x16x32_bf16 v[8:11], v[172:175], v[200:203], v[8:11]
	v_mfma_f32_16x16x32_bf16 v[4:7], v[158:161], v[208:211], v[4:7]
	v_mfma_f32_16x16x32_bf16 v[0:3], v[172:175], v[208:211], v[0:3]
	v_mfma_f32_16x16x32_bf16 v[28:31], v[162:165], v[188:191], v[28:31]
	v_mfma_f32_16x16x32_bf16 v[24:27], v[176:179], v[188:191], v[24:27]
	v_mfma_f32_16x16x32_bf16 v[20:23], v[162:165], v[196:199], v[20:23]
	v_mfma_f32_16x16x32_bf16 v[16:19], v[176:179], v[196:199], v[16:19]
	v_mfma_f32_16x16x32_bf16 v[12:15], v[162:165], v[204:207], v[12:15]
	v_mfma_f32_16x16x32_bf16 v[8:11], v[176:179], v[204:207], v[8:11]
	v_mfma_f32_16x16x32_bf16 v[4:7], v[162:165], v[212:215], v[4:7]
	v_mfma_f32_16x16x32_bf16 v[0:3], v[176:179], v[212:215], v[0:3]
	s_setprio 0
	s_barrier
	s_add_u32 s73, s73, 0x100
	s_addc_u32 s74, s74, 0
	s_cmp_ge_u32 s75, s59
	s_mov_b64 s[4:5], s[14:15]
	s_mov_b32 s38, s75
	s_cbranch_scc0 .LBB0_850
	s_branch .Lpost_850

; #define G_STAGE(bufoff, gbase, voff) do { _Pragma("unroll") for (int _i = 0; _i < 2; ++_i) \
;         __builtin_amdgcn_global_load_lds((const unsigned*)((const char*)(gbase) + voff[_i]), (LAS unsigned*)(lds + (bufoff) + ldsw + _i * 8192), 16, 0, 0); } while (0)
; #define WAIT_V(n) asm volatile("s_waitcnt vmcnt(" #n ")" ::: "memory")
; #define BAR __builtin_amdgcn_s_barrier()
; template <class Get, class Epi>
; DI void gemm_loop(int ntiles, int ld, char* shm, const Get& get, const Epi& epi) {
;     ...
;     for (int i = 0; i < 2; ++i) { int R, C; stage_rc(tid * 16 + i * 8192, R, C); const int rho = R & 31, Rb = (R & ~31) + 8 * ((rho & 15) >> 2) + 4 * (rho >> 4) + (rho & 3);
;         voffA[i] = (unsigned)(R * ld + C) * 2u; voffB[i] = (unsigned)(Rb * ld + C) * 2u; }
;     const size_t kstep = (size_t)(BK * 2), hstep = (size_t)HALF * ld * 2;
;     const unsigned ldsw = (unsigned)wid * 1024u;
;     const int aoff = lds_byte(wr * 64 + fr, fq * 8), boff = lds_byte(wc * 32 + fr, fq * 8);
;     ...
;     int L = bx; if (L >= ntiles) return;
;     Tile cur = get(L), nxt = cur;
;     AccT acc;
;     ...
;     G_ZERO;
;     bf16x8 At[4][2], B0[2][2], B1[2][2];
;     const char* cA = (const char*)cur.A + (size_t)cur.brow * ld * 2; const char* cB = (const char*)cur.Bt + (size_t)cur.bcol * ld * 2;
;     G_STAGE(G_SB(0, 0), cB, voffB); G_STAGE(G_SB(0, 1), cB + hstep, voffB); G_STAGE(G_SA(0, 0), cA, voffA); G_STAGE(G_SA(0, 1), cA + hstep, voffA);
;     if (wr == 1) BAR;
;     WAIT_V(2); BAR;
;     G_STAGE(G_SB(1, 0), cB + kstep, voffB); G_STAGE(G_SA(1, 0), cA + kstep, voffA); G_STAGE(G_SB(1, 1), cB + hstep + kstep, voffB);
;     WAIT_V(6); BAR;
.LBB0_1089:
	s_lshl_b32 s13, s10, 13
	s_lshl_b32 s10, s30, 12
	s_and_b32 s34, s10, 0x3000
	s_mov_b64 s[10:11], 0x80
	s_add_i32 m0, s45, 0x18000
	v_lshl_add_u64 v[6:7], v[6:7], 0, s[10:11]
	s_waitcnt vmcnt(2)
	s_barrier
	global_load_lds_dwordx4 v[6:7], off
	v_lshl_add_u64 v[4:5], v[4:5], 0, s[10:11]
	s_add_i32 m0, s45, 0x1a000
	s_add_i32 s54, s45, 0x8000
	s_add_i32 s55, s45, 0xa000
	global_load_lds_dwordx4 v[4:5], off
	v_lshl_add_u64 v[0:1], v[0:1], 0, s[10:11]
	s_mov_b32 m0, s54
	s_add_u32 s30, s14, 0x40080
	global_load_lds_dwordx4 v[0:1], off
	v_lshl_add_u64 v[0:1], v[2:3], 0, s[10:11]
	s_mov_b32 m0, s55
	s_addc_u32 s31, s15, 0
	global_load_lds_dwordx4 v[0:1], off
	s_add_i32 m0, s45, 0x1c000
	v_lshl_add_u64 v[0:1], s[30:31], 0, v[130:131]
	global_load_lds_dwordx4 v[0:1], off
	v_lshl_add_u64 v[0:1], s[30:31], 0, v[134:135]
	s_add_i32 m0, s45, 0x1e000
	v_lshlrev_b32_e32 v3, 2, v8
	global_load_lds_dwordx4 v[0:1], off
	v_and_b32_e32 v0, 15, v8
	v_and_b32_e32 v1, 48, v8
	v_lshlrev_b32_e32 v0, 6, v0
	v_and_b32_e32 v3, 32, v3
	v_or_b32_e32 v2, v0, v1
	v_bitop3_b32 v0, v0, v3, v1 bitop3:0x36
	v_or_b32_e32 v144, s34, v0
	v_lshlrev_b32_e32 v0, 14, v9
	v_and_b32_e32 v0, 0xffff8000, v0
	v_bitop3_b32 v1, v2, s13, v3 bitop3:0xde
	v_lshl_add_u32 v0, v10, 11, v0
	v_and_b32_e32 v2, 1, v9
	v_lshl_or_b32 v0, v2, 6, v0
	v_lshl_add_u32 v136, v11, 1, v0
	v_lshlrev_b32_e32 v0, 14, v12
	s_cmpk_lt_u32 s12, 0x100
	v_and_b32_e32 v0, 0xffff8000, v0
	s_waitcnt vmcnt(6)
	s_mov_b32 s100, 0
	s_cselect_b64 s[12:13], -1, 0
	s_add_u32 s30, s68, 0x1eda000
	v_lshl_add_u32 v0, v13, 11, v0
	v_and_b32_e32 v2, 1, v12
	s_addc_u32 s31, s69, 0
	v_lshl_or_b32 v0, v2, 6, v0
	s_add_i32 s57, 0, 0x10000
	s_add_i32 s58, 0, 0x14000
	v_mov_b32_e32 v137, v131
	v_lshl_add_u32 v138, v14, 1, v0
	v_mov_b32_e32 v139, v131
	v_add_u32_e32 v145, s57, v144
	v_add_u32_e32 v146, s58, v144
	v_add_u32_e32 v147, 0, v1
	s_movk_i32 s59, 0x1200
	s_barrier
	s_branch .LBB0_1092

; #define G_STAGE(bufoff, gbase, voff) do { _Pragma("unroll") for (int _i = 0; _i < 2; ++_i) \
;         __builtin_amdgcn_global_load_lds((const unsigned*)((const char*)(gbase) + voff[_i]), (LAS unsigned*)(lds + (bufoff) + ldsw + _i * 8192), 16, 0, 0); } while (0)
; #define G_LDA(dst, b, h) do { _Pragma("unroll") for (int m = 0; m < 4; ++m) _Pragma("unroll") for (int k = 0; k < 2; ++k) dst[m][k] = *(const LAS bf16x8*)(lds + G_SA(b, h) + aoff + m * 2048 + k * 1024); } while (0)
; #define G_LDB(dst, b, h) do { _Pragma("unroll") for (int n = 0; n < 2; ++n) _Pragma("unroll") for (int k = 0; k < 2; ++k) dst[n][k] = *(const LAS bf16x8*)(lds + G_SB(b, h) + boff + n * 2048 + k * 1024); } while (0)
; #define G_MMA(ai, bj, At_, Bt_) do { __builtin_amdgcn_s_setprio(1); _Pragma("unroll") for (int m = 0; m < 4; ++m) _Pragma("unroll") for (int n = 0; n < 2; ++n) _Pragma("unroll") for (int k = 0; k < 2; ++k) \
;         acc[ai][bj][m][n] = __builtin_amdgcn_mfma_f32_16x16x32_bf16(Bt_[n][k], At_[m][k], acc[ai][bj][m][n], 0, 0, 0); __builtin_amdgcn_s_setprio(0); } while (0)
; #define WAIT_V(n) asm volatile("s_waitcnt vmcnt(" #n ")" ::: "memory")
; #define WAIT_L(n) asm volatile("s_waitcnt lgkmcnt(" #n ")" ::: "memory")
; #define BAR __builtin_amdgcn_s_barrier()
; #define SCHED __builtin_amdgcn_sched_barrier(0)
; template <class Get, class Epi>
; DI void gemm_loop(int ntiles, int ld, char* shm, const Get& get, const Epi& epi) {
;     ...
;             const bool last = (t == nt - 2);
;             const char* a1 = cA + (size_t)(t + 1) * kstep;
;             const char* a2 = last ? nA : cA + (size_t)(t + 2) * kstep; const char* b2 = last ? nB : cB + (size_t)(t + 2) * kstep;
;             const char* a3 = a2 + kstep; const char* b3 = b2 + kstep;
;             G_LDB(B0, 0, 0); G_LDB(B1, 0, 1); SCHED; G_LDA(At, 0, 0); G_STAGE(G_SA(1, 1), a1 + hstep, voffA);
;             WAIT_V(8); WAIT_L(0); BAR; G_MMA(0, 0, At, B0); G_MMA(0, 1, At, B1); BAR; SCHED;
.Lpeel_1099:
	ds_read_b128 v[140:143], v145
	ds_read_b128 v[148:151], v145 offset:1024
	ds_read_b128 v[152:155], v145 offset:2048
	ds_read_b128 v[156:159], v145 offset:3072
	ds_read_b128 v[160:163], v146
	ds_read_b128 v[164:167], v146 offset:1024
	ds_read_b128 v[168:171], v146 offset:2048
	ds_read_b128 v[172:175], v146 offset:3072
	s_add_u32 s14, s52, 0xfffc0080
	s_addc_u32 s15, s53, -1
	s_cmp_eq_u32 s76, 12
	s_cselect_b32 s47, s39, s15
	s_cselect_b32 s46, s72, s14
	s_cselect_b32 s15, s37, s75
	s_cselect_b32 s14, s73, s74
	v_lshl_add_u64 v[208:209], s[52:53], 0, v[136:137]
	s_add_i32 m0, s45, 0xc000
	ds_read_b128 v[176:179], v147
	ds_read_b128 v[180:183], v147 offset:1024
	ds_read_b128 v[184:187], v147 offset:2048
	ds_read_b128 v[188:191], v147 offset:3072
	ds_read_b128 v[192:195], v147 offset:4096
	ds_read_b128 v[196:199], v147 offset:5120
	ds_read_b128 v[200:203], v147 offset:6144
	ds_read_b128 v[204:207], v147 offset:7168
	global_load_lds_dwordx4 v[208:209], off
	v_lshl_add_u64 v[208:209], s[52:53], 0, v[138:139]
	s_add_i32 m0, s45, 0xe000
	s_nop 0
	global_load_lds_dwordx4 v[208:209], off
	s_cmp_lg_u32 s100, 0
	s_cbranch_scc0 .Lrf_1099_0
	s_waitcnt vmcnt(16)
	s_branch .Lrj_1099_0

; #define G_STAGE(bufoff, gbase, voff) do { _Pragma("unroll") for (int _i = 0; _i < 2; ++_i) \
;         __builtin_amdgcn_global_load_lds((const unsigned*)((const char*)(gbase) + voff[_i]), (LAS unsigned*)(lds + (bufoff) + ldsw + _i * 8192), 16, 0, 0); } while (0)
; #define G_LDA(dst, b, h) do { _Pragma("unroll") for (int m = 0; m < 4; ++m) _Pragma("unroll") for (int k = 0; k < 2; ++k) dst[m][k] = *(const LAS bf16x8*)(lds + G_SA(b, h) + aoff + m * 2048 + k * 1024); } while (0)
; #define G_MMA(ai, bj, At_, Bt_) do { __builtin_amdgcn_s_setprio(1); _Pragma("unroll") for (int m = 0; m < 4; ++m) _Pragma("unroll") for (int n = 0; n < 2; ++n) _Pragma("unroll") for (int k = 0; k < 2; ++k) \
;         acc[ai][bj][m][n] = __builtin_amdgcn_mfma_f32_16x16x32_bf16(Bt_[n][k], At_[m][k], acc[ai][bj][m][n], 0, 0, 0); __builtin_amdgcn_s_setprio(0); } while (0)
; #define WAIT_V(n) asm volatile("s_waitcnt vmcnt(" #n ")" ::: "memory")
; #define WAIT_L(n) asm volatile("s_waitcnt lgkmcnt(" #n ")" ::: "memory")
; #define BAR __builtin_amdgcn_s_barrier()
; #define SCHED __builtin_amdgcn_sched_barrier(0)
; template <class Get, class Epi>
; DI void gemm_loop(int ntiles, int ld, char* shm, const Get& get, const Epi& epi) {
;     ...
;             WAIT_V(8); WAIT_L(0); BAR; G_MMA(0, 0, At, B0); G_MMA(0, 1, At, B1); BAR; SCHED;
;             G_LDA(At, 0, 1); G_STAGE(G_SB(0, 0), b2, voffB); G_STAGE(G_SB(0, 1), b2 + hstep, voffB); G_STAGE(G_SA(0, 0), a2, voffA);
;             WAIT_V(8); WAIT_L(0); BAR; G_MMA(1, 0, At, B0); G_MMA(1, 1, At, B1); BAR; SCHED;
.Lrj_1099_0:
	s_waitcnt lgkmcnt(0)
	s_barrier
	s_setprio 1
	s_waitcnt lgkmcnt(0)
	v_mfma_f32_16x16x32_bf16 v[124:127], v[140:143], v[176:179], 0
	v_mfma_f32_16x16x32_bf16 v[120:123], v[152:155], v[176:179], 0
	v_mfma_f32_16x16x32_bf16 v[116:119], v[140:143], v[184:187], 0
	v_mfma_f32_16x16x32_bf16 v[112:115], v[152:155], v[184:187], 0
	v_mfma_f32_16x16x32_bf16 v[108:111], v[140:143], v[192:195], 0
	v_mfma_f32_16x16x32_bf16 v[100:103], v[152:155], v[192:195], 0
	v_mfma_f32_16x16x32_bf16 v[92:95], v[140:143], v[200:203], 0
	v_mfma_f32_16x16x32_bf16 v[84:87], v[152:155], v[200:203], 0
	v_mfma_f32_16x16x32_bf16 v[124:127], v[148:151], v[180:183], v[124:127]
	v_mfma_f32_16x16x32_bf16 v[120:123], v[156:159], v[180:183], v[120:123]
	v_mfma_f32_16x16x32_bf16 v[116:119], v[148:151], v[188:191], v[116:119]
	v_mfma_f32_16x16x32_bf16 v[112:115], v[156:159], v[188:191], v[112:115]
	v_mfma_f32_16x16x32_bf16 v[108:111], v[148:151], v[196:199], v[108:111]
	v_mfma_f32_16x16x32_bf16 v[100:103], v[156:159], v[196:199], v[100:103]
	v_mfma_f32_16x16x32_bf16 v[92:95], v[148:151], v[204:207], v[92:95]
	v_mfma_f32_16x16x32_bf16 v[84:87], v[156:159], v[204:207], v[84:87]
	s_setprio 0
	s_setprio 1
	v_mfma_f32_16x16x32_bf16 v[104:107], v[160:163], v[176:179], 0
	v_mfma_f32_16x16x32_bf16 v[96:99], v[168:171], v[176:179], 0
	v_mfma_f32_16x16x32_bf16 v[88:91], v[160:163], v[184:187], 0
	v_mfma_f32_16x16x32_bf16 v[80:83], v[168:171], v[184:187], 0
	v_mfma_f32_16x16x32_bf16 v[76:79], v[160:163], v[192:195], 0
	v_mfma_f32_16x16x32_bf16 v[72:75], v[168:171], v[192:195], 0
	v_mfma_f32_16x16x32_bf16 v[68:71], v[160:163], v[200:203], 0
	v_mfma_f32_16x16x32_bf16 v[64:67], v[168:171], v[200:203], 0
	v_mfma_f32_16x16x32_bf16 v[104:107], v[164:167], v[180:183], v[104:107]
	v_mfma_f32_16x16x32_bf16 v[96:99], v[172:175], v[180:183], v[96:99]
	v_mfma_f32_16x16x32_bf16 v[88:91], v[164:167], v[188:191], v[88:91]
	v_mfma_f32_16x16x32_bf16 v[80:83], v[172:175], v[188:191], v[80:83]
	v_mfma_f32_16x16x32_bf16 v[76:79], v[164:167], v[196:199], v[76:79]
	v_mfma_f32_16x16x32_bf16 v[72:75], v[172:175], v[196:199], v[72:75]
	v_mfma_f32_16x16x32_bf16 v[68:71], v[164:167], v[204:207], v[68:71]
	v_mfma_f32_16x16x32_bf16 v[64:67], v[172:175], v[204:207], v[64:67]
	s_setprio 0
	s_barrier
	s_add_i32 s77, s57, s7
	v_lshl_add_u64 v[208:209], s[14:15], 0, v[130:131]
	s_mov_b32 m0, s77
	ds_read_b128 v[176:179], v147 offset:16384
	ds_read_b128 v[180:183], v147 offset:17408
	ds_read_b128 v[184:187], v147 offset:18432
	ds_read_b128 v[188:191], v147 offset:19456
	ds_read_b128 v[192:195], v147 offset:20480
	ds_read_b128 v[196:199], v147 offset:21504
	ds_read_b128 v[200:203], v147 offset:22528
	ds_read_b128 v[204:207], v147 offset:23552
	global_load_lds_dwordx4 v[208:209], off
	s_add_i32 m0, s77, 0x2000
	s_add_u32 s78, s14, 0x40000
	v_lshl_add_u64 v[210:211], s[14:15], 0, v[134:135]
	s_addc_u32 s79, s15, 0
	s_add_i32 s77, s58, s7
	global_load_lds_dwordx4 v[210:211], off
	v_lshl_add_u64 v[212:213], s[78:79], 0, v[130:131]
	s_mov_b32 m0, s77
	v_lshl_add_u64 v[214:215], s[46:47], 0, v[132:133]
	global_load_lds_dwordx4 v[212:213], off
	v_lshl_add_u64 v[212:213], s[78:79], 0, v[134:135]
	s_add_i32 m0, s77, 0x2000
	s_nop 0
	global_load_lds_dwordx4 v[212:213], off
	v_lshl_add_u64 v[212:213], s[46:47], 0, v[128:129]
	s_mov_b32 m0, s45
	s_nop 0
	global_load_lds_dwordx4 v[212:213], off
	s_mov_b32 m0, s49
	s_nop 0
	global_load_lds_dwordx4 v[214:215], off
	s_cmp_lg_u32 s100, 0
	s_cbranch_scc0 .Lrf_1099_1
	s_waitcnt vmcnt(16)
	s_branch .Lrj_1099_1

; #define G_STAGE(bufoff, gbase, voff) do { _Pragma("unroll") for (int _i = 0; _i < 2; ++_i) \
;         __builtin_amdgcn_global_load_lds((const unsigned*)((const char*)(gbase) + voff[_i]), (LAS unsigned*)(lds + (bufoff) + ldsw + _i * 8192), 16, 0, 0); } while (0)
; #define G_LDA(dst, b, h) do { _Pragma("unroll") for (int m = 0; m < 4; ++m) _Pragma("unroll") for (int k = 0; k < 2; ++k) dst[m][k] = *(const LAS bf16x8*)(lds + G_SA(b, h) + aoff + m * 2048 + k * 1024); } while (0)
; #define G_LDB(dst, b, h) do { _Pragma("unroll") for (int n = 0; n < 2; ++n) _Pragma("unroll") for (int k = 0; k < 2; ++k) dst[n][k] = *(const LAS bf16x8*)(lds + G_SB(b, h) + boff + n * 2048 + k * 1024); } while (0)
; #define G_MMA(ai, bj, At_, Bt_) do { __builtin_amdgcn_s_setprio(1); _Pragma("unroll") for (int m = 0; m < 4; ++m) _Pragma("unroll") for (int n = 0; n < 2; ++n) _Pragma("unroll") for (int k = 0; k < 2; ++k) \
;         acc[ai][bj][m][n] = __builtin_amdgcn_mfma_f32_16x16x32_bf16(Bt_[n][k], At_[m][k], acc[ai][bj][m][n], 0, 0, 0); __builtin_amdgcn_s_setprio(0); } while (0)
; #define WAIT_V(n) asm volatile("s_waitcnt vmcnt(" #n ")" ::: "memory")
; #define WAIT_L(n) asm volatile("s_waitcnt lgkmcnt(" #n ")" ::: "memory")
; #define BAR __builtin_amdgcn_s_barrier()
; #define SCHED __builtin_amdgcn_sched_barrier(0)
; template <class Get, class Epi>
; DI void gemm_loop(int ntiles, int ld, char* shm, const Get& get, const Epi& epi) {
;     ...
;             WAIT_V(8); WAIT_L(0); BAR; G_MMA(1, 0, At, B0); G_MMA(1, 1, At, B1); BAR; SCHED;
;             G_LDB(B0, 1, 0); G_LDB(B1, 1, 1); SCHED; G_LDA(At, 1, 0); G_STAGE(G_SA(0, 1), a2 + hstep, voffA);
;             WAIT_V(8); WAIT_L(0); BAR; G_MMA(0, 0, At, B0); G_MMA(0, 1, At, B1); BAR; SCHED;
.Lrj_1099_1:
	s_waitcnt lgkmcnt(0)
	s_barrier
	s_setprio 1
	s_waitcnt lgkmcnt(0)
	v_mfma_f32_16x16x32_bf16 v[60:63], v[140:143], v[176:179], 0
	v_mfma_f32_16x16x32_bf16 v[56:59], v[152:155], v[176:179], 0
	v_mfma_f32_16x16x32_bf16 v[52:55], v[140:143], v[184:187], 0
	v_mfma_f32_16x16x32_bf16 v[48:51], v[152:155], v[184:187], 0
	v_mfma_f32_16x16x32_bf16 v[44:47], v[140:143], v[192:195], 0
	v_mfma_f32_16x16x32_bf16 v[36:39], v[152:155], v[192:195], 0
	v_mfma_f32_16x16x32_bf16 v[28:31], v[140:143], v[200:203], 0
	v_mfma_f32_16x16x32_bf16 v[20:23], v[152:155], v[200:203], 0
	v_mfma_f32_16x16x32_bf16 v[60:63], v[148:151], v[180:183], v[60:63]
	v_mfma_f32_16x16x32_bf16 v[56:59], v[156:159], v[180:183], v[56:59]
	v_mfma_f32_16x16x32_bf16 v[52:55], v[148:151], v[188:191], v[52:55]
	v_mfma_f32_16x16x32_bf16 v[48:51], v[156:159], v[188:191], v[48:51]
	v_mfma_f32_16x16x32_bf16 v[44:47], v[148:151], v[196:199], v[44:47]
	v_mfma_f32_16x16x32_bf16 v[36:39], v[156:159], v[196:199], v[36:39]
	v_mfma_f32_16x16x32_bf16 v[28:31], v[148:151], v[204:207], v[28:31]
	v_mfma_f32_16x16x32_bf16 v[20:23], v[156:159], v[204:207], v[20:23]
	s_setprio 0
	s_setprio 1
	v_mfma_f32_16x16x32_bf16 v[40:43], v[160:163], v[176:179], 0
	v_mfma_f32_16x16x32_bf16 v[32:35], v[168:171], v[176:179], 0
	v_mfma_f32_16x16x32_bf16 v[24:27], v[160:163], v[184:187], 0
	v_mfma_f32_16x16x32_bf16 v[16:19], v[168:171], v[184:187], 0
	v_mfma_f32_16x16x32_bf16 v[12:15], v[160:163], v[192:195], 0
	v_mfma_f32_16x16x32_bf16 v[8:11], v[168:171], v[192:195], 0
	v_mfma_f32_16x16x32_bf16 v[4:7], v[160:163], v[200:203], 0
	v_mfma_f32_16x16x32_bf16 v[0:3], v[168:171], v[200:203], 0
	v_mfma_f32_16x16x32_bf16 v[40:43], v[164:167], v[180:183], v[40:43]
	v_mfma_f32_16x16x32_bf16 v[32:35], v[172:175], v[180:183], v[32:35]
	v_mfma_f32_16x16x32_bf16 v[24:27], v[164:167], v[188:191], v[24:27]
	v_mfma_f32_16x16x32_bf16 v[16:19], v[172:175], v[188:191], v[16:19]
	v_mfma_f32_16x16x32_bf16 v[12:15], v[164:167], v[196:199], v[12:15]
	v_mfma_f32_16x16x32_bf16 v[8:11], v[172:175], v[196:199], v[8:11]
	v_mfma_f32_16x16x32_bf16 v[4:7], v[164:167], v[204:207], v[4:7]
	v_mfma_f32_16x16x32_bf16 v[0:3], v[172:175], v[204:207], v[0:3]
	s_setprio 0
	s_barrier
	s_add_i32 s77, 0, 0x18000
	s_add_i32 s78, 0, 0x1c000
	v_add_u32_e32 v156, s77, v144
	v_add_u32_e32 v172, s78, v144
	ds_read_b128 v[140:143], v156
	ds_read_b128 v[148:151], v156 offset:1024
	ds_read_b128 v[152:155], v156 offset:2048
	ds_read_b128 v[156:159], v156 offset:3072
	ds_read_b128 v[160:163], v172
	ds_read_b128 v[164:167], v172 offset:1024
	ds_read_b128 v[168:171], v172 offset:2048
	ds_read_b128 v[172:175], v172 offset:3072
	s_add_u32 s46, s46, 0x40000
	s_addc_u32 s47, s47, 0
	s_mov_b32 m0, s50
	v_lshl_add_u64 v[216:217], s[46:47], 0, v[128:129]
	ds_read_b128 v[176:179], v147 offset:32768
	ds_read_b128 v[180:183], v147 offset:33792
	ds_read_b128 v[184:187], v147 offset:34816
	ds_read_b128 v[188:191], v147 offset:35840
	ds_read_b128 v[192:195], v147 offset:36864
	ds_read_b128 v[196:199], v147 offset:37888
	ds_read_b128 v[200:203], v147 offset:38912
	ds_read_b128 v[204:207], v147 offset:39936
	global_load_lds_dwordx4 v[216:217], off
	v_lshl_add_u64 v[216:217], s[46:47], 0, v[132:133]
	s_mov_b32 m0, s51
	s_nop 0
	global_load_lds_dwordx4 v[216:217], off
	s_waitcnt vmcnt(8)
	s_waitcnt lgkmcnt(0)
	s_barrier
	s_setprio 1
	s_waitcnt lgkmcnt(0)
	v_mfma_f32_16x16x32_bf16 v[124:127], v[140:143], v[176:179], v[124:127]
	v_mfma_f32_16x16x32_bf16 v[120:123], v[152:155], v[176:179], v[120:123]
	v_mfma_f32_16x16x32_bf16 v[116:119], v[140:143], v[184:187], v[116:119]
	v_mfma_f32_16x16x32_bf16 v[112:115], v[152:155], v[184:187], v[112:115]
	v_mfma_f32_16x16x32_bf16 v[108:111], v[140:143], v[192:195], v[108:111]
	v_mfma_f32_16x16x32_bf16 v[100:103], v[152:155], v[192:195], v[100:103]
	v_mfma_f32_16x16x32_bf16 v[92:95], v[140:143], v[200:203], v[92:95]
	v_mfma_f32_16x16x32_bf16 v[84:87], v[152:155], v[200:203], v[84:87]
	v_mfma_f32_16x16x32_bf16 v[124:127], v[148:151], v[180:183], v[124:127]
	v_mfma_f32_16x16x32_bf16 v[120:123], v[156:159], v[180:183], v[120:123]
	v_mfma_f32_16x16x32_bf16 v[116:119], v[148:151], v[188:191], v[116:119]
	v_mfma_f32_16x16x32_bf16 v[112:115], v[156:159], v[188:191], v[112:115]
	v_mfma_f32_16x16x32_bf16 v[108:111], v[148:151], v[196:199], v[108:111]
	v_mfma_f32_16x16x32_bf16 v[100:103], v[156:159], v[196:199], v[100:103]
	v_mfma_f32_16x16x32_bf16 v[92:95], v[148:151], v[204:207], v[92:95]
	v_mfma_f32_16x16x32_bf16 v[84:87], v[156:159], v[204:207], v[84:87]
	s_setprio 0
	s_setprio 1
	v_mfma_f32_16x16x32_bf16 v[104:107], v[160:163], v[176:179], v[104:107]
	v_mfma_f32_16x16x32_bf16 v[96:99], v[168:171], v[176:179], v[96:99]
	v_mfma_f32_16x16x32_bf16 v[88:91], v[160:163], v[184:187], v[88:91]
	v_mfma_f32_16x16x32_bf16 v[80:83], v[168:171], v[184:187], v[80:83]
	v_mfma_f32_16x16x32_bf16 v[76:79], v[160:163], v[192:195], v[76:79]
	v_mfma_f32_16x16x32_bf16 v[72:75], v[168:171], v[192:195], v[72:75]
	v_mfma_f32_16x16x32_bf16 v[68:71], v[160:163], v[200:203], v[68:71]
	v_mfma_f32_16x16x32_bf16 v[64:67], v[168:171], v[200:203], v[64:67]
	v_mfma_f32_16x16x32_bf16 v[104:107], v[164:167], v[180:183], v[104:107]
	v_mfma_f32_16x16x32_bf16 v[96:99], v[172:175], v[180:183], v[96:99]
	v_mfma_f32_16x16x32_bf16 v[88:91], v[164:167], v[188:191], v[88:91]
	v_mfma_f32_16x16x32_bf16 v[80:83], v[172:175], v[188:191], v[80:83]
	v_mfma_f32_16x16x32_bf16 v[76:79], v[164:167], v[196:199], v[76:79]
	v_mfma_f32_16x16x32_bf16 v[72:75], v[172:175], v[196:199], v[72:75]
	v_mfma_f32_16x16x32_bf16 v[68:71], v[164:167], v[204:207], v[68:71]
	v_mfma_f32_16x16x32_bf16 v[64:67], v[172:175], v[204:207], v[64:67]
	s_setprio 0
	s_barrier
; #define G_STAGE(bufoff, gbase, voff) do { _Pragma("unroll") for (int _i = 0; _i < 2; ++_i) \
;         __builtin_amdgcn_global_load_lds((const unsigned*)((const char*)(gbase) + voff[_i]), (LAS unsigned*)(lds + (bufoff) + ldsw + _i * 8192), 16, 0, 0); } while (0)
; #define G_LDA(dst, b, h) do { _Pragma("unroll") for (int m = 0; m < 4; ++m) _Pragma("unroll") for (int k = 0; k < 2; ++k) dst[m][k] = *(const LAS bf16x8*)(lds + G_SA(b, h) + aoff + m * 2048 + k * 1024); } while (0)
; #define G_MMA(ai, bj, At_, Bt_) do { __builtin_amdgcn_s_setprio(1); _Pragma("unroll") for (int m = 0; m < 4; ++m) _Pragma("unroll") for (int n = 0; n < 2; ++n) _Pragma("unroll") for (int k = 0; k < 2; ++k) \
;         acc[ai][bj][m][n] = __builtin_amdgcn_mfma_f32_16x16x32_bf16(Bt_[n][k], At_[m][k], acc[ai][bj][m][n], 0, 0, 0); __builtin_amdgcn_s_setprio(0); } while (0)
; #define WAIT_V(n) asm volatile("s_waitcnt vmcnt(" #n ")" ::: "memory")
; #define WAIT_L(n) asm volatile("s_waitcnt lgkmcnt(" #n ")" ::: "memory")
; #define BAR __builtin_amdgcn_s_barrier()
; #define SCHED __builtin_amdgcn_sched_barrier(0)
; template <class Get, class Epi>
; DI void gemm_loop(int ntiles, int ld, char* shm, const Get& get, const Epi& epi) {
;     ...
;             G_LDA(At, 1, 1); G_STAGE(G_SB(1, 0), b3, voffB); G_STAGE(G_SB(1, 1), b3 + hstep, voffB); G_STAGE(G_SA(1, 0), a3, voffA);
;             WAIT_V(8); WAIT_L(0); BAR; G_MMA(1, 0, At, B0); G_MMA(1, 1, At, B1); BAR; SCHED;
;         }
	s_add_i32 s46, s77, s7
	v_lshl_add_u64 v[208:209], v[208:209], 0, s[10:11]
	s_mov_b32 m0, s46
	ds_read_b128 v[176:179], v147 offset:49152
	ds_read_b128 v[180:183], v147 offset:50176
	ds_read_b128 v[184:187], v147 offset:51200
	ds_read_b128 v[188:191], v147 offset:52224
	ds_read_b128 v[192:195], v147 offset:53248
	ds_read_b128 v[196:199], v147 offset:54272
	ds_read_b128 v[200:203], v147 offset:55296
	ds_read_b128 v[204:207], v147 offset:56320
	global_load_lds_dwordx4 v[208:209], off
	s_add_i32 m0, s46, 0x2000
	s_add_u32 s14, s14, 0x40080
	v_lshl_add_u64 v[208:209], v[210:211], 0, s[10:11]
	s_addc_u32 s15, s15, 0
	s_add_i32 s46, s78, s7
	global_load_lds_dwordx4 v[208:209], off
	v_lshl_add_u64 v[208:209], s[14:15], 0, v[130:131]
	s_mov_b32 m0, s46
	s_nop 0
	global_load_lds_dwordx4 v[208:209], off
	v_lshl_add_u64 v[208:209], s[14:15], 0, v[134:135]
	s_add_i32 m0, s46, 0x2000
	s_nop 0
	global_load_lds_dwordx4 v[208:209], off
	v_lshl_add_u64 v[208:209], v[212:213], 0, s[10:11]
	s_mov_b32 m0, s54
	s_nop 0
	global_load_lds_dwordx4 v[208:209], off
	v_lshl_add_u64 v[208:209], v[214:215], 0, s[10:11]
	s_mov_b32 m0, s55
	s_nop 0
	global_load_lds_dwordx4 v[208:209], off
	s_waitcnt vmcnt(8)
	s_waitcnt lgkmcnt(0)
	s_barrier
	s_setprio 1
	s_waitcnt lgkmcnt(0)
	v_mfma_f32_16x16x32_bf16 v[60:63], v[140:143], v[176:179], v[60:63]
	v_mfma_f32_16x16x32_bf16 v[56:59], v[152:155], v[176:179], v[56:59]
	v_mfma_f32_16x16x32_bf16 v[52:55], v[140:143], v[184:187], v[52:55]
	v_mfma_f32_16x16x32_bf16 v[48:51], v[152:155], v[184:187], v[48:51]
	v_mfma_f32_16x16x32_bf16 v[44:47], v[140:143], v[192:195], v[44:47]
	v_mfma_f32_16x16x32_bf16 v[36:39], v[152:155], v[192:195], v[36:39]
	v_mfma_f32_16x16x32_bf16 v[28:31], v[140:143], v[200:203], v[28:31]
	v_mfma_f32_16x16x32_bf16 v[20:23], v[152:155], v[200:203], v[20:23]
	v_mfma_f32_16x16x32_bf16 v[60:63], v[148:151], v[180:183], v[60:63]
	v_mfma_f32_16x16x32_bf16 v[56:59], v[156:159], v[180:183], v[56:59]
	v_mfma_f32_16x16x32_bf16 v[52:55], v[148:151], v[188:191], v[52:55]
	v_mfma_f32_16x16x32_bf16 v[48:51], v[156:159], v[188:191], v[48:51]
	v_mfma_f32_16x16x32_bf16 v[44:47], v[148:151], v[196:199], v[44:47]
	v_mfma_f32_16x16x32_bf16 v[36:39], v[156:159], v[196:199], v[36:39]
	v_mfma_f32_16x16x32_bf16 v[28:31], v[148:151], v[204:207], v[28:31]
	v_mfma_f32_16x16x32_bf16 v[20:23], v[156:159], v[204:207], v[20:23]
	s_setprio 0
	s_setprio 1
	v_mfma_f32_16x16x32_bf16 v[40:43], v[160:163], v[176:179], v[40:43]
	v_mfma_f32_16x16x32_bf16 v[32:35], v[168:171], v[176:179], v[32:35]
	v_mfma_f32_16x16x32_bf16 v[24:27], v[160:163], v[184:187], v[24:27]
	v_mfma_f32_16x16x32_bf16 v[16:19], v[168:171], v[184:187], v[16:19]
	v_mfma_f32_16x16x32_bf16 v[12:15], v[160:163], v[192:195], v[12:15]
	v_mfma_f32_16x16x32_bf16 v[8:11], v[168:171], v[192:195], v[8:11]
	v_mfma_f32_16x16x32_bf16 v[4:7], v[160:163], v[200:203], v[4:7]
	v_mfma_f32_16x16x32_bf16 v[0:3], v[168:171], v[200:203], v[0:3]
	v_mfma_f32_16x16x32_bf16 v[40:43], v[164:167], v[180:183], v[40:43]
	v_mfma_f32_16x16x32_bf16 v[32:35], v[172:175], v[180:183], v[32:35]
	v_mfma_f32_16x16x32_bf16 v[24:27], v[164:167], v[188:191], v[24:27]
	v_mfma_f32_16x16x32_bf16 v[16:19], v[172:175], v[188:191], v[16:19]
	v_mfma_f32_16x16x32_bf16 v[12:15], v[164:167], v[196:199], v[12:15]
	v_mfma_f32_16x16x32_bf16 v[8:11], v[172:175], v[196:199], v[8:11]
	v_mfma_f32_16x16x32_bf16 v[4:7], v[164:167], v[204:207], v[4:7]
	v_mfma_f32_16x16x32_bf16 v[0:3], v[172:175], v[204:207], v[0:3]
	s_setprio 0
	s_barrier
	s_add_i32 s76, s76, 2
	s_add_u32 s52, s52, 0x100
	s_addc_u32 s53, s53, 0
	s_add_u32 s74, s74, 0x100
	s_addc_u32 s75, s75, 0
	s_cmp_gt_u32 s76, 13
	s_cbranch_scc0 .LBB0_1099
	s_branch .Lpost_1099

; #define G_STAGE(bufoff, gbase, voff) do { _Pragma("unroll") for (int _i = 0; _i < 2; ++_i) \
;         __builtin_amdgcn_global_load_lds((const unsigned*)((const char*)(gbase) + voff[_i]), (LAS unsigned*)(lds + (bufoff) + ldsw + _i * 8192), 16, 0, 0); } while (0)
; #define WAIT_V(n) asm volatile("s_waitcnt vmcnt(" #n ")" ::: "memory")
; #define BAR __builtin_amdgcn_s_barrier()
; template <class Get, class Epi>
; DI void gemm_loop(int ntiles, int ld, char* shm, const Get& get, const Epi& epi) {
;     ...
;     for (int i = 0; i < 2; ++i) { int R, C; stage_rc(tid * 16 + i * 8192, R, C); const int rho = R & 31, Rb = (R & ~31) + 8 * ((rho & 15) >> 2) + 4 * (rho >> 4) + (rho & 3);
;         voffA[i] = (unsigned)(R * ld + C) * 2u; voffB[i] = (unsigned)(Rb * ld + C) * 2u; }
;     const size_t kstep = (size_t)(BK * 2), hstep = (size_t)HALF * ld * 2;
;     const unsigned ldsw = (unsigned)wid * 1024u;
;     const int aoff = lds_byte(wr * 64 + fr, fq * 8), boff = lds_byte(wc * 32 + fr, fq * 8);
;     ...
;     int L = bx; if (L >= ntiles) return;
;     Tile cur = get(L), nxt = cur;
;     AccT acc;
;     ...
;     G_ZERO;
;     bf16x8 At[4][2], B0[2][2], B1[2][2];
;     const char* cA = (const char*)cur.A + (size_t)cur.brow * ld * 2; const char* cB = (const char*)cur.Bt + (size_t)cur.bcol * ld * 2;
;     G_STAGE(G_SB(0, 0), cB, voffB); G_STAGE(G_SB(0, 1), cB + hstep, voffB); G_STAGE(G_SA(0, 0), cA, voffA); G_STAGE(G_SA(0, 1), cA + hstep, voffA);
;     if (wr == 1) BAR;
;     WAIT_V(2); BAR;
;     G_STAGE(G_SB(1, 0), cB + kstep, voffB); G_STAGE(G_SA(1, 0), cA + kstep, voffA); G_STAGE(G_SB(1, 1), cB + hstep + kstep, voffB);
;     WAIT_V(6); BAR;
.LBB0_1450:
	s_add_u32 s53, s68, 0x838000
	s_addc_u32 s54, s69, 0
	s_lshl_b32 s3, s10, 13
	s_lshl_b32 s10, s11, 12
	s_and_b32 s13, s10, 0x3000
	s_mov_b64 s[10:11], 0x80
	s_add_i32 m0, s45, 0x18000
	v_lshl_add_u64 v[6:7], v[6:7], 0, s[10:11]
	s_waitcnt vmcnt(2)
	s_barrier
	global_load_lds_dwordx4 v[6:7], off
	v_lshl_add_u64 v[4:5], v[4:5], 0, s[10:11]
	s_add_i32 m0, s45, 0x1a000
	s_add_i32 s55, s45, 0x8000
	s_add_i32 s56, s45, 0xa000
	global_load_lds_dwordx4 v[4:5], off
	v_lshl_add_u64 v[0:1], v[0:1], 0, s[10:11]
	s_mov_b32 m0, s55
	s_add_u32 s30, s14, 0x40080
	global_load_lds_dwordx4 v[0:1], off
	v_lshl_add_u64 v[0:1], v[2:3], 0, s[10:11]
	s_mov_b32 m0, s56
	s_addc_u32 s31, s15, 0
	global_load_lds_dwordx4 v[0:1], off
	s_add_i32 m0, s45, 0x1c000
	v_lshl_add_u64 v[0:1], s[30:31], 0, v[148:149]
	global_load_lds_dwordx4 v[0:1], off
	v_lshl_add_u64 v[0:1], s[30:31], 0, v[152:153]
	s_add_i32 m0, s45, 0x1e000
	v_lshlrev_b32_e32 v3, 2, v8
	global_load_lds_dwordx4 v[0:1], off
	v_and_b32_e32 v0, 15, v8
	v_and_b32_e32 v1, 48, v8
	v_lshlrev_b32_e32 v0, 6, v0
	v_and_b32_e32 v3, 32, v3
	v_or_b32_e32 v2, v0, v1
	v_bitop3_b32 v0, v0, v3, v1 bitop3:0x36
	v_or_b32_e32 v168, s13, v0
	v_lshlrev_b32_e32 v0, 14, v9
	v_and_b32_e32 v0, 0xffff8000, v0
	v_bitop3_b32 v1, v2, s3, v3 bitop3:0xde
	v_lshl_add_u32 v0, v10, 11, v0
	v_and_b32_e32 v2, 1, v9
	v_lshl_or_b32 v0, v2, 6, v0
	v_lshl_add_u32 v154, v11, 1, v0
	v_lshlrev_b32_e32 v0, 14, v12
	s_cmpk_lt_u32 s12, 0x100
	v_and_b32_e32 v0, 0xffff8000, v0
	s_waitcnt vmcnt(6)
	s_mov_b32 s100, 0
	s_cselect_b64 s[12:13], -1, 0
	s_add_u32 s30, s68, 0x868000
	v_lshl_add_u32 v0, v13, 11, v0
	v_and_b32_e32 v2, 1, v12
	s_addc_u32 s31, s69, 0
	v_lshl_or_b32 v0, v2, 6, v0
	s_add_i32 s57, 0, 0x10000
	s_add_i32 s58, 0, 0x14000
	v_mov_b32_e32 v155, v149
	v_lshl_add_u32 v156, v14, 1, v0
	v_mov_b32_e32 v157, v149
	v_add_u32_e32 v169, s57, v168
	v_add_u32_e32 v170, s58, v168
	v_add_u32_e32 v171, 0, v1
	s_mov_b32 s71, s48
	s_barrier
	s_branch .LBB0_1453

; #define G_STAGE(bufoff, gbase, voff) do { _Pragma("unroll") for (int _i = 0; _i < 2; ++_i) \
;         __builtin_amdgcn_global_load_lds((const unsigned*)((const char*)(gbase) + voff[_i]), (LAS unsigned*)(lds + (bufoff) + ldsw + _i * 8192), 16, 0, 0); } while (0)
; #define G_LDA(dst, b, h) do { _Pragma("unroll") for (int m = 0; m < 4; ++m) _Pragma("unroll") for (int k = 0; k < 2; ++k) dst[m][k] = *(const LAS bf16x8*)(lds + G_SA(b, h) + aoff + m * 2048 + k * 1024); } while (0)
; #define G_LDB(dst, b, h) do { _Pragma("unroll") for (int n = 0; n < 2; ++n) _Pragma("unroll") for (int k = 0; k < 2; ++k) dst[n][k] = *(const LAS bf16x8*)(lds + G_SB(b, h) + boff + n * 2048 + k * 1024); } while (0)
; #define G_MMA(ai, bj, At_, Bt_) do { __builtin_amdgcn_s_setprio(1); _Pragma("unroll") for (int m = 0; m < 4; ++m) _Pragma("unroll") for (int n = 0; n < 2; ++n) _Pragma("unroll") for (int k = 0; k < 2; ++k) \
;         acc[ai][bj][m][n] = __builtin_amdgcn_mfma_f32_16x16x32_bf16(Bt_[n][k], At_[m][k], acc[ai][bj][m][n], 0, 0, 0); __builtin_amdgcn_s_setprio(0); } while (0)
; #define WAIT_V(n) asm volatile("s_waitcnt vmcnt(" #n ")" ::: "memory")
; #define WAIT_L(n) asm volatile("s_waitcnt lgkmcnt(" #n ")" ::: "memory")
; #define BAR __builtin_amdgcn_s_barrier()
; #define SCHED __builtin_amdgcn_sched_barrier(0)
; template <class Get, class Epi>
; DI void gemm_loop(int ntiles, int ld, char* shm, const Get& get, const Epi& epi) {
;     ...
;             const bool last = (t == nt - 2);
;             const char* a1 = cA + (size_t)(t + 1) * kstep;
;             const char* a2 = last ? nA : cA + (size_t)(t + 2) * kstep; const char* b2 = last ? nB : cB + (size_t)(t + 2) * kstep;
;             const char* a3 = a2 + kstep; const char* b3 = b2 + kstep;
;             G_LDB(B0, 0, 0); G_LDB(B1, 0, 1); SCHED; G_LDA(At, 0, 0); G_STAGE(G_SA(1, 1), a1 + hstep, voffA);
;             WAIT_V(8); WAIT_L(0); BAR; G_MMA(0, 0, At, B0); G_MMA(0, 1, At, B1); BAR; SCHED;
.Lpeel_1463:
	ds_read_b128 v[128:131], v169
	ds_read_b128 v[132:135], v169 offset:1024
	ds_read_b128 v[136:139], v169 offset:2048
	ds_read_b128 v[140:143], v169 offset:3072
	ds_read_b128 v[158:161], v170
	ds_read_b128 v[162:165], v170 offset:1024
	ds_read_b128 v[172:175], v170 offset:2048
	ds_read_b128 v[176:179], v170 offset:3072
	s_add_i32 s78, s14, 2
	s_add_u32 s15, s48, 0xfffc0080
	s_addc_u32 s46, s49, -1
	s_cmp_eq_u32 s75, s14
	s_cselect_b32 s14, s73, s76
	s_cselect_b32 s47, s3, s46
	s_cselect_b32 s46, s37, s15
	s_cselect_b32 s15, s39, s77
	v_lshl_add_u64 v[144:145], s[48:49], 0, v[154:155]
	s_add_i32 m0, s45, 0xc000
	ds_read_b128 v[180:183], v171
	ds_read_b128 v[184:187], v171 offset:1024
	ds_read_b128 v[188:191], v171 offset:2048
	ds_read_b128 v[192:195], v171 offset:3072
	ds_read_b128 v[196:199], v171 offset:4096
	ds_read_b128 v[200:203], v171 offset:5120
	ds_read_b128 v[204:207], v171 offset:6144
	ds_read_b128 v[208:211], v171 offset:7168
	global_load_lds_dwordx4 v[144:145], off
	v_lshl_add_u64 v[144:145], s[48:49], 0, v[156:157]
	s_add_i32 m0, s45, 0xe000
	s_nop 0
	global_load_lds_dwordx4 v[144:145], off
	s_cmp_lg_u32 s100, 0
	s_cbranch_scc0 .Lrf_1463_0
	s_waitcnt vmcnt(16)
	s_branch .Lrj_1463_0

; #define G_STAGE(bufoff, gbase, voff) do { _Pragma("unroll") for (int _i = 0; _i < 2; ++_i) \
;         __builtin_amdgcn_global_load_lds((const unsigned*)((const char*)(gbase) + voff[_i]), (LAS unsigned*)(lds + (bufoff) + ldsw + _i * 8192), 16, 0, 0); } while (0)
; #define G_LDA(dst, b, h) do { _Pragma("unroll") for (int m = 0; m < 4; ++m) _Pragma("unroll") for (int k = 0; k < 2; ++k) dst[m][k] = *(const LAS bf16x8*)(lds + G_SA(b, h) + aoff + m * 2048 + k * 1024); } while (0)
; #define G_MMA(ai, bj, At_, Bt_) do { __builtin_amdgcn_s_setprio(1); _Pragma("unroll") for (int m = 0; m < 4; ++m) _Pragma("unroll") for (int n = 0; n < 2; ++n) _Pragma("unroll") for (int k = 0; k < 2; ++k) \
;         acc[ai][bj][m][n] = __builtin_amdgcn_mfma_f32_16x16x32_bf16(Bt_[n][k], At_[m][k], acc[ai][bj][m][n], 0, 0, 0); __builtin_amdgcn_s_setprio(0); } while (0)
; #define WAIT_V(n) asm volatile("s_waitcnt vmcnt(" #n ")" ::: "memory")
; #define WAIT_L(n) asm volatile("s_waitcnt lgkmcnt(" #n ")" ::: "memory")
; #define BAR __builtin_amdgcn_s_barrier()
; #define SCHED __builtin_amdgcn_sched_barrier(0)
; template <class Get, class Epi>
; DI void gemm_loop(int ntiles, int ld, char* shm, const Get& get, const Epi& epi) {
;     ...
;             WAIT_V(8); WAIT_L(0); BAR; G_MMA(0, 0, At, B0); G_MMA(0, 1, At, B1); BAR; SCHED;
;             G_LDA(At, 0, 1); G_STAGE(G_SB(0, 0), b2, voffB); G_STAGE(G_SB(0, 1), b2 + hstep, voffB); G_STAGE(G_SA(0, 0), a2, voffA);
;             WAIT_V(8); WAIT_L(0); BAR; G_MMA(1, 0, At, B0); G_MMA(1, 1, At, B1); BAR; SCHED;
.Lrj_1463_0:
	s_waitcnt lgkmcnt(0)
	s_barrier
	s_setprio 1
	s_waitcnt lgkmcnt(0)
	v_mfma_f32_16x16x32_bf16 v[124:127], v[128:131], v[180:183], 0
	v_mfma_f32_16x16x32_bf16 v[120:123], v[136:139], v[180:183], 0
	v_mfma_f32_16x16x32_bf16 v[116:119], v[128:131], v[188:191], 0
	v_mfma_f32_16x16x32_bf16 v[112:115], v[136:139], v[188:191], 0
	v_mfma_f32_16x16x32_bf16 v[108:111], v[128:131], v[196:199], 0
	v_mfma_f32_16x16x32_bf16 v[104:107], v[136:139], v[196:199], 0
	v_mfma_f32_16x16x32_bf16 v[100:103], v[128:131], v[204:207], 0
	v_mfma_f32_16x16x32_bf16 v[96:99], v[136:139], v[204:207], 0
	v_mfma_f32_16x16x32_bf16 v[124:127], v[132:135], v[184:187], v[124:127]
	v_mfma_f32_16x16x32_bf16 v[120:123], v[140:143], v[184:187], v[120:123]
	v_mfma_f32_16x16x32_bf16 v[116:119], v[132:135], v[192:195], v[116:119]
	v_mfma_f32_16x16x32_bf16 v[112:115], v[140:143], v[192:195], v[112:115]
	v_mfma_f32_16x16x32_bf16 v[108:111], v[132:135], v[200:203], v[108:111]
	v_mfma_f32_16x16x32_bf16 v[104:107], v[140:143], v[200:203], v[104:107]
	v_mfma_f32_16x16x32_bf16 v[100:103], v[132:135], v[208:211], v[100:103]
	v_mfma_f32_16x16x32_bf16 v[96:99], v[140:143], v[208:211], v[96:99]
	s_setprio 0
	s_setprio 1
	v_mfma_f32_16x16x32_bf16 v[60:63], v[158:161], v[180:183], 0
	v_mfma_f32_16x16x32_bf16 v[56:59], v[172:175], v[180:183], 0
	v_mfma_f32_16x16x32_bf16 v[52:55], v[158:161], v[188:191], 0
	v_mfma_f32_16x16x32_bf16 v[48:51], v[172:175], v[188:191], 0
	v_mfma_f32_16x16x32_bf16 v[44:47], v[158:161], v[196:199], 0
	v_mfma_f32_16x16x32_bf16 v[40:43], v[172:175], v[196:199], 0
	v_mfma_f32_16x16x32_bf16 v[36:39], v[158:161], v[204:207], 0
	v_mfma_f32_16x16x32_bf16 v[32:35], v[172:175], v[204:207], 0
	v_mfma_f32_16x16x32_bf16 v[60:63], v[162:165], v[184:187], v[60:63]
	v_mfma_f32_16x16x32_bf16 v[56:59], v[176:179], v[184:187], v[56:59]
	v_mfma_f32_16x16x32_bf16 v[52:55], v[162:165], v[192:195], v[52:55]
	v_mfma_f32_16x16x32_bf16 v[48:51], v[176:179], v[192:195], v[48:51]
	v_mfma_f32_16x16x32_bf16 v[44:47], v[162:165], v[200:203], v[44:47]
	v_mfma_f32_16x16x32_bf16 v[40:43], v[176:179], v[200:203], v[40:43]
	v_mfma_f32_16x16x32_bf16 v[36:39], v[162:165], v[208:211], v[36:39]
	v_mfma_f32_16x16x32_bf16 v[32:35], v[176:179], v[208:211], v[32:35]
	s_setprio 0
	s_barrier
	s_add_i32 s79, s57, s7
	v_lshl_add_u64 v[144:145], s[14:15], 0, v[148:149]
	s_mov_b32 m0, s79
	ds_read_b128 v[180:183], v171 offset:16384
	ds_read_b128 v[184:187], v171 offset:17408
	ds_read_b128 v[188:191], v171 offset:18432
	ds_read_b128 v[192:195], v171 offset:19456
	ds_read_b128 v[196:199], v171 offset:20480
	ds_read_b128 v[200:203], v171 offset:21504
	ds_read_b128 v[204:207], v171 offset:22528
	ds_read_b128 v[208:211], v171 offset:23552
	global_load_lds_dwordx4 v[144:145], off
	s_add_i32 m0, s79, 0x2000
	s_add_u32 s80, s14, 0x40000
	v_lshl_add_u64 v[166:167], s[14:15], 0, v[152:153]
	s_addc_u32 s81, s15, 0
	s_add_i32 s79, s58, s7
	global_load_lds_dwordx4 v[166:167], off
	v_lshl_add_u64 v[212:213], s[80:81], 0, v[148:149]
	s_mov_b32 m0, s79
	v_lshl_add_u64 v[214:215], s[46:47], 0, v[150:151]
	global_load_lds_dwordx4 v[212:213], off
	v_lshl_add_u64 v[212:213], s[80:81], 0, v[152:153]
	s_add_i32 m0, s79, 0x2000
	s_nop 0
	global_load_lds_dwordx4 v[212:213], off
	v_lshl_add_u64 v[212:213], s[46:47], 0, v[146:147]
	s_mov_b32 m0, s45
	s_nop 0
	global_load_lds_dwordx4 v[212:213], off
	s_mov_b32 m0, s50
	s_nop 0
	global_load_lds_dwordx4 v[214:215], off
	s_cmp_lg_u32 s100, 0
	s_cbranch_scc0 .Lrf_1463_1
	s_waitcnt vmcnt(16)
	s_branch .Lrj_1463_1

; #define G_STAGE(bufoff, gbase, voff) do { _Pragma("unroll") for (int _i = 0; _i < 2; ++_i) \
;         __builtin_amdgcn_global_load_lds((const unsigned*)((const char*)(gbase) + voff[_i]), (LAS unsigned*)(lds + (bufoff) + ldsw + _i * 8192), 16, 0, 0); } while (0)
; #define G_LDA(dst, b, h) do { _Pragma("unroll") for (int m = 0; m < 4; ++m) _Pragma("unroll") for (int k = 0; k < 2; ++k) dst[m][k] = *(const LAS bf16x8*)(lds + G_SA(b, h) + aoff + m * 2048 + k * 1024); } while (0)
; #define G_LDB(dst, b, h) do { _Pragma("unroll") for (int n = 0; n < 2; ++n) _Pragma("unroll") for (int k = 0; k < 2; ++k) dst[n][k] = *(const LAS bf16x8*)(lds + G_SB(b, h) + boff + n * 2048 + k * 1024); } while (0)
; #define G_MMA(ai, bj, At_, Bt_) do { __builtin_amdgcn_s_setprio(1); _Pragma("unroll") for (int m = 0; m < 4; ++m) _Pragma("unroll") for (int n = 0; n < 2; ++n) _Pragma("unroll") for (int k = 0; k < 2; ++k) \
;         acc[ai][bj][m][n] = __builtin_amdgcn_mfma_f32_16x16x32_bf16(Bt_[n][k], At_[m][k], acc[ai][bj][m][n], 0, 0, 0); __builtin_amdgcn_s_setprio(0); } while (0)
; #define WAIT_V(n) asm volatile("s_waitcnt vmcnt(" #n ")" ::: "memory")
; #define WAIT_L(n) asm volatile("s_waitcnt lgkmcnt(" #n ")" ::: "memory")
; #define BAR __builtin_amdgcn_s_barrier()
; #define SCHED __builtin_amdgcn_sched_barrier(0)
; template <class Get, class Epi>
; DI void gemm_loop(int ntiles, int ld, char* shm, const Get& get, const Epi& epi) {
;     ...
;             WAIT_V(8); WAIT_L(0); BAR; G_MMA(1, 0, At, B0); G_MMA(1, 1, At, B1); BAR; SCHED;
;             G_LDB(B0, 1, 0); G_LDB(B1, 1, 1); SCHED; G_LDA(At, 1, 0); G_STAGE(G_SA(0, 1), a2 + hstep, voffA);
;             WAIT_V(8); WAIT_L(0); BAR; G_MMA(0, 0, At, B0); G_MMA(0, 1, At, B1); BAR; SCHED;
.Lrj_1463_1:
	s_waitcnt lgkmcnt(0)
	s_barrier
	s_setprio 1
	s_waitcnt lgkmcnt(0)
	v_mfma_f32_16x16x32_bf16 v[92:95], v[128:131], v[180:183], 0
	v_mfma_f32_16x16x32_bf16 v[88:91], v[136:139], v[180:183], 0
	v_mfma_f32_16x16x32_bf16 v[84:87], v[128:131], v[188:191], 0
	v_mfma_f32_16x16x32_bf16 v[80:83], v[136:139], v[188:191], 0
	v_mfma_f32_16x16x32_bf16 v[76:79], v[128:131], v[196:199], 0
	v_mfma_f32_16x16x32_bf16 v[72:75], v[136:139], v[196:199], 0
	v_mfma_f32_16x16x32_bf16 v[68:71], v[128:131], v[204:207], 0
	v_mfma_f32_16x16x32_bf16 v[64:67], v[136:139], v[204:207], 0
	v_mfma_f32_16x16x32_bf16 v[92:95], v[132:135], v[184:187], v[92:95]
	v_mfma_f32_16x16x32_bf16 v[88:91], v[140:143], v[184:187], v[88:91]
	v_mfma_f32_16x16x32_bf16 v[84:87], v[132:135], v[192:195], v[84:87]
	v_mfma_f32_16x16x32_bf16 v[80:83], v[140:143], v[192:195], v[80:83]
	v_mfma_f32_16x16x32_bf16 v[76:79], v[132:135], v[200:203], v[76:79]
	v_mfma_f32_16x16x32_bf16 v[72:75], v[140:143], v[200:203], v[72:75]
	v_mfma_f32_16x16x32_bf16 v[68:71], v[132:135], v[208:211], v[68:71]
	v_mfma_f32_16x16x32_bf16 v[64:67], v[140:143], v[208:211], v[64:67]
	s_setprio 0
	s_setprio 1
	v_mfma_f32_16x16x32_bf16 v[28:31], v[158:161], v[180:183], 0
	v_mfma_f32_16x16x32_bf16 v[24:27], v[172:175], v[180:183], 0
	v_mfma_f32_16x16x32_bf16 v[20:23], v[158:161], v[188:191], 0
	v_mfma_f32_16x16x32_bf16 v[16:19], v[172:175], v[188:191], 0
	v_mfma_f32_16x16x32_bf16 v[12:15], v[158:161], v[196:199], 0
	v_mfma_f32_16x16x32_bf16 v[8:11], v[172:175], v[196:199], 0
	v_mfma_f32_16x16x32_bf16 v[4:7], v[158:161], v[204:207], 0
	v_mfma_f32_16x16x32_bf16 v[0:3], v[172:175], v[204:207], 0
	v_mfma_f32_16x16x32_bf16 v[28:31], v[162:165], v[184:187], v[28:31]
	v_mfma_f32_16x16x32_bf16 v[24:27], v[176:179], v[184:187], v[24:27]
	v_mfma_f32_16x16x32_bf16 v[20:23], v[162:165], v[192:195], v[20:23]
	v_mfma_f32_16x16x32_bf16 v[16:19], v[176:179], v[192:195], v[16:19]
	v_mfma_f32_16x16x32_bf16 v[12:15], v[162:165], v[200:203], v[12:15]
	v_mfma_f32_16x16x32_bf16 v[8:11], v[176:179], v[200:203], v[8:11]
	v_mfma_f32_16x16x32_bf16 v[4:7], v[162:165], v[208:211], v[4:7]
	v_mfma_f32_16x16x32_bf16 v[0:3], v[176:179], v[208:211], v[0:3]
	s_setprio 0
	s_barrier
	s_add_i32 s79, 0, 0x18000
	s_add_i32 s80, 0, 0x1c000
	v_add_u32_e32 v140, s79, v168
	v_add_u32_e32 v176, s80, v168
	ds_read_b128 v[128:131], v140
	ds_read_b128 v[132:135], v140 offset:1024
	ds_read_b128 v[136:139], v140 offset:2048
	ds_read_b128 v[140:143], v140 offset:3072
	ds_read_b128 v[158:161], v176
	ds_read_b128 v[162:165], v176 offset:1024
	ds_read_b128 v[172:175], v176 offset:2048
	ds_read_b128 v[176:179], v176 offset:3072
	s_add_u32 s46, s46, 0x40000
	s_addc_u32 s47, s47, 0
	s_mov_b32 m0, s51
	v_lshl_add_u64 v[216:217], s[46:47], 0, v[146:147]
	ds_read_b128 v[180:183], v171 offset:32768
	ds_read_b128 v[184:187], v171 offset:33792
	ds_read_b128 v[188:191], v171 offset:34816
	ds_read_b128 v[192:195], v171 offset:35840
	ds_read_b128 v[196:199], v171 offset:36864
	ds_read_b128 v[200:203], v171 offset:37888
	ds_read_b128 v[204:207], v171 offset:38912
	ds_read_b128 v[208:211], v171 offset:39936
	global_load_lds_dwordx4 v[216:217], off
	v_lshl_add_u64 v[216:217], s[46:47], 0, v[150:151]
	s_mov_b32 m0, s52
	s_nop 0
	global_load_lds_dwordx4 v[216:217], off
	s_waitcnt vmcnt(8)
	s_waitcnt lgkmcnt(0)
	s_barrier
	s_setprio 1
	s_waitcnt lgkmcnt(0)
	v_mfma_f32_16x16x32_bf16 v[124:127], v[128:131], v[180:183], v[124:127]
	v_mfma_f32_16x16x32_bf16 v[120:123], v[136:139], v[180:183], v[120:123]
	v_mfma_f32_16x16x32_bf16 v[116:119], v[128:131], v[188:191], v[116:119]
	v_mfma_f32_16x16x32_bf16 v[112:115], v[136:139], v[188:191], v[112:115]
	v_mfma_f32_16x16x32_bf16 v[108:111], v[128:131], v[196:199], v[108:111]
	v_mfma_f32_16x16x32_bf16 v[104:107], v[136:139], v[196:199], v[104:107]
	v_mfma_f32_16x16x32_bf16 v[100:103], v[128:131], v[204:207], v[100:103]
	v_mfma_f32_16x16x32_bf16 v[96:99], v[136:139], v[204:207], v[96:99]
	v_mfma_f32_16x16x32_bf16 v[124:127], v[132:135], v[184:187], v[124:127]
	v_mfma_f32_16x16x32_bf16 v[120:123], v[140:143], v[184:187], v[120:123]
	v_mfma_f32_16x16x32_bf16 v[116:119], v[132:135], v[192:195], v[116:119]
	v_mfma_f32_16x16x32_bf16 v[112:115], v[140:143], v[192:195], v[112:115]
	v_mfma_f32_16x16x32_bf16 v[108:111], v[132:135], v[200:203], v[108:111]
	v_mfma_f32_16x16x32_bf16 v[104:107], v[140:143], v[200:203], v[104:107]
	v_mfma_f32_16x16x32_bf16 v[100:103], v[132:135], v[208:211], v[100:103]
	v_mfma_f32_16x16x32_bf16 v[96:99], v[140:143], v[208:211], v[96:99]
	s_setprio 0
	s_setprio 1
	v_mfma_f32_16x16x32_bf16 v[60:63], v[158:161], v[180:183], v[60:63]
	v_mfma_f32_16x16x32_bf16 v[56:59], v[172:175], v[180:183], v[56:59]
	v_mfma_f32_16x16x32_bf16 v[52:55], v[158:161], v[188:191], v[52:55]
	v_mfma_f32_16x16x32_bf16 v[48:51], v[172:175], v[188:191], v[48:51]
	v_mfma_f32_16x16x32_bf16 v[44:47], v[158:161], v[196:199], v[44:47]
	v_mfma_f32_16x16x32_bf16 v[40:43], v[172:175], v[196:199], v[40:43]
	v_mfma_f32_16x16x32_bf16 v[36:39], v[158:161], v[204:207], v[36:39]
	v_mfma_f32_16x16x32_bf16 v[32:35], v[172:175], v[204:207], v[32:35]
	v_mfma_f32_16x16x32_bf16 v[60:63], v[162:165], v[184:187], v[60:63]
	v_mfma_f32_16x16x32_bf16 v[56:59], v[176:179], v[184:187], v[56:59]
	v_mfma_f32_16x16x32_bf16 v[52:55], v[162:165], v[192:195], v[52:55]
	v_mfma_f32_16x16x32_bf16 v[48:51], v[176:179], v[192:195], v[48:51]
	v_mfma_f32_16x16x32_bf16 v[44:47], v[162:165], v[200:203], v[44:47]
	v_mfma_f32_16x16x32_bf16 v[40:43], v[176:179], v[200:203], v[40:43]
	v_mfma_f32_16x16x32_bf16 v[36:39], v[162:165], v[208:211], v[36:39]
	v_mfma_f32_16x16x32_bf16 v[32:35], v[176:179], v[208:211], v[32:35]
	s_setprio 0
	s_barrier
; #define G_STAGE(bufoff, gbase, voff) do { _Pragma("unroll") for (int _i = 0; _i < 2; ++_i) \
;         __builtin_amdgcn_global_load_lds((const unsigned*)((const char*)(gbase) + voff[_i]), (LAS unsigned*)(lds + (bufoff) + ldsw + _i * 8192), 16, 0, 0); } while (0)
; #define G_LDA(dst, b, h) do { _Pragma("unroll") for (int m = 0; m < 4; ++m) _Pragma("unroll") for (int k = 0; k < 2; ++k) dst[m][k] = *(const LAS bf16x8*)(lds + G_SA(b, h) + aoff + m * 2048 + k * 1024); } while (0)
; #define G_MMA(ai, bj, At_, Bt_) do { __builtin_amdgcn_s_setprio(1); _Pragma("unroll") for (int m = 0; m < 4; ++m) _Pragma("unroll") for (int n = 0; n < 2; ++n) _Pragma("unroll") for (int k = 0; k < 2; ++k) \
;         acc[ai][bj][m][n] = __builtin_amdgcn_mfma_f32_16x16x32_bf16(Bt_[n][k], At_[m][k], acc[ai][bj][m][n], 0, 0, 0); __builtin_amdgcn_s_setprio(0); } while (0)
; #define WAIT_V(n) asm volatile("s_waitcnt vmcnt(" #n ")" ::: "memory")
; #define WAIT_L(n) asm volatile("s_waitcnt lgkmcnt(" #n ")" ::: "memory")
; #define BAR __builtin_amdgcn_s_barrier()
; #define SCHED __builtin_amdgcn_sched_barrier(0)
; template <class Get, class Epi>
; DI void gemm_loop(int ntiles, int ld, char* shm, const Get& get, const Epi& epi) {
;     ...
;             G_LDA(At, 1, 1); G_STAGE(G_SB(1, 0), b3, voffB); G_STAGE(G_SB(1, 1), b3 + hstep, voffB); G_STAGE(G_SA(1, 0), a3, voffA);
;             WAIT_V(8); WAIT_L(0); BAR; G_MMA(1, 0, At, B0); G_MMA(1, 1, At, B1); BAR; SCHED;
;         }
	s_add_i32 s46, s79, s7
	v_lshl_add_u64 v[144:145], v[144:145], 0, s[10:11]
	s_mov_b32 m0, s46
	ds_read_b128 v[180:183], v171 offset:49152
	ds_read_b128 v[184:187], v171 offset:50176
	ds_read_b128 v[188:191], v171 offset:51200
	ds_read_b128 v[192:195], v171 offset:52224
	ds_read_b128 v[196:199], v171 offset:53248
	ds_read_b128 v[200:203], v171 offset:54272
	ds_read_b128 v[204:207], v171 offset:55296
	ds_read_b128 v[208:211], v171 offset:56320
	global_load_lds_dwordx4 v[144:145], off
	s_add_i32 m0, s46, 0x2000
	s_add_u32 s14, s14, 0x40080
	v_lshl_add_u64 v[144:145], v[166:167], 0, s[10:11]
	s_addc_u32 s15, s15, 0
	s_add_i32 s46, s80, s7
	global_load_lds_dwordx4 v[144:145], off
	v_lshl_add_u64 v[144:145], s[14:15], 0, v[148:149]
	s_mov_b32 m0, s46
	s_nop 0
	global_load_lds_dwordx4 v[144:145], off
	v_lshl_add_u64 v[144:145], s[14:15], 0, v[152:153]
	s_add_i32 m0, s46, 0x2000
	s_nop 0
	global_load_lds_dwordx4 v[144:145], off
	v_lshl_add_u64 v[144:145], v[212:213], 0, s[10:11]
	s_mov_b32 m0, s55
	s_nop 0
	global_load_lds_dwordx4 v[144:145], off
	v_lshl_add_u64 v[144:145], v[214:215], 0, s[10:11]
	s_mov_b32 m0, s56
	s_nop 0
	global_load_lds_dwordx4 v[144:145], off
	s_waitcnt vmcnt(8)
	s_waitcnt lgkmcnt(0)
	s_barrier
	s_setprio 1
	s_waitcnt lgkmcnt(0)
	v_mfma_f32_16x16x32_bf16 v[92:95], v[128:131], v[180:183], v[92:95]
	v_mfma_f32_16x16x32_bf16 v[88:91], v[136:139], v[180:183], v[88:91]
	v_mfma_f32_16x16x32_bf16 v[84:87], v[128:131], v[188:191], v[84:87]
	v_mfma_f32_16x16x32_bf16 v[80:83], v[136:139], v[188:191], v[80:83]
	v_mfma_f32_16x16x32_bf16 v[76:79], v[128:131], v[196:199], v[76:79]
	v_mfma_f32_16x16x32_bf16 v[72:75], v[136:139], v[196:199], v[72:75]
	v_mfma_f32_16x16x32_bf16 v[68:71], v[128:131], v[204:207], v[68:71]
	v_mfma_f32_16x16x32_bf16 v[64:67], v[136:139], v[204:207], v[64:67]
	v_mfma_f32_16x16x32_bf16 v[92:95], v[132:135], v[184:187], v[92:95]
	v_mfma_f32_16x16x32_bf16 v[88:91], v[140:143], v[184:187], v[88:91]
	v_mfma_f32_16x16x32_bf16 v[84:87], v[132:135], v[192:195], v[84:87]
	v_mfma_f32_16x16x32_bf16 v[80:83], v[140:143], v[192:195], v[80:83]
	v_mfma_f32_16x16x32_bf16 v[76:79], v[132:135], v[200:203], v[76:79]
	v_mfma_f32_16x16x32_bf16 v[72:75], v[140:143], v[200:203], v[72:75]
	v_mfma_f32_16x16x32_bf16 v[68:71], v[132:135], v[208:211], v[68:71]
	v_mfma_f32_16x16x32_bf16 v[64:67], v[140:143], v[208:211], v[64:67]
	s_setprio 0
	s_setprio 1
	v_mfma_f32_16x16x32_bf16 v[28:31], v[158:161], v[180:183], v[28:31]
	v_mfma_f32_16x16x32_bf16 v[24:27], v[172:175], v[180:183], v[24:27]
	v_mfma_f32_16x16x32_bf16 v[20:23], v[158:161], v[188:191], v[20:23]
	v_mfma_f32_16x16x32_bf16 v[16:19], v[172:175], v[188:191], v[16:19]
	v_mfma_f32_16x16x32_bf16 v[12:15], v[158:161], v[196:199], v[12:15]
	v_mfma_f32_16x16x32_bf16 v[8:11], v[172:175], v[196:199], v[8:11]
	v_mfma_f32_16x16x32_bf16 v[4:7], v[158:161], v[204:207], v[4:7]
	v_mfma_f32_16x16x32_bf16 v[0:3], v[172:175], v[204:207], v[0:3]
	v_mfma_f32_16x16x32_bf16 v[28:31], v[162:165], v[184:187], v[28:31]
	v_mfma_f32_16x16x32_bf16 v[24:27], v[176:179], v[184:187], v[24:27]
	v_mfma_f32_16x16x32_bf16 v[20:23], v[162:165], v[192:195], v[20:23]
	v_mfma_f32_16x16x32_bf16 v[16:19], v[176:179], v[192:195], v[16:19]
	v_mfma_f32_16x16x32_bf16 v[12:15], v[162:165], v[200:203], v[12:15]
	v_mfma_f32_16x16x32_bf16 v[8:11], v[176:179], v[200:203], v[8:11]
	v_mfma_f32_16x16x32_bf16 v[4:7], v[162:165], v[208:211], v[4:7]
	v_mfma_f32_16x16x32_bf16 v[0:3], v[176:179], v[208:211], v[0:3]
	s_setprio 0
	s_barrier
	s_add_u32 s48, s48, 0x100
	s_addc_u32 s49, s49, 0
	s_add_u32 s76, s76, 0x100
	s_addc_u32 s77, s77, 0
	s_cmp_ge_u32 s78, s74
	s_mov_b32 s14, s78
	s_cbranch_scc0 .LBB0_1463
	s_branch .Lpost_1463

; #define G_STAGE(bufoff, gbase, voff) do { _Pragma("unroll") for (int _i = 0; _i < 2; ++_i) \
;         __builtin_amdgcn_global_load_lds((const unsigned*)((const char*)(gbase) + voff[_i]), (LAS unsigned*)(lds + (bufoff) + ldsw + _i * 8192), 16, 0, 0); } while (0)
; #define WAIT_V(n) asm volatile("s_waitcnt vmcnt(" #n ")" ::: "memory")
; #define BAR __builtin_amdgcn_s_barrier()
; template <class Get, class Epi>
; DI void gemm_loop(int ntiles, int ld, char* shm, const Get& get, const Epi& epi) {
;     ...
;     const int aoff = lds_byte(wr * 64 + fr, fq * 8), boff = lds_byte(wc * 32 + fr, fq * 8);
;     ...
;     const char* cA = (const char*)cur.A + (size_t)cur.brow * ld * 2; const char* cB = (const char*)cur.Bt + (size_t)cur.bcol * ld * 2;
;     G_STAGE(G_SB(0, 0), cB, voffB); G_STAGE(G_SB(0, 1), cB + hstep, voffB); G_STAGE(G_SA(0, 0), cA, voffA); G_STAGE(G_SA(0, 1), cA + hstep, voffA);
;     if (wr == 1) BAR;
;     WAIT_V(2); BAR;
;     G_STAGE(G_SB(1, 0), cB + kstep, voffB); G_STAGE(G_SA(1, 0), cA + kstep, voffA); G_STAGE(G_SB(1, 1), cB + hstep + kstep, voffB);
;     WAIT_V(6); BAR;
.LBB0_1688:
	s_lshl_b32 s2, s2, 12
	s_lshl_b32 s5, s3, 13
	s_and_b32 s8, s2, 0x3000
	s_mov_b64 s[2:3], 0x80
	s_add_i32 m0, s35, 0x18000
	v_lshl_add_u64 v[6:7], v[6:7], 0, s[2:3]
	s_waitcnt vmcnt(2)
	s_barrier
	global_load_lds_dwordx4 v[6:7], off
	v_lshl_add_u64 v[4:5], v[4:5], 0, s[2:3]
	s_add_i32 m0, s35, 0x1a000
	s_add_i32 s46, s35, 0x8000
	s_add_i32 s47, s35, 0xa000
	global_load_lds_dwordx4 v[4:5], off
	v_lshl_add_u64 v[0:1], v[0:1], 0, s[2:3]
	s_mov_b32 m0, s46
	s_add_u32 s6, s14, 0x40080
	global_load_lds_dwordx4 v[0:1], off
	v_lshl_add_u64 v[0:1], v[2:3], 0, s[2:3]
	s_mov_b32 m0, s47
	s_addc_u32 s7, s15, 0
	global_load_lds_dwordx4 v[0:1], off
	s_add_i32 m0, s35, 0x1c000
	v_lshl_add_u64 v[0:1], s[6:7], 0, v[132:133]
	global_load_lds_dwordx4 v[0:1], off
	v_lshl_add_u64 v[0:1], s[6:7], 0, v[128:129]
	s_add_i32 m0, s35, 0x1e000
	v_lshlrev_b32_e32 v3, 2, v9
	global_load_lds_dwordx4 v[0:1], off
	v_and_b32_e32 v0, 15, v9
	v_and_b32_e32 v1, 48, v9
	v_lshlrev_b32_e32 v0, 6, v0
	v_and_b32_e32 v3, 32, v3
	v_or_b32_e32 v2, v0, v1
	v_bitop3_b32 v0, v0, v3, v1 bitop3:0x36
	v_or_b32_e32 v140, s8, v0
	v_lshlrev_b32_e32 v0, 14, v13
	v_and_b32_e32 v0, 0xffff8000, v0
	v_bitop3_b32 v1, v2, s5, v3 bitop3:0xde
	v_lshl_add_u32 v0, v12, 11, v0
	v_and_b32_e32 v2, 1, v13
	v_lshl_or_b32 v0, v2, 6, v0
	v_lshl_add_u32 v136, v14, 1, v0
	v_lshlrev_b32_e32 v0, 14, v8
	v_and_b32_e32 v0, 0xffff8000, v0
	s_waitcnt vmcnt(6)
	s_mov_b32 s100, 0
	s_cmpk_lt_u32 s4, 0x100
	v_lshl_add_u32 v0, v10, 11, v0
	v_and_b32_e32 v2, 1, v8
	s_cselect_b64 s[4:5], -1, 0
	v_lshl_or_b32 v0, v2, 6, v0
	s_add_i32 s48, 0, 0x10000
	s_add_i32 s49, 0, 0x14000
	v_mov_b32_e32 v137, v133
	v_lshl_add_u32 v138, v11, 1, v0
	v_mov_b32_e32 v139, v133
	v_add_u32_e32 v141, s48, v140
	v_add_u32_e32 v142, s49, v140
	v_add_u32_e32 v143, 0, v1
	s_movk_i32 s50, 0x1600
	s_barrier
	s_branch .LBB0_1691

; #define G_STAGE(bufoff, gbase, voff) do { _Pragma("unroll") for (int _i = 0; _i < 2; ++_i) \
;         __builtin_amdgcn_global_load_lds((const unsigned*)((const char*)(gbase) + voff[_i]), (LAS unsigned*)(lds + (bufoff) + ldsw + _i * 8192), 16, 0, 0); } while (0)
; #define G_LDA(dst, b, h) do { _Pragma("unroll") for (int m = 0; m < 4; ++m) _Pragma("unroll") for (int k = 0; k < 2; ++k) dst[m][k] = *(const LAS bf16x8*)(lds + G_SA(b, h) + aoff + m * 2048 + k * 1024); } while (0)
; #define G_LDB(dst, b, h) do { _Pragma("unroll") for (int n = 0; n < 2; ++n) _Pragma("unroll") for (int k = 0; k < 2; ++k) dst[n][k] = *(const LAS bf16x8*)(lds + G_SB(b, h) + boff + n * 2048 + k * 1024); } while (0)
; #define G_MMA(ai, bj, At_, Bt_) do { __builtin_amdgcn_s_setprio(1); _Pragma("unroll") for (int m = 0; m < 4; ++m) _Pragma("unroll") for (int n = 0; n < 2; ++n) _Pragma("unroll") for (int k = 0; k < 2; ++k) \
;         acc[ai][bj][m][n] = __builtin_amdgcn_mfma_f32_16x16x32_bf16(Bt_[n][k], At_[m][k], acc[ai][bj][m][n], 0, 0, 0); __builtin_amdgcn_s_setprio(0); } while (0)
; #define WAIT_V(n) asm volatile("s_waitcnt vmcnt(" #n ")" ::: "memory")
; #define WAIT_L(n) asm volatile("s_waitcnt lgkmcnt(" #n ")" ::: "memory")
; #define BAR __builtin_amdgcn_s_barrier()
; #define SCHED __builtin_amdgcn_sched_barrier(0)
; template <class Get, class Epi>
; DI void gemm_loop(int ntiles, int ld, char* shm, const Get& get, const Epi& epi) {
;     ...
;             G_LDB(B0, 0, 0); G_LDB(B1, 0, 1); SCHED; G_LDA(At, 0, 0); G_STAGE(G_SA(1, 1), a1 + hstep, voffA);
;             WAIT_V(8); WAIT_L(0); BAR; G_MMA(0, 0, At, B0); G_MMA(0, 1, At, B1); BAR; SCHED;
.Lpeel_1694:
	ds_read_b128 v[144:147], v141
	ds_read_b128 v[148:151], v141 offset:1024
	ds_read_b128 v[152:155], v141 offset:2048
	ds_read_b128 v[156:159], v141 offset:3072
	ds_read_b128 v[160:163], v142
	ds_read_b128 v[164:167], v142 offset:1024
	ds_read_b128 v[168:171], v142 offset:2048
	ds_read_b128 v[172:175], v142 offset:3072
	s_add_u32 s14, s38, 0xfffc0080
	s_addc_u32 s15, s39, -1
	s_cmp_eq_u32 s57, 12
	s_cselect_b32 s41, s9, s15
	s_cselect_b32 s40, s53, s14
	s_cselect_b32 s15, s11, s56
	s_cselect_b32 s14, s54, s55
	v_lshl_add_u64 v[208:209], s[38:39], 0, v[136:137]
	s_add_i32 m0, s35, 0xc000
	ds_read_b128 v[176:179], v143
	ds_read_b128 v[180:183], v143 offset:1024
	ds_read_b128 v[184:187], v143 offset:2048
	ds_read_b128 v[188:191], v143 offset:3072
	ds_read_b128 v[192:195], v143 offset:4096
	ds_read_b128 v[196:199], v143 offset:5120
	ds_read_b128 v[200:203], v143 offset:6144
	ds_read_b128 v[204:207], v143 offset:7168
	global_load_lds_dwordx4 v[208:209], off
	v_lshl_add_u64 v[208:209], s[38:39], 0, v[138:139]
	s_add_i32 m0, s35, 0xe000
	s_nop 0
	global_load_lds_dwordx4 v[208:209], off
	s_cmp_lg_u32 s100, 0
	s_cbranch_scc0 .Lrf_1694_0
	s_waitcnt vmcnt(16)
	s_branch .Lrj_1694_0

; #define G_STAGE(bufoff, gbase, voff) do { _Pragma("unroll") for (int _i = 0; _i < 2; ++_i) \
;         __builtin_amdgcn_global_load_lds((const unsigned*)((const char*)(gbase) + voff[_i]), (LAS unsigned*)(lds + (bufoff) + ldsw + _i * 8192), 16, 0, 0); } while (0)
; #define G_LDA(dst, b, h) do { _Pragma("unroll") for (int m = 0; m < 4; ++m) _Pragma("unroll") for (int k = 0; k < 2; ++k) dst[m][k] = *(const LAS bf16x8*)(lds + G_SA(b, h) + aoff + m * 2048 + k * 1024); } while (0)
; #define G_MMA(ai, bj, At_, Bt_) do { __builtin_amdgcn_s_setprio(1); _Pragma("unroll") for (int m = 0; m < 4; ++m) _Pragma("unroll") for (int n = 0; n < 2; ++n) _Pragma("unroll") for (int k = 0; k < 2; ++k) \
;         acc[ai][bj][m][n] = __builtin_amdgcn_mfma_f32_16x16x32_bf16(Bt_[n][k], At_[m][k], acc[ai][bj][m][n], 0, 0, 0); __builtin_amdgcn_s_setprio(0); } while (0)
; #define WAIT_V(n) asm volatile("s_waitcnt vmcnt(" #n ")" ::: "memory")
; #define WAIT_L(n) asm volatile("s_waitcnt lgkmcnt(" #n ")" ::: "memory")
; #define BAR __builtin_amdgcn_s_barrier()
; #define SCHED __builtin_amdgcn_sched_barrier(0)
; template <class Get, class Epi>
; DI void gemm_loop(int ntiles, int ld, char* shm, const Get& get, const Epi& epi) {
;     ...
;             WAIT_V(8); WAIT_L(0); BAR; G_MMA(0, 0, At, B0); G_MMA(0, 1, At, B1); BAR; SCHED;
;             G_LDA(At, 0, 1); G_STAGE(G_SB(0, 0), b2, voffB); G_STAGE(G_SB(0, 1), b2 + hstep, voffB); G_STAGE(G_SA(0, 0), a2, voffA);
;             WAIT_V(8); WAIT_L(0); BAR; G_MMA(1, 0, At, B0); G_MMA(1, 1, At, B1); BAR; SCHED;
.Lrj_1694_0:
	s_waitcnt lgkmcnt(0)
	s_barrier
	s_setprio 1
	s_waitcnt lgkmcnt(0)
	v_mfma_f32_16x16x32_bf16 v[124:127], v[144:147], v[176:179], 0
	v_mfma_f32_16x16x32_bf16 v[120:123], v[152:155], v[176:179], 0
	v_mfma_f32_16x16x32_bf16 v[108:111], v[144:147], v[184:187], 0
	v_mfma_f32_16x16x32_bf16 v[104:107], v[152:155], v[184:187], 0
	v_mfma_f32_16x16x32_bf16 v[92:95], v[144:147], v[192:195], 0
	v_mfma_f32_16x16x32_bf16 v[88:91], v[152:155], v[192:195], 0
	v_mfma_f32_16x16x32_bf16 v[76:79], v[144:147], v[200:203], 0
	v_mfma_f32_16x16x32_bf16 v[72:75], v[152:155], v[200:203], 0
	v_mfma_f32_16x16x32_bf16 v[124:127], v[148:151], v[180:183], v[124:127]
	v_mfma_f32_16x16x32_bf16 v[120:123], v[156:159], v[180:183], v[120:123]
	v_mfma_f32_16x16x32_bf16 v[108:111], v[148:151], v[188:191], v[108:111]
	v_mfma_f32_16x16x32_bf16 v[104:107], v[156:159], v[188:191], v[104:107]
	v_mfma_f32_16x16x32_bf16 v[92:95], v[148:151], v[196:199], v[92:95]
	v_mfma_f32_16x16x32_bf16 v[88:91], v[156:159], v[196:199], v[88:91]
	v_mfma_f32_16x16x32_bf16 v[76:79], v[148:151], v[204:207], v[76:79]
	v_mfma_f32_16x16x32_bf16 v[72:75], v[156:159], v[204:207], v[72:75]
	s_setprio 0
	s_setprio 1
	v_mfma_f32_16x16x32_bf16 v[116:119], v[160:163], v[176:179], 0
	v_mfma_f32_16x16x32_bf16 v[112:115], v[168:171], v[176:179], 0
	v_mfma_f32_16x16x32_bf16 v[100:103], v[160:163], v[184:187], 0
	v_mfma_f32_16x16x32_bf16 v[96:99], v[168:171], v[184:187], 0
	v_mfma_f32_16x16x32_bf16 v[84:87], v[160:163], v[192:195], 0
	v_mfma_f32_16x16x32_bf16 v[80:83], v[168:171], v[192:195], 0
	v_mfma_f32_16x16x32_bf16 v[68:71], v[160:163], v[200:203], 0
	v_mfma_f32_16x16x32_bf16 v[64:67], v[168:171], v[200:203], 0
	v_mfma_f32_16x16x32_bf16 v[116:119], v[164:167], v[180:183], v[116:119]
	v_mfma_f32_16x16x32_bf16 v[112:115], v[172:175], v[180:183], v[112:115]
	v_mfma_f32_16x16x32_bf16 v[100:103], v[164:167], v[188:191], v[100:103]
	v_mfma_f32_16x16x32_bf16 v[96:99], v[172:175], v[188:191], v[96:99]
	v_mfma_f32_16x16x32_bf16 v[84:87], v[164:167], v[196:199], v[84:87]
	v_mfma_f32_16x16x32_bf16 v[80:83], v[172:175], v[196:199], v[80:83]
	v_mfma_f32_16x16x32_bf16 v[68:71], v[164:167], v[204:207], v[68:71]
	v_mfma_f32_16x16x32_bf16 v[64:67], v[172:175], v[204:207], v[64:67]
	s_setprio 0
	s_barrier
	s_add_i32 s58, s48, s42
	v_lshl_add_u64 v[208:209], s[14:15], 0, v[132:133]
	s_mov_b32 m0, s58
	ds_read_b128 v[176:179], v143 offset:16384
	ds_read_b128 v[180:183], v143 offset:17408
	ds_read_b128 v[184:187], v143 offset:18432
	ds_read_b128 v[188:191], v143 offset:19456
	ds_read_b128 v[192:195], v143 offset:20480
	ds_read_b128 v[196:199], v143 offset:21504
	ds_read_b128 v[200:203], v143 offset:22528
	ds_read_b128 v[204:207], v143 offset:23552
	global_load_lds_dwordx4 v[208:209], off
	s_add_i32 m0, s58, 0x2000
	s_add_u32 s58, s14, 0x40000
	v_lshl_add_u64 v[210:211], s[14:15], 0, v[128:129]
	s_addc_u32 s59, s15, 0
	s_add_i32 s71, s49, s42
	global_load_lds_dwordx4 v[210:211], off
	v_lshl_add_u64 v[212:213], s[58:59], 0, v[132:133]
	s_mov_b32 m0, s71
	v_lshl_add_u64 v[214:215], s[40:41], 0, v[130:131]
	global_load_lds_dwordx4 v[212:213], off
	v_lshl_add_u64 v[212:213], s[58:59], 0, v[128:129]
	s_add_i32 m0, s71, 0x2000
	s_nop 0
	global_load_lds_dwordx4 v[212:213], off
	v_lshl_add_u64 v[212:213], s[40:41], 0, v[134:135]
	s_mov_b32 m0, s35
	s_nop 0
	global_load_lds_dwordx4 v[212:213], off
	s_mov_b32 m0, s37
	s_nop 0
	global_load_lds_dwordx4 v[214:215], off
	s_cmp_lg_u32 s100, 0
	s_cbranch_scc0 .Lrf_1694_1
	s_waitcnt vmcnt(16)
	s_branch .Lrj_1694_1

; #define G_STAGE(bufoff, gbase, voff) do { _Pragma("unroll") for (int _i = 0; _i < 2; ++_i) \
;         __builtin_amdgcn_global_load_lds((const unsigned*)((const char*)(gbase) + voff[_i]), (LAS unsigned*)(lds + (bufoff) + ldsw + _i * 8192), 16, 0, 0); } while (0)
; #define G_LDA(dst, b, h) do { _Pragma("unroll") for (int m = 0; m < 4; ++m) _Pragma("unroll") for (int k = 0; k < 2; ++k) dst[m][k] = *(const LAS bf16x8*)(lds + G_SA(b, h) + aoff + m * 2048 + k * 1024); } while (0)
; #define G_LDB(dst, b, h) do { _Pragma("unroll") for (int n = 0; n < 2; ++n) _Pragma("unroll") for (int k = 0; k < 2; ++k) dst[n][k] = *(const LAS bf16x8*)(lds + G_SB(b, h) + boff + n * 2048 + k * 1024); } while (0)
; #define G_MMA(ai, bj, At_, Bt_) do { __builtin_amdgcn_s_setprio(1); _Pragma("unroll") for (int m = 0; m < 4; ++m) _Pragma("unroll") for (int n = 0; n < 2; ++n) _Pragma("unroll") for (int k = 0; k < 2; ++k) \
;         acc[ai][bj][m][n] = __builtin_amdgcn_mfma_f32_16x16x32_bf16(Bt_[n][k], At_[m][k], acc[ai][bj][m][n], 0, 0, 0); __builtin_amdgcn_s_setprio(0); } while (0)
; #define WAIT_V(n) asm volatile("s_waitcnt vmcnt(" #n ")" ::: "memory")
; #define WAIT_L(n) asm volatile("s_waitcnt lgkmcnt(" #n ")" ::: "memory")
; #define BAR __builtin_amdgcn_s_barrier()
; #define SCHED __builtin_amdgcn_sched_barrier(0)
; template <class Get, class Epi>
; DI void gemm_loop(int ntiles, int ld, char* shm, const Get& get, const Epi& epi) {
;     ...
;             WAIT_V(8); WAIT_L(0); BAR; G_MMA(1, 0, At, B0); G_MMA(1, 1, At, B1); BAR; SCHED;
;             G_LDB(B0, 1, 0); G_LDB(B1, 1, 1); SCHED; G_LDA(At, 1, 0); G_STAGE(G_SA(0, 1), a2 + hstep, voffA);
;             WAIT_V(8); WAIT_L(0); BAR; G_MMA(0, 0, At, B0); G_MMA(0, 1, At, B1); BAR; SCHED;
.Lrj_1694_1:
	s_waitcnt lgkmcnt(0)
	s_barrier
	s_setprio 1
	s_waitcnt lgkmcnt(0)
	v_mfma_f32_16x16x32_bf16 v[60:63], v[144:147], v[176:179], 0
	v_mfma_f32_16x16x32_bf16 v[56:59], v[152:155], v[176:179], 0
	v_mfma_f32_16x16x32_bf16 v[44:47], v[144:147], v[184:187], 0
	v_mfma_f32_16x16x32_bf16 v[40:43], v[152:155], v[184:187], 0
	v_mfma_f32_16x16x32_bf16 v[28:31], v[144:147], v[192:195], 0
	v_mfma_f32_16x16x32_bf16 v[24:27], v[152:155], v[192:195], 0
	v_mfma_f32_16x16x32_bf16 v[12:15], v[144:147], v[200:203], 0
	v_mfma_f32_16x16x32_bf16 v[8:11], v[152:155], v[200:203], 0
	v_mfma_f32_16x16x32_bf16 v[60:63], v[148:151], v[180:183], v[60:63]
	v_mfma_f32_16x16x32_bf16 v[56:59], v[156:159], v[180:183], v[56:59]
	v_mfma_f32_16x16x32_bf16 v[44:47], v[148:151], v[188:191], v[44:47]
	v_mfma_f32_16x16x32_bf16 v[40:43], v[156:159], v[188:191], v[40:43]
	v_mfma_f32_16x16x32_bf16 v[28:31], v[148:151], v[196:199], v[28:31]
	v_mfma_f32_16x16x32_bf16 v[24:27], v[156:159], v[196:199], v[24:27]
	v_mfma_f32_16x16x32_bf16 v[12:15], v[148:151], v[204:207], v[12:15]
	v_mfma_f32_16x16x32_bf16 v[8:11], v[156:159], v[204:207], v[8:11]
	s_setprio 0
	s_setprio 1
	v_mfma_f32_16x16x32_bf16 v[52:55], v[160:163], v[176:179], 0
	v_mfma_f32_16x16x32_bf16 v[48:51], v[168:171], v[176:179], 0
	v_mfma_f32_16x16x32_bf16 v[36:39], v[160:163], v[184:187], 0
	v_mfma_f32_16x16x32_bf16 v[32:35], v[168:171], v[184:187], 0
	v_mfma_f32_16x16x32_bf16 v[20:23], v[160:163], v[192:195], 0
	v_mfma_f32_16x16x32_bf16 v[16:19], v[168:171], v[192:195], 0
	v_mfma_f32_16x16x32_bf16 v[4:7], v[160:163], v[200:203], 0
	v_mfma_f32_16x16x32_bf16 v[0:3], v[168:171], v[200:203], 0
	v_mfma_f32_16x16x32_bf16 v[52:55], v[164:167], v[180:183], v[52:55]
	v_mfma_f32_16x16x32_bf16 v[48:51], v[172:175], v[180:183], v[48:51]
	v_mfma_f32_16x16x32_bf16 v[36:39], v[164:167], v[188:191], v[36:39]
	v_mfma_f32_16x16x32_bf16 v[32:35], v[172:175], v[188:191], v[32:35]
	v_mfma_f32_16x16x32_bf16 v[20:23], v[164:167], v[196:199], v[20:23]
	v_mfma_f32_16x16x32_bf16 v[16:19], v[172:175], v[196:199], v[16:19]
	v_mfma_f32_16x16x32_bf16 v[4:7], v[164:167], v[204:207], v[4:7]
	v_mfma_f32_16x16x32_bf16 v[0:3], v[172:175], v[204:207], v[0:3]
	s_setprio 0
	s_barrier
	s_add_i32 s58, 0, 0x18000
	s_add_i32 s59, 0, 0x1c000
	v_add_u32_e32 v156, s58, v140
	v_add_u32_e32 v172, s59, v140
	ds_read_b128 v[144:147], v156
	ds_read_b128 v[148:151], v156 offset:1024
	ds_read_b128 v[152:155], v156 offset:2048
	ds_read_b128 v[156:159], v156 offset:3072
	ds_read_b128 v[160:163], v172
	ds_read_b128 v[164:167], v172 offset:1024
	ds_read_b128 v[168:171], v172 offset:2048
	ds_read_b128 v[172:175], v172 offset:3072
	s_add_u32 s40, s40, 0x40000
	s_addc_u32 s41, s41, 0
	s_mov_b32 m0, s44
	v_lshl_add_u64 v[216:217], s[40:41], 0, v[134:135]
	ds_read_b128 v[176:179], v143 offset:32768
	ds_read_b128 v[180:183], v143 offset:33792
	ds_read_b128 v[184:187], v143 offset:34816
	ds_read_b128 v[188:191], v143 offset:35840
	ds_read_b128 v[192:195], v143 offset:36864
	ds_read_b128 v[196:199], v143 offset:37888
	ds_read_b128 v[200:203], v143 offset:38912
	ds_read_b128 v[204:207], v143 offset:39936
	global_load_lds_dwordx4 v[216:217], off
	v_lshl_add_u64 v[216:217], s[40:41], 0, v[130:131]
	s_mov_b32 m0, s45
	s_nop 0
	global_load_lds_dwordx4 v[216:217], off
	s_waitcnt vmcnt(8)
	s_waitcnt lgkmcnt(0)
	s_barrier
	s_setprio 1
	s_waitcnt lgkmcnt(0)
	v_mfma_f32_16x16x32_bf16 v[124:127], v[144:147], v[176:179], v[124:127]
	v_mfma_f32_16x16x32_bf16 v[120:123], v[152:155], v[176:179], v[120:123]
	v_mfma_f32_16x16x32_bf16 v[108:111], v[144:147], v[184:187], v[108:111]
	v_mfma_f32_16x16x32_bf16 v[104:107], v[152:155], v[184:187], v[104:107]
	v_mfma_f32_16x16x32_bf16 v[92:95], v[144:147], v[192:195], v[92:95]
	v_mfma_f32_16x16x32_bf16 v[88:91], v[152:155], v[192:195], v[88:91]
	v_mfma_f32_16x16x32_bf16 v[76:79], v[144:147], v[200:203], v[76:79]
	v_mfma_f32_16x16x32_bf16 v[72:75], v[152:155], v[200:203], v[72:75]
	v_mfma_f32_16x16x32_bf16 v[124:127], v[148:151], v[180:183], v[124:127]
	v_mfma_f32_16x16x32_bf16 v[120:123], v[156:159], v[180:183], v[120:123]
	v_mfma_f32_16x16x32_bf16 v[108:111], v[148:151], v[188:191], v[108:111]
	v_mfma_f32_16x16x32_bf16 v[104:107], v[156:159], v[188:191], v[104:107]
	v_mfma_f32_16x16x32_bf16 v[92:95], v[148:151], v[196:199], v[92:95]
	v_mfma_f32_16x16x32_bf16 v[88:91], v[156:159], v[196:199], v[88:91]
	v_mfma_f32_16x16x32_bf16 v[76:79], v[148:151], v[204:207], v[76:79]
	v_mfma_f32_16x16x32_bf16 v[72:75], v[156:159], v[204:207], v[72:75]
	s_setprio 0
	s_setprio 1
	v_mfma_f32_16x16x32_bf16 v[116:119], v[160:163], v[176:179], v[116:119]
	v_mfma_f32_16x16x32_bf16 v[112:115], v[168:171], v[176:179], v[112:115]
	v_mfma_f32_16x16x32_bf16 v[100:103], v[160:163], v[184:187], v[100:103]
	v_mfma_f32_16x16x32_bf16 v[96:99], v[168:171], v[184:187], v[96:99]
	v_mfma_f32_16x16x32_bf16 v[84:87], v[160:163], v[192:195], v[84:87]
	v_mfma_f32_16x16x32_bf16 v[80:83], v[168:171], v[192:195], v[80:83]
	v_mfma_f32_16x16x32_bf16 v[68:71], v[160:163], v[200:203], v[68:71]
	v_mfma_f32_16x16x32_bf16 v[64:67], v[168:171], v[200:203], v[64:67]
	v_mfma_f32_16x16x32_bf16 v[116:119], v[164:167], v[180:183], v[116:119]
	v_mfma_f32_16x16x32_bf16 v[112:115], v[172:175], v[180:183], v[112:115]
	v_mfma_f32_16x16x32_bf16 v[100:103], v[164:167], v[188:191], v[100:103]
	v_mfma_f32_16x16x32_bf16 v[96:99], v[172:175], v[188:191], v[96:99]
	v_mfma_f32_16x16x32_bf16 v[84:87], v[164:167], v[196:199], v[84:87]
	v_mfma_f32_16x16x32_bf16 v[80:83], v[172:175], v[196:199], v[80:83]
	v_mfma_f32_16x16x32_bf16 v[68:71], v[164:167], v[204:207], v[68:71]
	v_mfma_f32_16x16x32_bf16 v[64:67], v[172:175], v[204:207], v[64:67]
	s_setprio 0
	s_barrier
; #define G_STAGE(bufoff, gbase, voff) do { _Pragma("unroll") for (int _i = 0; _i < 2; ++_i) \
;         __builtin_amdgcn_global_load_lds((const unsigned*)((const char*)(gbase) + voff[_i]), (LAS unsigned*)(lds + (bufoff) + ldsw + _i * 8192), 16, 0, 0); } while (0)
; #define G_LDA(dst, b, h) do { _Pragma("unroll") for (int m = 0; m < 4; ++m) _Pragma("unroll") for (int k = 0; k < 2; ++k) dst[m][k] = *(const LAS bf16x8*)(lds + G_SA(b, h) + aoff + m * 2048 + k * 1024); } while (0)
; #define G_MMA(ai, bj, At_, Bt_) do { __builtin_amdgcn_s_setprio(1); _Pragma("unroll") for (int m = 0; m < 4; ++m) _Pragma("unroll") for (int n = 0; n < 2; ++n) _Pragma("unroll") for (int k = 0; k < 2; ++k) \
;         acc[ai][bj][m][n] = __builtin_amdgcn_mfma_f32_16x16x32_bf16(Bt_[n][k], At_[m][k], acc[ai][bj][m][n], 0, 0, 0); __builtin_amdgcn_s_setprio(0); } while (0)
; #define WAIT_V(n) asm volatile("s_waitcnt vmcnt(" #n ")" ::: "memory")
; #define WAIT_L(n) asm volatile("s_waitcnt lgkmcnt(" #n ")" ::: "memory")
; #define BAR __builtin_amdgcn_s_barrier()
; #define SCHED __builtin_amdgcn_sched_barrier(0)
; template <class Get, class Epi>
; DI void gemm_loop(int ntiles, int ld, char* shm, const Get& get, const Epi& epi) {
;     ...
;             G_LDA(At, 1, 1); G_STAGE(G_SB(1, 0), b3, voffB); G_STAGE(G_SB(1, 1), b3 + hstep, voffB); G_STAGE(G_SA(1, 0), a3, voffA);
;             WAIT_V(8); WAIT_L(0); BAR; G_MMA(1, 0, At, B0); G_MMA(1, 1, At, B1); BAR; SCHED;
;         }
	s_add_i32 s40, s58, s42
	v_lshl_add_u64 v[208:209], v[208:209], 0, s[2:3]
	s_mov_b32 m0, s40
	ds_read_b128 v[176:179], v143 offset:49152
	ds_read_b128 v[180:183], v143 offset:50176
	ds_read_b128 v[184:187], v143 offset:51200
	ds_read_b128 v[188:191], v143 offset:52224
	ds_read_b128 v[192:195], v143 offset:53248
	ds_read_b128 v[196:199], v143 offset:54272
	ds_read_b128 v[200:203], v143 offset:55296
	ds_read_b128 v[204:207], v143 offset:56320
	global_load_lds_dwordx4 v[208:209], off
	s_add_i32 m0, s40, 0x2000
	s_add_u32 s14, s14, 0x40080
	v_lshl_add_u64 v[208:209], v[210:211], 0, s[2:3]
	s_addc_u32 s15, s15, 0
	s_add_i32 s40, s59, s42
	global_load_lds_dwordx4 v[208:209], off
	v_lshl_add_u64 v[208:209], s[14:15], 0, v[132:133]
	s_mov_b32 m0, s40
	s_nop 0
	global_load_lds_dwordx4 v[208:209], off
	v_lshl_add_u64 v[208:209], s[14:15], 0, v[128:129]
	s_add_i32 m0, s40, 0x2000
	s_nop 0
	global_load_lds_dwordx4 v[208:209], off
	v_lshl_add_u64 v[208:209], v[212:213], 0, s[2:3]
	s_mov_b32 m0, s46
	s_nop 0
	global_load_lds_dwordx4 v[208:209], off
	v_lshl_add_u64 v[208:209], v[214:215], 0, s[2:3]
	s_mov_b32 m0, s47
	s_nop 0
	global_load_lds_dwordx4 v[208:209], off
	s_waitcnt vmcnt(8)
	s_waitcnt lgkmcnt(0)
	s_barrier
	s_setprio 1
	s_waitcnt lgkmcnt(0)
	v_mfma_f32_16x16x32_bf16 v[60:63], v[144:147], v[176:179], v[60:63]
	v_mfma_f32_16x16x32_bf16 v[56:59], v[152:155], v[176:179], v[56:59]
	v_mfma_f32_16x16x32_bf16 v[44:47], v[144:147], v[184:187], v[44:47]
	v_mfma_f32_16x16x32_bf16 v[40:43], v[152:155], v[184:187], v[40:43]
	v_mfma_f32_16x16x32_bf16 v[28:31], v[144:147], v[192:195], v[28:31]
	v_mfma_f32_16x16x32_bf16 v[24:27], v[152:155], v[192:195], v[24:27]
	v_mfma_f32_16x16x32_bf16 v[12:15], v[144:147], v[200:203], v[12:15]
	v_mfma_f32_16x16x32_bf16 v[8:11], v[152:155], v[200:203], v[8:11]
	v_mfma_f32_16x16x32_bf16 v[60:63], v[148:151], v[180:183], v[60:63]
	v_mfma_f32_16x16x32_bf16 v[56:59], v[156:159], v[180:183], v[56:59]
	v_mfma_f32_16x16x32_bf16 v[44:47], v[148:151], v[188:191], v[44:47]
	v_mfma_f32_16x16x32_bf16 v[40:43], v[156:159], v[188:191], v[40:43]
	v_mfma_f32_16x16x32_bf16 v[28:31], v[148:151], v[196:199], v[28:31]
	v_mfma_f32_16x16x32_bf16 v[24:27], v[156:159], v[196:199], v[24:27]
	v_mfma_f32_16x16x32_bf16 v[12:15], v[148:151], v[204:207], v[12:15]
	v_mfma_f32_16x16x32_bf16 v[8:11], v[156:159], v[204:207], v[8:11]
	s_setprio 0
	s_setprio 1
	v_mfma_f32_16x16x32_bf16 v[52:55], v[160:163], v[176:179], v[52:55]
	v_mfma_f32_16x16x32_bf16 v[48:51], v[168:171], v[176:179], v[48:51]
	v_mfma_f32_16x16x32_bf16 v[36:39], v[160:163], v[184:187], v[36:39]
	v_mfma_f32_16x16x32_bf16 v[32:35], v[168:171], v[184:187], v[32:35]
	v_mfma_f32_16x16x32_bf16 v[20:23], v[160:163], v[192:195], v[20:23]
	v_mfma_f32_16x16x32_bf16 v[16:19], v[168:171], v[192:195], v[16:19]
	v_mfma_f32_16x16x32_bf16 v[4:7], v[160:163], v[200:203], v[4:7]
	v_mfma_f32_16x16x32_bf16 v[0:3], v[168:171], v[200:203], v[0:3]
	v_mfma_f32_16x16x32_bf16 v[52:55], v[164:167], v[180:183], v[52:55]
	v_mfma_f32_16x16x32_bf16 v[48:51], v[172:175], v[180:183], v[48:51]
	v_mfma_f32_16x16x32_bf16 v[36:39], v[164:167], v[188:191], v[36:39]
	v_mfma_f32_16x16x32_bf16 v[32:35], v[172:175], v[188:191], v[32:35]
	v_mfma_f32_16x16x32_bf16 v[20:23], v[164:167], v[196:199], v[20:23]
	v_mfma_f32_16x16x32_bf16 v[16:19], v[172:175], v[196:199], v[16:19]
	v_mfma_f32_16x16x32_bf16 v[4:7], v[164:167], v[204:207], v[4:7]
	v_mfma_f32_16x16x32_bf16 v[0:3], v[172:175], v[204:207], v[0:3]
	s_setprio 0
	s_barrier
	s_add_i32 s57, s57, 2
	s_add_u32 s38, s38, 0x100
	s_addc_u32 s39, s39, 0
	s_add_u32 s55, s55, 0x100
	s_addc_u32 s56, s56, 0
	s_cmp_gt_u32 s57, 13
	s_cbranch_scc0 .LBB0_1694
	s_branch .Lpost_1694

; #define G_STAGE(bufoff, gbase, voff) do { _Pragma("unroll") for (int _i = 0; _i < 2; ++_i) \
;         __builtin_amdgcn_global_load_lds((const unsigned*)((const char*)(gbase) + voff[_i]), (LAS unsigned*)(lds + (bufoff) + ldsw + _i * 8192), 16, 0, 0); } while (0)
; #define WAIT_V(n) asm volatile("s_waitcnt vmcnt(" #n ")" ::: "memory")
; #define BAR __builtin_amdgcn_s_barrier()
; template <class Get, class Epi>
; DI void gemm_loop(int ntiles, int ld, char* shm, const Get& get, const Epi& epi) {
;     ...
;     const int aoff = lds_byte(wr * 64 + fr, fq * 8), boff = lds_byte(wc * 32 + fr, fq * 8);
;     ...
;     const char* cA = (const char*)cur.A + (size_t)cur.brow * ld * 2; const char* cB = (const char*)cur.Bt + (size_t)cur.bcol * ld * 2;
;     G_STAGE(G_SB(0, 0), cB, voffB); G_STAGE(G_SB(0, 1), cB + hstep, voffB); G_STAGE(G_SA(0, 0), cA, voffA); G_STAGE(G_SA(0, 1), cA + hstep, voffA);
;     if (wr == 1) BAR;
;     WAIT_V(2); BAR;
;     G_STAGE(G_SB(1, 0), cB + kstep, voffB); G_STAGE(G_SA(1, 0), cA + kstep, voffA); G_STAGE(G_SB(1, 1), cB + hstep + kstep, voffB);
;     WAIT_V(6); BAR;
.LBB0_1764:
	s_add_u32 s49, s68, 0x83b000
	s_addc_u32 s50, s69, 0
	s_lshl_b32 s10, s10, 12
	s_and_b32 s13, s10, 0x3000
	s_mov_b64 s[10:11], 0x80
	s_add_i32 m0, s45, 0x18000
	v_lshl_add_u64 v[6:7], v[6:7], 0, s[10:11]
	s_lshl_b32 s3, s3, 13
	s_waitcnt vmcnt(2)
	s_barrier
	global_load_lds_dwordx4 v[6:7], off
	v_lshl_add_u64 v[4:5], v[4:5], 0, s[10:11]
	s_add_i32 m0, s45, 0x1a000
	s_add_i32 s51, s45, 0x8000
	s_add_i32 s52, s45, 0xa000
	global_load_lds_dwordx4 v[4:5], off
	v_lshl_add_u64 v[0:1], v[0:1], 0, s[10:11]
	s_mov_b32 m0, s51
	s_add_u32 s30, s14, 0xb0080
	global_load_lds_dwordx4 v[0:1], off
	v_lshl_add_u64 v[0:1], v[2:3], 0, s[10:11]
	s_mov_b32 m0, s52
	s_addc_u32 s31, s15, 0
	global_load_lds_dwordx4 v[0:1], off
	s_add_i32 m0, s45, 0x1c000
	v_lshl_add_u64 v[0:1], s[30:31], 0, v[148:149]
	global_load_lds_dwordx4 v[0:1], off
	v_lshl_add_u64 v[0:1], s[30:31], 0, v[152:153]
	s_add_i32 m0, s45, 0x1e000
	v_lshlrev_b32_e32 v3, 2, v8
	global_load_lds_dwordx4 v[0:1], off
	v_and_b32_e32 v0, 15, v8
	v_and_b32_e32 v1, 48, v8
	v_lshlrev_b32_e32 v0, 6, v0
	v_and_b32_e32 v3, 32, v3
	v_or_b32_e32 v2, v0, v1
	v_bitop3_b32 v0, v0, v3, v1 bitop3:0x36
	v_bitop3_b32 v2, v2, s3, v3 bitop3:0xde
	v_or_b32_e32 v168, s13, v0
	v_lshrrev_b32_e32 v1, 1, v9
	v_mul_lo_u32 v0, v11, s2
	s_mov_b32 s3, 0xb000
	v_mad_u64_u32 v[0:1], s[36:37], v1, s3, v[0:1]
	v_or_b32_e32 v0, v0, v10
	s_mov_b64 s[34:35], 0xb0080
	v_add_lshl_u32 v0, v0, v12, 1
	v_mov_b32_e32 v1, v149
	v_lshl_add_u64 v[154:155], v[0:1], 0, s[34:35]
	v_lshrrev_b32_e32 v1, 1, v13
	v_mul_lo_u32 v0, v14, s2
	s_cmpk_lt_u32 s12, 0x100
	v_mad_u64_u32 v[0:1], s[2:3], v1, s3, v[0:1]
	s_waitcnt vmcnt(6)
	s_mov_b32 s100, 0
	s_cselect_b64 s[12:13], -1, 0
	s_add_u32 s30, s68, 0x86b000
	v_or_b32_e32 v0, v0, v15
	s_addc_u32 s31, s69, 0
	v_add_lshl_u32 v0, v0, v16, 1
	v_mov_b32_e32 v1, v149
	s_add_i32 s53, 0, 0x10000
	s_add_i32 s54, 0, 0x14000
	v_lshl_add_u64 v[156:157], v[0:1], 0, s[34:35]
	v_add_u32_e32 v169, s53, v168
	v_add_u32_e32 v170, s54, v168
	v_add_u32_e32 v171, 0, v2
	s_mov_b64 s[34:35], 0xa0000
	s_mov_b32 s56, s40
	s_mov_b32 s57, s72
	s_mov_b32 s58, s71
	s_barrier
	s_branch .LBB0_1767

; #define G_STAGE(bufoff, gbase, voff) do { _Pragma("unroll") for (int _i = 0; _i < 2; ++_i) \
;         __builtin_amdgcn_global_load_lds((const unsigned*)((const char*)(gbase) + voff[_i]), (LAS unsigned*)(lds + (bufoff) + ldsw + _i * 8192), 16, 0, 0); } while (0)
; #define G_LDA(dst, b, h) do { _Pragma("unroll") for (int m = 0; m < 4; ++m) _Pragma("unroll") for (int k = 0; k < 2; ++k) dst[m][k] = *(const LAS bf16x8*)(lds + G_SA(b, h) + aoff + m * 2048 + k * 1024); } while (0)
; #define G_LDB(dst, b, h) do { _Pragma("unroll") for (int n = 0; n < 2; ++n) _Pragma("unroll") for (int k = 0; k < 2; ++k) dst[n][k] = *(const LAS bf16x8*)(lds + G_SB(b, h) + boff + n * 2048 + k * 1024); } while (0)
; #define G_MMA(ai, bj, At_, Bt_) do { __builtin_amdgcn_s_setprio(1); _Pragma("unroll") for (int m = 0; m < 4; ++m) _Pragma("unroll") for (int n = 0; n < 2; ++n) _Pragma("unroll") for (int k = 0; k < 2; ++k) \
;         acc[ai][bj][m][n] = __builtin_amdgcn_mfma_f32_16x16x32_bf16(Bt_[n][k], At_[m][k], acc[ai][bj][m][n], 0, 0, 0); __builtin_amdgcn_s_setprio(0); } while (0)
; #define WAIT_V(n) asm volatile("s_waitcnt vmcnt(" #n ")" ::: "memory")
; #define WAIT_L(n) asm volatile("s_waitcnt lgkmcnt(" #n ")" ::: "memory")
; #define BAR __builtin_amdgcn_s_barrier()
; #define SCHED __builtin_amdgcn_sched_barrier(0)
; template <class Get, class Epi>
; DI void gemm_loop(int ntiles, int ld, char* shm, const Get& get, const Epi& epi) {
;     ...
;             G_LDB(B0, 0, 0); G_LDB(B1, 0, 1); SCHED; G_LDA(At, 0, 0); G_STAGE(G_SA(1, 1), a1 + hstep, voffA);
;             WAIT_V(8); WAIT_L(0); BAR; G_MMA(0, 0, At, B0); G_MMA(0, 1, At, B1); BAR; SCHED;
.Lpeel_1781:
	ds_read_b128 v[128:131], v169
	ds_read_b128 v[132:135], v169 offset:1024
	ds_read_b128 v[136:139], v169 offset:2048
	ds_read_b128 v[140:143], v169 offset:3072
	ds_read_b128 v[158:161], v170
	ds_read_b128 v[162:165], v170 offset:1024
	ds_read_b128 v[172:175], v170 offset:2048
	ds_read_b128 v[176:179], v170 offset:3072
	s_add_i32 s77, s40, 2
	s_add_u32 s14, s4, 0x100
	s_addc_u32 s15, s5, 0
	s_cmp_eq_u32 s74, s40
	s_cselect_b32 s40, s38, s75
	s_cselect_b32 s43, s37, s15
	s_cselect_b32 s42, s36, s14
	s_cselect_b32 s41, s39, s76
	v_lshl_add_u64 v[144:145], s[4:5], 0, v[154:155]
	s_add_i32 m0, s45, 0xc000
	ds_read_b128 v[180:183], v171
	ds_read_b128 v[184:187], v171 offset:1024
	ds_read_b128 v[188:191], v171 offset:2048
	ds_read_b128 v[192:195], v171 offset:3072
	ds_read_b128 v[196:199], v171 offset:4096
	ds_read_b128 v[200:203], v171 offset:5120
	ds_read_b128 v[204:207], v171 offset:6144
	ds_read_b128 v[208:211], v171 offset:7168
	global_load_lds_dwordx4 v[144:145], off
	v_lshl_add_u64 v[144:145], s[4:5], 0, v[156:157]
	s_add_i32 m0, s45, 0xe000
	s_nop 0
	global_load_lds_dwordx4 v[144:145], off
	s_cmp_lg_u32 s100, 0
	s_cbranch_scc0 .Lrf_1781_0
	s_waitcnt vmcnt(16)
	s_branch .Lrj_1781_0

; #define G_STAGE(bufoff, gbase, voff) do { _Pragma("unroll") for (int _i = 0; _i < 2; ++_i) \
;         __builtin_amdgcn_global_load_lds((const unsigned*)((const char*)(gbase) + voff[_i]), (LAS unsigned*)(lds + (bufoff) + ldsw + _i * 8192), 16, 0, 0); } while (0)
; #define G_LDA(dst, b, h) do { _Pragma("unroll") for (int m = 0; m < 4; ++m) _Pragma("unroll") for (int k = 0; k < 2; ++k) dst[m][k] = *(const LAS bf16x8*)(lds + G_SA(b, h) + aoff + m * 2048 + k * 1024); } while (0)
; #define G_MMA(ai, bj, At_, Bt_) do { __builtin_amdgcn_s_setprio(1); _Pragma("unroll") for (int m = 0; m < 4; ++m) _Pragma("unroll") for (int n = 0; n < 2; ++n) _Pragma("unroll") for (int k = 0; k < 2; ++k) \
;         acc[ai][bj][m][n] = __builtin_amdgcn_mfma_f32_16x16x32_bf16(Bt_[n][k], At_[m][k], acc[ai][bj][m][n], 0, 0, 0); __builtin_amdgcn_s_setprio(0); } while (0)
; #define WAIT_V(n) asm volatile("s_waitcnt vmcnt(" #n ")" ::: "memory")
; #define WAIT_L(n) asm volatile("s_waitcnt lgkmcnt(" #n ")" ::: "memory")
; #define BAR __builtin_amdgcn_s_barrier()
; #define SCHED __builtin_amdgcn_sched_barrier(0)
; template <class Get, class Epi>
; DI void gemm_loop(int ntiles, int ld, char* shm, const Get& get, const Epi& epi) {
;     ...
;             WAIT_V(8); WAIT_L(0); BAR; G_MMA(0, 0, At, B0); G_MMA(0, 1, At, B1); BAR; SCHED;
;             G_LDA(At, 0, 1); G_STAGE(G_SB(0, 0), b2, voffB); G_STAGE(G_SB(0, 1), b2 + hstep, voffB); G_STAGE(G_SA(0, 0), a2, voffA);
;             WAIT_V(8); WAIT_L(0); BAR; G_MMA(1, 0, At, B0); G_MMA(1, 1, At, B1); BAR; SCHED;
.Lrj_1781_0:
	s_waitcnt lgkmcnt(0)
	s_barrier
	s_setprio 1
	s_waitcnt lgkmcnt(0)
	v_mfma_f32_16x16x32_bf16 v[124:127], v[128:131], v[180:183], 0
	v_mfma_f32_16x16x32_bf16 v[120:123], v[136:139], v[180:183], 0
	v_mfma_f32_16x16x32_bf16 v[116:119], v[128:131], v[188:191], 0
	v_mfma_f32_16x16x32_bf16 v[112:115], v[136:139], v[188:191], 0
	v_mfma_f32_16x16x32_bf16 v[108:111], v[128:131], v[196:199], 0
	v_mfma_f32_16x16x32_bf16 v[104:107], v[136:139], v[196:199], 0
	v_mfma_f32_16x16x32_bf16 v[100:103], v[128:131], v[204:207], 0
	v_mfma_f32_16x16x32_bf16 v[96:99], v[136:139], v[204:207], 0
	v_mfma_f32_16x16x32_bf16 v[124:127], v[132:135], v[184:187], v[124:127]
	v_mfma_f32_16x16x32_bf16 v[120:123], v[140:143], v[184:187], v[120:123]
	v_mfma_f32_16x16x32_bf16 v[116:119], v[132:135], v[192:195], v[116:119]
	v_mfma_f32_16x16x32_bf16 v[112:115], v[140:143], v[192:195], v[112:115]
	v_mfma_f32_16x16x32_bf16 v[108:111], v[132:135], v[200:203], v[108:111]
	v_mfma_f32_16x16x32_bf16 v[104:107], v[140:143], v[200:203], v[104:107]
	v_mfma_f32_16x16x32_bf16 v[100:103], v[132:135], v[208:211], v[100:103]
	v_mfma_f32_16x16x32_bf16 v[96:99], v[140:143], v[208:211], v[96:99]
	s_setprio 0
	s_setprio 1
	v_mfma_f32_16x16x32_bf16 v[60:63], v[158:161], v[180:183], 0
	v_mfma_f32_16x16x32_bf16 v[56:59], v[172:175], v[180:183], 0
	v_mfma_f32_16x16x32_bf16 v[52:55], v[158:161], v[188:191], 0
	v_mfma_f32_16x16x32_bf16 v[48:51], v[172:175], v[188:191], 0
	v_mfma_f32_16x16x32_bf16 v[44:47], v[158:161], v[196:199], 0
	v_mfma_f32_16x16x32_bf16 v[40:43], v[172:175], v[196:199], 0
	v_mfma_f32_16x16x32_bf16 v[36:39], v[158:161], v[204:207], 0
	v_mfma_f32_16x16x32_bf16 v[32:35], v[172:175], v[204:207], 0
	v_mfma_f32_16x16x32_bf16 v[60:63], v[162:165], v[184:187], v[60:63]
	v_mfma_f32_16x16x32_bf16 v[56:59], v[176:179], v[184:187], v[56:59]
	v_mfma_f32_16x16x32_bf16 v[52:55], v[162:165], v[192:195], v[52:55]
	v_mfma_f32_16x16x32_bf16 v[48:51], v[176:179], v[192:195], v[48:51]
	v_mfma_f32_16x16x32_bf16 v[44:47], v[162:165], v[200:203], v[44:47]
	v_mfma_f32_16x16x32_bf16 v[40:43], v[176:179], v[200:203], v[40:43]
	v_mfma_f32_16x16x32_bf16 v[36:39], v[162:165], v[208:211], v[36:39]
	v_mfma_f32_16x16x32_bf16 v[32:35], v[176:179], v[208:211], v[32:35]
	s_setprio 0
	s_barrier
	s_add_i32 s4, s53, s44
	v_lshl_add_u64 v[144:145], s[40:41], 0, v[148:149]
	s_mov_b32 m0, s4
	ds_read_b128 v[180:183], v171 offset:16384
	ds_read_b128 v[184:187], v171 offset:17408
	ds_read_b128 v[188:191], v171 offset:18432
	ds_read_b128 v[192:195], v171 offset:19456
	ds_read_b128 v[196:199], v171 offset:20480
	ds_read_b128 v[200:203], v171 offset:21504
	ds_read_b128 v[204:207], v171 offset:22528
	ds_read_b128 v[208:211], v171 offset:23552
	global_load_lds_dwordx4 v[144:145], off
	s_add_i32 m0, s4, 0x2000
	s_add_u32 s4, s40, 0xb0000
	v_lshl_add_u64 v[166:167], s[40:41], 0, v[152:153]
	s_addc_u32 s5, s41, 0
	s_add_i32 s78, s54, s44
	global_load_lds_dwordx4 v[166:167], off
	v_lshl_add_u64 v[212:213], s[4:5], 0, v[148:149]
	s_mov_b32 m0, s78
	v_lshl_add_u64 v[214:215], s[42:43], 0, v[150:151]
	global_load_lds_dwordx4 v[212:213], off
	v_lshl_add_u64 v[212:213], s[4:5], 0, v[152:153]
	s_add_i32 m0, s78, 0x2000
	s_nop 0
	global_load_lds_dwordx4 v[212:213], off
	v_lshl_add_u64 v[212:213], s[42:43], 0, v[146:147]
	s_mov_b32 m0, s45
	s_nop 0
	global_load_lds_dwordx4 v[212:213], off
	s_mov_b32 m0, s46
	s_nop 0
	global_load_lds_dwordx4 v[214:215], off
	s_cmp_lg_u32 s100, 0
	s_cbranch_scc0 .Lrf_1781_1
	s_waitcnt vmcnt(16)
	s_branch .Lrj_1781_1

; #define G_STAGE(bufoff, gbase, voff) do { _Pragma("unroll") for (int _i = 0; _i < 2; ++_i) \
;         __builtin_amdgcn_global_load_lds((const unsigned*)((const char*)(gbase) + voff[_i]), (LAS unsigned*)(lds + (bufoff) + ldsw + _i * 8192), 16, 0, 0); } while (0)
; #define G_LDA(dst, b, h) do { _Pragma("unroll") for (int m = 0; m < 4; ++m) _Pragma("unroll") for (int k = 0; k < 2; ++k) dst[m][k] = *(const LAS bf16x8*)(lds + G_SA(b, h) + aoff + m * 2048 + k * 1024); } while (0)
; #define G_LDB(dst, b, h) do { _Pragma("unroll") for (int n = 0; n < 2; ++n) _Pragma("unroll") for (int k = 0; k < 2; ++k) dst[n][k] = *(const LAS bf16x8*)(lds + G_SB(b, h) + boff + n * 2048 + k * 1024); } while (0)
; #define G_MMA(ai, bj, At_, Bt_) do { __builtin_amdgcn_s_setprio(1); _Pragma("unroll") for (int m = 0; m < 4; ++m) _Pragma("unroll") for (int n = 0; n < 2; ++n) _Pragma("unroll") for (int k = 0; k < 2; ++k) \
;         acc[ai][bj][m][n] = __builtin_amdgcn_mfma_f32_16x16x32_bf16(Bt_[n][k], At_[m][k], acc[ai][bj][m][n], 0, 0, 0); __builtin_amdgcn_s_setprio(0); } while (0)
; #define WAIT_V(n) asm volatile("s_waitcnt vmcnt(" #n ")" ::: "memory")
; #define WAIT_L(n) asm volatile("s_waitcnt lgkmcnt(" #n ")" ::: "memory")
; #define BAR __builtin_amdgcn_s_barrier()
; #define SCHED __builtin_amdgcn_sched_barrier(0)
; template <class Get, class Epi>
; DI void gemm_loop(int ntiles, int ld, char* shm, const Get& get, const Epi& epi) {
;     ...
;             WAIT_V(8); WAIT_L(0); BAR; G_MMA(1, 0, At, B0); G_MMA(1, 1, At, B1); BAR; SCHED;
;             G_LDB(B0, 1, 0); G_LDB(B1, 1, 1); SCHED; G_LDA(At, 1, 0); G_STAGE(G_SA(0, 1), a2 + hstep, voffA);
;             WAIT_V(8); WAIT_L(0); BAR; G_MMA(0, 0, At, B0); G_MMA(0, 1, At, B1); BAR; SCHED;
.Lrj_1781_1:
	s_waitcnt lgkmcnt(0)
	s_barrier
	s_setprio 1
	s_waitcnt lgkmcnt(0)
	v_mfma_f32_16x16x32_bf16 v[92:95], v[128:131], v[180:183], 0
	v_mfma_f32_16x16x32_bf16 v[88:91], v[136:139], v[180:183], 0
	v_mfma_f32_16x16x32_bf16 v[84:87], v[128:131], v[188:191], 0
	v_mfma_f32_16x16x32_bf16 v[80:83], v[136:139], v[188:191], 0
	v_mfma_f32_16x16x32_bf16 v[76:79], v[128:131], v[196:199], 0
	v_mfma_f32_16x16x32_bf16 v[72:75], v[136:139], v[196:199], 0
	v_mfma_f32_16x16x32_bf16 v[68:71], v[128:131], v[204:207], 0
	v_mfma_f32_16x16x32_bf16 v[64:67], v[136:139], v[204:207], 0
	v_mfma_f32_16x16x32_bf16 v[92:95], v[132:135], v[184:187], v[92:95]
	v_mfma_f32_16x16x32_bf16 v[88:91], v[140:143], v[184:187], v[88:91]
	v_mfma_f32_16x16x32_bf16 v[84:87], v[132:135], v[192:195], v[84:87]
	v_mfma_f32_16x16x32_bf16 v[80:83], v[140:143], v[192:195], v[80:83]
	v_mfma_f32_16x16x32_bf16 v[76:79], v[132:135], v[200:203], v[76:79]
	v_mfma_f32_16x16x32_bf16 v[72:75], v[140:143], v[200:203], v[72:75]
	v_mfma_f32_16x16x32_bf16 v[68:71], v[132:135], v[208:211], v[68:71]
	v_mfma_f32_16x16x32_bf16 v[64:67], v[140:143], v[208:211], v[64:67]
	s_setprio 0
	s_setprio 1
	v_mfma_f32_16x16x32_bf16 v[28:31], v[158:161], v[180:183], 0
	v_mfma_f32_16x16x32_bf16 v[24:27], v[172:175], v[180:183], 0
	v_mfma_f32_16x16x32_bf16 v[20:23], v[158:161], v[188:191], 0
	v_mfma_f32_16x16x32_bf16 v[16:19], v[172:175], v[188:191], 0
	v_mfma_f32_16x16x32_bf16 v[12:15], v[158:161], v[196:199], 0
	v_mfma_f32_16x16x32_bf16 v[8:11], v[172:175], v[196:199], 0
	v_mfma_f32_16x16x32_bf16 v[4:7], v[158:161], v[204:207], 0
	v_mfma_f32_16x16x32_bf16 v[0:3], v[172:175], v[204:207], 0
	v_mfma_f32_16x16x32_bf16 v[28:31], v[162:165], v[184:187], v[28:31]
	v_mfma_f32_16x16x32_bf16 v[24:27], v[176:179], v[184:187], v[24:27]
	v_mfma_f32_16x16x32_bf16 v[20:23], v[162:165], v[192:195], v[20:23]
	v_mfma_f32_16x16x32_bf16 v[16:19], v[176:179], v[192:195], v[16:19]
	v_mfma_f32_16x16x32_bf16 v[12:15], v[162:165], v[200:203], v[12:15]
	v_mfma_f32_16x16x32_bf16 v[8:11], v[176:179], v[200:203], v[8:11]
	v_mfma_f32_16x16x32_bf16 v[4:7], v[162:165], v[208:211], v[4:7]
	v_mfma_f32_16x16x32_bf16 v[0:3], v[176:179], v[208:211], v[0:3]
	s_setprio 0
	s_barrier
	s_add_i32 s78, 0, 0x18000
	s_add_i32 s79, 0, 0x1c000
	v_add_u32_e32 v140, s78, v168
	v_add_u32_e32 v176, s79, v168
	ds_read_b128 v[128:131], v140
	ds_read_b128 v[132:135], v140 offset:1024
	ds_read_b128 v[136:139], v140 offset:2048
	ds_read_b128 v[140:143], v140 offset:3072
	ds_read_b128 v[158:161], v176
	ds_read_b128 v[162:165], v176 offset:1024
	ds_read_b128 v[172:175], v176 offset:2048
	ds_read_b128 v[176:179], v176 offset:3072
	s_add_u32 s4, s42, 0xb0000
	s_addc_u32 s5, s43, 0
	s_mov_b32 m0, s47
	v_lshl_add_u64 v[216:217], s[4:5], 0, v[146:147]
	ds_read_b128 v[180:183], v171 offset:32768
	ds_read_b128 v[184:187], v171 offset:33792
	ds_read_b128 v[188:191], v171 offset:34816
	ds_read_b128 v[192:195], v171 offset:35840
	ds_read_b128 v[196:199], v171 offset:36864
	ds_read_b128 v[200:203], v171 offset:37888
	ds_read_b128 v[204:207], v171 offset:38912
	ds_read_b128 v[208:211], v171 offset:39936
	global_load_lds_dwordx4 v[216:217], off
	v_lshl_add_u64 v[216:217], s[4:5], 0, v[150:151]
	s_mov_b32 m0, s48
	s_nop 0
	global_load_lds_dwordx4 v[216:217], off
	s_waitcnt vmcnt(8)
	s_waitcnt lgkmcnt(0)
	s_barrier
	s_setprio 1
	s_waitcnt lgkmcnt(0)
	v_mfma_f32_16x16x32_bf16 v[124:127], v[128:131], v[180:183], v[124:127]
	v_mfma_f32_16x16x32_bf16 v[120:123], v[136:139], v[180:183], v[120:123]
	v_mfma_f32_16x16x32_bf16 v[116:119], v[128:131], v[188:191], v[116:119]
	v_mfma_f32_16x16x32_bf16 v[112:115], v[136:139], v[188:191], v[112:115]
	v_mfma_f32_16x16x32_bf16 v[108:111], v[128:131], v[196:199], v[108:111]
	v_mfma_f32_16x16x32_bf16 v[104:107], v[136:139], v[196:199], v[104:107]
	v_mfma_f32_16x16x32_bf16 v[100:103], v[128:131], v[204:207], v[100:103]
	v_mfma_f32_16x16x32_bf16 v[96:99], v[136:139], v[204:207], v[96:99]
	v_mfma_f32_16x16x32_bf16 v[124:127], v[132:135], v[184:187], v[124:127]
	v_mfma_f32_16x16x32_bf16 v[120:123], v[140:143], v[184:187], v[120:123]
	v_mfma_f32_16x16x32_bf16 v[116:119], v[132:135], v[192:195], v[116:119]
	v_mfma_f32_16x16x32_bf16 v[112:115], v[140:143], v[192:195], v[112:115]
	v_mfma_f32_16x16x32_bf16 v[108:111], v[132:135], v[200:203], v[108:111]
	v_mfma_f32_16x16x32_bf16 v[104:107], v[140:143], v[200:203], v[104:107]
	v_mfma_f32_16x16x32_bf16 v[100:103], v[132:135], v[208:211], v[100:103]
	v_mfma_f32_16x16x32_bf16 v[96:99], v[140:143], v[208:211], v[96:99]
	s_setprio 0
	s_setprio 1
	v_mfma_f32_16x16x32_bf16 v[60:63], v[158:161], v[180:183], v[60:63]
	v_mfma_f32_16x16x32_bf16 v[56:59], v[172:175], v[180:183], v[56:59]
	v_mfma_f32_16x16x32_bf16 v[52:55], v[158:161], v[188:191], v[52:55]
	v_mfma_f32_16x16x32_bf16 v[48:51], v[172:175], v[188:191], v[48:51]
	v_mfma_f32_16x16x32_bf16 v[44:47], v[158:161], v[196:199], v[44:47]
	v_mfma_f32_16x16x32_bf16 v[40:43], v[172:175], v[196:199], v[40:43]
	v_mfma_f32_16x16x32_bf16 v[36:39], v[158:161], v[204:207], v[36:39]
	v_mfma_f32_16x16x32_bf16 v[32:35], v[172:175], v[204:207], v[32:35]
	v_mfma_f32_16x16x32_bf16 v[60:63], v[162:165], v[184:187], v[60:63]
	v_mfma_f32_16x16x32_bf16 v[56:59], v[176:179], v[184:187], v[56:59]
	v_mfma_f32_16x16x32_bf16 v[52:55], v[162:165], v[192:195], v[52:55]
	v_mfma_f32_16x16x32_bf16 v[48:51], v[176:179], v[192:195], v[48:51]
	v_mfma_f32_16x16x32_bf16 v[44:47], v[162:165], v[200:203], v[44:47]
	v_mfma_f32_16x16x32_bf16 v[40:43], v[176:179], v[200:203], v[40:43]
	v_mfma_f32_16x16x32_bf16 v[36:39], v[162:165], v[208:211], v[36:39]
	v_mfma_f32_16x16x32_bf16 v[32:35], v[176:179], v[208:211], v[32:35]
	s_setprio 0
	s_barrier
; #define G_STAGE(bufoff, gbase, voff) do { _Pragma("unroll") for (int _i = 0; _i < 2; ++_i) \
;         __builtin_amdgcn_global_load_lds((const unsigned*)((const char*)(gbase) + voff[_i]), (LAS unsigned*)(lds + (bufoff) + ldsw + _i * 8192), 16, 0, 0); } while (0)
; #define G_LDA(dst, b, h) do { _Pragma("unroll") for (int m = 0; m < 4; ++m) _Pragma("unroll") for (int k = 0; k < 2; ++k) dst[m][k] = *(const LAS bf16x8*)(lds + G_SA(b, h) + aoff + m * 2048 + k * 1024); } while (0)
; #define G_MMA(ai, bj, At_, Bt_) do { __builtin_amdgcn_s_setprio(1); _Pragma("unroll") for (int m = 0; m < 4; ++m) _Pragma("unroll") for (int n = 0; n < 2; ++n) _Pragma("unroll") for (int k = 0; k < 2; ++k) \
;         acc[ai][bj][m][n] = __builtin_amdgcn_mfma_f32_16x16x32_bf16(Bt_[n][k], At_[m][k], acc[ai][bj][m][n], 0, 0, 0); __builtin_amdgcn_s_setprio(0); } while (0)
; #define WAIT_V(n) asm volatile("s_waitcnt vmcnt(" #n ")" ::: "memory")
; #define WAIT_L(n) asm volatile("s_waitcnt lgkmcnt(" #n ")" ::: "memory")
; #define BAR __builtin_amdgcn_s_barrier()
; #define SCHED __builtin_amdgcn_sched_barrier(0)
; template <class Get, class Epi>
; DI void gemm_loop(int ntiles, int ld, char* shm, const Get& get, const Epi& epi) {
;     ...
;             G_LDA(At, 1, 1); G_STAGE(G_SB(1, 0), b3, voffB); G_STAGE(G_SB(1, 1), b3 + hstep, voffB); G_STAGE(G_SA(1, 0), a3, voffA);
;             WAIT_V(8); WAIT_L(0); BAR; G_MMA(1, 0, At, B0); G_MMA(1, 1, At, B1); BAR; SCHED;
;         }
	s_add_i32 s4, s78, s44
	v_lshl_add_u64 v[144:145], v[144:145], 0, s[10:11]
	s_mov_b32 m0, s4
	ds_read_b128 v[180:183], v171 offset:49152
	ds_read_b128 v[184:187], v171 offset:50176
	ds_read_b128 v[188:191], v171 offset:51200
	ds_read_b128 v[192:195], v171 offset:52224
	ds_read_b128 v[196:199], v171 offset:53248
	ds_read_b128 v[200:203], v171 offset:54272
	ds_read_b128 v[204:207], v171 offset:55296
	ds_read_b128 v[208:211], v171 offset:56320
	global_load_lds_dwordx4 v[144:145], off
	s_add_i32 m0, s4, 0x2000
	s_add_u32 s4, s40, 0xb0080
	v_lshl_add_u64 v[144:145], v[166:167], 0, s[10:11]
	s_addc_u32 s5, s41, 0
	s_add_i32 s40, s79, s44
	global_load_lds_dwordx4 v[144:145], off
	v_lshl_add_u64 v[144:145], s[4:5], 0, v[148:149]
	s_mov_b32 m0, s40
	s_nop 0
	global_load_lds_dwordx4 v[144:145], off
	v_lshl_add_u64 v[144:145], s[4:5], 0, v[152:153]
	s_add_i32 m0, s40, 0x2000
	s_nop 0
	global_load_lds_dwordx4 v[144:145], off
	v_lshl_add_u64 v[144:145], v[212:213], 0, s[10:11]
	s_mov_b32 m0, s51
	s_nop 0
	global_load_lds_dwordx4 v[144:145], off
	v_lshl_add_u64 v[144:145], v[214:215], 0, s[10:11]
	s_mov_b32 m0, s52
	s_nop 0
	global_load_lds_dwordx4 v[144:145], off
	s_waitcnt vmcnt(8)
	s_waitcnt lgkmcnt(0)
	s_barrier
	s_setprio 1
	s_waitcnt lgkmcnt(0)
	v_mfma_f32_16x16x32_bf16 v[92:95], v[128:131], v[180:183], v[92:95]
	v_mfma_f32_16x16x32_bf16 v[88:91], v[136:139], v[180:183], v[88:91]
	v_mfma_f32_16x16x32_bf16 v[84:87], v[128:131], v[188:191], v[84:87]
	v_mfma_f32_16x16x32_bf16 v[80:83], v[136:139], v[188:191], v[80:83]
	v_mfma_f32_16x16x32_bf16 v[76:79], v[128:131], v[196:199], v[76:79]
	v_mfma_f32_16x16x32_bf16 v[72:75], v[136:139], v[196:199], v[72:75]
	v_mfma_f32_16x16x32_bf16 v[68:71], v[128:131], v[204:207], v[68:71]
	v_mfma_f32_16x16x32_bf16 v[64:67], v[136:139], v[204:207], v[64:67]
	v_mfma_f32_16x16x32_bf16 v[92:95], v[132:135], v[184:187], v[92:95]
	v_mfma_f32_16x16x32_bf16 v[88:91], v[140:143], v[184:187], v[88:91]
	v_mfma_f32_16x16x32_bf16 v[84:87], v[132:135], v[192:195], v[84:87]
	v_mfma_f32_16x16x32_bf16 v[80:83], v[140:143], v[192:195], v[80:83]
	v_mfma_f32_16x16x32_bf16 v[76:79], v[132:135], v[200:203], v[76:79]
	v_mfma_f32_16x16x32_bf16 v[72:75], v[140:143], v[200:203], v[72:75]
	v_mfma_f32_16x16x32_bf16 v[68:71], v[132:135], v[208:211], v[68:71]
	v_mfma_f32_16x16x32_bf16 v[64:67], v[140:143], v[208:211], v[64:67]
	s_setprio 0
	s_setprio 1
	v_mfma_f32_16x16x32_bf16 v[28:31], v[158:161], v[180:183], v[28:31]
	v_mfma_f32_16x16x32_bf16 v[24:27], v[172:175], v[180:183], v[24:27]
	v_mfma_f32_16x16x32_bf16 v[20:23], v[158:161], v[188:191], v[20:23]
	v_mfma_f32_16x16x32_bf16 v[16:19], v[172:175], v[188:191], v[16:19]
	v_mfma_f32_16x16x32_bf16 v[12:15], v[158:161], v[196:199], v[12:15]
	v_mfma_f32_16x16x32_bf16 v[8:11], v[172:175], v[196:199], v[8:11]
	v_mfma_f32_16x16x32_bf16 v[4:7], v[158:161], v[204:207], v[4:7]
	v_mfma_f32_16x16x32_bf16 v[0:3], v[172:175], v[204:207], v[0:3]
	v_mfma_f32_16x16x32_bf16 v[28:31], v[162:165], v[184:187], v[28:31]
	v_mfma_f32_16x16x32_bf16 v[24:27], v[176:179], v[184:187], v[24:27]
	v_mfma_f32_16x16x32_bf16 v[20:23], v[162:165], v[192:195], v[20:23]
	v_mfma_f32_16x16x32_bf16 v[16:19], v[176:179], v[192:195], v[16:19]
	v_mfma_f32_16x16x32_bf16 v[12:15], v[162:165], v[200:203], v[12:15]
	v_mfma_f32_16x16x32_bf16 v[8:11], v[176:179], v[200:203], v[8:11]
	v_mfma_f32_16x16x32_bf16 v[4:7], v[162:165], v[208:211], v[4:7]
	v_mfma_f32_16x16x32_bf16 v[0:3], v[176:179], v[208:211], v[0:3]
	s_setprio 0
	s_barrier
	s_add_u32 s75, s75, 0x100
	s_addc_u32 s76, s76, 0
	s_cmp_ge_u32 s77, s73
	s_mov_b64 s[4:5], s[14:15]
	s_mov_b32 s40, s77
	s_cbranch_scc0 .LBB0_1781
	s_branch .Lpost_1781

; #define G_STAGE(bufoff, gbase, voff) do { _Pragma("unroll") for (int _i = 0; _i < 2; ++_i) \
;         __builtin_amdgcn_global_load_lds((const unsigned*)((const char*)(gbase) + voff[_i]), (LAS unsigned*)(lds + (bufoff) + ldsw + _i * 8192), 16, 0, 0); } while (0)
; #define WAIT_V(n) asm volatile("s_waitcnt vmcnt(" #n ")" ::: "memory")
; #define BAR __builtin_amdgcn_s_barrier()
; template <class Get, class Epi>
; DI void gemm_loop(int ntiles, int ld, char* shm, const Get& get, const Epi& epi) {
;     ...
;     const int aoff = lds_byte(wr * 64 + fr, fq * 8), boff = lds_byte(wc * 32 + fr, fq * 8);
;     ...
;     const char* cA = (const char*)cur.A + (size_t)cur.brow * ld * 2; const char* cB = (const char*)cur.Bt + (size_t)cur.bcol * ld * 2;
;     G_STAGE(G_SB(0, 0), cB, voffB); G_STAGE(G_SB(0, 1), cB + hstep, voffB); G_STAGE(G_SA(0, 0), cA, voffA); G_STAGE(G_SA(0, 1), cA + hstep, voffA);
;     if (wr == 1) BAR;
;     WAIT_V(2); BAR;
;     G_STAGE(G_SB(1, 0), cB + kstep, voffB); G_STAGE(G_SA(1, 0), cA + kstep, voffA); G_STAGE(G_SB(1, 1), cB + hstep + kstep, voffB);
;     WAIT_V(6); BAR;
.LBB0_2016:
	s_lshl_b32 s10, s10, 12
	s_lshl_b32 s3, s11, 13
	s_and_b32 s15, s10, 0x3000
	s_mov_b64 s[10:11], 0x80
	s_add_i32 m0, s50, 0x18000
	v_lshl_add_u64 v[6:7], v[6:7], 0, s[10:11]
	s_waitcnt vmcnt(2)
	s_barrier
	global_load_lds_dwordx4 v[6:7], off
	v_lshl_add_u64 v[4:5], v[4:5], 0, s[10:11]
	s_add_i32 m0, s50, 0x1a000
	s_add_i32 s73, s50, 0x8000
	s_add_i32 s74, s50, 0xa000
	global_load_lds_dwordx4 v[4:5], off
	v_lshl_add_u64 v[0:1], v[0:1], 0, s[10:11]
	s_mov_b32 m0, s73
	s_add_u32 s36, s6, 0x40080
	global_load_lds_dwordx4 v[0:1], off
	v_lshl_add_u64 v[0:1], v[2:3], 0, s[10:11]
	s_mov_b32 m0, s74
	s_addc_u32 s37, s7, 0
	global_load_lds_dwordx4 v[0:1], off
	s_add_i32 m0, s50, 0x1c000
	v_lshl_add_u64 v[0:1], s[36:37], 0, v[140:141]
	global_load_lds_dwordx4 v[0:1], off
	v_lshl_add_u64 v[0:1], s[36:37], 0, v[136:137]
	s_add_i32 m0, s50, 0x1e000
	v_lshlrev_b32_e32 v3, 2, v9
	global_load_lds_dwordx4 v[0:1], off
	v_and_b32_e32 v0, 15, v9
	v_and_b32_e32 v1, 48, v9
	v_lshlrev_b32_e32 v0, 6, v0
	v_and_b32_e32 v3, 32, v3
	v_or_b32_e32 v2, v0, v1
	v_bitop3_b32 v0, v0, v3, v1 bitop3:0x36
	v_or_b32_e32 v172, s15, v0
	v_lshlrev_b32_e32 v0, 14, v13
	v_and_b32_e32 v0, 0xffff8000, v0
	v_bitop3_b32 v1, v2, s3, v3 bitop3:0xde
	v_lshl_add_u32 v0, v12, 11, v0
	v_and_b32_e32 v2, 1, v13
	v_lshl_or_b32 v0, v2, 6, v0
	v_lshl_add_u32 v146, v14, 1, v0
	v_lshlrev_b32_e32 v0, 14, v8
	v_and_b32_e32 v0, 0xffff8000, v0
	s_waitcnt vmcnt(6)
	s_mov_b32 s100, 0
	s_cmpk_lt_u32 s14, 0x100
	v_lshl_add_u32 v0, v10, 11, v0
	v_and_b32_e32 v2, 1, v8
	s_cselect_b64 s[36:37], -1, 0
	v_lshl_or_b32 v0, v2, 6, v0
	s_add_i32 s75, 0, 0x10000
	s_add_i32 s76, 0, 0x14000
	v_mov_b32_e32 v147, v145
	v_lshl_add_u32 v148, v11, 1, v0
	v_mov_b32_e32 v149, v145
	v_add_u32_e32 v173, s75, v172
	v_add_u32_e32 v174, s76, v172
	v_add_u32_e32 v175, 0, v1
	s_mov_b32 s77, 0x8e38e38f
	s_mov_b32 s78, 0xe38e38e3
	s_movk_i32 s79, 0xf700
	s_movk_i32 s80, 0xff
	s_movk_i32 s81, 0x48
	v_mbcnt_hi_u32_b32 v176, -1, v253
	v_mov_b32_e32 v177, 0xff
	v_mov_b32_e32 v178, 0x9ff
	s_barrier
	s_branch .LBB0_2019

; #define G_STAGE(bufoff, gbase, voff) do { _Pragma("unroll") for (int _i = 0; _i < 2; ++_i) \
;         __builtin_amdgcn_global_load_lds((const unsigned*)((const char*)(gbase) + voff[_i]), (LAS unsigned*)(lds + (bufoff) + ldsw + _i * 8192), 16, 0, 0); } while (0)
; #define G_LDA(dst, b, h) do { _Pragma("unroll") for (int m = 0; m < 4; ++m) _Pragma("unroll") for (int k = 0; k < 2; ++k) dst[m][k] = *(const LAS bf16x8*)(lds + G_SA(b, h) + aoff + m * 2048 + k * 1024); } while (0)
; #define G_LDB(dst, b, h) do { _Pragma("unroll") for (int n = 0; n < 2; ++n) _Pragma("unroll") for (int k = 0; k < 2; ++k) dst[n][k] = *(const LAS bf16x8*)(lds + G_SB(b, h) + boff + n * 2048 + k * 1024); } while (0)
; #define G_MMA(ai, bj, At_, Bt_) do { __builtin_amdgcn_s_setprio(1); _Pragma("unroll") for (int m = 0; m < 4; ++m) _Pragma("unroll") for (int n = 0; n < 2; ++n) _Pragma("unroll") for (int k = 0; k < 2; ++k) \
;         acc[ai][bj][m][n] = __builtin_amdgcn_mfma_f32_16x16x32_bf16(Bt_[n][k], At_[m][k], acc[ai][bj][m][n], 0, 0, 0); __builtin_amdgcn_s_setprio(0); } while (0)
; #define WAIT_V(n) asm volatile("s_waitcnt vmcnt(" #n ")" ::: "memory")
; #define WAIT_L(n) asm volatile("s_waitcnt lgkmcnt(" #n ")" ::: "memory")
; #define BAR __builtin_amdgcn_s_barrier()
; #define SCHED __builtin_amdgcn_sched_barrier(0)
; template <class Get, class Epi>
; DI void gemm_loop(int ntiles, int ld, char* shm, const Get& get, const Epi& epi) {
;     ...
;             G_LDB(B0, 0, 0); G_LDB(B1, 0, 1); SCHED; G_LDA(At, 0, 0); G_STAGE(G_SA(1, 1), a1 + hstep, voffA);
;             WAIT_V(8); WAIT_L(0); BAR; G_MMA(0, 0, At, B0); G_MMA(0, 1, At, B1); BAR; SCHED;
.Lpeel_2022:
	ds_read_b128 v[96:99], v173
	ds_read_b128 v[108:111], v173 offset:1024
	ds_read_b128 v[150:153], v173 offset:2048
	ds_read_b128 v[154:157], v173 offset:3072
	ds_read_b128 v[158:161], v174
	ds_read_b128 v[162:165], v174 offset:1024
	ds_read_b128 v[166:169], v174 offset:2048
	ds_read_b128 v[180:183], v174 offset:3072
	s_add_u32 s6, s4, 0xfffc0080
	s_addc_u32 s7, s5, -1
	s_cmp_eq_u32 s56, 12
	s_cselect_b32 s15, s3, s7
	s_cselect_b32 s14, s41, s6
	s_cselect_b32 s7, s43, s55
	s_cselect_b32 s6, s53, s54
	v_lshl_add_u64 v[170:171], s[4:5], 0, v[146:147]
	s_add_i32 m0, s50, 0xc000
	ds_read_b128 v[184:187], v175
	ds_read_b128 v[188:191], v175 offset:1024
	ds_read_b128 v[192:195], v175 offset:2048
	ds_read_b128 v[196:199], v175 offset:3072
	ds_read_b128 v[200:203], v175 offset:4096
	ds_read_b128 v[204:207], v175 offset:5120
	ds_read_b128 v[208:211], v175 offset:6144
	ds_read_b128 v[212:215], v175 offset:7168
	global_load_lds_dwordx4 v[170:171], off
	v_lshl_add_u64 v[170:171], s[4:5], 0, v[148:149]
	s_add_i32 m0, s50, 0xe000
	s_nop 0
	global_load_lds_dwordx4 v[170:171], off
	s_cmp_lg_u32 s100, 0
	s_cbranch_scc0 .Lrf_2022_0
	s_waitcnt vmcnt(16)
	s_branch .Lrj_2022_0

; #define G_STAGE(bufoff, gbase, voff) do { _Pragma("unroll") for (int _i = 0; _i < 2; ++_i) \
;         __builtin_amdgcn_global_load_lds((const unsigned*)((const char*)(gbase) + voff[_i]), (LAS unsigned*)(lds + (bufoff) + ldsw + _i * 8192), 16, 0, 0); } while (0)
; #define G_LDA(dst, b, h) do { _Pragma("unroll") for (int m = 0; m < 4; ++m) _Pragma("unroll") for (int k = 0; k < 2; ++k) dst[m][k] = *(const LAS bf16x8*)(lds + G_SA(b, h) + aoff + m * 2048 + k * 1024); } while (0)
; #define G_MMA(ai, bj, At_, Bt_) do { __builtin_amdgcn_s_setprio(1); _Pragma("unroll") for (int m = 0; m < 4; ++m) _Pragma("unroll") for (int n = 0; n < 2; ++n) _Pragma("unroll") for (int k = 0; k < 2; ++k) \
;         acc[ai][bj][m][n] = __builtin_amdgcn_mfma_f32_16x16x32_bf16(Bt_[n][k], At_[m][k], acc[ai][bj][m][n], 0, 0, 0); __builtin_amdgcn_s_setprio(0); } while (0)
; #define WAIT_V(n) asm volatile("s_waitcnt vmcnt(" #n ")" ::: "memory")
; #define WAIT_L(n) asm volatile("s_waitcnt lgkmcnt(" #n ")" ::: "memory")
; #define BAR __builtin_amdgcn_s_barrier()
; #define SCHED __builtin_amdgcn_sched_barrier(0)
; template <class Get, class Epi>
; DI void gemm_loop(int ntiles, int ld, char* shm, const Get& get, const Epi& epi) {
;     ...
;             WAIT_V(8); WAIT_L(0); BAR; G_MMA(0, 0, At, B0); G_MMA(0, 1, At, B1); BAR; SCHED;
;             G_LDA(At, 0, 1); G_STAGE(G_SB(0, 0), b2, voffB); G_STAGE(G_SB(0, 1), b2 + hstep, voffB); G_STAGE(G_SA(0, 0), a2, voffA);
;             WAIT_V(8); WAIT_L(0); BAR; G_MMA(1, 0, At, B0); G_MMA(1, 1, At, B1); BAR; SCHED;
.Lrj_2022_0:
	s_waitcnt lgkmcnt(0)
	s_barrier
	s_setprio 1
	s_waitcnt lgkmcnt(0)
	v_mfma_f32_16x16x32_bf16 v[132:135], v[96:99], v[184:187], 0
	v_mfma_f32_16x16x32_bf16 v[124:127], v[150:153], v[184:187], 0
	v_mfma_f32_16x16x32_bf16 v[128:131], v[96:99], v[192:195], 0
	v_mfma_f32_16x16x32_bf16 v[120:123], v[150:153], v[192:195], 0
	v_mfma_f32_16x16x32_bf16 v[116:119], v[96:99], v[200:203], 0
	v_mfma_f32_16x16x32_bf16 v[104:107], v[150:153], v[200:203], 0
	v_mfma_f32_16x16x32_bf16 v[112:115], v[96:99], v[208:211], 0
	v_mfma_f32_16x16x32_bf16 v[100:103], v[150:153], v[208:211], 0
	v_mfma_f32_16x16x32_bf16 v[132:135], v[108:111], v[188:191], v[132:135]
	v_mfma_f32_16x16x32_bf16 v[124:127], v[154:157], v[188:191], v[124:127]
	v_mfma_f32_16x16x32_bf16 v[128:131], v[108:111], v[196:199], v[128:131]
	v_mfma_f32_16x16x32_bf16 v[120:123], v[154:157], v[196:199], v[120:123]
	v_mfma_f32_16x16x32_bf16 v[116:119], v[108:111], v[204:207], v[116:119]
	v_mfma_f32_16x16x32_bf16 v[104:107], v[154:157], v[204:207], v[104:107]
	v_mfma_f32_16x16x32_bf16 v[112:115], v[108:111], v[212:215], v[112:115]
	v_mfma_f32_16x16x32_bf16 v[100:103], v[154:157], v[212:215], v[100:103]
	s_setprio 0
	s_setprio 1
	v_mfma_f32_16x16x32_bf16 v[60:63], v[158:161], v[184:187], 0
	v_mfma_f32_16x16x32_bf16 v[52:55], v[166:169], v[184:187], 0
	v_mfma_f32_16x16x32_bf16 v[56:59], v[158:161], v[192:195], 0
	v_mfma_f32_16x16x32_bf16 v[48:51], v[166:169], v[192:195], 0
	v_mfma_f32_16x16x32_bf16 v[44:47], v[158:161], v[200:203], 0
	v_mfma_f32_16x16x32_bf16 v[36:39], v[166:169], v[200:203], 0
	v_mfma_f32_16x16x32_bf16 v[40:43], v[158:161], v[208:211], 0
	v_mfma_f32_16x16x32_bf16 v[32:35], v[166:169], v[208:211], 0
	v_mfma_f32_16x16x32_bf16 v[60:63], v[162:165], v[188:191], v[60:63]
	v_mfma_f32_16x16x32_bf16 v[52:55], v[180:183], v[188:191], v[52:55]
	v_mfma_f32_16x16x32_bf16 v[56:59], v[162:165], v[196:199], v[56:59]
	v_mfma_f32_16x16x32_bf16 v[48:51], v[180:183], v[196:199], v[48:51]
	v_mfma_f32_16x16x32_bf16 v[44:47], v[162:165], v[204:207], v[44:47]
	v_mfma_f32_16x16x32_bf16 v[36:39], v[180:183], v[204:207], v[36:39]
	v_mfma_f32_16x16x32_bf16 v[40:43], v[162:165], v[212:215], v[40:43]
	v_mfma_f32_16x16x32_bf16 v[32:35], v[180:183], v[212:215], v[32:35]
	s_setprio 0
	s_barrier
	s_add_i32 s57, s75, s46
	v_lshl_add_u64 v[170:171], s[6:7], 0, v[140:141]
	s_mov_b32 m0, s57
	ds_read_b128 v[184:187], v175 offset:16384
	ds_read_b128 v[188:191], v175 offset:17408
	ds_read_b128 v[192:195], v175 offset:18432
	ds_read_b128 v[196:199], v175 offset:19456
	ds_read_b128 v[200:203], v175 offset:20480
	ds_read_b128 v[204:207], v175 offset:21504
	ds_read_b128 v[208:211], v175 offset:22528
	ds_read_b128 v[212:215], v175 offset:23552
	global_load_lds_dwordx4 v[170:171], off
	s_add_i32 m0, s57, 0x2000
	s_add_u32 s58, s6, 0x40000
	v_lshl_add_u64 v[216:217], s[6:7], 0, v[136:137]
	s_addc_u32 s59, s7, 0
	s_add_i32 s57, s76, s46
	global_load_lds_dwordx4 v[216:217], off
	v_lshl_add_u64 v[218:219], s[58:59], 0, v[140:141]
	s_mov_b32 m0, s57
	v_lshl_add_u64 v[220:221], s[14:15], 0, v[138:139]
	global_load_lds_dwordx4 v[218:219], off
	v_lshl_add_u64 v[218:219], s[58:59], 0, v[136:137]
	s_add_i32 m0, s57, 0x2000
	s_nop 0
	global_load_lds_dwordx4 v[218:219], off
	v_lshl_add_u64 v[218:219], s[14:15], 0, v[142:143]
	s_mov_b32 m0, s50
	s_nop 0
	global_load_lds_dwordx4 v[218:219], off
	s_mov_b32 m0, s51
	s_nop 0
	global_load_lds_dwordx4 v[220:221], off
	s_cmp_lg_u32 s100, 0
	s_cbranch_scc0 .Lrf_2022_1
	s_waitcnt vmcnt(16)
	s_branch .Lrj_2022_1

; #define G_STAGE(bufoff, gbase, voff) do { _Pragma("unroll") for (int _i = 0; _i < 2; ++_i) \
;         __builtin_amdgcn_global_load_lds((const unsigned*)((const char*)(gbase) + voff[_i]), (LAS unsigned*)(lds + (bufoff) + ldsw + _i * 8192), 16, 0, 0); } while (0)
; #define G_LDA(dst, b, h) do { _Pragma("unroll") for (int m = 0; m < 4; ++m) _Pragma("unroll") for (int k = 0; k < 2; ++k) dst[m][k] = *(const LAS bf16x8*)(lds + G_SA(b, h) + aoff + m * 2048 + k * 1024); } while (0)
; #define G_LDB(dst, b, h) do { _Pragma("unroll") for (int n = 0; n < 2; ++n) _Pragma("unroll") for (int k = 0; k < 2; ++k) dst[n][k] = *(const LAS bf16x8*)(lds + G_SB(b, h) + boff + n * 2048 + k * 1024); } while (0)
; #define G_MMA(ai, bj, At_, Bt_) do { __builtin_amdgcn_s_setprio(1); _Pragma("unroll") for (int m = 0; m < 4; ++m) _Pragma("unroll") for (int n = 0; n < 2; ++n) _Pragma("unroll") for (int k = 0; k < 2; ++k) \
;         acc[ai][bj][m][n] = __builtin_amdgcn_mfma_f32_16x16x32_bf16(Bt_[n][k], At_[m][k], acc[ai][bj][m][n], 0, 0, 0); __builtin_amdgcn_s_setprio(0); } while (0)
; #define WAIT_V(n) asm volatile("s_waitcnt vmcnt(" #n ")" ::: "memory")
; #define WAIT_L(n) asm volatile("s_waitcnt lgkmcnt(" #n ")" ::: "memory")
; #define BAR __builtin_amdgcn_s_barrier()
; #define SCHED __builtin_amdgcn_sched_barrier(0)
; template <class Get, class Epi>
; DI void gemm_loop(int ntiles, int ld, char* shm, const Get& get, const Epi& epi) {
;     ...
;             WAIT_V(8); WAIT_L(0); BAR; G_MMA(1, 0, At, B0); G_MMA(1, 1, At, B1); BAR; SCHED;
;             G_LDB(B0, 1, 0); G_LDB(B1, 1, 1); SCHED; G_LDA(At, 1, 0); G_STAGE(G_SA(0, 1), a2 + hstep, voffA);
;             WAIT_V(8); WAIT_L(0); BAR; G_MMA(0, 0, At, B0); G_MMA(0, 1, At, B1); BAR; SCHED;
.Lrj_2022_1:
	s_waitcnt lgkmcnt(0)
	s_barrier
	s_setprio 1
	s_waitcnt lgkmcnt(0)
	v_mfma_f32_16x16x32_bf16 v[92:95], v[96:99], v[184:187], 0
	v_mfma_f32_16x16x32_bf16 v[84:87], v[150:153], v[184:187], 0
	v_mfma_f32_16x16x32_bf16 v[88:91], v[96:99], v[192:195], 0
	v_mfma_f32_16x16x32_bf16 v[80:83], v[150:153], v[192:195], 0
	v_mfma_f32_16x16x32_bf16 v[76:79], v[96:99], v[200:203], 0
	v_mfma_f32_16x16x32_bf16 v[68:71], v[150:153], v[200:203], 0
	v_mfma_f32_16x16x32_bf16 v[72:75], v[96:99], v[208:211], 0
	v_mfma_f32_16x16x32_bf16 v[64:67], v[150:153], v[208:211], 0
	v_mfma_f32_16x16x32_bf16 v[92:95], v[108:111], v[188:191], v[92:95]
	v_mfma_f32_16x16x32_bf16 v[84:87], v[154:157], v[188:191], v[84:87]
	v_mfma_f32_16x16x32_bf16 v[88:91], v[108:111], v[196:199], v[88:91]
	v_mfma_f32_16x16x32_bf16 v[80:83], v[154:157], v[196:199], v[80:83]
	v_mfma_f32_16x16x32_bf16 v[76:79], v[108:111], v[204:207], v[76:79]
	v_mfma_f32_16x16x32_bf16 v[68:71], v[154:157], v[204:207], v[68:71]
	v_mfma_f32_16x16x32_bf16 v[72:75], v[108:111], v[212:215], v[72:75]
	v_mfma_f32_16x16x32_bf16 v[64:67], v[154:157], v[212:215], v[64:67]
	s_setprio 0
	s_setprio 1
	v_mfma_f32_16x16x32_bf16 v[28:31], v[158:161], v[184:187], 0
	v_mfma_f32_16x16x32_bf16 v[20:23], v[166:169], v[184:187], 0
	v_mfma_f32_16x16x32_bf16 v[24:27], v[158:161], v[192:195], 0
	v_mfma_f32_16x16x32_bf16 v[16:19], v[166:169], v[192:195], 0
	v_mfma_f32_16x16x32_bf16 v[12:15], v[158:161], v[200:203], 0
	v_mfma_f32_16x16x32_bf16 v[4:7], v[166:169], v[200:203], 0
	v_mfma_f32_16x16x32_bf16 v[8:11], v[158:161], v[208:211], 0
	v_mfma_f32_16x16x32_bf16 v[0:3], v[166:169], v[208:211], 0
	v_mfma_f32_16x16x32_bf16 v[28:31], v[162:165], v[188:191], v[28:31]
	v_mfma_f32_16x16x32_bf16 v[20:23], v[180:183], v[188:191], v[20:23]
	v_mfma_f32_16x16x32_bf16 v[24:27], v[162:165], v[196:199], v[24:27]
	v_mfma_f32_16x16x32_bf16 v[16:19], v[180:183], v[196:199], v[16:19]
	v_mfma_f32_16x16x32_bf16 v[12:15], v[162:165], v[204:207], v[12:15]
	v_mfma_f32_16x16x32_bf16 v[4:7], v[180:183], v[204:207], v[4:7]
	v_mfma_f32_16x16x32_bf16 v[8:11], v[162:165], v[212:215], v[8:11]
	v_mfma_f32_16x16x32_bf16 v[0:3], v[180:183], v[212:215], v[0:3]
	s_setprio 0
	s_barrier
	s_add_i32 s57, 0, 0x18000
	v_add_u32_e32 v144, s57, v172
	s_add_i32 s58, 0, 0x1c000
	ds_read_b128 v[96:99], v144
	ds_read_b128 v[108:111], v144 offset:1024
	ds_read_b128 v[150:153], v144 offset:2048
	ds_read_b128 v[154:157], v144 offset:3072
	v_add_u32_e32 v144, s58, v172
	ds_read_b128 v[158:161], v144
	ds_read_b128 v[162:165], v144 offset:1024
	ds_read_b128 v[166:169], v144 offset:2048
	ds_read_b128 v[180:183], v144 offset:3072
	s_add_u32 s14, s14, 0x40000
	s_addc_u32 s15, s15, 0
	s_mov_b32 m0, s71
	v_lshl_add_u64 v[222:223], s[14:15], 0, v[142:143]
	ds_read_b128 v[184:187], v175 offset:32768
	ds_read_b128 v[188:191], v175 offset:33792
	ds_read_b128 v[192:195], v175 offset:34816
	ds_read_b128 v[196:199], v175 offset:35840
	ds_read_b128 v[200:203], v175 offset:36864
	ds_read_b128 v[204:207], v175 offset:37888
	ds_read_b128 v[208:211], v175 offset:38912
	ds_read_b128 v[212:215], v175 offset:39936
	global_load_lds_dwordx4 v[222:223], off
	v_lshl_add_u64 v[222:223], s[14:15], 0, v[138:139]
	s_mov_b32 m0, s72
	s_nop 0
	global_load_lds_dwordx4 v[222:223], off
	s_waitcnt vmcnt(8)
	s_waitcnt lgkmcnt(0)
	s_barrier
	s_setprio 1
	s_waitcnt lgkmcnt(0)
	v_mfma_f32_16x16x32_bf16 v[132:135], v[96:99], v[184:187], v[132:135]
	v_mfma_f32_16x16x32_bf16 v[124:127], v[150:153], v[184:187], v[124:127]
	v_mfma_f32_16x16x32_bf16 v[128:131], v[96:99], v[192:195], v[128:131]
	v_mfma_f32_16x16x32_bf16 v[120:123], v[150:153], v[192:195], v[120:123]
	v_mfma_f32_16x16x32_bf16 v[116:119], v[96:99], v[200:203], v[116:119]
	v_mfma_f32_16x16x32_bf16 v[104:107], v[150:153], v[200:203], v[104:107]
	v_mfma_f32_16x16x32_bf16 v[112:115], v[96:99], v[208:211], v[112:115]
	v_mfma_f32_16x16x32_bf16 v[100:103], v[150:153], v[208:211], v[100:103]
	v_mfma_f32_16x16x32_bf16 v[132:135], v[108:111], v[188:191], v[132:135]
	v_mfma_f32_16x16x32_bf16 v[124:127], v[154:157], v[188:191], v[124:127]
	v_mfma_f32_16x16x32_bf16 v[128:131], v[108:111], v[196:199], v[128:131]
	v_mfma_f32_16x16x32_bf16 v[120:123], v[154:157], v[196:199], v[120:123]
	v_mfma_f32_16x16x32_bf16 v[116:119], v[108:111], v[204:207], v[116:119]
	v_mfma_f32_16x16x32_bf16 v[104:107], v[154:157], v[204:207], v[104:107]
	v_mfma_f32_16x16x32_bf16 v[112:115], v[108:111], v[212:215], v[112:115]
	v_mfma_f32_16x16x32_bf16 v[100:103], v[154:157], v[212:215], v[100:103]
	s_setprio 0
	s_setprio 1
	v_mfma_f32_16x16x32_bf16 v[60:63], v[158:161], v[184:187], v[60:63]
	v_mfma_f32_16x16x32_bf16 v[52:55], v[166:169], v[184:187], v[52:55]
	v_mfma_f32_16x16x32_bf16 v[56:59], v[158:161], v[192:195], v[56:59]
	v_mfma_f32_16x16x32_bf16 v[48:51], v[166:169], v[192:195], v[48:51]
	v_mfma_f32_16x16x32_bf16 v[44:47], v[158:161], v[200:203], v[44:47]
	v_mfma_f32_16x16x32_bf16 v[36:39], v[166:169], v[200:203], v[36:39]
	v_mfma_f32_16x16x32_bf16 v[40:43], v[158:161], v[208:211], v[40:43]
	v_mfma_f32_16x16x32_bf16 v[32:35], v[166:169], v[208:211], v[32:35]
	v_mfma_f32_16x16x32_bf16 v[60:63], v[162:165], v[188:191], v[60:63]
	v_mfma_f32_16x16x32_bf16 v[52:55], v[180:183], v[188:191], v[52:55]
	v_mfma_f32_16x16x32_bf16 v[56:59], v[162:165], v[196:199], v[56:59]
	v_mfma_f32_16x16x32_bf16 v[48:51], v[180:183], v[196:199], v[48:51]
	v_mfma_f32_16x16x32_bf16 v[44:47], v[162:165], v[204:207], v[44:47]
	v_mfma_f32_16x16x32_bf16 v[36:39], v[180:183], v[204:207], v[36:39]
	v_mfma_f32_16x16x32_bf16 v[40:43], v[162:165], v[212:215], v[40:43]
	v_mfma_f32_16x16x32_bf16 v[32:35], v[180:183], v[212:215], v[32:35]
	s_setprio 0
	s_barrier
; #define G_STAGE(bufoff, gbase, voff) do { _Pragma("unroll") for (int _i = 0; _i < 2; ++_i) \
;         __builtin_amdgcn_global_load_lds((const unsigned*)((const char*)(gbase) + voff[_i]), (LAS unsigned*)(lds + (bufoff) + ldsw + _i * 8192), 16, 0, 0); } while (0)
; #define G_LDA(dst, b, h) do { _Pragma("unroll") for (int m = 0; m < 4; ++m) _Pragma("unroll") for (int k = 0; k < 2; ++k) dst[m][k] = *(const LAS bf16x8*)(lds + G_SA(b, h) + aoff + m * 2048 + k * 1024); } while (0)
; #define G_MMA(ai, bj, At_, Bt_) do { __builtin_amdgcn_s_setprio(1); _Pragma("unroll") for (int m = 0; m < 4; ++m) _Pragma("unroll") for (int n = 0; n < 2; ++n) _Pragma("unroll") for (int k = 0; k < 2; ++k) \
;         acc[ai][bj][m][n] = __builtin_amdgcn_mfma_f32_16x16x32_bf16(Bt_[n][k], At_[m][k], acc[ai][bj][m][n], 0, 0, 0); __builtin_amdgcn_s_setprio(0); } while (0)
; #define WAIT_V(n) asm volatile("s_waitcnt vmcnt(" #n ")" ::: "memory")
; #define WAIT_L(n) asm volatile("s_waitcnt lgkmcnt(" #n ")" ::: "memory")
; #define BAR __builtin_amdgcn_s_barrier()
; #define SCHED __builtin_amdgcn_sched_barrier(0)
; template <class Get, class Epi>
; DI void gemm_loop(int ntiles, int ld, char* shm, const Get& get, const Epi& epi) {
;     ...
;             G_LDA(At, 1, 1); G_STAGE(G_SB(1, 0), b3, voffB); G_STAGE(G_SB(1, 1), b3 + hstep, voffB); G_STAGE(G_SA(1, 0), a3, voffA);
;             WAIT_V(8); WAIT_L(0); BAR; G_MMA(1, 0, At, B0); G_MMA(1, 1, At, B1); BAR; SCHED;
;         }
	s_add_i32 s14, s57, s46
	v_lshl_add_u64 v[170:171], v[170:171], 0, s[10:11]
	s_mov_b32 m0, s14
	ds_read_b128 v[184:187], v175 offset:49152
	ds_read_b128 v[188:191], v175 offset:50176
	ds_read_b128 v[192:195], v175 offset:51200
	ds_read_b128 v[196:199], v175 offset:52224
	ds_read_b128 v[200:203], v175 offset:53248
	ds_read_b128 v[204:207], v175 offset:54272
	ds_read_b128 v[208:211], v175 offset:55296
	ds_read_b128 v[212:215], v175 offset:56320
	global_load_lds_dwordx4 v[170:171], off
	s_add_i32 m0, s14, 0x2000
	s_add_u32 s6, s6, 0x40080
	v_lshl_add_u64 v[170:171], v[216:217], 0, s[10:11]
	s_addc_u32 s7, s7, 0
	s_add_i32 s14, s58, s46
	global_load_lds_dwordx4 v[170:171], off
	v_lshl_add_u64 v[170:171], s[6:7], 0, v[140:141]
	s_mov_b32 m0, s14
	s_nop 0
	global_load_lds_dwordx4 v[170:171], off
	v_lshl_add_u64 v[170:171], s[6:7], 0, v[136:137]
	s_add_i32 m0, s14, 0x2000
	s_nop 0
	global_load_lds_dwordx4 v[170:171], off
	v_lshl_add_u64 v[170:171], v[218:219], 0, s[10:11]
	s_mov_b32 m0, s73
	s_nop 0
	global_load_lds_dwordx4 v[170:171], off
	v_lshl_add_u64 v[170:171], v[220:221], 0, s[10:11]
	s_mov_b32 m0, s74
	s_nop 0
	global_load_lds_dwordx4 v[170:171], off
	s_waitcnt vmcnt(8)
	s_waitcnt lgkmcnt(0)
	s_barrier
	s_setprio 1
	s_waitcnt lgkmcnt(0)
	v_mfma_f32_16x16x32_bf16 v[92:95], v[96:99], v[184:187], v[92:95]
	v_mfma_f32_16x16x32_bf16 v[84:87], v[150:153], v[184:187], v[84:87]
	v_mfma_f32_16x16x32_bf16 v[88:91], v[96:99], v[192:195], v[88:91]
	v_mfma_f32_16x16x32_bf16 v[80:83], v[150:153], v[192:195], v[80:83]
	v_mfma_f32_16x16x32_bf16 v[76:79], v[96:99], v[200:203], v[76:79]
	v_mfma_f32_16x16x32_bf16 v[68:71], v[150:153], v[200:203], v[68:71]
	v_mfma_f32_16x16x32_bf16 v[72:75], v[96:99], v[208:211], v[72:75]
	v_mfma_f32_16x16x32_bf16 v[64:67], v[150:153], v[208:211], v[64:67]
	v_mfma_f32_16x16x32_bf16 v[92:95], v[108:111], v[188:191], v[92:95]
	v_mfma_f32_16x16x32_bf16 v[84:87], v[154:157], v[188:191], v[84:87]
	v_mfma_f32_16x16x32_bf16 v[88:91], v[108:111], v[196:199], v[88:91]
	v_mfma_f32_16x16x32_bf16 v[80:83], v[154:157], v[196:199], v[80:83]
	v_mfma_f32_16x16x32_bf16 v[76:79], v[108:111], v[204:207], v[76:79]
	v_mfma_f32_16x16x32_bf16 v[68:71], v[154:157], v[204:207], v[68:71]
	v_mfma_f32_16x16x32_bf16 v[72:75], v[108:111], v[212:215], v[72:75]
	v_mfma_f32_16x16x32_bf16 v[64:67], v[154:157], v[212:215], v[64:67]
	s_setprio 0
	s_setprio 1
	v_mfma_f32_16x16x32_bf16 v[28:31], v[158:161], v[184:187], v[28:31]
	v_mfma_f32_16x16x32_bf16 v[20:23], v[166:169], v[184:187], v[20:23]
	v_mfma_f32_16x16x32_bf16 v[24:27], v[158:161], v[192:195], v[24:27]
	v_mfma_f32_16x16x32_bf16 v[16:19], v[166:169], v[192:195], v[16:19]
	v_mfma_f32_16x16x32_bf16 v[12:15], v[158:161], v[200:203], v[12:15]
	v_mfma_f32_16x16x32_bf16 v[4:7], v[166:169], v[200:203], v[4:7]
	v_mfma_f32_16x16x32_bf16 v[8:11], v[158:161], v[208:211], v[8:11]
	v_mfma_f32_16x16x32_bf16 v[0:3], v[166:169], v[208:211], v[0:3]
	v_mfma_f32_16x16x32_bf16 v[28:31], v[162:165], v[188:191], v[28:31]
	v_mfma_f32_16x16x32_bf16 v[20:23], v[180:183], v[188:191], v[20:23]
	v_mfma_f32_16x16x32_bf16 v[24:27], v[162:165], v[196:199], v[24:27]
	v_mfma_f32_16x16x32_bf16 v[16:19], v[180:183], v[196:199], v[16:19]
	v_mfma_f32_16x16x32_bf16 v[12:15], v[162:165], v[204:207], v[12:15]
	v_mfma_f32_16x16x32_bf16 v[4:7], v[180:183], v[204:207], v[4:7]
	v_mfma_f32_16x16x32_bf16 v[8:11], v[162:165], v[212:215], v[8:11]
	v_mfma_f32_16x16x32_bf16 v[0:3], v[180:183], v[212:215], v[0:3]
	s_setprio 0
	s_barrier
	s_add_i32 s56, s56, 2
	s_add_u32 s4, s4, 0x100
	s_addc_u32 s5, s5, 0
	s_add_u32 s54, s54, 0x100
	s_addc_u32 s55, s55, 0
	s_cmp_gt_u32 s56, 13
	s_cbranch_scc0 .LBB0_2022
	s_branch .Lpost_2022

; #define BAR __builtin_amdgcn_s_barrier()
; template <class Get, class Epi>
; DI void gemm_loop(int ntiles, int ld, char* shm, const Get& get, const Epi& epi) {
;     ...
;         if (wr == 0) BAR;
;         { int tx2 = threadIdx.x, brow2 = cur.brow, bcol2 = cur.bcol, Lo = L; asm volatile("" : "+v"(tx2), "+s"(brow2), "+s"(bcol2), "+s"(Lo));
;           const int wid2 = tx2 >> 6, lane2 = tx2 & 63; epi(Lo, acc, brow2, bcol2, wid2 >> 2, wid2 & 3, lane2 & 15, lane2 >> 4); }
;         if (!has_next) break;
.Lpost_2022:
	s_mov_b32 s100, 1
	s_and_b64 vcc, exec, s[36:37]
	s_cbranch_vccz .LBB0_2025
	s_barrier

; #define G_STAGE(bufoff, gbase, voff) do { _Pragma("unroll") for (int _i = 0; _i < 2; ++_i) \
;         __builtin_amdgcn_global_load_lds((const unsigned*)((const char*)(gbase) + voff[_i]), (LAS unsigned*)(lds + (bufoff) + ldsw + _i * 8192), 16, 0, 0); } while (0)
; #define WAIT_V(n) asm volatile("s_waitcnt vmcnt(" #n ")" ::: "memory")
; #define BAR __builtin_amdgcn_s_barrier()
; template <class Get, class Epi>
; DI void gemm_loop(int ntiles, int ld, char* shm, const Get& get, const Epi& epi) {
;     ...
;     const int aoff = lds_byte(wr * 64 + fr, fq * 8), boff = lds_byte(wc * 32 + fr, fq * 8);
;     ...
;     const char* cA = (const char*)cur.A + (size_t)cur.brow * ld * 2; const char* cB = (const char*)cur.Bt + (size_t)cur.bcol * ld * 2;
;     G_STAGE(G_SB(0, 0), cB, voffB); G_STAGE(G_SB(0, 1), cB + hstep, voffB); G_STAGE(G_SA(0, 0), cA, voffA); G_STAGE(G_SA(0, 1), cA + hstep, voffA);
;     if (wr == 1) BAR;
;     WAIT_V(2); BAR;
;     G_STAGE(G_SB(1, 0), cB + kstep, voffB); G_STAGE(G_SA(1, 0), cA + kstep, voffA); G_STAGE(G_SB(1, 1), cB + hstep + kstep, voffB);
;     WAIT_V(6); BAR;
.LBB0_2561:
	s_add_u32 s57, s68, 0x86e000
	s_addc_u32 s58, s69, 0
	s_lshl_b32 s3, s8, 13
	s_lshl_b32 s8, s9, 12
	s_and_b32 s11, s8, 0x3000
	s_mov_b64 s[8:9], 0x80
	s_add_i32 m0, s51, 0x18000
	v_lshl_add_u64 v[6:7], v[6:7], 0, s[8:9]
	s_waitcnt vmcnt(2)
	s_barrier
	global_load_lds_dwordx4 v[6:7], off
	v_lshl_add_u64 v[4:5], v[4:5], 0, s[8:9]
	s_add_i32 m0, s51, 0x1a000
	s_add_i32 s59, s51, 0x8000
	s_add_i32 s71, s51, 0xa000
	global_load_lds_dwordx4 v[4:5], off
	v_lshl_add_u64 v[0:1], v[0:1], 0, s[8:9]
	s_mov_b32 m0, s59
	s_add_u32 s12, s14, 0x40080
	global_load_lds_dwordx4 v[0:1], off
	v_lshl_add_u64 v[0:1], v[2:3], 0, s[8:9]
	s_mov_b32 m0, s71
	s_addc_u32 s13, s15, 0
	global_load_lds_dwordx4 v[0:1], off
	s_add_i32 m0, s51, 0x1c000
	v_lshl_add_u64 v[0:1], s[12:13], 0, v[148:149]
	global_load_lds_dwordx4 v[0:1], off
	v_lshl_add_u64 v[0:1], s[12:13], 0, v[152:153]
	s_add_i32 m0, s51, 0x1e000
	v_lshlrev_b32_e32 v3, 2, v8
	global_load_lds_dwordx4 v[0:1], off
	v_and_b32_e32 v0, 15, v8
	v_and_b32_e32 v1, 48, v8
	v_lshlrev_b32_e32 v0, 6, v0
	v_and_b32_e32 v3, 32, v3
	v_or_b32_e32 v2, v0, v1
	v_bitop3_b32 v0, v0, v3, v1 bitop3:0x36
	v_or_b32_e32 v168, s11, v0
	v_lshlrev_b32_e32 v0, 14, v9
	v_and_b32_e32 v0, 0xffff8000, v0
	v_bitop3_b32 v1, v2, s3, v3 bitop3:0xde
	v_lshl_add_u32 v0, v10, 11, v0
	v_and_b32_e32 v2, 1, v9
	v_lshl_or_b32 v0, v2, 6, v0
	v_lshl_add_u32 v154, v11, 1, v0
	v_lshlrev_b32_e32 v0, 14, v12
	s_cmpk_lt_u32 s10, 0x100
	v_and_b32_e32 v0, 0xffff8000, v0
	s_waitcnt vmcnt(6)
	s_mov_b32 s100, 0
	s_cselect_b64 s[10:11], -1, 0
	s_add_u32 s12, s68, 0x89e000
	v_lshl_add_u32 v0, v13, 11, v0
	v_and_b32_e32 v2, 1, v12
	s_addc_u32 s13, s69, 0
	v_lshl_or_b32 v0, v2, 6, v0
	s_add_i32 s72, 0, 0x10000
	s_add_i32 s73, 0, 0x14000
	v_mov_b32_e32 v155, v149
	v_lshl_add_u32 v156, v14, 1, v0
	v_mov_b32_e32 v157, v149
	v_add_u32_e32 v169, s72, v168
	v_add_u32_e32 v170, s73, v168
	v_add_u32_e32 v171, 0, v1
	s_mov_b64 s[34:35], 0x90000
	s_mov_b64 s[36:37], 0xa0000
	s_mov_b32 s75, s52
	s_barrier
	s_branch .LBB0_2564

; #define G_STAGE(bufoff, gbase, voff) do { _Pragma("unroll") for (int _i = 0; _i < 2; ++_i) \
;         __builtin_amdgcn_global_load_lds((const unsigned*)((const char*)(gbase) + voff[_i]), (LAS unsigned*)(lds + (bufoff) + ldsw + _i * 8192), 16, 0, 0); } while (0)
; #define G_LDA(dst, b, h) do { _Pragma("unroll") for (int m = 0; m < 4; ++m) _Pragma("unroll") for (int k = 0; k < 2; ++k) dst[m][k] = *(const LAS bf16x8*)(lds + G_SA(b, h) + aoff + m * 2048 + k * 1024); } while (0)
; #define G_LDB(dst, b, h) do { _Pragma("unroll") for (int n = 0; n < 2; ++n) _Pragma("unroll") for (int k = 0; k < 2; ++k) dst[n][k] = *(const LAS bf16x8*)(lds + G_SB(b, h) + boff + n * 2048 + k * 1024); } while (0)
; #define G_MMA(ai, bj, At_, Bt_) do { __builtin_amdgcn_s_setprio(1); _Pragma("unroll") for (int m = 0; m < 4; ++m) _Pragma("unroll") for (int n = 0; n < 2; ++n) _Pragma("unroll") for (int k = 0; k < 2; ++k) \
;         acc[ai][bj][m][n] = __builtin_amdgcn_mfma_f32_16x16x32_bf16(Bt_[n][k], At_[m][k], acc[ai][bj][m][n], 0, 0, 0); __builtin_amdgcn_s_setprio(0); } while (0)
; #define WAIT_V(n) asm volatile("s_waitcnt vmcnt(" #n ")" ::: "memory")
; #define WAIT_L(n) asm volatile("s_waitcnt lgkmcnt(" #n ")" ::: "memory")
; #define BAR __builtin_amdgcn_s_barrier()
; #define SCHED __builtin_amdgcn_sched_barrier(0)
; template <class Get, class Epi>
; DI void gemm_loop(int ntiles, int ld, char* shm, const Get& get, const Epi& epi) {
;     ...
;             G_LDB(B0, 0, 0); G_LDB(B1, 0, 1); SCHED; G_LDA(At, 0, 0); G_STAGE(G_SA(1, 1), a1 + hstep, voffA);
;             WAIT_V(8); WAIT_L(0); BAR; G_MMA(0, 0, At, B0); G_MMA(0, 1, At, B1); BAR; SCHED;
.Lpeel_2574:
	ds_read_b128 v[128:131], v169
	ds_read_b128 v[132:135], v169 offset:1024
	ds_read_b128 v[136:139], v169 offset:2048
	ds_read_b128 v[140:143], v169 offset:3072
	ds_read_b128 v[158:161], v170
	ds_read_b128 v[162:165], v170 offset:1024
	ds_read_b128 v[172:175], v170 offset:2048
	ds_read_b128 v[176:179], v170 offset:3072
	s_add_i32 s82, s14, 2
	s_add_u32 s15, s52, 0xfffc0080
	s_addc_u32 s46, s53, -1
	s_cmp_eq_u32 s79, s14
	s_cselect_b32 s14, s77, s80
	s_cselect_b32 s47, s3, s46
	s_cselect_b32 s46, s41, s15
	s_cselect_b32 s15, s43, s81
	v_lshl_add_u64 v[144:145], s[52:53], 0, v[154:155]
	s_add_i32 m0, s51, 0xc000
	ds_read_b128 v[180:183], v171
	ds_read_b128 v[184:187], v171 offset:1024
	ds_read_b128 v[188:191], v171 offset:2048
	ds_read_b128 v[192:195], v171 offset:3072
	ds_read_b128 v[196:199], v171 offset:4096
	ds_read_b128 v[200:203], v171 offset:5120
	ds_read_b128 v[204:207], v171 offset:6144
	ds_read_b128 v[208:211], v171 offset:7168
	global_load_lds_dwordx4 v[144:145], off
	v_lshl_add_u64 v[144:145], s[52:53], 0, v[156:157]
	s_add_i32 m0, s51, 0xe000
	s_nop 0
	global_load_lds_dwordx4 v[144:145], off
	s_cmp_lg_u32 s100, 0
	s_cbranch_scc0 .Lrf_2574_0
	s_waitcnt vmcnt(16)
	s_branch .Lrj_2574_0

; #define G_STAGE(bufoff, gbase, voff) do { _Pragma("unroll") for (int _i = 0; _i < 2; ++_i) \
;         __builtin_amdgcn_global_load_lds((const unsigned*)((const char*)(gbase) + voff[_i]), (LAS unsigned*)(lds + (bufoff) + ldsw + _i * 8192), 16, 0, 0); } while (0)
; #define G_LDA(dst, b, h) do { _Pragma("unroll") for (int m = 0; m < 4; ++m) _Pragma("unroll") for (int k = 0; k < 2; ++k) dst[m][k] = *(const LAS bf16x8*)(lds + G_SA(b, h) + aoff + m * 2048 + k * 1024); } while (0)
; #define G_MMA(ai, bj, At_, Bt_) do { __builtin_amdgcn_s_setprio(1); _Pragma("unroll") for (int m = 0; m < 4; ++m) _Pragma("unroll") for (int n = 0; n < 2; ++n) _Pragma("unroll") for (int k = 0; k < 2; ++k) \
;         acc[ai][bj][m][n] = __builtin_amdgcn_mfma_f32_16x16x32_bf16(Bt_[n][k], At_[m][k], acc[ai][bj][m][n], 0, 0, 0); __builtin_amdgcn_s_setprio(0); } while (0)
; #define WAIT_V(n) asm volatile("s_waitcnt vmcnt(" #n ")" ::: "memory")
; #define WAIT_L(n) asm volatile("s_waitcnt lgkmcnt(" #n ")" ::: "memory")
; #define BAR __builtin_amdgcn_s_barrier()
; #define SCHED __builtin_amdgcn_sched_barrier(0)
; template <class Get, class Epi>
; DI void gemm_loop(int ntiles, int ld, char* shm, const Get& get, const Epi& epi) {
;     ...
;             WAIT_V(8); WAIT_L(0); BAR; G_MMA(0, 0, At, B0); G_MMA(0, 1, At, B1); BAR; SCHED;
;             G_LDA(At, 0, 1); G_STAGE(G_SB(0, 0), b2, voffB); G_STAGE(G_SB(0, 1), b2 + hstep, voffB); G_STAGE(G_SA(0, 0), a2, voffA);
;             WAIT_V(8); WAIT_L(0); BAR; G_MMA(1, 0, At, B0); G_MMA(1, 1, At, B1); BAR; SCHED;
.Lrj_2574_0:
	s_waitcnt lgkmcnt(0)
	s_barrier
	s_setprio 1
	s_waitcnt lgkmcnt(0)
	v_mfma_f32_16x16x32_bf16 v[124:127], v[128:131], v[180:183], 0
	v_mfma_f32_16x16x32_bf16 v[120:123], v[136:139], v[180:183], 0
	v_mfma_f32_16x16x32_bf16 v[116:119], v[128:131], v[188:191], 0
	v_mfma_f32_16x16x32_bf16 v[112:115], v[136:139], v[188:191], 0
	v_mfma_f32_16x16x32_bf16 v[108:111], v[128:131], v[196:199], 0
	v_mfma_f32_16x16x32_bf16 v[104:107], v[136:139], v[196:199], 0
	v_mfma_f32_16x16x32_bf16 v[100:103], v[128:131], v[204:207], 0
	v_mfma_f32_16x16x32_bf16 v[96:99], v[136:139], v[204:207], 0
	v_mfma_f32_16x16x32_bf16 v[124:127], v[132:135], v[184:187], v[124:127]
	v_mfma_f32_16x16x32_bf16 v[120:123], v[140:143], v[184:187], v[120:123]
	v_mfma_f32_16x16x32_bf16 v[116:119], v[132:135], v[192:195], v[116:119]
	v_mfma_f32_16x16x32_bf16 v[112:115], v[140:143], v[192:195], v[112:115]
	v_mfma_f32_16x16x32_bf16 v[108:111], v[132:135], v[200:203], v[108:111]
	v_mfma_f32_16x16x32_bf16 v[104:107], v[140:143], v[200:203], v[104:107]
	v_mfma_f32_16x16x32_bf16 v[100:103], v[132:135], v[208:211], v[100:103]
	v_mfma_f32_16x16x32_bf16 v[96:99], v[140:143], v[208:211], v[96:99]
	s_setprio 0
	s_setprio 1
	v_mfma_f32_16x16x32_bf16 v[60:63], v[158:161], v[180:183], 0
	v_mfma_f32_16x16x32_bf16 v[56:59], v[172:175], v[180:183], 0
	v_mfma_f32_16x16x32_bf16 v[52:55], v[158:161], v[188:191], 0
	v_mfma_f32_16x16x32_bf16 v[48:51], v[172:175], v[188:191], 0
	v_mfma_f32_16x16x32_bf16 v[44:47], v[158:161], v[196:199], 0
	v_mfma_f32_16x16x32_bf16 v[40:43], v[172:175], v[196:199], 0
	v_mfma_f32_16x16x32_bf16 v[36:39], v[158:161], v[204:207], 0
	v_mfma_f32_16x16x32_bf16 v[32:35], v[172:175], v[204:207], 0
	v_mfma_f32_16x16x32_bf16 v[60:63], v[162:165], v[184:187], v[60:63]
	v_mfma_f32_16x16x32_bf16 v[56:59], v[176:179], v[184:187], v[56:59]
	v_mfma_f32_16x16x32_bf16 v[52:55], v[162:165], v[192:195], v[52:55]
	v_mfma_f32_16x16x32_bf16 v[48:51], v[176:179], v[192:195], v[48:51]
	v_mfma_f32_16x16x32_bf16 v[44:47], v[162:165], v[200:203], v[44:47]
	v_mfma_f32_16x16x32_bf16 v[40:43], v[176:179], v[200:203], v[40:43]
	v_mfma_f32_16x16x32_bf16 v[36:39], v[162:165], v[208:211], v[36:39]
	v_mfma_f32_16x16x32_bf16 v[32:35], v[176:179], v[208:211], v[32:35]
	s_setprio 0
	s_barrier
	s_add_i32 s83, s72, s31
	v_lshl_add_u64 v[144:145], s[14:15], 0, v[148:149]
	s_mov_b32 m0, s83
	ds_read_b128 v[180:183], v171 offset:16384
	ds_read_b128 v[184:187], v171 offset:17408
	ds_read_b128 v[188:191], v171 offset:18432
	ds_read_b128 v[192:195], v171 offset:19456
	ds_read_b128 v[196:199], v171 offset:20480
	ds_read_b128 v[200:203], v171 offset:21504
	ds_read_b128 v[204:207], v171 offset:22528
	ds_read_b128 v[208:211], v171 offset:23552
	global_load_lds_dwordx4 v[144:145], off
	s_add_i32 m0, s83, 0x2000
	s_add_u32 s84, s14, 0x40000
	v_lshl_add_u64 v[166:167], s[14:15], 0, v[152:153]
	s_addc_u32 s85, s15, 0
	s_add_i32 s83, s73, s31
	global_load_lds_dwordx4 v[166:167], off
	v_lshl_add_u64 v[212:213], s[84:85], 0, v[148:149]
	s_mov_b32 m0, s83
	v_lshl_add_u64 v[214:215], s[46:47], 0, v[150:151]
	global_load_lds_dwordx4 v[212:213], off
	v_lshl_add_u64 v[212:213], s[84:85], 0, v[152:153]
	s_add_i32 m0, s83, 0x2000
	s_nop 0
	global_load_lds_dwordx4 v[212:213], off
	v_lshl_add_u64 v[212:213], s[46:47], 0, v[146:147]
	s_mov_b32 m0, s51
	s_nop 0
	global_load_lds_dwordx4 v[212:213], off
	s_mov_b32 m0, s54
	s_nop 0
	global_load_lds_dwordx4 v[214:215], off
	s_cmp_lg_u32 s100, 0
	s_cbranch_scc0 .Lrf_2574_1
	s_waitcnt vmcnt(16)
	s_branch .Lrj_2574_1

; #define G_STAGE(bufoff, gbase, voff) do { _Pragma("unroll") for (int _i = 0; _i < 2; ++_i) \
;         __builtin_amdgcn_global_load_lds((const unsigned*)((const char*)(gbase) + voff[_i]), (LAS unsigned*)(lds + (bufoff) + ldsw + _i * 8192), 16, 0, 0); } while (0)
; #define G_LDA(dst, b, h) do { _Pragma("unroll") for (int m = 0; m < 4; ++m) _Pragma("unroll") for (int k = 0; k < 2; ++k) dst[m][k] = *(const LAS bf16x8*)(lds + G_SA(b, h) + aoff + m * 2048 + k * 1024); } while (0)
; #define G_LDB(dst, b, h) do { _Pragma("unroll") for (int n = 0; n < 2; ++n) _Pragma("unroll") for (int k = 0; k < 2; ++k) dst[n][k] = *(const LAS bf16x8*)(lds + G_SB(b, h) + boff + n * 2048 + k * 1024); } while (0)
; #define G_MMA(ai, bj, At_, Bt_) do { __builtin_amdgcn_s_setprio(1); _Pragma("unroll") for (int m = 0; m < 4; ++m) _Pragma("unroll") for (int n = 0; n < 2; ++n) _Pragma("unroll") for (int k = 0; k < 2; ++k) \
;         acc[ai][bj][m][n] = __builtin_amdgcn_mfma_f32_16x16x32_bf16(Bt_[n][k], At_[m][k], acc[ai][bj][m][n], 0, 0, 0); __builtin_amdgcn_s_setprio(0); } while (0)
; #define WAIT_V(n) asm volatile("s_waitcnt vmcnt(" #n ")" ::: "memory")
; #define WAIT_L(n) asm volatile("s_waitcnt lgkmcnt(" #n ")" ::: "memory")
; #define BAR __builtin_amdgcn_s_barrier()
; #define SCHED __builtin_amdgcn_sched_barrier(0)
; template <class Get, class Epi>
; DI void gemm_loop(int ntiles, int ld, char* shm, const Get& get, const Epi& epi) {
;     ...
;             WAIT_V(8); WAIT_L(0); BAR; G_MMA(1, 0, At, B0); G_MMA(1, 1, At, B1); BAR; SCHED;
;             G_LDB(B0, 1, 0); G_LDB(B1, 1, 1); SCHED; G_LDA(At, 1, 0); G_STAGE(G_SA(0, 1), a2 + hstep, voffA);
;             WAIT_V(8); WAIT_L(0); BAR; G_MMA(0, 0, At, B0); G_MMA(0, 1, At, B1); BAR; SCHED;
.Lrj_2574_1:
	s_waitcnt lgkmcnt(0)
	s_barrier
	s_setprio 1
	s_waitcnt lgkmcnt(0)
	v_mfma_f32_16x16x32_bf16 v[92:95], v[128:131], v[180:183], 0
	v_mfma_f32_16x16x32_bf16 v[88:91], v[136:139], v[180:183], 0
	v_mfma_f32_16x16x32_bf16 v[84:87], v[128:131], v[188:191], 0
	v_mfma_f32_16x16x32_bf16 v[80:83], v[136:139], v[188:191], 0
	v_mfma_f32_16x16x32_bf16 v[76:79], v[128:131], v[196:199], 0
	v_mfma_f32_16x16x32_bf16 v[72:75], v[136:139], v[196:199], 0
	v_mfma_f32_16x16x32_bf16 v[68:71], v[128:131], v[204:207], 0
	v_mfma_f32_16x16x32_bf16 v[64:67], v[136:139], v[204:207], 0
	v_mfma_f32_16x16x32_bf16 v[92:95], v[132:135], v[184:187], v[92:95]
	v_mfma_f32_16x16x32_bf16 v[88:91], v[140:143], v[184:187], v[88:91]
	v_mfma_f32_16x16x32_bf16 v[84:87], v[132:135], v[192:195], v[84:87]
	v_mfma_f32_16x16x32_bf16 v[80:83], v[140:143], v[192:195], v[80:83]
	v_mfma_f32_16x16x32_bf16 v[76:79], v[132:135], v[200:203], v[76:79]
	v_mfma_f32_16x16x32_bf16 v[72:75], v[140:143], v[200:203], v[72:75]
	v_mfma_f32_16x16x32_bf16 v[68:71], v[132:135], v[208:211], v[68:71]
	v_mfma_f32_16x16x32_bf16 v[64:67], v[140:143], v[208:211], v[64:67]
	s_setprio 0
	s_setprio 1
	v_mfma_f32_16x16x32_bf16 v[28:31], v[158:161], v[180:183], 0
	v_mfma_f32_16x16x32_bf16 v[24:27], v[172:175], v[180:183], 0
	v_mfma_f32_16x16x32_bf16 v[20:23], v[158:161], v[188:191], 0
	v_mfma_f32_16x16x32_bf16 v[16:19], v[172:175], v[188:191], 0
	v_mfma_f32_16x16x32_bf16 v[12:15], v[158:161], v[196:199], 0
	v_mfma_f32_16x16x32_bf16 v[8:11], v[172:175], v[196:199], 0
	v_mfma_f32_16x16x32_bf16 v[4:7], v[158:161], v[204:207], 0
	v_mfma_f32_16x16x32_bf16 v[0:3], v[172:175], v[204:207], 0
	v_mfma_f32_16x16x32_bf16 v[28:31], v[162:165], v[184:187], v[28:31]
	v_mfma_f32_16x16x32_bf16 v[24:27], v[176:179], v[184:187], v[24:27]
	v_mfma_f32_16x16x32_bf16 v[20:23], v[162:165], v[192:195], v[20:23]
	v_mfma_f32_16x16x32_bf16 v[16:19], v[176:179], v[192:195], v[16:19]
	v_mfma_f32_16x16x32_bf16 v[12:15], v[162:165], v[200:203], v[12:15]
	v_mfma_f32_16x16x32_bf16 v[8:11], v[176:179], v[200:203], v[8:11]
	v_mfma_f32_16x16x32_bf16 v[4:7], v[162:165], v[208:211], v[4:7]
	v_mfma_f32_16x16x32_bf16 v[0:3], v[176:179], v[208:211], v[0:3]
	s_setprio 0
	s_barrier
	s_add_i32 s83, 0, 0x18000
	s_add_i32 s84, 0, 0x1c000
	v_add_u32_e32 v140, s83, v168
	v_add_u32_e32 v176, s84, v168
	ds_read_b128 v[128:131], v140
	ds_read_b128 v[132:135], v140 offset:1024
	ds_read_b128 v[136:139], v140 offset:2048
	ds_read_b128 v[140:143], v140 offset:3072
	ds_read_b128 v[158:161], v176
	ds_read_b128 v[162:165], v176 offset:1024
	ds_read_b128 v[172:175], v176 offset:2048
	ds_read_b128 v[176:179], v176 offset:3072
	s_add_u32 s46, s46, 0x40000
	s_addc_u32 s47, s47, 0
	s_mov_b32 m0, s55
	v_lshl_add_u64 v[216:217], s[46:47], 0, v[146:147]
	ds_read_b128 v[180:183], v171 offset:32768
	ds_read_b128 v[184:187], v171 offset:33792
	ds_read_b128 v[188:191], v171 offset:34816
	ds_read_b128 v[192:195], v171 offset:35840
	ds_read_b128 v[196:199], v171 offset:36864
	ds_read_b128 v[200:203], v171 offset:37888
	ds_read_b128 v[204:207], v171 offset:38912
	ds_read_b128 v[208:211], v171 offset:39936
	global_load_lds_dwordx4 v[216:217], off
	v_lshl_add_u64 v[216:217], s[46:47], 0, v[150:151]
	s_mov_b32 m0, s56
	s_nop 0
	global_load_lds_dwordx4 v[216:217], off
	s_waitcnt vmcnt(8)
	s_waitcnt lgkmcnt(0)
	s_barrier
	s_setprio 1
	s_waitcnt lgkmcnt(0)
	v_mfma_f32_16x16x32_bf16 v[124:127], v[128:131], v[180:183], v[124:127]
	v_mfma_f32_16x16x32_bf16 v[120:123], v[136:139], v[180:183], v[120:123]
	v_mfma_f32_16x16x32_bf16 v[116:119], v[128:131], v[188:191], v[116:119]
	v_mfma_f32_16x16x32_bf16 v[112:115], v[136:139], v[188:191], v[112:115]
	v_mfma_f32_16x16x32_bf16 v[108:111], v[128:131], v[196:199], v[108:111]
	v_mfma_f32_16x16x32_bf16 v[104:107], v[136:139], v[196:199], v[104:107]
	v_mfma_f32_16x16x32_bf16 v[100:103], v[128:131], v[204:207], v[100:103]
	v_mfma_f32_16x16x32_bf16 v[96:99], v[136:139], v[204:207], v[96:99]
	v_mfma_f32_16x16x32_bf16 v[124:127], v[132:135], v[184:187], v[124:127]
	v_mfma_f32_16x16x32_bf16 v[120:123], v[140:143], v[184:187], v[120:123]
	v_mfma_f32_16x16x32_bf16 v[116:119], v[132:135], v[192:195], v[116:119]
	v_mfma_f32_16x16x32_bf16 v[112:115], v[140:143], v[192:195], v[112:115]
	v_mfma_f32_16x16x32_bf16 v[108:111], v[132:135], v[200:203], v[108:111]
	v_mfma_f32_16x16x32_bf16 v[104:107], v[140:143], v[200:203], v[104:107]
	v_mfma_f32_16x16x32_bf16 v[100:103], v[132:135], v[208:211], v[100:103]
	v_mfma_f32_16x16x32_bf16 v[96:99], v[140:143], v[208:211], v[96:99]
	s_setprio 0
	s_setprio 1
	v_mfma_f32_16x16x32_bf16 v[60:63], v[158:161], v[180:183], v[60:63]
	v_mfma_f32_16x16x32_bf16 v[56:59], v[172:175], v[180:183], v[56:59]
	v_mfma_f32_16x16x32_bf16 v[52:55], v[158:161], v[188:191], v[52:55]
	v_mfma_f32_16x16x32_bf16 v[48:51], v[172:175], v[188:191], v[48:51]
	v_mfma_f32_16x16x32_bf16 v[44:47], v[158:161], v[196:199], v[44:47]
	v_mfma_f32_16x16x32_bf16 v[40:43], v[172:175], v[196:199], v[40:43]
	v_mfma_f32_16x16x32_bf16 v[36:39], v[158:161], v[204:207], v[36:39]
	v_mfma_f32_16x16x32_bf16 v[32:35], v[172:175], v[204:207], v[32:35]
	v_mfma_f32_16x16x32_bf16 v[60:63], v[162:165], v[184:187], v[60:63]
	v_mfma_f32_16x16x32_bf16 v[56:59], v[176:179], v[184:187], v[56:59]
	v_mfma_f32_16x16x32_bf16 v[52:55], v[162:165], v[192:195], v[52:55]
	v_mfma_f32_16x16x32_bf16 v[48:51], v[176:179], v[192:195], v[48:51]
	v_mfma_f32_16x16x32_bf16 v[44:47], v[162:165], v[200:203], v[44:47]
	v_mfma_f32_16x16x32_bf16 v[40:43], v[176:179], v[200:203], v[40:43]
	v_mfma_f32_16x16x32_bf16 v[36:39], v[162:165], v[208:211], v[36:39]
	v_mfma_f32_16x16x32_bf16 v[32:35], v[176:179], v[208:211], v[32:35]
	s_setprio 0
	s_barrier
; #define G_STAGE(bufoff, gbase, voff) do { _Pragma("unroll") for (int _i = 0; _i < 2; ++_i) \
;         __builtin_amdgcn_global_load_lds((const unsigned*)((const char*)(gbase) + voff[_i]), (LAS unsigned*)(lds + (bufoff) + ldsw + _i * 8192), 16, 0, 0); } while (0)
; #define G_LDA(dst, b, h) do { _Pragma("unroll") for (int m = 0; m < 4; ++m) _Pragma("unroll") for (int k = 0; k < 2; ++k) dst[m][k] = *(const LAS bf16x8*)(lds + G_SA(b, h) + aoff + m * 2048 + k * 1024); } while (0)
; #define G_MMA(ai, bj, At_, Bt_) do { __builtin_amdgcn_s_setprio(1); _Pragma("unroll") for (int m = 0; m < 4; ++m) _Pragma("unroll") for (int n = 0; n < 2; ++n) _Pragma("unroll") for (int k = 0; k < 2; ++k) \
;         acc[ai][bj][m][n] = __builtin_amdgcn_mfma_f32_16x16x32_bf16(Bt_[n][k], At_[m][k], acc[ai][bj][m][n], 0, 0, 0); __builtin_amdgcn_s_setprio(0); } while (0)
; #define WAIT_V(n) asm volatile("s_waitcnt vmcnt(" #n ")" ::: "memory")
; #define WAIT_L(n) asm volatile("s_waitcnt lgkmcnt(" #n ")" ::: "memory")
; #define BAR __builtin_amdgcn_s_barrier()
; #define SCHED __builtin_amdgcn_sched_barrier(0)
; template <class Get, class Epi>
; DI void gemm_loop(int ntiles, int ld, char* shm, const Get& get, const Epi& epi) {
;     ...
;             G_LDA(At, 1, 1); G_STAGE(G_SB(1, 0), b3, voffB); G_STAGE(G_SB(1, 1), b3 + hstep, voffB); G_STAGE(G_SA(1, 0), a3, voffA);
;             WAIT_V(8); WAIT_L(0); BAR; G_MMA(1, 0, At, B0); G_MMA(1, 1, At, B1); BAR; SCHED;
;         }
	s_add_i32 s46, s83, s31
	v_lshl_add_u64 v[144:145], v[144:145], 0, s[8:9]
	s_mov_b32 m0, s46
	ds_read_b128 v[180:183], v171 offset:49152
	ds_read_b128 v[184:187], v171 offset:50176
	ds_read_b128 v[188:191], v171 offset:51200
	ds_read_b128 v[192:195], v171 offset:52224
	ds_read_b128 v[196:199], v171 offset:53248
	ds_read_b128 v[200:203], v171 offset:54272
	ds_read_b128 v[204:207], v171 offset:55296
	ds_read_b128 v[208:211], v171 offset:56320
	global_load_lds_dwordx4 v[144:145], off
	s_add_i32 m0, s46, 0x2000
	s_add_u32 s14, s14, 0x40080
	v_lshl_add_u64 v[144:145], v[166:167], 0, s[8:9]
	s_addc_u32 s15, s15, 0
	s_add_i32 s46, s84, s31
	global_load_lds_dwordx4 v[144:145], off
	v_lshl_add_u64 v[144:145], s[14:15], 0, v[148:149]
	s_mov_b32 m0, s46
	s_nop 0
	global_load_lds_dwordx4 v[144:145], off
	v_lshl_add_u64 v[144:145], s[14:15], 0, v[152:153]
	s_add_i32 m0, s46, 0x2000
	s_nop 0
	global_load_lds_dwordx4 v[144:145], off
	v_lshl_add_u64 v[144:145], v[212:213], 0, s[8:9]
	s_mov_b32 m0, s59
	s_nop 0
	global_load_lds_dwordx4 v[144:145], off
	v_lshl_add_u64 v[144:145], v[214:215], 0, s[8:9]
	s_mov_b32 m0, s71
	s_nop 0
	global_load_lds_dwordx4 v[144:145], off
	s_waitcnt vmcnt(8)
	s_waitcnt lgkmcnt(0)
	s_barrier
	s_setprio 1
	s_waitcnt lgkmcnt(0)
	v_mfma_f32_16x16x32_bf16 v[92:95], v[128:131], v[180:183], v[92:95]
	v_mfma_f32_16x16x32_bf16 v[88:91], v[136:139], v[180:183], v[88:91]
	v_mfma_f32_16x16x32_bf16 v[84:87], v[128:131], v[188:191], v[84:87]
	v_mfma_f32_16x16x32_bf16 v[80:83], v[136:139], v[188:191], v[80:83]
	v_mfma_f32_16x16x32_bf16 v[76:79], v[128:131], v[196:199], v[76:79]
	v_mfma_f32_16x16x32_bf16 v[72:75], v[136:139], v[196:199], v[72:75]
	v_mfma_f32_16x16x32_bf16 v[68:71], v[128:131], v[204:207], v[68:71]
	v_mfma_f32_16x16x32_bf16 v[64:67], v[136:139], v[204:207], v[64:67]
	v_mfma_f32_16x16x32_bf16 v[92:95], v[132:135], v[184:187], v[92:95]
	v_mfma_f32_16x16x32_bf16 v[88:91], v[140:143], v[184:187], v[88:91]
	v_mfma_f32_16x16x32_bf16 v[84:87], v[132:135], v[192:195], v[84:87]
	v_mfma_f32_16x16x32_bf16 v[80:83], v[140:143], v[192:195], v[80:83]
	v_mfma_f32_16x16x32_bf16 v[76:79], v[132:135], v[200:203], v[76:79]
	v_mfma_f32_16x16x32_bf16 v[72:75], v[140:143], v[200:203], v[72:75]
	v_mfma_f32_16x16x32_bf16 v[68:71], v[132:135], v[208:211], v[68:71]
	v_mfma_f32_16x16x32_bf16 v[64:67], v[140:143], v[208:211], v[64:67]
	s_setprio 0
	s_setprio 1
	v_mfma_f32_16x16x32_bf16 v[28:31], v[158:161], v[180:183], v[28:31]
	v_mfma_f32_16x16x32_bf16 v[24:27], v[172:175], v[180:183], v[24:27]
	v_mfma_f32_16x16x32_bf16 v[20:23], v[158:161], v[188:191], v[20:23]
	v_mfma_f32_16x16x32_bf16 v[16:19], v[172:175], v[188:191], v[16:19]
	v_mfma_f32_16x16x32_bf16 v[12:15], v[158:161], v[196:199], v[12:15]
	v_mfma_f32_16x16x32_bf16 v[8:11], v[172:175], v[196:199], v[8:11]
	v_mfma_f32_16x16x32_bf16 v[4:7], v[158:161], v[204:207], v[4:7]
	v_mfma_f32_16x16x32_bf16 v[0:3], v[172:175], v[204:207], v[0:3]
	v_mfma_f32_16x16x32_bf16 v[28:31], v[162:165], v[184:187], v[28:31]
	v_mfma_f32_16x16x32_bf16 v[24:27], v[176:179], v[184:187], v[24:27]
	v_mfma_f32_16x16x32_bf16 v[20:23], v[162:165], v[192:195], v[20:23]
	v_mfma_f32_16x16x32_bf16 v[16:19], v[176:179], v[192:195], v[16:19]
	v_mfma_f32_16x16x32_bf16 v[12:15], v[162:165], v[200:203], v[12:15]
	v_mfma_f32_16x16x32_bf16 v[8:11], v[176:179], v[200:203], v[8:11]
	v_mfma_f32_16x16x32_bf16 v[4:7], v[162:165], v[208:211], v[4:7]
	v_mfma_f32_16x16x32_bf16 v[0:3], v[176:179], v[208:211], v[0:3]
	s_setprio 0
	s_barrier
	s_add_u32 s52, s52, 0x100
	s_addc_u32 s53, s53, 0
	s_add_u32 s80, s80, 0x100
	s_addc_u32 s81, s81, 0
	s_cmp_ge_u32 s82, s78
	s_mov_b32 s14, s82
	s_cbranch_scc0 .LBB0_2574
	s_branch .Lpost_2574

; #define G_STAGE(bufoff, gbase, voff) do { _Pragma("unroll") for (int _i = 0; _i < 2; ++_i) \
;         __builtin_amdgcn_global_load_lds((const unsigned*)((const char*)(gbase) + voff[_i]), (LAS unsigned*)(lds + (bufoff) + ldsw + _i * 8192), 16, 0, 0); } while (0)
; #define WAIT_V(n) asm volatile("s_waitcnt vmcnt(" #n ")" ::: "memory")
; #define BAR __builtin_amdgcn_s_barrier()
; template <class Get, class Epi>
; DI void gemm_loop(int ntiles, int ld, char* shm, const Get& get, const Epi& epi) {
;     ...
;     const int aoff = lds_byte(wr * 64 + fr, fq * 8), boff = lds_byte(wc * 32 + fr, fq * 8);
;     ...
;     const char* cA = (const char*)cur.A + (size_t)cur.brow * ld * 2; const char* cB = (const char*)cur.Bt + (size_t)cur.bcol * ld * 2;
;     G_STAGE(G_SB(0, 0), cB, voffB); G_STAGE(G_SB(0, 1), cB + hstep, voffB); G_STAGE(G_SA(0, 0), cA, voffA); G_STAGE(G_SA(0, 1), cA + hstep, voffA);
;     if (wr == 1) BAR;
;     WAIT_V(2); BAR;
;     G_STAGE(G_SB(1, 0), cB + kstep, voffB); G_STAGE(G_SA(1, 0), cA + kstep, voffA); G_STAGE(G_SB(1, 1), cB + hstep + kstep, voffB);
;     WAIT_V(6); BAR;
.LBB0_2875:
	s_add_u32 s53, s68, 0x871000
	s_addc_u32 s54, s69, 0
	s_lshl_b32 s10, s10, 12
	s_and_b32 s13, s10, 0x3000
	s_mov_b64 s[10:11], 0x80
	s_add_i32 m0, s49, 0x18000
	v_lshl_add_u64 v[6:7], v[6:7], 0, s[10:11]
	s_lshl_b32 s3, s3, 13
	s_waitcnt vmcnt(2)
	s_barrier
	global_load_lds_dwordx4 v[6:7], off
	v_lshl_add_u64 v[4:5], v[4:5], 0, s[10:11]
	s_add_i32 m0, s49, 0x1a000
	s_add_i32 s55, s49, 0x8000
	s_add_i32 s56, s49, 0xa000
	global_load_lds_dwordx4 v[4:5], off
	v_lshl_add_u64 v[0:1], v[0:1], 0, s[10:11]
	s_mov_b32 m0, s55
	s_add_u32 s30, s14, 0xb0080
	global_load_lds_dwordx4 v[0:1], off
	v_lshl_add_u64 v[0:1], v[2:3], 0, s[10:11]
	s_mov_b32 m0, s56
	s_addc_u32 s31, s15, 0
	global_load_lds_dwordx4 v[0:1], off
	s_add_i32 m0, s49, 0x1c000
	v_lshl_add_u64 v[0:1], s[30:31], 0, v[148:149]
	global_load_lds_dwordx4 v[0:1], off
	v_lshl_add_u64 v[0:1], s[30:31], 0, v[152:153]
	s_add_i32 m0, s49, 0x1e000
	v_lshlrev_b32_e32 v3, 2, v8
	global_load_lds_dwordx4 v[0:1], off
	v_and_b32_e32 v0, 15, v8
	v_and_b32_e32 v1, 48, v8
	v_lshlrev_b32_e32 v0, 6, v0
	v_and_b32_e32 v3, 32, v3
	v_or_b32_e32 v2, v0, v1
	v_bitop3_b32 v0, v0, v3, v1 bitop3:0x36
	v_bitop3_b32 v2, v2, s3, v3 bitop3:0xde
	v_or_b32_e32 v168, s13, v0
	v_lshrrev_b32_e32 v1, 1, v9
	v_mul_lo_u32 v0, v11, s2
	s_mov_b32 s3, 0xb000
	v_mad_u64_u32 v[0:1], s[36:37], v1, s3, v[0:1]
	v_or_b32_e32 v0, v0, v10
	s_mov_b64 s[34:35], 0xb0080
	v_add_lshl_u32 v0, v0, v12, 1
	v_mov_b32_e32 v1, v149
	v_lshl_add_u64 v[154:155], v[0:1], 0, s[34:35]
	v_lshrrev_b32_e32 v1, 1, v13
	v_mul_lo_u32 v0, v14, s2
	s_cmpk_lt_u32 s12, 0x100
	v_mad_u64_u32 v[0:1], s[2:3], v1, s3, v[0:1]
	s_waitcnt vmcnt(6)
	s_mov_b32 s100, 0
	s_cselect_b64 s[12:13], -1, 0
	s_add_u32 s30, s68, 0x8a1000
	v_or_b32_e32 v0, v0, v15
	s_addc_u32 s31, s69, 0
	v_add_lshl_u32 v0, v0, v16, 1
	v_mov_b32_e32 v1, v149
	s_add_i32 s58, 0, 0x10000
	s_add_i32 s59, 0, 0x14000
	v_lshl_add_u64 v[156:157], v[0:1], 0, s[34:35]
	s_movk_i32 s57, 0x180
	v_add_u32_e32 v169, s58, v168
	v_add_u32_e32 v170, s59, v168
	v_add_u32_e32 v171, 0, v2
	s_movk_i32 s71, 0xffc0
	s_mov_b64 s[34:35], 0x80000
	s_mov_b64 s[36:37], 0x90000
	s_mov_b64 s[38:39], 0xa0000
	s_mov_b32 s73, s44
	s_mov_b32 s74, s78
	s_mov_b32 s75, s77
	s_barrier
	s_branch .LBB0_2878

; #define G_STAGE(bufoff, gbase, voff) do { _Pragma("unroll") for (int _i = 0; _i < 2; ++_i) \
;         __builtin_amdgcn_global_load_lds((const unsigned*)((const char*)(gbase) + voff[_i]), (LAS unsigned*)(lds + (bufoff) + ldsw + _i * 8192), 16, 0, 0); } while (0)
; #define G_LDA(dst, b, h) do { _Pragma("unroll") for (int m = 0; m < 4; ++m) _Pragma("unroll") for (int k = 0; k < 2; ++k) dst[m][k] = *(const LAS bf16x8*)(lds + G_SA(b, h) + aoff + m * 2048 + k * 1024); } while (0)
; #define G_LDB(dst, b, h) do { _Pragma("unroll") for (int n = 0; n < 2; ++n) _Pragma("unroll") for (int k = 0; k < 2; ++k) dst[n][k] = *(const LAS bf16x8*)(lds + G_SB(b, h) + boff + n * 2048 + k * 1024); } while (0)
; #define G_MMA(ai, bj, At_, Bt_) do { __builtin_amdgcn_s_setprio(1); _Pragma("unroll") for (int m = 0; m < 4; ++m) _Pragma("unroll") for (int n = 0; n < 2; ++n) _Pragma("unroll") for (int k = 0; k < 2; ++k) \
;         acc[ai][bj][m][n] = __builtin_amdgcn_mfma_f32_16x16x32_bf16(Bt_[n][k], At_[m][k], acc[ai][bj][m][n], 0, 0, 0); __builtin_amdgcn_s_setprio(0); } while (0)
; #define WAIT_V(n) asm volatile("s_waitcnt vmcnt(" #n ")" ::: "memory")
; #define WAIT_L(n) asm volatile("s_waitcnt lgkmcnt(" #n ")" ::: "memory")
; #define BAR __builtin_amdgcn_s_barrier()
; #define SCHED __builtin_amdgcn_sched_barrier(0)
; template <class Get, class Epi>
; DI void gemm_loop(int ntiles, int ld, char* shm, const Get& get, const Epi& epi) {
;     ...
;             G_LDB(B0, 0, 0); G_LDB(B1, 0, 1); SCHED; G_LDA(At, 0, 0); G_STAGE(G_SA(1, 1), a1 + hstep, voffA);
;             WAIT_V(8); WAIT_L(0); BAR; G_MMA(0, 0, At, B0); G_MMA(0, 1, At, B1); BAR; SCHED;
.Lpeel_2892:
	ds_read_b128 v[128:131], v169
	ds_read_b128 v[132:135], v169 offset:1024
	ds_read_b128 v[136:139], v169 offset:2048
	ds_read_b128 v[140:143], v169 offset:3072
	ds_read_b128 v[158:161], v170
	ds_read_b128 v[162:165], v170 offset:1024
	ds_read_b128 v[172:175], v170 offset:2048
	ds_read_b128 v[176:179], v170 offset:3072
	s_add_i32 s83, s44, 2
	s_add_u32 s14, s4, 0x100
	s_addc_u32 s15, s5, 0
	s_cmp_eq_u32 s80, s44
	s_cselect_b32 s44, s42, s81
	s_cselect_b32 s47, s41, s15
	s_cselect_b32 s46, s40, s14
	s_cselect_b32 s45, s43, s82
	v_lshl_add_u64 v[144:145], s[4:5], 0, v[154:155]
	s_add_i32 m0, s49, 0xc000
	ds_read_b128 v[180:183], v171
	ds_read_b128 v[184:187], v171 offset:1024
	ds_read_b128 v[188:191], v171 offset:2048
	ds_read_b128 v[192:195], v171 offset:3072
	ds_read_b128 v[196:199], v171 offset:4096
	ds_read_b128 v[200:203], v171 offset:5120
	ds_read_b128 v[204:207], v171 offset:6144
	ds_read_b128 v[208:211], v171 offset:7168
	global_load_lds_dwordx4 v[144:145], off
	v_lshl_add_u64 v[144:145], s[4:5], 0, v[156:157]
	s_add_i32 m0, s49, 0xe000
	s_nop 0
	global_load_lds_dwordx4 v[144:145], off
	s_cmp_lg_u32 s100, 0
	s_cbranch_scc0 .Lrf_2892_0
	s_waitcnt vmcnt(16)
	s_branch .Lrj_2892_0

; #define G_STAGE(bufoff, gbase, voff) do { _Pragma("unroll") for (int _i = 0; _i < 2; ++_i) \
;         __builtin_amdgcn_global_load_lds((const unsigned*)((const char*)(gbase) + voff[_i]), (LAS unsigned*)(lds + (bufoff) + ldsw + _i * 8192), 16, 0, 0); } while (0)
; #define G_LDA(dst, b, h) do { _Pragma("unroll") for (int m = 0; m < 4; ++m) _Pragma("unroll") for (int k = 0; k < 2; ++k) dst[m][k] = *(const LAS bf16x8*)(lds + G_SA(b, h) + aoff + m * 2048 + k * 1024); } while (0)
; #define G_MMA(ai, bj, At_, Bt_) do { __builtin_amdgcn_s_setprio(1); _Pragma("unroll") for (int m = 0; m < 4; ++m) _Pragma("unroll") for (int n = 0; n < 2; ++n) _Pragma("unroll") for (int k = 0; k < 2; ++k) \
;         acc[ai][bj][m][n] = __builtin_amdgcn_mfma_f32_16x16x32_bf16(Bt_[n][k], At_[m][k], acc[ai][bj][m][n], 0, 0, 0); __builtin_amdgcn_s_setprio(0); } while (0)
; #define WAIT_V(n) asm volatile("s_waitcnt vmcnt(" #n ")" ::: "memory")
; #define WAIT_L(n) asm volatile("s_waitcnt lgkmcnt(" #n ")" ::: "memory")
; #define BAR __builtin_amdgcn_s_barrier()
; #define SCHED __builtin_amdgcn_sched_barrier(0)
; template <class Get, class Epi>
; DI void gemm_loop(int ntiles, int ld, char* shm, const Get& get, const Epi& epi) {
;     ...
;             WAIT_V(8); WAIT_L(0); BAR; G_MMA(0, 0, At, B0); G_MMA(0, 1, At, B1); BAR; SCHED;
;             G_LDA(At, 0, 1); G_STAGE(G_SB(0, 0), b2, voffB); G_STAGE(G_SB(0, 1), b2 + hstep, voffB); G_STAGE(G_SA(0, 0), a2, voffA);
;             WAIT_V(8); WAIT_L(0); BAR; G_MMA(1, 0, At, B0); G_MMA(1, 1, At, B1); BAR; SCHED;
.Lrj_2892_0:
	s_waitcnt lgkmcnt(0)
	s_barrier
	s_setprio 1
	s_waitcnt lgkmcnt(0)
	v_mfma_f32_16x16x32_bf16 v[124:127], v[128:131], v[180:183], 0
	v_mfma_f32_16x16x32_bf16 v[120:123], v[136:139], v[180:183], 0
	v_mfma_f32_16x16x32_bf16 v[116:119], v[128:131], v[188:191], 0
	v_mfma_f32_16x16x32_bf16 v[112:115], v[136:139], v[188:191], 0
	v_mfma_f32_16x16x32_bf16 v[108:111], v[128:131], v[196:199], 0
	v_mfma_f32_16x16x32_bf16 v[104:107], v[136:139], v[196:199], 0
	v_mfma_f32_16x16x32_bf16 v[100:103], v[128:131], v[204:207], 0
	v_mfma_f32_16x16x32_bf16 v[96:99], v[136:139], v[204:207], 0
	v_mfma_f32_16x16x32_bf16 v[124:127], v[132:135], v[184:187], v[124:127]
	v_mfma_f32_16x16x32_bf16 v[120:123], v[140:143], v[184:187], v[120:123]
	v_mfma_f32_16x16x32_bf16 v[116:119], v[132:135], v[192:195], v[116:119]
	v_mfma_f32_16x16x32_bf16 v[112:115], v[140:143], v[192:195], v[112:115]
	v_mfma_f32_16x16x32_bf16 v[108:111], v[132:135], v[200:203], v[108:111]
	v_mfma_f32_16x16x32_bf16 v[104:107], v[140:143], v[200:203], v[104:107]
	v_mfma_f32_16x16x32_bf16 v[100:103], v[132:135], v[208:211], v[100:103]
	v_mfma_f32_16x16x32_bf16 v[96:99], v[140:143], v[208:211], v[96:99]
	s_setprio 0
	s_setprio 1
	v_mfma_f32_16x16x32_bf16 v[60:63], v[158:161], v[180:183], 0
	v_mfma_f32_16x16x32_bf16 v[56:59], v[172:175], v[180:183], 0
	v_mfma_f32_16x16x32_bf16 v[52:55], v[158:161], v[188:191], 0
	v_mfma_f32_16x16x32_bf16 v[48:51], v[172:175], v[188:191], 0
	v_mfma_f32_16x16x32_bf16 v[44:47], v[158:161], v[196:199], 0
	v_mfma_f32_16x16x32_bf16 v[40:43], v[172:175], v[196:199], 0
	v_mfma_f32_16x16x32_bf16 v[36:39], v[158:161], v[204:207], 0
	v_mfma_f32_16x16x32_bf16 v[32:35], v[172:175], v[204:207], 0
	v_mfma_f32_16x16x32_bf16 v[60:63], v[162:165], v[184:187], v[60:63]
	v_mfma_f32_16x16x32_bf16 v[56:59], v[176:179], v[184:187], v[56:59]
	v_mfma_f32_16x16x32_bf16 v[52:55], v[162:165], v[192:195], v[52:55]
	v_mfma_f32_16x16x32_bf16 v[48:51], v[176:179], v[192:195], v[48:51]
	v_mfma_f32_16x16x32_bf16 v[44:47], v[162:165], v[200:203], v[44:47]
	v_mfma_f32_16x16x32_bf16 v[40:43], v[176:179], v[200:203], v[40:43]
	v_mfma_f32_16x16x32_bf16 v[36:39], v[162:165], v[208:211], v[36:39]
	v_mfma_f32_16x16x32_bf16 v[32:35], v[176:179], v[208:211], v[32:35]
	s_setprio 0
	s_barrier
	s_add_i32 s4, s58, s48
	v_lshl_add_u64 v[144:145], s[44:45], 0, v[148:149]
	s_mov_b32 m0, s4
	ds_read_b128 v[180:183], v171 offset:16384
	ds_read_b128 v[184:187], v171 offset:17408
	ds_read_b128 v[188:191], v171 offset:18432
	ds_read_b128 v[192:195], v171 offset:19456
	ds_read_b128 v[196:199], v171 offset:20480
	ds_read_b128 v[200:203], v171 offset:21504
	ds_read_b128 v[204:207], v171 offset:22528
	ds_read_b128 v[208:211], v171 offset:23552
	global_load_lds_dwordx4 v[144:145], off
	s_add_i32 m0, s4, 0x2000
	s_add_u32 s4, s44, 0xb0000
	v_lshl_add_u64 v[166:167], s[44:45], 0, v[152:153]
	s_addc_u32 s5, s45, 0
	s_add_i32 s84, s59, s48
	global_load_lds_dwordx4 v[166:167], off
	v_lshl_add_u64 v[212:213], s[4:5], 0, v[148:149]
	s_mov_b32 m0, s84
	v_lshl_add_u64 v[214:215], s[46:47], 0, v[150:151]
	global_load_lds_dwordx4 v[212:213], off
	v_lshl_add_u64 v[212:213], s[4:5], 0, v[152:153]
	s_add_i32 m0, s84, 0x2000
	s_nop 0
	global_load_lds_dwordx4 v[212:213], off
	v_lshl_add_u64 v[212:213], s[46:47], 0, v[146:147]
	s_mov_b32 m0, s49
	s_nop 0
	global_load_lds_dwordx4 v[212:213], off
	s_mov_b32 m0, s50
	s_nop 0
	global_load_lds_dwordx4 v[214:215], off
	s_cmp_lg_u32 s100, 0
	s_cbranch_scc0 .Lrf_2892_1
	s_waitcnt vmcnt(16)
	s_branch .Lrj_2892_1

; #define G_STAGE(bufoff, gbase, voff) do { _Pragma("unroll") for (int _i = 0; _i < 2; ++_i) \
;         __builtin_amdgcn_global_load_lds((const unsigned*)((const char*)(gbase) + voff[_i]), (LAS unsigned*)(lds + (bufoff) + ldsw + _i * 8192), 16, 0, 0); } while (0)
; #define G_LDA(dst, b, h) do { _Pragma("unroll") for (int m = 0; m < 4; ++m) _Pragma("unroll") for (int k = 0; k < 2; ++k) dst[m][k] = *(const LAS bf16x8*)(lds + G_SA(b, h) + aoff + m * 2048 + k * 1024); } while (0)
; #define G_LDB(dst, b, h) do { _Pragma("unroll") for (int n = 0; n < 2; ++n) _Pragma("unroll") for (int k = 0; k < 2; ++k) dst[n][k] = *(const LAS bf16x8*)(lds + G_SB(b, h) + boff + n * 2048 + k * 1024); } while (0)
; #define G_MMA(ai, bj, At_, Bt_) do { __builtin_amdgcn_s_setprio(1); _Pragma("unroll") for (int m = 0; m < 4; ++m) _Pragma("unroll") for (int n = 0; n < 2; ++n) _Pragma("unroll") for (int k = 0; k < 2; ++k) \
;         acc[ai][bj][m][n] = __builtin_amdgcn_mfma_f32_16x16x32_bf16(Bt_[n][k], At_[m][k], acc[ai][bj][m][n], 0, 0, 0); __builtin_amdgcn_s_setprio(0); } while (0)
; #define WAIT_V(n) asm volatile("s_waitcnt vmcnt(" #n ")" ::: "memory")
; #define WAIT_L(n) asm volatile("s_waitcnt lgkmcnt(" #n ")" ::: "memory")
; #define BAR __builtin_amdgcn_s_barrier()
; #define SCHED __builtin_amdgcn_sched_barrier(0)
; template <class Get, class Epi>
; DI void gemm_loop(int ntiles, int ld, char* shm, const Get& get, const Epi& epi) {
;     ...
;             WAIT_V(8); WAIT_L(0); BAR; G_MMA(1, 0, At, B0); G_MMA(1, 1, At, B1); BAR; SCHED;
;             G_LDB(B0, 1, 0); G_LDB(B1, 1, 1); SCHED; G_LDA(At, 1, 0); G_STAGE(G_SA(0, 1), a2 + hstep, voffA);
;             WAIT_V(8); WAIT_L(0); BAR; G_MMA(0, 0, At, B0); G_MMA(0, 1, At, B1); BAR; SCHED;
.Lrj_2892_1:
	s_waitcnt lgkmcnt(0)
	s_barrier
	s_setprio 1
	s_waitcnt lgkmcnt(0)
	v_mfma_f32_16x16x32_bf16 v[92:95], v[128:131], v[180:183], 0
	v_mfma_f32_16x16x32_bf16 v[88:91], v[136:139], v[180:183], 0
	v_mfma_f32_16x16x32_bf16 v[84:87], v[128:131], v[188:191], 0
	v_mfma_f32_16x16x32_bf16 v[80:83], v[136:139], v[188:191], 0
	v_mfma_f32_16x16x32_bf16 v[76:79], v[128:131], v[196:199], 0
	v_mfma_f32_16x16x32_bf16 v[72:75], v[136:139], v[196:199], 0
	v_mfma_f32_16x16x32_bf16 v[68:71], v[128:131], v[204:207], 0
	v_mfma_f32_16x16x32_bf16 v[64:67], v[136:139], v[204:207], 0
	v_mfma_f32_16x16x32_bf16 v[92:95], v[132:135], v[184:187], v[92:95]
	v_mfma_f32_16x16x32_bf16 v[88:91], v[140:143], v[184:187], v[88:91]
	v_mfma_f32_16x16x32_bf16 v[84:87], v[132:135], v[192:195], v[84:87]
	v_mfma_f32_16x16x32_bf16 v[80:83], v[140:143], v[192:195], v[80:83]
	v_mfma_f32_16x16x32_bf16 v[76:79], v[132:135], v[200:203], v[76:79]
	v_mfma_f32_16x16x32_bf16 v[72:75], v[140:143], v[200:203], v[72:75]
	v_mfma_f32_16x16x32_bf16 v[68:71], v[132:135], v[208:211], v[68:71]
	v_mfma_f32_16x16x32_bf16 v[64:67], v[140:143], v[208:211], v[64:67]
	s_setprio 0
	s_setprio 1
	v_mfma_f32_16x16x32_bf16 v[28:31], v[158:161], v[180:183], 0
	v_mfma_f32_16x16x32_bf16 v[24:27], v[172:175], v[180:183], 0
	v_mfma_f32_16x16x32_bf16 v[20:23], v[158:161], v[188:191], 0
	v_mfma_f32_16x16x32_bf16 v[16:19], v[172:175], v[188:191], 0
	v_mfma_f32_16x16x32_bf16 v[12:15], v[158:161], v[196:199], 0
	v_mfma_f32_16x16x32_bf16 v[8:11], v[172:175], v[196:199], 0
	v_mfma_f32_16x16x32_bf16 v[4:7], v[158:161], v[204:207], 0
	v_mfma_f32_16x16x32_bf16 v[0:3], v[172:175], v[204:207], 0
	v_mfma_f32_16x16x32_bf16 v[28:31], v[162:165], v[184:187], v[28:31]
	v_mfma_f32_16x16x32_bf16 v[24:27], v[176:179], v[184:187], v[24:27]
	v_mfma_f32_16x16x32_bf16 v[20:23], v[162:165], v[192:195], v[20:23]
	v_mfma_f32_16x16x32_bf16 v[16:19], v[176:179], v[192:195], v[16:19]
	v_mfma_f32_16x16x32_bf16 v[12:15], v[162:165], v[200:203], v[12:15]
	v_mfma_f32_16x16x32_bf16 v[8:11], v[176:179], v[200:203], v[8:11]
	v_mfma_f32_16x16x32_bf16 v[4:7], v[162:165], v[208:211], v[4:7]
	v_mfma_f32_16x16x32_bf16 v[0:3], v[176:179], v[208:211], v[0:3]
	s_setprio 0
	s_barrier
	s_add_i32 s84, 0, 0x18000
	s_add_i32 s85, 0, 0x1c000
	v_add_u32_e32 v140, s84, v168
	v_add_u32_e32 v176, s85, v168
	ds_read_b128 v[128:131], v140
	ds_read_b128 v[132:135], v140 offset:1024
	ds_read_b128 v[136:139], v140 offset:2048
	ds_read_b128 v[140:143], v140 offset:3072
	ds_read_b128 v[158:161], v176
	ds_read_b128 v[162:165], v176 offset:1024
	ds_read_b128 v[172:175], v176 offset:2048
	ds_read_b128 v[176:179], v176 offset:3072
	s_add_u32 s4, s46, 0xb0000
	s_addc_u32 s5, s47, 0
	s_mov_b32 m0, s51
	v_lshl_add_u64 v[216:217], s[4:5], 0, v[146:147]
	ds_read_b128 v[180:183], v171 offset:32768
	ds_read_b128 v[184:187], v171 offset:33792
	ds_read_b128 v[188:191], v171 offset:34816
	ds_read_b128 v[192:195], v171 offset:35840
	ds_read_b128 v[196:199], v171 offset:36864
	ds_read_b128 v[200:203], v171 offset:37888
	ds_read_b128 v[204:207], v171 offset:38912
	ds_read_b128 v[208:211], v171 offset:39936
	global_load_lds_dwordx4 v[216:217], off
	v_lshl_add_u64 v[216:217], s[4:5], 0, v[150:151]
	s_mov_b32 m0, s52
	s_nop 0
	global_load_lds_dwordx4 v[216:217], off
	s_waitcnt vmcnt(8)
	s_waitcnt lgkmcnt(0)
	s_barrier
	s_setprio 1
	s_waitcnt lgkmcnt(0)
	v_mfma_f32_16x16x32_bf16 v[124:127], v[128:131], v[180:183], v[124:127]
	v_mfma_f32_16x16x32_bf16 v[120:123], v[136:139], v[180:183], v[120:123]
	v_mfma_f32_16x16x32_bf16 v[116:119], v[128:131], v[188:191], v[116:119]
	v_mfma_f32_16x16x32_bf16 v[112:115], v[136:139], v[188:191], v[112:115]
	v_mfma_f32_16x16x32_bf16 v[108:111], v[128:131], v[196:199], v[108:111]
	v_mfma_f32_16x16x32_bf16 v[104:107], v[136:139], v[196:199], v[104:107]
	v_mfma_f32_16x16x32_bf16 v[100:103], v[128:131], v[204:207], v[100:103]
	v_mfma_f32_16x16x32_bf16 v[96:99], v[136:139], v[204:207], v[96:99]
	v_mfma_f32_16x16x32_bf16 v[124:127], v[132:135], v[184:187], v[124:127]
	v_mfma_f32_16x16x32_bf16 v[120:123], v[140:143], v[184:187], v[120:123]
	v_mfma_f32_16x16x32_bf16 v[116:119], v[132:135], v[192:195], v[116:119]
	v_mfma_f32_16x16x32_bf16 v[112:115], v[140:143], v[192:195], v[112:115]
	v_mfma_f32_16x16x32_bf16 v[108:111], v[132:135], v[200:203], v[108:111]
	v_mfma_f32_16x16x32_bf16 v[104:107], v[140:143], v[200:203], v[104:107]
	v_mfma_f32_16x16x32_bf16 v[100:103], v[132:135], v[208:211], v[100:103]
	v_mfma_f32_16x16x32_bf16 v[96:99], v[140:143], v[208:211], v[96:99]
	s_setprio 0
	s_setprio 1
	v_mfma_f32_16x16x32_bf16 v[60:63], v[158:161], v[180:183], v[60:63]
	v_mfma_f32_16x16x32_bf16 v[56:59], v[172:175], v[180:183], v[56:59]
	v_mfma_f32_16x16x32_bf16 v[52:55], v[158:161], v[188:191], v[52:55]
	v_mfma_f32_16x16x32_bf16 v[48:51], v[172:175], v[188:191], v[48:51]
	v_mfma_f32_16x16x32_bf16 v[44:47], v[158:161], v[196:199], v[44:47]
	v_mfma_f32_16x16x32_bf16 v[40:43], v[172:175], v[196:199], v[40:43]
	v_mfma_f32_16x16x32_bf16 v[36:39], v[158:161], v[204:207], v[36:39]
	v_mfma_f32_16x16x32_bf16 v[32:35], v[172:175], v[204:207], v[32:35]
	v_mfma_f32_16x16x32_bf16 v[60:63], v[162:165], v[184:187], v[60:63]
	v_mfma_f32_16x16x32_bf16 v[56:59], v[176:179], v[184:187], v[56:59]
	v_mfma_f32_16x16x32_bf16 v[52:55], v[162:165], v[192:195], v[52:55]
	v_mfma_f32_16x16x32_bf16 v[48:51], v[176:179], v[192:195], v[48:51]
	v_mfma_f32_16x16x32_bf16 v[44:47], v[162:165], v[200:203], v[44:47]
	v_mfma_f32_16x16x32_bf16 v[40:43], v[176:179], v[200:203], v[40:43]
	v_mfma_f32_16x16x32_bf16 v[36:39], v[162:165], v[208:211], v[36:39]
	v_mfma_f32_16x16x32_bf16 v[32:35], v[176:179], v[208:211], v[32:35]
	s_setprio 0
	s_barrier
; #define G_STAGE(bufoff, gbase, voff) do { _Pragma("unroll") for (int _i = 0; _i < 2; ++_i) \
;         __builtin_amdgcn_global_load_lds((const unsigned*)((const char*)(gbase) + voff[_i]), (LAS unsigned*)(lds + (bufoff) + ldsw + _i * 8192), 16, 0, 0); } while (0)
; #define G_LDA(dst, b, h) do { _Pragma("unroll") for (int m = 0; m < 4; ++m) _Pragma("unroll") for (int k = 0; k < 2; ++k) dst[m][k] = *(const LAS bf16x8*)(lds + G_SA(b, h) + aoff + m * 2048 + k * 1024); } while (0)
; #define G_MMA(ai, bj, At_, Bt_) do { __builtin_amdgcn_s_setprio(1); _Pragma("unroll") for (int m = 0; m < 4; ++m) _Pragma("unroll") for (int n = 0; n < 2; ++n) _Pragma("unroll") for (int k = 0; k < 2; ++k) \
;         acc[ai][bj][m][n] = __builtin_amdgcn_mfma_f32_16x16x32_bf16(Bt_[n][k], At_[m][k], acc[ai][bj][m][n], 0, 0, 0); __builtin_amdgcn_s_setprio(0); } while (0)
; #define WAIT_V(n) asm volatile("s_waitcnt vmcnt(" #n ")" ::: "memory")
; #define WAIT_L(n) asm volatile("s_waitcnt lgkmcnt(" #n ")" ::: "memory")
; #define BAR __builtin_amdgcn_s_barrier()
; #define SCHED __builtin_amdgcn_sched_barrier(0)
; template <class Get, class Epi>
; DI void gemm_loop(int ntiles, int ld, char* shm, const Get& get, const Epi& epi) {
;     ...
;             G_LDA(At, 1, 1); G_STAGE(G_SB(1, 0), b3, voffB); G_STAGE(G_SB(1, 1), b3 + hstep, voffB); G_STAGE(G_SA(1, 0), a3, voffA);
;             WAIT_V(8); WAIT_L(0); BAR; G_MMA(1, 0, At, B0); G_MMA(1, 1, At, B1); BAR; SCHED;
;         }
	s_add_i32 s4, s84, s48
	v_lshl_add_u64 v[144:145], v[144:145], 0, s[10:11]
	s_mov_b32 m0, s4
	ds_read_b128 v[180:183], v171 offset:49152
	ds_read_b128 v[184:187], v171 offset:50176
	ds_read_b128 v[188:191], v171 offset:51200
	ds_read_b128 v[192:195], v171 offset:52224
	ds_read_b128 v[196:199], v171 offset:53248
	ds_read_b128 v[200:203], v171 offset:54272
	ds_read_b128 v[204:207], v171 offset:55296
	ds_read_b128 v[208:211], v171 offset:56320
	global_load_lds_dwordx4 v[144:145], off
	s_add_i32 m0, s4, 0x2000
	s_add_u32 s4, s44, 0xb0080
	v_lshl_add_u64 v[144:145], v[166:167], 0, s[10:11]
	s_addc_u32 s5, s45, 0
	s_add_i32 s44, s85, s48
	global_load_lds_dwordx4 v[144:145], off
	v_lshl_add_u64 v[144:145], s[4:5], 0, v[148:149]
	s_mov_b32 m0, s44
	s_nop 0
	global_load_lds_dwordx4 v[144:145], off
	v_lshl_add_u64 v[144:145], s[4:5], 0, v[152:153]
	s_add_i32 m0, s44, 0x2000
	s_nop 0
	global_load_lds_dwordx4 v[144:145], off
	v_lshl_add_u64 v[144:145], v[212:213], 0, s[10:11]
	s_mov_b32 m0, s55
	s_nop 0
	global_load_lds_dwordx4 v[144:145], off
	v_lshl_add_u64 v[144:145], v[214:215], 0, s[10:11]
	s_mov_b32 m0, s56
	s_nop 0
	global_load_lds_dwordx4 v[144:145], off
	s_waitcnt vmcnt(8)
	s_waitcnt lgkmcnt(0)
	s_barrier
	s_setprio 1
	s_waitcnt lgkmcnt(0)
	v_mfma_f32_16x16x32_bf16 v[92:95], v[128:131], v[180:183], v[92:95]
	v_mfma_f32_16x16x32_bf16 v[88:91], v[136:139], v[180:183], v[88:91]
	v_mfma_f32_16x16x32_bf16 v[84:87], v[128:131], v[188:191], v[84:87]
	v_mfma_f32_16x16x32_bf16 v[80:83], v[136:139], v[188:191], v[80:83]
	v_mfma_f32_16x16x32_bf16 v[76:79], v[128:131], v[196:199], v[76:79]
	v_mfma_f32_16x16x32_bf16 v[72:75], v[136:139], v[196:199], v[72:75]
	v_mfma_f32_16x16x32_bf16 v[68:71], v[128:131], v[204:207], v[68:71]
	v_mfma_f32_16x16x32_bf16 v[64:67], v[136:139], v[204:207], v[64:67]
	v_mfma_f32_16x16x32_bf16 v[92:95], v[132:135], v[184:187], v[92:95]
	v_mfma_f32_16x16x32_bf16 v[88:91], v[140:143], v[184:187], v[88:91]
	v_mfma_f32_16x16x32_bf16 v[84:87], v[132:135], v[192:195], v[84:87]
	v_mfma_f32_16x16x32_bf16 v[80:83], v[140:143], v[192:195], v[80:83]
	v_mfma_f32_16x16x32_bf16 v[76:79], v[132:135], v[200:203], v[76:79]
	v_mfma_f32_16x16x32_bf16 v[72:75], v[140:143], v[200:203], v[72:75]
	v_mfma_f32_16x16x32_bf16 v[68:71], v[132:135], v[208:211], v[68:71]
	v_mfma_f32_16x16x32_bf16 v[64:67], v[140:143], v[208:211], v[64:67]
	s_setprio 0
	s_setprio 1
	v_mfma_f32_16x16x32_bf16 v[28:31], v[158:161], v[180:183], v[28:31]
	v_mfma_f32_16x16x32_bf16 v[24:27], v[172:175], v[180:183], v[24:27]
	v_mfma_f32_16x16x32_bf16 v[20:23], v[158:161], v[188:191], v[20:23]
	v_mfma_f32_16x16x32_bf16 v[16:19], v[172:175], v[188:191], v[16:19]
	v_mfma_f32_16x16x32_bf16 v[12:15], v[158:161], v[196:199], v[12:15]
	v_mfma_f32_16x16x32_bf16 v[8:11], v[172:175], v[196:199], v[8:11]
	v_mfma_f32_16x16x32_bf16 v[4:7], v[158:161], v[204:207], v[4:7]
	v_mfma_f32_16x16x32_bf16 v[0:3], v[172:175], v[204:207], v[0:3]
	v_mfma_f32_16x16x32_bf16 v[28:31], v[162:165], v[184:187], v[28:31]
	v_mfma_f32_16x16x32_bf16 v[24:27], v[176:179], v[184:187], v[24:27]
	v_mfma_f32_16x16x32_bf16 v[20:23], v[162:165], v[192:195], v[20:23]
	v_mfma_f32_16x16x32_bf16 v[16:19], v[176:179], v[192:195], v[16:19]
	v_mfma_f32_16x16x32_bf16 v[12:15], v[162:165], v[200:203], v[12:15]
	v_mfma_f32_16x16x32_bf16 v[8:11], v[176:179], v[200:203], v[8:11]
	v_mfma_f32_16x16x32_bf16 v[4:7], v[162:165], v[208:211], v[4:7]
	v_mfma_f32_16x16x32_bf16 v[0:3], v[176:179], v[208:211], v[0:3]
	s_setprio 0
	s_barrier
	s_add_u32 s81, s81, 0x100
	s_addc_u32 s82, s82, 0
	s_cmp_ge_u32 s83, s79
	s_mov_b64 s[4:5], s[14:15]
	s_mov_b32 s44, s83
	s_cbranch_scc0 .LBB0_2892
	s_branch .Lpost_2892

; #define G_STAGE(bufoff, gbase, voff) do { _Pragma("unroll") for (int _i = 0; _i < 2; ++_i) \
;         __builtin_amdgcn_global_load_lds((const unsigned*)((const char*)(gbase) + voff[_i]), (LAS unsigned*)(lds + (bufoff) + ldsw + _i * 8192), 16, 0, 0); } while (0)
; #define WAIT_V(n) asm volatile("s_waitcnt vmcnt(" #n ")" ::: "memory")
; #define BAR __builtin_amdgcn_s_barrier()
; template <class Get, class Epi>
; DI void gemm_loop(int ntiles, int ld, char* shm, const Get& get, const Epi& epi) {
;     ...
;     const int aoff = lds_byte(wr * 64 + fr, fq * 8), boff = lds_byte(wc * 32 + fr, fq * 8);
;     ...
;     const char* cA = (const char*)cur.A + (size_t)cur.brow * ld * 2; const char* cB = (const char*)cur.Bt + (size_t)cur.bcol * ld * 2;
;     G_STAGE(G_SB(0, 0), cB, voffB); G_STAGE(G_SB(0, 1), cB + hstep, voffB); G_STAGE(G_SA(0, 0), cA, voffA); G_STAGE(G_SA(0, 1), cA + hstep, voffA);
;     if (wr == 1) BAR;
;     WAIT_V(2); BAR;
;     G_STAGE(G_SB(1, 0), cB + kstep, voffB); G_STAGE(G_SA(1, 0), cA + kstep, voffA); G_STAGE(G_SB(1, 1), cB + hstep + kstep, voffB);
;     WAIT_V(6); BAR;
.LBB0_3131:
	s_lshl_b32 s11, s8, 13
	s_lshl_b32 s8, s13, 12
	s_and_b32 s13, s8, 0x3000
	s_mov_b64 s[8:9], 0x80
	s_add_i32 m0, s35, 0x18000
	v_lshl_add_u64 v[6:7], v[6:7], 0, s[8:9]
	s_waitcnt vmcnt(2)
	s_barrier
	global_load_lds_dwordx4 v[6:7], off
	v_lshl_add_u64 v[4:5], v[4:5], 0, s[8:9]
	s_add_i32 m0, s35, 0x1a000
	s_add_i32 s55, s35, 0x8000
	s_add_i32 s56, s35, 0xa000
	global_load_lds_dwordx4 v[4:5], off
	v_lshl_add_u64 v[0:1], v[0:1], 0, s[8:9]
	s_mov_b32 m0, s55
	s_add_u32 s30, s14, 0x40080
	global_load_lds_dwordx4 v[0:1], off
	v_lshl_add_u64 v[0:1], v[2:3], 0, s[8:9]
	s_mov_b32 m0, s56
	s_addc_u32 s31, s15, 0
	global_load_lds_dwordx4 v[0:1], off
	s_add_i32 m0, s35, 0x1c000
	v_lshl_add_u64 v[0:1], s[30:31], 0, v[130:131]
	global_load_lds_dwordx4 v[0:1], off
	v_lshl_add_u64 v[0:1], s[30:31], 0, v[134:135]
	s_add_i32 m0, s35, 0x1e000
	v_lshlrev_b32_e32 v3, 2, v8
	global_load_lds_dwordx4 v[0:1], off
	v_and_b32_e32 v0, 15, v8
	v_and_b32_e32 v1, 48, v8
	v_lshlrev_b32_e32 v0, 6, v0
	v_and_b32_e32 v3, 32, v3
	v_or_b32_e32 v2, v0, v1
	v_bitop3_b32 v0, v0, v3, v1 bitop3:0x36
	v_or_b32_e32 v140, s13, v0
	v_lshlrev_b32_e32 v0, 14, v9
	v_and_b32_e32 v0, 0xffff8000, v0
	v_bitop3_b32 v1, v2, s11, v3 bitop3:0xde
	v_lshl_add_u32 v0, v10, 11, v0
	v_and_b32_e32 v2, 1, v9
	v_lshl_or_b32 v0, v2, 6, v0
	v_lshl_add_u32 v136, v11, 1, v0
	v_lshlrev_b32_e32 v0, 14, v12
	s_cmpk_lt_u32 s12, 0x100
	v_and_b32_e32 v0, 0xffff8000, v0
	s_waitcnt vmcnt(6)
	s_mov_b32 s100, 0
	s_cselect_b64 s[12:13], -1, 0
	s_add_u32 s30, s68, 0x1d5a000
	v_lshl_add_u32 v0, v13, 11, v0
	v_and_b32_e32 v2, 1, v12
	s_addc_u32 s31, s69, 0
	v_lshl_or_b32 v0, v2, 6, v0
	s_add_i32 s57, 0, 0x10000
	s_add_i32 s58, 0, 0x14000
	v_mov_b32_e32 v137, v131
	v_lshl_add_u32 v138, v14, 1, v0
	v_mov_b32_e32 v139, v131
	v_add_u32_e32 v141, s57, v140
	v_add_u32_e32 v142, s58, v140
	v_add_u32_e32 v143, 0, v1
	s_barrier
	s_branch .LBB0_3134

; #define G_STAGE(bufoff, gbase, voff) do { _Pragma("unroll") for (int _i = 0; _i < 2; ++_i) \
;         __builtin_amdgcn_global_load_lds((const unsigned*)((const char*)(gbase) + voff[_i]), (LAS unsigned*)(lds + (bufoff) + ldsw + _i * 8192), 16, 0, 0); } while (0)
; #define G_LDA(dst, b, h) do { _Pragma("unroll") for (int m = 0; m < 4; ++m) _Pragma("unroll") for (int k = 0; k < 2; ++k) dst[m][k] = *(const LAS bf16x8*)(lds + G_SA(b, h) + aoff + m * 2048 + k * 1024); } while (0)
; #define G_LDB(dst, b, h) do { _Pragma("unroll") for (int n = 0; n < 2; ++n) _Pragma("unroll") for (int k = 0; k < 2; ++k) dst[n][k] = *(const LAS bf16x8*)(lds + G_SB(b, h) + boff + n * 2048 + k * 1024); } while (0)
; #define G_MMA(ai, bj, At_, Bt_) do { __builtin_amdgcn_s_setprio(1); _Pragma("unroll") for (int m = 0; m < 4; ++m) _Pragma("unroll") for (int n = 0; n < 2; ++n) _Pragma("unroll") for (int k = 0; k < 2; ++k) \
;         acc[ai][bj][m][n] = __builtin_amdgcn_mfma_f32_16x16x32_bf16(Bt_[n][k], At_[m][k], acc[ai][bj][m][n], 0, 0, 0); __builtin_amdgcn_s_setprio(0); } while (0)
; #define WAIT_V(n) asm volatile("s_waitcnt vmcnt(" #n ")" ::: "memory")
; #define WAIT_L(n) asm volatile("s_waitcnt lgkmcnt(" #n ")" ::: "memory")
; #define BAR __builtin_amdgcn_s_barrier()
; #define SCHED __builtin_amdgcn_sched_barrier(0)
; template <class Get, class Epi>
; DI void gemm_loop(int ntiles, int ld, char* shm, const Get& get, const Epi& epi) {
;     ...
;             G_LDB(B0, 0, 0); G_LDB(B1, 0, 1); SCHED; G_LDA(At, 0, 0); G_STAGE(G_SA(1, 1), a1 + hstep, voffA);
;             WAIT_V(8); WAIT_L(0); BAR; G_MMA(0, 0, At, B0); G_MMA(0, 1, At, B1); BAR; SCHED;
.Lpeel_3141:
	ds_read_b128 v[144:147], v141
	ds_read_b128 v[148:151], v141 offset:1024
	ds_read_b128 v[152:155], v141 offset:2048
	ds_read_b128 v[156:159], v141 offset:3072
	ds_read_b128 v[160:163], v142
	ds_read_b128 v[164:167], v142 offset:1024
	ds_read_b128 v[168:171], v142 offset:2048
	ds_read_b128 v[172:175], v142 offset:3072
	s_add_u32 s14, s48, 0xfffc0080
	s_addc_u32 s15, s49, -1
	s_cmp_eq_u32 s70, 12
	s_cselect_b32 s47, s11, s15
	s_cselect_b32 s46, s39, s14
	s_cselect_b32 s15, s41, s65
	s_cselect_b32 s14, s63, s64
	v_lshl_add_u64 v[208:209], s[48:49], 0, v[136:137]
	s_add_i32 m0, s35, 0xc000
	ds_read_b128 v[176:179], v143
	ds_read_b128 v[180:183], v143 offset:1024
	ds_read_b128 v[184:187], v143 offset:2048
	ds_read_b128 v[188:191], v143 offset:3072
	ds_read_b128 v[192:195], v143 offset:4096
	ds_read_b128 v[196:199], v143 offset:5120
	ds_read_b128 v[200:203], v143 offset:6144
	ds_read_b128 v[204:207], v143 offset:7168
	global_load_lds_dwordx4 v[208:209], off
	v_lshl_add_u64 v[208:209], s[48:49], 0, v[138:139]
	s_add_i32 m0, s35, 0xe000
	s_nop 0
	global_load_lds_dwordx4 v[208:209], off
	s_cmp_lg_u32 s100, 0
	s_cbranch_scc0 .Lrf_3141_0
	s_waitcnt vmcnt(16)
	s_branch .Lrj_3141_0

; #define G_STAGE(bufoff, gbase, voff) do { _Pragma("unroll") for (int _i = 0; _i < 2; ++_i) \
;         __builtin_amdgcn_global_load_lds((const unsigned*)((const char*)(gbase) + voff[_i]), (LAS unsigned*)(lds + (bufoff) + ldsw + _i * 8192), 16, 0, 0); } while (0)
; #define G_LDA(dst, b, h) do { _Pragma("unroll") for (int m = 0; m < 4; ++m) _Pragma("unroll") for (int k = 0; k < 2; ++k) dst[m][k] = *(const LAS bf16x8*)(lds + G_SA(b, h) + aoff + m * 2048 + k * 1024); } while (0)
; #define G_MMA(ai, bj, At_, Bt_) do { __builtin_amdgcn_s_setprio(1); _Pragma("unroll") for (int m = 0; m < 4; ++m) _Pragma("unroll") for (int n = 0; n < 2; ++n) _Pragma("unroll") for (int k = 0; k < 2; ++k) \
;         acc[ai][bj][m][n] = __builtin_amdgcn_mfma_f32_16x16x32_bf16(Bt_[n][k], At_[m][k], acc[ai][bj][m][n], 0, 0, 0); __builtin_amdgcn_s_setprio(0); } while (0)
; #define WAIT_V(n) asm volatile("s_waitcnt vmcnt(" #n ")" ::: "memory")
; #define WAIT_L(n) asm volatile("s_waitcnt lgkmcnt(" #n ")" ::: "memory")
; #define BAR __builtin_amdgcn_s_barrier()
; #define SCHED __builtin_amdgcn_sched_barrier(0)
; template <class Get, class Epi>
; DI void gemm_loop(int ntiles, int ld, char* shm, const Get& get, const Epi& epi) {
;     ...
;             WAIT_V(8); WAIT_L(0); BAR; G_MMA(0, 0, At, B0); G_MMA(0, 1, At, B1); BAR; SCHED;
;             G_LDA(At, 0, 1); G_STAGE(G_SB(0, 0), b2, voffB); G_STAGE(G_SB(0, 1), b2 + hstep, voffB); G_STAGE(G_SA(0, 0), a2, voffA);
;             WAIT_V(8); WAIT_L(0); BAR; G_MMA(1, 0, At, B0); G_MMA(1, 1, At, B1); BAR; SCHED;
.Lrj_3141_0:
	s_waitcnt lgkmcnt(0)
	s_barrier
	s_setprio 1
	s_waitcnt lgkmcnt(0)
	v_mfma_f32_16x16x32_bf16 v[124:127], v[144:147], v[176:179], 0
	v_mfma_f32_16x16x32_bf16 v[120:123], v[152:155], v[176:179], 0
	v_mfma_f32_16x16x32_bf16 v[116:119], v[144:147], v[184:187], 0
	v_mfma_f32_16x16x32_bf16 v[112:115], v[152:155], v[184:187], 0
	v_mfma_f32_16x16x32_bf16 v[100:103], v[144:147], v[192:195], 0
	v_mfma_f32_16x16x32_bf16 v[96:99], v[152:155], v[192:195], 0
	v_mfma_f32_16x16x32_bf16 v[84:87], v[144:147], v[200:203], 0
	v_mfma_f32_16x16x32_bf16 v[80:83], v[152:155], v[200:203], 0
	v_mfma_f32_16x16x32_bf16 v[124:127], v[148:151], v[180:183], v[124:127]
	v_mfma_f32_16x16x32_bf16 v[120:123], v[156:159], v[180:183], v[120:123]
	v_mfma_f32_16x16x32_bf16 v[116:119], v[148:151], v[188:191], v[116:119]
	v_mfma_f32_16x16x32_bf16 v[112:115], v[156:159], v[188:191], v[112:115]
	v_mfma_f32_16x16x32_bf16 v[100:103], v[148:151], v[196:199], v[100:103]
	v_mfma_f32_16x16x32_bf16 v[96:99], v[156:159], v[196:199], v[96:99]
	v_mfma_f32_16x16x32_bf16 v[84:87], v[148:151], v[204:207], v[84:87]
	v_mfma_f32_16x16x32_bf16 v[80:83], v[156:159], v[204:207], v[80:83]
	s_setprio 0
	s_setprio 1
	v_mfma_f32_16x16x32_bf16 v[108:111], v[160:163], v[176:179], 0
	v_mfma_f32_16x16x32_bf16 v[104:107], v[168:171], v[176:179], 0
	v_mfma_f32_16x16x32_bf16 v[92:95], v[160:163], v[184:187], 0
	v_mfma_f32_16x16x32_bf16 v[88:91], v[168:171], v[184:187], 0
	v_mfma_f32_16x16x32_bf16 v[76:79], v[160:163], v[192:195], 0
	v_mfma_f32_16x16x32_bf16 v[72:75], v[168:171], v[192:195], 0
	v_mfma_f32_16x16x32_bf16 v[68:71], v[160:163], v[200:203], 0
	v_mfma_f32_16x16x32_bf16 v[64:67], v[168:171], v[200:203], 0
	v_mfma_f32_16x16x32_bf16 v[108:111], v[164:167], v[180:183], v[108:111]
	v_mfma_f32_16x16x32_bf16 v[104:107], v[172:175], v[180:183], v[104:107]
	v_mfma_f32_16x16x32_bf16 v[92:95], v[164:167], v[188:191], v[92:95]
	v_mfma_f32_16x16x32_bf16 v[88:91], v[172:175], v[188:191], v[88:91]
	v_mfma_f32_16x16x32_bf16 v[76:79], v[164:167], v[196:199], v[76:79]
	v_mfma_f32_16x16x32_bf16 v[72:75], v[172:175], v[196:199], v[72:75]
	v_mfma_f32_16x16x32_bf16 v[68:71], v[164:167], v[204:207], v[68:71]
	v_mfma_f32_16x16x32_bf16 v[64:67], v[172:175], v[204:207], v[64:67]
	s_setprio 0
	s_barrier
	s_add_i32 s71, s57, s50
	v_lshl_add_u64 v[208:209], s[14:15], 0, v[130:131]
	s_mov_b32 m0, s71
	ds_read_b128 v[176:179], v143 offset:16384
	ds_read_b128 v[180:183], v143 offset:17408
	ds_read_b128 v[184:187], v143 offset:18432
	ds_read_b128 v[188:191], v143 offset:19456
	ds_read_b128 v[192:195], v143 offset:20480
	ds_read_b128 v[196:199], v143 offset:21504
	ds_read_b128 v[200:203], v143 offset:22528
	ds_read_b128 v[204:207], v143 offset:23552
	global_load_lds_dwordx4 v[208:209], off
	s_add_i32 m0, s71, 0x2000
	s_add_u32 s72, s14, 0x40000
	v_lshl_add_u64 v[210:211], s[14:15], 0, v[134:135]
	s_addc_u32 s73, s15, 0
	s_add_i32 s71, s58, s50
	global_load_lds_dwordx4 v[210:211], off
	v_lshl_add_u64 v[212:213], s[72:73], 0, v[130:131]
	s_mov_b32 m0, s71
	v_lshl_add_u64 v[214:215], s[46:47], 0, v[132:133]
	global_load_lds_dwordx4 v[212:213], off
	v_lshl_add_u64 v[212:213], s[72:73], 0, v[134:135]
	s_add_i32 m0, s71, 0x2000
	s_nop 0
	global_load_lds_dwordx4 v[212:213], off
	v_lshl_add_u64 v[212:213], s[46:47], 0, v[128:129]
	s_mov_b32 m0, s35
	s_nop 0
	global_load_lds_dwordx4 v[212:213], off
	s_mov_b32 m0, s51
	s_nop 0
	global_load_lds_dwordx4 v[214:215], off
	s_cmp_lg_u32 s100, 0
	s_cbranch_scc0 .Lrf_3141_1
	s_waitcnt vmcnt(16)
	s_branch .Lrj_3141_1

; #define G_STAGE(bufoff, gbase, voff) do { _Pragma("unroll") for (int _i = 0; _i < 2; ++_i) \
;         __builtin_amdgcn_global_load_lds((const unsigned*)((const char*)(gbase) + voff[_i]), (LAS unsigned*)(lds + (bufoff) + ldsw + _i * 8192), 16, 0, 0); } while (0)
; #define G_LDA(dst, b, h) do { _Pragma("unroll") for (int m = 0; m < 4; ++m) _Pragma("unroll") for (int k = 0; k < 2; ++k) dst[m][k] = *(const LAS bf16x8*)(lds + G_SA(b, h) + aoff + m * 2048 + k * 1024); } while (0)
; #define G_LDB(dst, b, h) do { _Pragma("unroll") for (int n = 0; n < 2; ++n) _Pragma("unroll") for (int k = 0; k < 2; ++k) dst[n][k] = *(const LAS bf16x8*)(lds + G_SB(b, h) + boff + n * 2048 + k * 1024); } while (0)
; #define G_MMA(ai, bj, At_, Bt_) do { __builtin_amdgcn_s_setprio(1); _Pragma("unroll") for (int m = 0; m < 4; ++m) _Pragma("unroll") for (int n = 0; n < 2; ++n) _Pragma("unroll") for (int k = 0; k < 2; ++k) \
;         acc[ai][bj][m][n] = __builtin_amdgcn_mfma_f32_16x16x32_bf16(Bt_[n][k], At_[m][k], acc[ai][bj][m][n], 0, 0, 0); __builtin_amdgcn_s_setprio(0); } while (0)
; #define WAIT_V(n) asm volatile("s_waitcnt vmcnt(" #n ")" ::: "memory")
; #define WAIT_L(n) asm volatile("s_waitcnt lgkmcnt(" #n ")" ::: "memory")
; #define BAR __builtin_amdgcn_s_barrier()
; #define SCHED __builtin_amdgcn_sched_barrier(0)
; template <class Get, class Epi>
; DI void gemm_loop(int ntiles, int ld, char* shm, const Get& get, const Epi& epi) {
;     ...
;             WAIT_V(8); WAIT_L(0); BAR; G_MMA(1, 0, At, B0); G_MMA(1, 1, At, B1); BAR; SCHED;
;             G_LDB(B0, 1, 0); G_LDB(B1, 1, 1); SCHED; G_LDA(At, 1, 0); G_STAGE(G_SA(0, 1), a2 + hstep, voffA);
;             WAIT_V(8); WAIT_L(0); BAR; G_MMA(0, 0, At, B0); G_MMA(0, 1, At, B1); BAR; SCHED;
.Lrj_3141_1:
	s_waitcnt lgkmcnt(0)
	s_barrier
	s_setprio 1
	s_waitcnt lgkmcnt(0)
	v_mfma_f32_16x16x32_bf16 v[60:63], v[144:147], v[176:179], 0
	v_mfma_f32_16x16x32_bf16 v[56:59], v[152:155], v[176:179], 0
	v_mfma_f32_16x16x32_bf16 v[52:55], v[144:147], v[184:187], 0
	v_mfma_f32_16x16x32_bf16 v[48:51], v[152:155], v[184:187], 0
	v_mfma_f32_16x16x32_bf16 v[36:39], v[144:147], v[192:195], 0
	v_mfma_f32_16x16x32_bf16 v[32:35], v[152:155], v[192:195], 0
	v_mfma_f32_16x16x32_bf16 v[20:23], v[144:147], v[200:203], 0
	v_mfma_f32_16x16x32_bf16 v[16:19], v[152:155], v[200:203], 0
	v_mfma_f32_16x16x32_bf16 v[60:63], v[148:151], v[180:183], v[60:63]
	v_mfma_f32_16x16x32_bf16 v[56:59], v[156:159], v[180:183], v[56:59]
	v_mfma_f32_16x16x32_bf16 v[52:55], v[148:151], v[188:191], v[52:55]
	v_mfma_f32_16x16x32_bf16 v[48:51], v[156:159], v[188:191], v[48:51]
	v_mfma_f32_16x16x32_bf16 v[36:39], v[148:151], v[196:199], v[36:39]
	v_mfma_f32_16x16x32_bf16 v[32:35], v[156:159], v[196:199], v[32:35]
	v_mfma_f32_16x16x32_bf16 v[20:23], v[148:151], v[204:207], v[20:23]
	v_mfma_f32_16x16x32_bf16 v[16:19], v[156:159], v[204:207], v[16:19]
	s_setprio 0
	s_setprio 1
	v_mfma_f32_16x16x32_bf16 v[44:47], v[160:163], v[176:179], 0
	v_mfma_f32_16x16x32_bf16 v[40:43], v[168:171], v[176:179], 0
	v_mfma_f32_16x16x32_bf16 v[28:31], v[160:163], v[184:187], 0
	v_mfma_f32_16x16x32_bf16 v[24:27], v[168:171], v[184:187], 0
	v_mfma_f32_16x16x32_bf16 v[12:15], v[160:163], v[192:195], 0
	v_mfma_f32_16x16x32_bf16 v[8:11], v[168:171], v[192:195], 0
	v_mfma_f32_16x16x32_bf16 v[4:7], v[160:163], v[200:203], 0
	v_mfma_f32_16x16x32_bf16 v[0:3], v[168:171], v[200:203], 0
	v_mfma_f32_16x16x32_bf16 v[44:47], v[164:167], v[180:183], v[44:47]
	v_mfma_f32_16x16x32_bf16 v[40:43], v[172:175], v[180:183], v[40:43]
	v_mfma_f32_16x16x32_bf16 v[28:31], v[164:167], v[188:191], v[28:31]
	v_mfma_f32_16x16x32_bf16 v[24:27], v[172:175], v[188:191], v[24:27]
	v_mfma_f32_16x16x32_bf16 v[12:15], v[164:167], v[196:199], v[12:15]
	v_mfma_f32_16x16x32_bf16 v[8:11], v[172:175], v[196:199], v[8:11]
	v_mfma_f32_16x16x32_bf16 v[4:7], v[164:167], v[204:207], v[4:7]
	v_mfma_f32_16x16x32_bf16 v[0:3], v[172:175], v[204:207], v[0:3]
	s_setprio 0
	s_barrier
	s_add_i32 s71, 0, 0x18000
	s_add_i32 s72, 0, 0x1c000
	v_add_u32_e32 v156, s71, v140
	v_add_u32_e32 v172, s72, v140
	ds_read_b128 v[144:147], v156
	ds_read_b128 v[148:151], v156 offset:1024
	ds_read_b128 v[152:155], v156 offset:2048
	ds_read_b128 v[156:159], v156 offset:3072
	ds_read_b128 v[160:163], v172
	ds_read_b128 v[164:167], v172 offset:1024
	ds_read_b128 v[168:171], v172 offset:2048
	ds_read_b128 v[172:175], v172 offset:3072
	s_add_u32 s46, s46, 0x40000
	s_addc_u32 s47, s47, 0
	s_mov_b32 m0, s52
	v_lshl_add_u64 v[216:217], s[46:47], 0, v[128:129]
	ds_read_b128 v[176:179], v143 offset:32768
	ds_read_b128 v[180:183], v143 offset:33792
	ds_read_b128 v[184:187], v143 offset:34816
	ds_read_b128 v[188:191], v143 offset:35840
	ds_read_b128 v[192:195], v143 offset:36864
	ds_read_b128 v[196:199], v143 offset:37888
	ds_read_b128 v[200:203], v143 offset:38912
	ds_read_b128 v[204:207], v143 offset:39936
	global_load_lds_dwordx4 v[216:217], off
	v_lshl_add_u64 v[216:217], s[46:47], 0, v[132:133]
	s_mov_b32 m0, s53
	s_nop 0
	global_load_lds_dwordx4 v[216:217], off
	s_waitcnt vmcnt(8)
	s_waitcnt lgkmcnt(0)
	s_barrier
	s_setprio 1
	s_waitcnt lgkmcnt(0)
	v_mfma_f32_16x16x32_bf16 v[124:127], v[144:147], v[176:179], v[124:127]
	v_mfma_f32_16x16x32_bf16 v[120:123], v[152:155], v[176:179], v[120:123]
	v_mfma_f32_16x16x32_bf16 v[116:119], v[144:147], v[184:187], v[116:119]
	v_mfma_f32_16x16x32_bf16 v[112:115], v[152:155], v[184:187], v[112:115]
	v_mfma_f32_16x16x32_bf16 v[100:103], v[144:147], v[192:195], v[100:103]
	v_mfma_f32_16x16x32_bf16 v[96:99], v[152:155], v[192:195], v[96:99]
	v_mfma_f32_16x16x32_bf16 v[84:87], v[144:147], v[200:203], v[84:87]
	v_mfma_f32_16x16x32_bf16 v[80:83], v[152:155], v[200:203], v[80:83]
	v_mfma_f32_16x16x32_bf16 v[124:127], v[148:151], v[180:183], v[124:127]
	v_mfma_f32_16x16x32_bf16 v[120:123], v[156:159], v[180:183], v[120:123]
	v_mfma_f32_16x16x32_bf16 v[116:119], v[148:151], v[188:191], v[116:119]
	v_mfma_f32_16x16x32_bf16 v[112:115], v[156:159], v[188:191], v[112:115]
	v_mfma_f32_16x16x32_bf16 v[100:103], v[148:151], v[196:199], v[100:103]
	v_mfma_f32_16x16x32_bf16 v[96:99], v[156:159], v[196:199], v[96:99]
	v_mfma_f32_16x16x32_bf16 v[84:87], v[148:151], v[204:207], v[84:87]
	v_mfma_f32_16x16x32_bf16 v[80:83], v[156:159], v[204:207], v[80:83]
	s_setprio 0
	s_setprio 1
	v_mfma_f32_16x16x32_bf16 v[108:111], v[160:163], v[176:179], v[108:111]
	v_mfma_f32_16x16x32_bf16 v[104:107], v[168:171], v[176:179], v[104:107]
	v_mfma_f32_16x16x32_bf16 v[92:95], v[160:163], v[184:187], v[92:95]
	v_mfma_f32_16x16x32_bf16 v[88:91], v[168:171], v[184:187], v[88:91]
	v_mfma_f32_16x16x32_bf16 v[76:79], v[160:163], v[192:195], v[76:79]
	v_mfma_f32_16x16x32_bf16 v[72:75], v[168:171], v[192:195], v[72:75]
	v_mfma_f32_16x16x32_bf16 v[68:71], v[160:163], v[200:203], v[68:71]
	v_mfma_f32_16x16x32_bf16 v[64:67], v[168:171], v[200:203], v[64:67]
	v_mfma_f32_16x16x32_bf16 v[108:111], v[164:167], v[180:183], v[108:111]
	v_mfma_f32_16x16x32_bf16 v[104:107], v[172:175], v[180:183], v[104:107]
	v_mfma_f32_16x16x32_bf16 v[92:95], v[164:167], v[188:191], v[92:95]
	v_mfma_f32_16x16x32_bf16 v[88:91], v[172:175], v[188:191], v[88:91]
	v_mfma_f32_16x16x32_bf16 v[76:79], v[164:167], v[196:199], v[76:79]
	v_mfma_f32_16x16x32_bf16 v[72:75], v[172:175], v[196:199], v[72:75]
	v_mfma_f32_16x16x32_bf16 v[68:71], v[164:167], v[204:207], v[68:71]
	v_mfma_f32_16x16x32_bf16 v[64:67], v[172:175], v[204:207], v[64:67]
	s_setprio 0
	s_barrier
; #define G_STAGE(bufoff, gbase, voff) do { _Pragma("unroll") for (int _i = 0; _i < 2; ++_i) \
;         __builtin_amdgcn_global_load_lds((const unsigned*)((const char*)(gbase) + voff[_i]), (LAS unsigned*)(lds + (bufoff) + ldsw + _i * 8192), 16, 0, 0); } while (0)
; #define G_LDA(dst, b, h) do { _Pragma("unroll") for (int m = 0; m < 4; ++m) _Pragma("unroll") for (int k = 0; k < 2; ++k) dst[m][k] = *(const LAS bf16x8*)(lds + G_SA(b, h) + aoff + m * 2048 + k * 1024); } while (0)
; #define G_MMA(ai, bj, At_, Bt_) do { __builtin_amdgcn_s_setprio(1); _Pragma("unroll") for (int m = 0; m < 4; ++m) _Pragma("unroll") for (int n = 0; n < 2; ++n) _Pragma("unroll") for (int k = 0; k < 2; ++k) \
;         acc[ai][bj][m][n] = __builtin_amdgcn_mfma_f32_16x16x32_bf16(Bt_[n][k], At_[m][k], acc[ai][bj][m][n], 0, 0, 0); __builtin_amdgcn_s_setprio(0); } while (0)
; #define WAIT_V(n) asm volatile("s_waitcnt vmcnt(" #n ")" ::: "memory")
; #define WAIT_L(n) asm volatile("s_waitcnt lgkmcnt(" #n ")" ::: "memory")
; #define BAR __builtin_amdgcn_s_barrier()
; #define SCHED __builtin_amdgcn_sched_barrier(0)
; template <class Get, class Epi>
; DI void gemm_loop(int ntiles, int ld, char* shm, const Get& get, const Epi& epi) {
;     ...
;             G_LDA(At, 1, 1); G_STAGE(G_SB(1, 0), b3, voffB); G_STAGE(G_SB(1, 1), b3 + hstep, voffB); G_STAGE(G_SA(1, 0), a3, voffA);
;             WAIT_V(8); WAIT_L(0); BAR; G_MMA(1, 0, At, B0); G_MMA(1, 1, At, B1); BAR; SCHED;
;         }
	s_add_i32 s46, s71, s50
	v_lshl_add_u64 v[208:209], v[208:209], 0, s[8:9]
	s_mov_b32 m0, s46
	ds_read_b128 v[176:179], v143 offset:49152
	ds_read_b128 v[180:183], v143 offset:50176
	ds_read_b128 v[184:187], v143 offset:51200
	ds_read_b128 v[188:191], v143 offset:52224
	ds_read_b128 v[192:195], v143 offset:53248
	ds_read_b128 v[196:199], v143 offset:54272
	ds_read_b128 v[200:203], v143 offset:55296
	ds_read_b128 v[204:207], v143 offset:56320
	global_load_lds_dwordx4 v[208:209], off
	s_add_i32 m0, s46, 0x2000
	s_add_u32 s14, s14, 0x40080
	v_lshl_add_u64 v[208:209], v[210:211], 0, s[8:9]
	s_addc_u32 s15, s15, 0
	s_add_i32 s46, s72, s50
	global_load_lds_dwordx4 v[208:209], off
	v_lshl_add_u64 v[208:209], s[14:15], 0, v[130:131]
	s_mov_b32 m0, s46
	s_nop 0
	global_load_lds_dwordx4 v[208:209], off
	v_lshl_add_u64 v[208:209], s[14:15], 0, v[134:135]
	s_add_i32 m0, s46, 0x2000
	s_nop 0
	global_load_lds_dwordx4 v[208:209], off
	v_lshl_add_u64 v[208:209], v[212:213], 0, s[8:9]
	s_mov_b32 m0, s55
	s_nop 0
	global_load_lds_dwordx4 v[208:209], off
	v_lshl_add_u64 v[208:209], v[214:215], 0, s[8:9]
	s_mov_b32 m0, s56
	s_nop 0
	global_load_lds_dwordx4 v[208:209], off
	s_waitcnt vmcnt(8)
	s_waitcnt lgkmcnt(0)
	s_barrier
	s_setprio 1
	s_waitcnt lgkmcnt(0)
	v_mfma_f32_16x16x32_bf16 v[60:63], v[144:147], v[176:179], v[60:63]
	v_mfma_f32_16x16x32_bf16 v[56:59], v[152:155], v[176:179], v[56:59]
	v_mfma_f32_16x16x32_bf16 v[52:55], v[144:147], v[184:187], v[52:55]
	v_mfma_f32_16x16x32_bf16 v[48:51], v[152:155], v[184:187], v[48:51]
	v_mfma_f32_16x16x32_bf16 v[36:39], v[144:147], v[192:195], v[36:39]
	v_mfma_f32_16x16x32_bf16 v[32:35], v[152:155], v[192:195], v[32:35]
	v_mfma_f32_16x16x32_bf16 v[20:23], v[144:147], v[200:203], v[20:23]
	v_mfma_f32_16x16x32_bf16 v[16:19], v[152:155], v[200:203], v[16:19]
	v_mfma_f32_16x16x32_bf16 v[60:63], v[148:151], v[180:183], v[60:63]
	v_mfma_f32_16x16x32_bf16 v[56:59], v[156:159], v[180:183], v[56:59]
	v_mfma_f32_16x16x32_bf16 v[52:55], v[148:151], v[188:191], v[52:55]
	v_mfma_f32_16x16x32_bf16 v[48:51], v[156:159], v[188:191], v[48:51]
	v_mfma_f32_16x16x32_bf16 v[36:39], v[148:151], v[196:199], v[36:39]
	v_mfma_f32_16x16x32_bf16 v[32:35], v[156:159], v[196:199], v[32:35]
	v_mfma_f32_16x16x32_bf16 v[20:23], v[148:151], v[204:207], v[20:23]
	v_mfma_f32_16x16x32_bf16 v[16:19], v[156:159], v[204:207], v[16:19]
	s_setprio 0
	s_setprio 1
	v_mfma_f32_16x16x32_bf16 v[44:47], v[160:163], v[176:179], v[44:47]
	v_mfma_f32_16x16x32_bf16 v[40:43], v[168:171], v[176:179], v[40:43]
	v_mfma_f32_16x16x32_bf16 v[28:31], v[160:163], v[184:187], v[28:31]
	v_mfma_f32_16x16x32_bf16 v[24:27], v[168:171], v[184:187], v[24:27]
	v_mfma_f32_16x16x32_bf16 v[12:15], v[160:163], v[192:195], v[12:15]
	v_mfma_f32_16x16x32_bf16 v[8:11], v[168:171], v[192:195], v[8:11]
	v_mfma_f32_16x16x32_bf16 v[4:7], v[160:163], v[200:203], v[4:7]
	v_mfma_f32_16x16x32_bf16 v[0:3], v[168:171], v[200:203], v[0:3]
	v_mfma_f32_16x16x32_bf16 v[44:47], v[164:167], v[180:183], v[44:47]
	v_mfma_f32_16x16x32_bf16 v[40:43], v[172:175], v[180:183], v[40:43]
	v_mfma_f32_16x16x32_bf16 v[28:31], v[164:167], v[188:191], v[28:31]
	v_mfma_f32_16x16x32_bf16 v[24:27], v[172:175], v[188:191], v[24:27]
	v_mfma_f32_16x16x32_bf16 v[12:15], v[164:167], v[196:199], v[12:15]
	v_mfma_f32_16x16x32_bf16 v[8:11], v[172:175], v[196:199], v[8:11]
	v_mfma_f32_16x16x32_bf16 v[4:7], v[164:167], v[204:207], v[4:7]
	v_mfma_f32_16x16x32_bf16 v[0:3], v[172:175], v[204:207], v[0:3]
	s_setprio 0
	s_barrier
	s_add_i32 s70, s70, 2
	s_add_u32 s48, s48, 0x100
	s_addc_u32 s49, s49, 0
	s_add_u32 s64, s64, 0x100
	s_addc_u32 s65, s65, 0
	s_cmp_gt_u32 s70, 13
	s_cbranch_scc0 .LBB0_3141
	s_branch .Lpost_3141

; #define G_STAGE(bufoff, gbase, voff) do { _Pragma("unroll") for (int _i = 0; _i < 2; ++_i) \
;         __builtin_amdgcn_global_load_lds((const unsigned*)((const char*)(gbase) + voff[_i]), (LAS unsigned*)(lds + (bufoff) + ldsw + _i * 8192), 16, 0, 0); } while (0)
; #define WAIT_V(n) asm volatile("s_waitcnt vmcnt(" #n ")" ::: "memory")
; #define BAR __builtin_amdgcn_s_barrier()
; template <class Get, class Epi>
; DI void gemm_loop(int ntiles, int ld, char* shm, const Get& get, const Epi& epi) {
;     ...
;     const int aoff = lds_byte(wr * 64 + fr, fq * 8), boff = lds_byte(wc * 32 + fr, fq * 8);
;     ...
;     const char* cA = (const char*)cur.A + (size_t)cur.brow * ld * 2; const char* cB = (const char*)cur.Bt + (size_t)cur.bcol * ld * 2;
;     G_STAGE(G_SB(0, 0), cB, voffB); G_STAGE(G_SB(0, 1), cB + hstep, voffB); G_STAGE(G_SA(0, 0), cA, voffA); G_STAGE(G_SA(0, 1), cA + hstep, voffA);
;     if (wr == 1) BAR;
;     WAIT_V(2); BAR;
;     G_STAGE(G_SB(1, 0), cB + kstep, voffB); G_STAGE(G_SA(1, 0), cA + kstep, voffA); G_STAGE(G_SB(1, 1), cB + hstep + kstep, voffB);
;     WAIT_V(6); BAR;
.LBB0_3456:
	s_add_u32 s52, s68, 0x8a4000
	s_addc_u32 s53, s69, 0
	s_lshl_b32 s3, s4, 13
	s_lshl_b32 s4, s5, 12
	s_and_b32 s7, s4, 0x3000
	s_mov_b64 s[4:5], 0x80
	s_add_i32 m0, s43, 0x18000
	v_lshl_add_u64 v[6:7], v[6:7], 0, s[4:5]
	s_waitcnt vmcnt(2)
	s_barrier
	global_load_lds_dwordx4 v[6:7], off
	v_lshl_add_u64 v[4:5], v[4:5], 0, s[4:5]
	s_add_i32 m0, s43, 0x1a000
	s_add_i32 s54, s43, 0x8000
	s_add_i32 s55, s43, 0xa000
	global_load_lds_dwordx4 v[4:5], off
	v_lshl_add_u64 v[0:1], v[0:1], 0, s[4:5]
	s_mov_b32 m0, s54
	s_add_u32 s8, s14, 0x40080
	global_load_lds_dwordx4 v[0:1], off
	v_lshl_add_u64 v[0:1], v[2:3], 0, s[4:5]
	s_mov_b32 m0, s55
	s_addc_u32 s9, s15, 0
	global_load_lds_dwordx4 v[0:1], off
	s_add_i32 m0, s43, 0x1c000
	v_lshl_add_u64 v[0:1], s[8:9], 0, v[148:149]
	global_load_lds_dwordx4 v[0:1], off
	v_lshl_add_u64 v[0:1], s[8:9], 0, v[152:153]
	s_add_i32 m0, s43, 0x1e000
	v_lshlrev_b32_e32 v3, 2, v8
	global_load_lds_dwordx4 v[0:1], off
	v_and_b32_e32 v0, 15, v8
	v_and_b32_e32 v1, 48, v8
	v_lshlrev_b32_e32 v0, 6, v0
	v_and_b32_e32 v3, 32, v3
	v_or_b32_e32 v2, v0, v1
	v_bitop3_b32 v0, v0, v3, v1 bitop3:0x36
	v_or_b32_e32 v168, s7, v0
	v_lshlrev_b32_e32 v0, 14, v9
	v_and_b32_e32 v0, 0xffff8000, v0
	v_bitop3_b32 v1, v2, s3, v3 bitop3:0xde
	v_lshl_add_u32 v0, v10, 11, v0
	v_and_b32_e32 v2, 1, v9
	v_lshl_or_b32 v0, v2, 6, v0
	v_lshl_add_u32 v154, v11, 1, v0
	v_lshlrev_b32_e32 v0, 14, v12
	s_cmpk_lt_u32 s6, 0x100
	v_and_b32_e32 v0, 0xffff8000, v0
	s_waitcnt vmcnt(6)
	s_mov_b32 s100, 0
	s_cselect_b64 s[6:7], -1, 0
	s_add_u32 s8, s68, 0x8d4000
	v_lshl_add_u32 v0, v13, 11, v0
	v_and_b32_e32 v2, 1, v12
	s_addc_u32 s9, s69, 0
	v_lshl_or_b32 v0, v2, 6, v0
	s_add_i32 s56, 0, 0x10000
	s_add_i32 s57, 0, 0x14000
	v_mov_b32_e32 v155, v149
	v_lshl_add_u32 v156, v14, 1, v0
	v_mov_b32_e32 v157, v149
	v_add_u32_e32 v169, s56, v168
	v_add_u32_e32 v170, s57, v168
	v_add_u32_e32 v171, 0, v1
	s_movk_i32 s58, 0xffc0
	s_mov_b64 s[10:11], 0x80000
	s_mov_b64 s[12:13], 0x90000
	s_mov_b64 s[24:25], 0xa0000
	s_barrier
	s_branch .LBB0_3459

; #define G_STAGE(bufoff, gbase, voff) do { _Pragma("unroll") for (int _i = 0; _i < 2; ++_i) \
;         __builtin_amdgcn_global_load_lds((const unsigned*)((const char*)(gbase) + voff[_i]), (LAS unsigned*)(lds + (bufoff) + ldsw + _i * 8192), 16, 0, 0); } while (0)
; #define G_LDA(dst, b, h) do { _Pragma("unroll") for (int m = 0; m < 4; ++m) _Pragma("unroll") for (int k = 0; k < 2; ++k) dst[m][k] = *(const LAS bf16x8*)(lds + G_SA(b, h) + aoff + m * 2048 + k * 1024); } while (0)
; #define G_LDB(dst, b, h) do { _Pragma("unroll") for (int n = 0; n < 2; ++n) _Pragma("unroll") for (int k = 0; k < 2; ++k) dst[n][k] = *(const LAS bf16x8*)(lds + G_SB(b, h) + boff + n * 2048 + k * 1024); } while (0)
; #define G_MMA(ai, bj, At_, Bt_) do { __builtin_amdgcn_s_setprio(1); _Pragma("unroll") for (int m = 0; m < 4; ++m) _Pragma("unroll") for (int n = 0; n < 2; ++n) _Pragma("unroll") for (int k = 0; k < 2; ++k) \
;         acc[ai][bj][m][n] = __builtin_amdgcn_mfma_f32_16x16x32_bf16(Bt_[n][k], At_[m][k], acc[ai][bj][m][n], 0, 0, 0); __builtin_amdgcn_s_setprio(0); } while (0)
; #define WAIT_V(n) asm volatile("s_waitcnt vmcnt(" #n ")" ::: "memory")
; #define WAIT_L(n) asm volatile("s_waitcnt lgkmcnt(" #n ")" ::: "memory")
; #define BAR __builtin_amdgcn_s_barrier()
; #define SCHED __builtin_amdgcn_sched_barrier(0)
; template <class Get, class Epi>
; DI void gemm_loop(int ntiles, int ld, char* shm, const Get& get, const Epi& epi) {
;     ...
;             G_LDB(B0, 0, 0); G_LDB(B1, 0, 1); SCHED; G_LDA(At, 0, 0); G_STAGE(G_SA(1, 1), a1 + hstep, voffA);
;             WAIT_V(8); WAIT_L(0); BAR; G_MMA(0, 0, At, B0); G_MMA(0, 1, At, B1); BAR; SCHED;
.Lpeel_3466:
	ds_read_b128 v[128:131], v169
	ds_read_b128 v[132:135], v169 offset:1024
	ds_read_b128 v[136:139], v169 offset:2048
	ds_read_b128 v[140:143], v169 offset:3072
	ds_read_b128 v[158:161], v170
	ds_read_b128 v[162:165], v170 offset:1024
	ds_read_b128 v[172:175], v170 offset:2048
	ds_read_b128 v[176:179], v170 offset:3072
	s_add_u32 s14, s44, 0xfffc0080
	s_addc_u32 s15, s45, -1
	s_cmp_eq_u32 s71, 12
	s_cselect_b32 s47, s3, s15
	s_cselect_b32 s46, s35, s14
	s_cselect_b32 s15, s37, s70
	s_cselect_b32 s14, s64, s65
	v_lshl_add_u64 v[144:145], s[44:45], 0, v[154:155]
	s_add_i32 m0, s43, 0xc000
	ds_read_b128 v[180:183], v171
	ds_read_b128 v[184:187], v171 offset:1024
	ds_read_b128 v[188:191], v171 offset:2048
	ds_read_b128 v[192:195], v171 offset:3072
	ds_read_b128 v[196:199], v171 offset:4096
	ds_read_b128 v[200:203], v171 offset:5120
	ds_read_b128 v[204:207], v171 offset:6144
	ds_read_b128 v[208:211], v171 offset:7168
	global_load_lds_dwordx4 v[144:145], off
	v_lshl_add_u64 v[144:145], s[44:45], 0, v[156:157]
	s_add_i32 m0, s43, 0xe000
	s_nop 0
	global_load_lds_dwordx4 v[144:145], off
	s_cmp_lg_u32 s100, 0
	s_cbranch_scc0 .Lrf_3466_0
	s_waitcnt vmcnt(16)
	s_branch .Lrj_3466_0

; #define G_STAGE(bufoff, gbase, voff) do { _Pragma("unroll") for (int _i = 0; _i < 2; ++_i) \
;         __builtin_amdgcn_global_load_lds((const unsigned*)((const char*)(gbase) + voff[_i]), (LAS unsigned*)(lds + (bufoff) + ldsw + _i * 8192), 16, 0, 0); } while (0)
; #define G_LDA(dst, b, h) do { _Pragma("unroll") for (int m = 0; m < 4; ++m) _Pragma("unroll") for (int k = 0; k < 2; ++k) dst[m][k] = *(const LAS bf16x8*)(lds + G_SA(b, h) + aoff + m * 2048 + k * 1024); } while (0)
; #define G_MMA(ai, bj, At_, Bt_) do { __builtin_amdgcn_s_setprio(1); _Pragma("unroll") for (int m = 0; m < 4; ++m) _Pragma("unroll") for (int n = 0; n < 2; ++n) _Pragma("unroll") for (int k = 0; k < 2; ++k) \
;         acc[ai][bj][m][n] = __builtin_amdgcn_mfma_f32_16x16x32_bf16(Bt_[n][k], At_[m][k], acc[ai][bj][m][n], 0, 0, 0); __builtin_amdgcn_s_setprio(0); } while (0)
; #define WAIT_V(n) asm volatile("s_waitcnt vmcnt(" #n ")" ::: "memory")
; #define WAIT_L(n) asm volatile("s_waitcnt lgkmcnt(" #n ")" ::: "memory")
; #define BAR __builtin_amdgcn_s_barrier()
; #define SCHED __builtin_amdgcn_sched_barrier(0)
; template <class Get, class Epi>
; DI void gemm_loop(int ntiles, int ld, char* shm, const Get& get, const Epi& epi) {
;     ...
;             WAIT_V(8); WAIT_L(0); BAR; G_MMA(0, 0, At, B0); G_MMA(0, 1, At, B1); BAR; SCHED;
;             G_LDA(At, 0, 1); G_STAGE(G_SB(0, 0), b2, voffB); G_STAGE(G_SB(0, 1), b2 + hstep, voffB); G_STAGE(G_SA(0, 0), a2, voffA);
;             WAIT_V(8); WAIT_L(0); BAR; G_MMA(1, 0, At, B0); G_MMA(1, 1, At, B1); BAR; SCHED;
.Lrj_3466_0:
	s_waitcnt lgkmcnt(0)
	s_barrier
	s_setprio 1
	s_waitcnt lgkmcnt(0)
	v_mfma_f32_16x16x32_bf16 v[124:127], v[128:131], v[180:183], 0
	v_mfma_f32_16x16x32_bf16 v[120:123], v[136:139], v[180:183], 0
	v_mfma_f32_16x16x32_bf16 v[116:119], v[128:131], v[188:191], 0
	v_mfma_f32_16x16x32_bf16 v[112:115], v[136:139], v[188:191], 0
	v_mfma_f32_16x16x32_bf16 v[108:111], v[128:131], v[196:199], 0
	v_mfma_f32_16x16x32_bf16 v[104:107], v[136:139], v[196:199], 0
	v_mfma_f32_16x16x32_bf16 v[100:103], v[128:131], v[204:207], 0
	v_mfma_f32_16x16x32_bf16 v[96:99], v[136:139], v[204:207], 0
	v_mfma_f32_16x16x32_bf16 v[124:127], v[132:135], v[184:187], v[124:127]
	v_mfma_f32_16x16x32_bf16 v[120:123], v[140:143], v[184:187], v[120:123]
	v_mfma_f32_16x16x32_bf16 v[116:119], v[132:135], v[192:195], v[116:119]
	v_mfma_f32_16x16x32_bf16 v[112:115], v[140:143], v[192:195], v[112:115]
	v_mfma_f32_16x16x32_bf16 v[108:111], v[132:135], v[200:203], v[108:111]
	v_mfma_f32_16x16x32_bf16 v[104:107], v[140:143], v[200:203], v[104:107]
	v_mfma_f32_16x16x32_bf16 v[100:103], v[132:135], v[208:211], v[100:103]
	v_mfma_f32_16x16x32_bf16 v[96:99], v[140:143], v[208:211], v[96:99]
	s_setprio 0
	s_setprio 1
	v_mfma_f32_16x16x32_bf16 v[60:63], v[158:161], v[180:183], 0
	v_mfma_f32_16x16x32_bf16 v[56:59], v[172:175], v[180:183], 0
	v_mfma_f32_16x16x32_bf16 v[52:55], v[158:161], v[188:191], 0
	v_mfma_f32_16x16x32_bf16 v[48:51], v[172:175], v[188:191], 0
	v_mfma_f32_16x16x32_bf16 v[44:47], v[158:161], v[196:199], 0
	v_mfma_f32_16x16x32_bf16 v[40:43], v[172:175], v[196:199], 0
	v_mfma_f32_16x16x32_bf16 v[36:39], v[158:161], v[204:207], 0
	v_mfma_f32_16x16x32_bf16 v[32:35], v[172:175], v[204:207], 0
	v_mfma_f32_16x16x32_bf16 v[60:63], v[162:165], v[184:187], v[60:63]
	v_mfma_f32_16x16x32_bf16 v[56:59], v[176:179], v[184:187], v[56:59]
	v_mfma_f32_16x16x32_bf16 v[52:55], v[162:165], v[192:195], v[52:55]
	v_mfma_f32_16x16x32_bf16 v[48:51], v[176:179], v[192:195], v[48:51]
	v_mfma_f32_16x16x32_bf16 v[44:47], v[162:165], v[200:203], v[44:47]
	v_mfma_f32_16x16x32_bf16 v[40:43], v[176:179], v[200:203], v[40:43]
	v_mfma_f32_16x16x32_bf16 v[36:39], v[162:165], v[208:211], v[36:39]
	v_mfma_f32_16x16x32_bf16 v[32:35], v[176:179], v[208:211], v[32:35]
	s_setprio 0
	s_barrier
	s_add_i32 s72, s56, s48
	v_lshl_add_u64 v[144:145], s[14:15], 0, v[148:149]
	s_mov_b32 m0, s72
	ds_read_b128 v[180:183], v171 offset:16384
	ds_read_b128 v[184:187], v171 offset:17408
	ds_read_b128 v[188:191], v171 offset:18432
	ds_read_b128 v[192:195], v171 offset:19456
	ds_read_b128 v[196:199], v171 offset:20480
	ds_read_b128 v[200:203], v171 offset:21504
	ds_read_b128 v[204:207], v171 offset:22528
	ds_read_b128 v[208:211], v171 offset:23552
	global_load_lds_dwordx4 v[144:145], off
	s_add_i32 m0, s72, 0x2000
	s_add_u32 s72, s14, 0x40000
	v_lshl_add_u64 v[166:167], s[14:15], 0, v[152:153]
	s_addc_u32 s73, s15, 0
	s_add_i32 s74, s57, s48
	global_load_lds_dwordx4 v[166:167], off
	v_lshl_add_u64 v[212:213], s[72:73], 0, v[148:149]
	s_mov_b32 m0, s74
	v_lshl_add_u64 v[214:215], s[46:47], 0, v[150:151]
	global_load_lds_dwordx4 v[212:213], off
	v_lshl_add_u64 v[212:213], s[72:73], 0, v[152:153]
	s_add_i32 m0, s74, 0x2000
	s_nop 0
	global_load_lds_dwordx4 v[212:213], off
	v_lshl_add_u64 v[212:213], s[46:47], 0, v[146:147]
	s_mov_b32 m0, s43
	s_nop 0
	global_load_lds_dwordx4 v[212:213], off
	s_mov_b32 m0, s49
	s_nop 0
	global_load_lds_dwordx4 v[214:215], off
	s_cmp_lg_u32 s100, 0
	s_cbranch_scc0 .Lrf_3466_1
	s_waitcnt vmcnt(16)
	s_branch .Lrj_3466_1

; #define G_STAGE(bufoff, gbase, voff) do { _Pragma("unroll") for (int _i = 0; _i < 2; ++_i) \
;         __builtin_amdgcn_global_load_lds((const unsigned*)((const char*)(gbase) + voff[_i]), (LAS unsigned*)(lds + (bufoff) + ldsw + _i * 8192), 16, 0, 0); } while (0)
; #define G_LDA(dst, b, h) do { _Pragma("unroll") for (int m = 0; m < 4; ++m) _Pragma("unroll") for (int k = 0; k < 2; ++k) dst[m][k] = *(const LAS bf16x8*)(lds + G_SA(b, h) + aoff + m * 2048 + k * 1024); } while (0)
; #define G_LDB(dst, b, h) do { _Pragma("unroll") for (int n = 0; n < 2; ++n) _Pragma("unroll") for (int k = 0; k < 2; ++k) dst[n][k] = *(const LAS bf16x8*)(lds + G_SB(b, h) + boff + n * 2048 + k * 1024); } while (0)
; #define G_MMA(ai, bj, At_, Bt_) do { __builtin_amdgcn_s_setprio(1); _Pragma("unroll") for (int m = 0; m < 4; ++m) _Pragma("unroll") for (int n = 0; n < 2; ++n) _Pragma("unroll") for (int k = 0; k < 2; ++k) \
;         acc[ai][bj][m][n] = __builtin_amdgcn_mfma_f32_16x16x32_bf16(Bt_[n][k], At_[m][k], acc[ai][bj][m][n], 0, 0, 0); __builtin_amdgcn_s_setprio(0); } while (0)
; #define WAIT_V(n) asm volatile("s_waitcnt vmcnt(" #n ")" ::: "memory")
; #define WAIT_L(n) asm volatile("s_waitcnt lgkmcnt(" #n ")" ::: "memory")
; #define BAR __builtin_amdgcn_s_barrier()
; #define SCHED __builtin_amdgcn_sched_barrier(0)
; template <class Get, class Epi>
; DI void gemm_loop(int ntiles, int ld, char* shm, const Get& get, const Epi& epi) {
;     ...
;             WAIT_V(8); WAIT_L(0); BAR; G_MMA(1, 0, At, B0); G_MMA(1, 1, At, B1); BAR; SCHED;
;             G_LDB(B0, 1, 0); G_LDB(B1, 1, 1); SCHED; G_LDA(At, 1, 0); G_STAGE(G_SA(0, 1), a2 + hstep, voffA);
;             WAIT_V(8); WAIT_L(0); BAR; G_MMA(0, 0, At, B0); G_MMA(0, 1, At, B1); BAR; SCHED;
.Lrj_3466_1:
	s_waitcnt lgkmcnt(0)
	s_barrier
	s_setprio 1
	s_waitcnt lgkmcnt(0)
	v_mfma_f32_16x16x32_bf16 v[92:95], v[128:131], v[180:183], 0
	v_mfma_f32_16x16x32_bf16 v[88:91], v[136:139], v[180:183], 0
	v_mfma_f32_16x16x32_bf16 v[84:87], v[128:131], v[188:191], 0
	v_mfma_f32_16x16x32_bf16 v[80:83], v[136:139], v[188:191], 0
	v_mfma_f32_16x16x32_bf16 v[76:79], v[128:131], v[196:199], 0
	v_mfma_f32_16x16x32_bf16 v[72:75], v[136:139], v[196:199], 0
	v_mfma_f32_16x16x32_bf16 v[68:71], v[128:131], v[204:207], 0
	v_mfma_f32_16x16x32_bf16 v[64:67], v[136:139], v[204:207], 0
	v_mfma_f32_16x16x32_bf16 v[92:95], v[132:135], v[184:187], v[92:95]
	v_mfma_f32_16x16x32_bf16 v[88:91], v[140:143], v[184:187], v[88:91]
	v_mfma_f32_16x16x32_bf16 v[84:87], v[132:135], v[192:195], v[84:87]
	v_mfma_f32_16x16x32_bf16 v[80:83], v[140:143], v[192:195], v[80:83]
	v_mfma_f32_16x16x32_bf16 v[76:79], v[132:135], v[200:203], v[76:79]
	v_mfma_f32_16x16x32_bf16 v[72:75], v[140:143], v[200:203], v[72:75]
	v_mfma_f32_16x16x32_bf16 v[68:71], v[132:135], v[208:211], v[68:71]
	v_mfma_f32_16x16x32_bf16 v[64:67], v[140:143], v[208:211], v[64:67]
	s_setprio 0
	s_setprio 1
	v_mfma_f32_16x16x32_bf16 v[28:31], v[158:161], v[180:183], 0
	v_mfma_f32_16x16x32_bf16 v[24:27], v[172:175], v[180:183], 0
	v_mfma_f32_16x16x32_bf16 v[20:23], v[158:161], v[188:191], 0
	v_mfma_f32_16x16x32_bf16 v[16:19], v[172:175], v[188:191], 0
	v_mfma_f32_16x16x32_bf16 v[12:15], v[158:161], v[196:199], 0
	v_mfma_f32_16x16x32_bf16 v[8:11], v[172:175], v[196:199], 0
	v_mfma_f32_16x16x32_bf16 v[4:7], v[158:161], v[204:207], 0
	v_mfma_f32_16x16x32_bf16 v[0:3], v[172:175], v[204:207], 0
	v_mfma_f32_16x16x32_bf16 v[28:31], v[162:165], v[184:187], v[28:31]
	v_mfma_f32_16x16x32_bf16 v[24:27], v[176:179], v[184:187], v[24:27]
	v_mfma_f32_16x16x32_bf16 v[20:23], v[162:165], v[192:195], v[20:23]
	v_mfma_f32_16x16x32_bf16 v[16:19], v[176:179], v[192:195], v[16:19]
	v_mfma_f32_16x16x32_bf16 v[12:15], v[162:165], v[200:203], v[12:15]
	v_mfma_f32_16x16x32_bf16 v[8:11], v[176:179], v[200:203], v[8:11]
	v_mfma_f32_16x16x32_bf16 v[4:7], v[162:165], v[208:211], v[4:7]
	v_mfma_f32_16x16x32_bf16 v[0:3], v[176:179], v[208:211], v[0:3]
	s_setprio 0
	s_barrier
	s_add_i32 s72, 0, 0x18000
	s_add_i32 s73, 0, 0x1c000
	v_add_u32_e32 v140, s72, v168
	v_add_u32_e32 v176, s73, v168
	ds_read_b128 v[128:131], v140
	ds_read_b128 v[132:135], v140 offset:1024
	ds_read_b128 v[136:139], v140 offset:2048
	ds_read_b128 v[140:143], v140 offset:3072
	ds_read_b128 v[158:161], v176
	ds_read_b128 v[162:165], v176 offset:1024
	ds_read_b128 v[172:175], v176 offset:2048
	ds_read_b128 v[176:179], v176 offset:3072
	s_add_u32 s46, s46, 0x40000
	s_addc_u32 s47, s47, 0
	s_mov_b32 m0, s50
	v_lshl_add_u64 v[216:217], s[46:47], 0, v[146:147]
	ds_read_b128 v[180:183], v171 offset:32768
	ds_read_b128 v[184:187], v171 offset:33792
	ds_read_b128 v[188:191], v171 offset:34816
	ds_read_b128 v[192:195], v171 offset:35840
	ds_read_b128 v[196:199], v171 offset:36864
	ds_read_b128 v[200:203], v171 offset:37888
	ds_read_b128 v[204:207], v171 offset:38912
	ds_read_b128 v[208:211], v171 offset:39936
	global_load_lds_dwordx4 v[216:217], off
	v_lshl_add_u64 v[216:217], s[46:47], 0, v[150:151]
	s_mov_b32 m0, s51
	s_nop 0
	global_load_lds_dwordx4 v[216:217], off
	s_waitcnt vmcnt(8)
	s_waitcnt lgkmcnt(0)
	s_barrier
	s_setprio 1
	s_waitcnt lgkmcnt(0)
	v_mfma_f32_16x16x32_bf16 v[124:127], v[128:131], v[180:183], v[124:127]
	v_mfma_f32_16x16x32_bf16 v[120:123], v[136:139], v[180:183], v[120:123]
	v_mfma_f32_16x16x32_bf16 v[116:119], v[128:131], v[188:191], v[116:119]
	v_mfma_f32_16x16x32_bf16 v[112:115], v[136:139], v[188:191], v[112:115]
	v_mfma_f32_16x16x32_bf16 v[108:111], v[128:131], v[196:199], v[108:111]
	v_mfma_f32_16x16x32_bf16 v[104:107], v[136:139], v[196:199], v[104:107]
	v_mfma_f32_16x16x32_bf16 v[100:103], v[128:131], v[204:207], v[100:103]
	v_mfma_f32_16x16x32_bf16 v[96:99], v[136:139], v[204:207], v[96:99]
	v_mfma_f32_16x16x32_bf16 v[124:127], v[132:135], v[184:187], v[124:127]
	v_mfma_f32_16x16x32_bf16 v[120:123], v[140:143], v[184:187], v[120:123]
	v_mfma_f32_16x16x32_bf16 v[116:119], v[132:135], v[192:195], v[116:119]
	v_mfma_f32_16x16x32_bf16 v[112:115], v[140:143], v[192:195], v[112:115]
	v_mfma_f32_16x16x32_bf16 v[108:111], v[132:135], v[200:203], v[108:111]
	v_mfma_f32_16x16x32_bf16 v[104:107], v[140:143], v[200:203], v[104:107]
	v_mfma_f32_16x16x32_bf16 v[100:103], v[132:135], v[208:211], v[100:103]
	v_mfma_f32_16x16x32_bf16 v[96:99], v[140:143], v[208:211], v[96:99]
	s_setprio 0
	s_setprio 1
	v_mfma_f32_16x16x32_bf16 v[60:63], v[158:161], v[180:183], v[60:63]
	v_mfma_f32_16x16x32_bf16 v[56:59], v[172:175], v[180:183], v[56:59]
	v_mfma_f32_16x16x32_bf16 v[52:55], v[158:161], v[188:191], v[52:55]
	v_mfma_f32_16x16x32_bf16 v[48:51], v[172:175], v[188:191], v[48:51]
	v_mfma_f32_16x16x32_bf16 v[44:47], v[158:161], v[196:199], v[44:47]
	v_mfma_f32_16x16x32_bf16 v[40:43], v[172:175], v[196:199], v[40:43]
	v_mfma_f32_16x16x32_bf16 v[36:39], v[158:161], v[204:207], v[36:39]
	v_mfma_f32_16x16x32_bf16 v[32:35], v[172:175], v[204:207], v[32:35]
	v_mfma_f32_16x16x32_bf16 v[60:63], v[162:165], v[184:187], v[60:63]
	v_mfma_f32_16x16x32_bf16 v[56:59], v[176:179], v[184:187], v[56:59]
	v_mfma_f32_16x16x32_bf16 v[52:55], v[162:165], v[192:195], v[52:55]
	v_mfma_f32_16x16x32_bf16 v[48:51], v[176:179], v[192:195], v[48:51]
	v_mfma_f32_16x16x32_bf16 v[44:47], v[162:165], v[200:203], v[44:47]
	v_mfma_f32_16x16x32_bf16 v[40:43], v[176:179], v[200:203], v[40:43]
	v_mfma_f32_16x16x32_bf16 v[36:39], v[162:165], v[208:211], v[36:39]
	v_mfma_f32_16x16x32_bf16 v[32:35], v[176:179], v[208:211], v[32:35]
	s_setprio 0
	s_barrier
; #define G_STAGE(bufoff, gbase, voff) do { _Pragma("unroll") for (int _i = 0; _i < 2; ++_i) \
;         __builtin_amdgcn_global_load_lds((const unsigned*)((const char*)(gbase) + voff[_i]), (LAS unsigned*)(lds + (bufoff) + ldsw + _i * 8192), 16, 0, 0); } while (0)
; #define G_LDA(dst, b, h) do { _Pragma("unroll") for (int m = 0; m < 4; ++m) _Pragma("unroll") for (int k = 0; k < 2; ++k) dst[m][k] = *(const LAS bf16x8*)(lds + G_SA(b, h) + aoff + m * 2048 + k * 1024); } while (0)
; #define G_MMA(ai, bj, At_, Bt_) do { __builtin_amdgcn_s_setprio(1); _Pragma("unroll") for (int m = 0; m < 4; ++m) _Pragma("unroll") for (int n = 0; n < 2; ++n) _Pragma("unroll") for (int k = 0; k < 2; ++k) \
;         acc[ai][bj][m][n] = __builtin_amdgcn_mfma_f32_16x16x32_bf16(Bt_[n][k], At_[m][k], acc[ai][bj][m][n], 0, 0, 0); __builtin_amdgcn_s_setprio(0); } while (0)
; #define WAIT_V(n) asm volatile("s_waitcnt vmcnt(" #n ")" ::: "memory")
; #define WAIT_L(n) asm volatile("s_waitcnt lgkmcnt(" #n ")" ::: "memory")
; #define BAR __builtin_amdgcn_s_barrier()
; #define SCHED __builtin_amdgcn_sched_barrier(0)
; template <class Get, class Epi>
; DI void gemm_loop(int ntiles, int ld, char* shm, const Get& get, const Epi& epi) {
;     ...
;             G_LDA(At, 1, 1); G_STAGE(G_SB(1, 0), b3, voffB); G_STAGE(G_SB(1, 1), b3 + hstep, voffB); G_STAGE(G_SA(1, 0), a3, voffA);
;             WAIT_V(8); WAIT_L(0); BAR; G_MMA(1, 0, At, B0); G_MMA(1, 1, At, B1); BAR; SCHED;
;         }
	s_add_i32 s46, s72, s48
	v_lshl_add_u64 v[144:145], v[144:145], 0, s[4:5]
	s_mov_b32 m0, s46
	ds_read_b128 v[180:183], v171 offset:49152
	ds_read_b128 v[184:187], v171 offset:50176
	ds_read_b128 v[188:191], v171 offset:51200
	ds_read_b128 v[192:195], v171 offset:52224
	ds_read_b128 v[196:199], v171 offset:53248
	ds_read_b128 v[200:203], v171 offset:54272
	ds_read_b128 v[204:207], v171 offset:55296
	ds_read_b128 v[208:211], v171 offset:56320
	global_load_lds_dwordx4 v[144:145], off
	s_add_i32 m0, s46, 0x2000
	s_add_u32 s14, s14, 0x40080
	v_lshl_add_u64 v[144:145], v[166:167], 0, s[4:5]
	s_addc_u32 s15, s15, 0
	s_add_i32 s46, s73, s48
	global_load_lds_dwordx4 v[144:145], off
	v_lshl_add_u64 v[144:145], s[14:15], 0, v[148:149]
	s_mov_b32 m0, s46
	s_nop 0
	global_load_lds_dwordx4 v[144:145], off
	v_lshl_add_u64 v[144:145], s[14:15], 0, v[152:153]
	s_add_i32 m0, s46, 0x2000
	s_nop 0
	global_load_lds_dwordx4 v[144:145], off
	v_lshl_add_u64 v[144:145], v[212:213], 0, s[4:5]
	s_mov_b32 m0, s54
	s_nop 0
	global_load_lds_dwordx4 v[144:145], off
	v_lshl_add_u64 v[144:145], v[214:215], 0, s[4:5]
	s_mov_b32 m0, s55
	s_nop 0
	global_load_lds_dwordx4 v[144:145], off
	s_waitcnt vmcnt(8)
	s_waitcnt lgkmcnt(0)
	s_barrier
	s_setprio 1
	s_waitcnt lgkmcnt(0)
	v_mfma_f32_16x16x32_bf16 v[92:95], v[128:131], v[180:183], v[92:95]
	v_mfma_f32_16x16x32_bf16 v[88:91], v[136:139], v[180:183], v[88:91]
	v_mfma_f32_16x16x32_bf16 v[84:87], v[128:131], v[188:191], v[84:87]
	v_mfma_f32_16x16x32_bf16 v[80:83], v[136:139], v[188:191], v[80:83]
	v_mfma_f32_16x16x32_bf16 v[76:79], v[128:131], v[196:199], v[76:79]
	v_mfma_f32_16x16x32_bf16 v[72:75], v[136:139], v[196:199], v[72:75]
	v_mfma_f32_16x16x32_bf16 v[68:71], v[128:131], v[204:207], v[68:71]
	v_mfma_f32_16x16x32_bf16 v[64:67], v[136:139], v[204:207], v[64:67]
	v_mfma_f32_16x16x32_bf16 v[92:95], v[132:135], v[184:187], v[92:95]
	v_mfma_f32_16x16x32_bf16 v[88:91], v[140:143], v[184:187], v[88:91]
	v_mfma_f32_16x16x32_bf16 v[84:87], v[132:135], v[192:195], v[84:87]
	v_mfma_f32_16x16x32_bf16 v[80:83], v[140:143], v[192:195], v[80:83]
	v_mfma_f32_16x16x32_bf16 v[76:79], v[132:135], v[200:203], v[76:79]
	v_mfma_f32_16x16x32_bf16 v[72:75], v[140:143], v[200:203], v[72:75]
	v_mfma_f32_16x16x32_bf16 v[68:71], v[132:135], v[208:211], v[68:71]
	v_mfma_f32_16x16x32_bf16 v[64:67], v[140:143], v[208:211], v[64:67]
	s_setprio 0
	s_setprio 1
	v_mfma_f32_16x16x32_bf16 v[28:31], v[158:161], v[180:183], v[28:31]
	v_mfma_f32_16x16x32_bf16 v[24:27], v[172:175], v[180:183], v[24:27]
	v_mfma_f32_16x16x32_bf16 v[20:23], v[158:161], v[188:191], v[20:23]
	v_mfma_f32_16x16x32_bf16 v[16:19], v[172:175], v[188:191], v[16:19]
	v_mfma_f32_16x16x32_bf16 v[12:15], v[158:161], v[196:199], v[12:15]
	v_mfma_f32_16x16x32_bf16 v[8:11], v[172:175], v[196:199], v[8:11]
	v_mfma_f32_16x16x32_bf16 v[4:7], v[158:161], v[204:207], v[4:7]
	v_mfma_f32_16x16x32_bf16 v[0:3], v[172:175], v[204:207], v[0:3]
	v_mfma_f32_16x16x32_bf16 v[28:31], v[162:165], v[184:187], v[28:31]
	v_mfma_f32_16x16x32_bf16 v[24:27], v[176:179], v[184:187], v[24:27]
	v_mfma_f32_16x16x32_bf16 v[20:23], v[162:165], v[192:195], v[20:23]
	v_mfma_f32_16x16x32_bf16 v[16:19], v[176:179], v[192:195], v[16:19]
	v_mfma_f32_16x16x32_bf16 v[12:15], v[162:165], v[200:203], v[12:15]
	v_mfma_f32_16x16x32_bf16 v[8:11], v[176:179], v[200:203], v[8:11]
	v_mfma_f32_16x16x32_bf16 v[4:7], v[162:165], v[208:211], v[4:7]
	v_mfma_f32_16x16x32_bf16 v[0:3], v[176:179], v[208:211], v[0:3]
	s_setprio 0
	s_barrier
	s_add_i32 s71, s71, 2
	s_add_u32 s44, s44, 0x100
	s_addc_u32 s45, s45, 0
	s_add_u32 s65, s65, 0x100
	s_addc_u32 s70, s70, 0
	s_cmp_gt_u32 s71, 13
	s_cbranch_scc0 .LBB0_3466
	s_branch .Lpost_3466

; #define BAR __builtin_amdgcn_s_barrier()
; template <class Get, class Epi>
; DI void gemm_loop(int ntiles, int ld, char* shm, const Get& get, const Epi& epi) {
;     ...
;         if (wr == 0) BAR;
;         { int tx2 = threadIdx.x, brow2 = cur.brow, bcol2 = cur.bcol, Lo = L; asm volatile("" : "+v"(tx2), "+s"(brow2), "+s"(bcol2), "+s"(Lo));
;           const int wid2 = tx2 >> 6, lane2 = tx2 & 63; epi(Lo, acc, brow2, bcol2, wid2 >> 2, wid2 & 3, lane2 & 15, lane2 >> 4); }
;         if (!has_next) break;
.Lpost_3466:
	s_mov_b32 s100, 1
	s_and_b64 vcc, exec, s[6:7]
	s_cbranch_vccz .LBB0_3469
	s_barrier

; #define G_STAGE(bufoff, gbase, voff) do { _Pragma("unroll") for (int _i = 0; _i < 2; ++_i) \
;         __builtin_amdgcn_global_load_lds((const unsigned*)((const char*)(gbase) + voff[_i]), (LAS unsigned*)(lds + (bufoff) + ldsw + _i * 8192), 16, 0, 0); } while (0)
; #define WAIT_V(n) asm volatile("s_waitcnt vmcnt(" #n ")" ::: "memory")
; #define BAR __builtin_amdgcn_s_barrier()
; template <class Get, class Epi>
; DI void gemm_loop(int ntiles, int ld, char* shm, const Get& get, const Epi& epi) {
;     ...
;     for (int i = 0; i < 2; ++i) { int R, C; stage_rc(tid * 16 + i * 8192, R, C); const int rho = R & 31, Rb = (R & ~31) + 8 * ((rho & 15) >> 2) + 4 * (rho >> 4) + (rho & 3);
;         voffA[i] = (unsigned)(R * ld + C) * 2u; voffB[i] = (unsigned)(Rb * ld + C) * 2u; }
;     const size_t kstep = (size_t)(BK * 2), hstep = (size_t)HALF * ld * 2;
;     const unsigned ldsw = (unsigned)wid * 1024u;
;     const int aoff = lds_byte(wr * 64 + fr, fq * 8), boff = lds_byte(wc * 32 + fr, fq * 8);
;     ...
;     int L = bx; if (L >= ntiles) return;
;     Tile cur = get(L), nxt = cur;
;     AccT acc;
;     ...
;     G_ZERO;
;     bf16x8 At[4][2], B0[2][2], B1[2][2];
;     const char* cA = (const char*)cur.A + (size_t)cur.brow * ld * 2; const char* cB = (const char*)cur.Bt + (size_t)cur.bcol * ld * 2;
;     G_STAGE(G_SB(0, 0), cB, voffB); G_STAGE(G_SB(0, 1), cB + hstep, voffB); G_STAGE(G_SA(0, 0), cA, voffA); G_STAGE(G_SA(0, 1), cA + hstep, voffA);
;     if (wr == 1) BAR;
;     WAIT_V(2); BAR;
;     G_STAGE(G_SB(1, 0), cB + kstep, voffB); G_STAGE(G_SA(1, 0), cA + kstep, voffA); G_STAGE(G_SB(1, 1), cB + hstep + kstep, voffB);
;     WAIT_V(6); BAR;
.LBB0_3673:
	s_lshl_b32 s2, s2, 12
	s_lshl_b32 s5, s3, 13
	s_and_b32 s8, s2, 0x3000
	s_mov_b64 s[2:3], 0x80
	s_add_i32 m0, s25, 0x18000
	v_lshl_add_u64 v[6:7], v[6:7], 0, s[2:3]
	s_waitcnt vmcnt(2)
	s_barrier
	global_load_lds_dwordx4 v[6:7], off
	v_lshl_add_u64 v[4:5], v[4:5], 0, s[2:3]
	s_add_i32 m0, s25, 0x1a000
	s_add_i32 s42, s25, 0x8000
	s_add_i32 s43, s25, 0xa000
	global_load_lds_dwordx4 v[4:5], off
	v_lshl_add_u64 v[0:1], v[0:1], 0, s[2:3]
	s_mov_b32 m0, s42
	s_add_u32 s6, s14, 0x40080
	global_load_lds_dwordx4 v[0:1], off
	v_lshl_add_u64 v[0:1], v[2:3], 0, s[2:3]
	s_mov_b32 m0, s43
	s_addc_u32 s7, s15, 0
	global_load_lds_dwordx4 v[0:1], off
	s_add_i32 m0, s25, 0x1c000
	v_lshl_add_u64 v[0:1], s[6:7], 0, v[132:133]
	global_load_lds_dwordx4 v[0:1], off
	v_lshl_add_u64 v[0:1], s[6:7], 0, v[128:129]
	s_add_i32 m0, s25, 0x1e000
	v_lshlrev_b32_e32 v3, 2, v9
	global_load_lds_dwordx4 v[0:1], off
	v_and_b32_e32 v0, 15, v9
	v_and_b32_e32 v1, 48, v9
	v_lshlrev_b32_e32 v0, 6, v0
	v_and_b32_e32 v3, 32, v3
	v_or_b32_e32 v2, v0, v1
	v_bitop3_b32 v0, v0, v3, v1 bitop3:0x36
	v_or_b32_e32 v140, s8, v0
	v_lshlrev_b32_e32 v0, 14, v13
	v_and_b32_e32 v0, 0xffff8000, v0
	v_bitop3_b32 v1, v2, s5, v3 bitop3:0xde
	v_lshl_add_u32 v0, v12, 11, v0
	v_and_b32_e32 v2, 1, v13
	v_lshl_or_b32 v0, v2, 6, v0
	v_lshl_add_u32 v136, v14, 1, v0
	v_lshlrev_b32_e32 v0, 14, v8
	v_and_b32_e32 v0, 0xffff8000, v0
	s_waitcnt vmcnt(6)
	s_mov_b32 s100, 0
	s_cmpk_lt_u32 s4, 0x100
	v_lshl_add_u32 v0, v10, 11, v0
	v_and_b32_e32 v2, 1, v8
	s_cselect_b64 s[4:5], -1, 0
	v_lshl_or_b32 v0, v2, 6, v0
	s_add_i32 s44, 0, 0x10000
	s_add_i32 s45, 0, 0x14000
	v_mov_b32_e32 v137, v133
	v_lshl_add_u32 v138, v11, 1, v0
	v_mov_b32_e32 v139, v133
	v_add_u32_e32 v141, s44, v140
	v_add_u32_e32 v142, s45, v140
	v_add_u32_e32 v143, 0, v1
	s_movk_i32 s46, 0x1600
	s_barrier
	s_branch .LBB0_3676

; #define G_STAGE(bufoff, gbase, voff) do { _Pragma("unroll") for (int _i = 0; _i < 2; ++_i) \
;         __builtin_amdgcn_global_load_lds((const unsigned*)((const char*)(gbase) + voff[_i]), (LAS unsigned*)(lds + (bufoff) + ldsw + _i * 8192), 16, 0, 0); } while (0)
; #define G_LDA(dst, b, h) do { _Pragma("unroll") for (int m = 0; m < 4; ++m) _Pragma("unroll") for (int k = 0; k < 2; ++k) dst[m][k] = *(const LAS bf16x8*)(lds + G_SA(b, h) + aoff + m * 2048 + k * 1024); } while (0)
; #define G_LDB(dst, b, h) do { _Pragma("unroll") for (int n = 0; n < 2; ++n) _Pragma("unroll") for (int k = 0; k < 2; ++k) dst[n][k] = *(const LAS bf16x8*)(lds + G_SB(b, h) + boff + n * 2048 + k * 1024); } while (0)
; #define G_MMA(ai, bj, At_, Bt_) do { __builtin_amdgcn_s_setprio(1); _Pragma("unroll") for (int m = 0; m < 4; ++m) _Pragma("unroll") for (int n = 0; n < 2; ++n) _Pragma("unroll") for (int k = 0; k < 2; ++k) \
;         acc[ai][bj][m][n] = __builtin_amdgcn_mfma_f32_16x16x32_bf16(Bt_[n][k], At_[m][k], acc[ai][bj][m][n], 0, 0, 0); __builtin_amdgcn_s_setprio(0); } while (0)
; #define WAIT_V(n) asm volatile("s_waitcnt vmcnt(" #n ")" ::: "memory")
; #define WAIT_L(n) asm volatile("s_waitcnt lgkmcnt(" #n ")" ::: "memory")
; #define BAR __builtin_amdgcn_s_barrier()
; #define SCHED __builtin_amdgcn_sched_barrier(0)
; template <class Get, class Epi>
; DI void gemm_loop(int ntiles, int ld, char* shm, const Get& get, const Epi& epi) {
;     ...
;             G_LDB(B0, 0, 0); G_LDB(B1, 0, 1); SCHED; G_LDA(At, 0, 0); G_STAGE(G_SA(1, 1), a1 + hstep, voffA);
;             WAIT_V(8); WAIT_L(0); BAR; G_MMA(0, 0, At, B0); G_MMA(0, 1, At, B1); BAR; SCHED;
.Lpeel_3679:
	ds_read_b128 v[144:147], v141
	ds_read_b128 v[148:151], v141 offset:1024
	ds_read_b128 v[152:155], v141 offset:2048
	ds_read_b128 v[156:159], v141 offset:3072
	ds_read_b128 v[160:163], v142
	ds_read_b128 v[164:167], v142 offset:1024
	ds_read_b128 v[168:171], v142 offset:2048
	ds_read_b128 v[172:175], v142 offset:3072
	s_add_u32 s14, s34, 0xfffc0080
	s_addc_u32 s15, s35, -1
	s_cmp_eq_u32 s53, 12
	s_cselect_b32 s37, s9, s15
	s_cselect_b32 s36, s49, s14
	s_cselect_b32 s15, s11, s52
	s_cselect_b32 s14, s50, s51
	v_lshl_add_u64 v[208:209], s[34:35], 0, v[136:137]
	s_add_i32 m0, s25, 0xc000
	ds_read_b128 v[176:179], v143
	ds_read_b128 v[180:183], v143 offset:1024
	ds_read_b128 v[184:187], v143 offset:2048
	ds_read_b128 v[188:191], v143 offset:3072
	ds_read_b128 v[192:195], v143 offset:4096
	ds_read_b128 v[196:199], v143 offset:5120
	ds_read_b128 v[200:203], v143 offset:6144
	ds_read_b128 v[204:207], v143 offset:7168
	global_load_lds_dwordx4 v[208:209], off
	v_lshl_add_u64 v[208:209], s[34:35], 0, v[138:139]
	s_add_i32 m0, s25, 0xe000
	s_nop 0
	global_load_lds_dwordx4 v[208:209], off
	s_cmp_lg_u32 s100, 0
	s_cbranch_scc0 .Lrf_3679_0
	s_waitcnt vmcnt(16)
	s_branch .Lrj_3679_0

; #define G_STAGE(bufoff, gbase, voff) do { _Pragma("unroll") for (int _i = 0; _i < 2; ++_i) \
;         __builtin_amdgcn_global_load_lds((const unsigned*)((const char*)(gbase) + voff[_i]), (LAS unsigned*)(lds + (bufoff) + ldsw + _i * 8192), 16, 0, 0); } while (0)
; #define G_LDA(dst, b, h) do { _Pragma("unroll") for (int m = 0; m < 4; ++m) _Pragma("unroll") for (int k = 0; k < 2; ++k) dst[m][k] = *(const LAS bf16x8*)(lds + G_SA(b, h) + aoff + m * 2048 + k * 1024); } while (0)
; #define G_MMA(ai, bj, At_, Bt_) do { __builtin_amdgcn_s_setprio(1); _Pragma("unroll") for (int m = 0; m < 4; ++m) _Pragma("unroll") for (int n = 0; n < 2; ++n) _Pragma("unroll") for (int k = 0; k < 2; ++k) \
;         acc[ai][bj][m][n] = __builtin_amdgcn_mfma_f32_16x16x32_bf16(Bt_[n][k], At_[m][k], acc[ai][bj][m][n], 0, 0, 0); __builtin_amdgcn_s_setprio(0); } while (0)
; #define WAIT_V(n) asm volatile("s_waitcnt vmcnt(" #n ")" ::: "memory")
; #define WAIT_L(n) asm volatile("s_waitcnt lgkmcnt(" #n ")" ::: "memory")
; #define BAR __builtin_amdgcn_s_barrier()
; #define SCHED __builtin_amdgcn_sched_barrier(0)
; template <class Get, class Epi>
; DI void gemm_loop(int ntiles, int ld, char* shm, const Get& get, const Epi& epi) {
;     ...
;             WAIT_V(8); WAIT_L(0); BAR; G_MMA(0, 0, At, B0); G_MMA(0, 1, At, B1); BAR; SCHED;
;             G_LDA(At, 0, 1); G_STAGE(G_SB(0, 0), b2, voffB); G_STAGE(G_SB(0, 1), b2 + hstep, voffB); G_STAGE(G_SA(0, 0), a2, voffA);
;             WAIT_V(8); WAIT_L(0); BAR; G_MMA(1, 0, At, B0); G_MMA(1, 1, At, B1); BAR; SCHED;
.Lrj_3679_0:
	s_waitcnt lgkmcnt(0)
	s_barrier
	s_setprio 1
	s_waitcnt lgkmcnt(0)
	v_mfma_f32_16x16x32_bf16 v[124:127], v[144:147], v[176:179], 0
	v_mfma_f32_16x16x32_bf16 v[120:123], v[152:155], v[176:179], 0
	v_mfma_f32_16x16x32_bf16 v[108:111], v[144:147], v[184:187], 0
	v_mfma_f32_16x16x32_bf16 v[104:107], v[152:155], v[184:187], 0
	v_mfma_f32_16x16x32_bf16 v[92:95], v[144:147], v[192:195], 0
	v_mfma_f32_16x16x32_bf16 v[88:91], v[152:155], v[192:195], 0
	v_mfma_f32_16x16x32_bf16 v[76:79], v[144:147], v[200:203], 0
	v_mfma_f32_16x16x32_bf16 v[72:75], v[152:155], v[200:203], 0
	v_mfma_f32_16x16x32_bf16 v[124:127], v[148:151], v[180:183], v[124:127]
	v_mfma_f32_16x16x32_bf16 v[120:123], v[156:159], v[180:183], v[120:123]
	v_mfma_f32_16x16x32_bf16 v[108:111], v[148:151], v[188:191], v[108:111]
	v_mfma_f32_16x16x32_bf16 v[104:107], v[156:159], v[188:191], v[104:107]
	v_mfma_f32_16x16x32_bf16 v[92:95], v[148:151], v[196:199], v[92:95]
	v_mfma_f32_16x16x32_bf16 v[88:91], v[156:159], v[196:199], v[88:91]
	v_mfma_f32_16x16x32_bf16 v[76:79], v[148:151], v[204:207], v[76:79]
	v_mfma_f32_16x16x32_bf16 v[72:75], v[156:159], v[204:207], v[72:75]
	s_setprio 0
	s_setprio 1
	v_mfma_f32_16x16x32_bf16 v[116:119], v[160:163], v[176:179], 0
	v_mfma_f32_16x16x32_bf16 v[112:115], v[168:171], v[176:179], 0
	v_mfma_f32_16x16x32_bf16 v[100:103], v[160:163], v[184:187], 0
	v_mfma_f32_16x16x32_bf16 v[96:99], v[168:171], v[184:187], 0
	v_mfma_f32_16x16x32_bf16 v[84:87], v[160:163], v[192:195], 0
	v_mfma_f32_16x16x32_bf16 v[80:83], v[168:171], v[192:195], 0
	v_mfma_f32_16x16x32_bf16 v[68:71], v[160:163], v[200:203], 0
	v_mfma_f32_16x16x32_bf16 v[64:67], v[168:171], v[200:203], 0
	v_mfma_f32_16x16x32_bf16 v[116:119], v[164:167], v[180:183], v[116:119]
	v_mfma_f32_16x16x32_bf16 v[112:115], v[172:175], v[180:183], v[112:115]
	v_mfma_f32_16x16x32_bf16 v[100:103], v[164:167], v[188:191], v[100:103]
	v_mfma_f32_16x16x32_bf16 v[96:99], v[172:175], v[188:191], v[96:99]
	v_mfma_f32_16x16x32_bf16 v[84:87], v[164:167], v[196:199], v[84:87]
	v_mfma_f32_16x16x32_bf16 v[80:83], v[172:175], v[196:199], v[80:83]
	v_mfma_f32_16x16x32_bf16 v[68:71], v[164:167], v[204:207], v[68:71]
	v_mfma_f32_16x16x32_bf16 v[64:67], v[172:175], v[204:207], v[64:67]
	s_setprio 0
	s_barrier
	s_add_i32 s54, s44, s38
	v_lshl_add_u64 v[208:209], s[14:15], 0, v[132:133]
	s_mov_b32 m0, s54
	ds_read_b128 v[176:179], v143 offset:16384
	ds_read_b128 v[180:183], v143 offset:17408
	ds_read_b128 v[184:187], v143 offset:18432
	ds_read_b128 v[188:191], v143 offset:19456
	ds_read_b128 v[192:195], v143 offset:20480
	ds_read_b128 v[196:199], v143 offset:21504
	ds_read_b128 v[200:203], v143 offset:22528
	ds_read_b128 v[204:207], v143 offset:23552
	global_load_lds_dwordx4 v[208:209], off
	s_add_i32 m0, s54, 0x2000
	s_add_u32 s54, s14, 0x40000
	v_lshl_add_u64 v[210:211], s[14:15], 0, v[128:129]
	s_addc_u32 s55, s15, 0
	s_add_i32 s56, s45, s38
	global_load_lds_dwordx4 v[210:211], off
	v_lshl_add_u64 v[212:213], s[54:55], 0, v[132:133]
	s_mov_b32 m0, s56
	v_lshl_add_u64 v[214:215], s[36:37], 0, v[130:131]
	global_load_lds_dwordx4 v[212:213], off
	v_lshl_add_u64 v[212:213], s[54:55], 0, v[128:129]
	s_add_i32 m0, s56, 0x2000
	s_nop 0
	global_load_lds_dwordx4 v[212:213], off
	v_lshl_add_u64 v[212:213], s[36:37], 0, v[134:135]
	s_mov_b32 m0, s25
	s_nop 0
	global_load_lds_dwordx4 v[212:213], off
	s_mov_b32 m0, s31
	s_nop 0
	global_load_lds_dwordx4 v[214:215], off
	s_cmp_lg_u32 s100, 0
	s_cbranch_scc0 .Lrf_3679_1
	s_waitcnt vmcnt(16)
	s_branch .Lrj_3679_1

; #define G_STAGE(bufoff, gbase, voff) do { _Pragma("unroll") for (int _i = 0; _i < 2; ++_i) \
;         __builtin_amdgcn_global_load_lds((const unsigned*)((const char*)(gbase) + voff[_i]), (LAS unsigned*)(lds + (bufoff) + ldsw + _i * 8192), 16, 0, 0); } while (0)
; #define G_LDA(dst, b, h) do { _Pragma("unroll") for (int m = 0; m < 4; ++m) _Pragma("unroll") for (int k = 0; k < 2; ++k) dst[m][k] = *(const LAS bf16x8*)(lds + G_SA(b, h) + aoff + m * 2048 + k * 1024); } while (0)
; #define G_LDB(dst, b, h) do { _Pragma("unroll") for (int n = 0; n < 2; ++n) _Pragma("unroll") for (int k = 0; k < 2; ++k) dst[n][k] = *(const LAS bf16x8*)(lds + G_SB(b, h) + boff + n * 2048 + k * 1024); } while (0)
; #define G_MMA(ai, bj, At_, Bt_) do { __builtin_amdgcn_s_setprio(1); _Pragma("unroll") for (int m = 0; m < 4; ++m) _Pragma("unroll") for (int n = 0; n < 2; ++n) _Pragma("unroll") for (int k = 0; k < 2; ++k) \
;         acc[ai][bj][m][n] = __builtin_amdgcn_mfma_f32_16x16x32_bf16(Bt_[n][k], At_[m][k], acc[ai][bj][m][n], 0, 0, 0); __builtin_amdgcn_s_setprio(0); } while (0)
; #define WAIT_V(n) asm volatile("s_waitcnt vmcnt(" #n ")" ::: "memory")
; #define WAIT_L(n) asm volatile("s_waitcnt lgkmcnt(" #n ")" ::: "memory")
; #define BAR __builtin_amdgcn_s_barrier()
; #define SCHED __builtin_amdgcn_sched_barrier(0)
; template <class Get, class Epi>
; DI void gemm_loop(int ntiles, int ld, char* shm, const Get& get, const Epi& epi) {
;     ...
;             WAIT_V(8); WAIT_L(0); BAR; G_MMA(1, 0, At, B0); G_MMA(1, 1, At, B1); BAR; SCHED;
;             G_LDB(B0, 1, 0); G_LDB(B1, 1, 1); SCHED; G_LDA(At, 1, 0); G_STAGE(G_SA(0, 1), a2 + hstep, voffA);
;             WAIT_V(8); WAIT_L(0); BAR; G_MMA(0, 0, At, B0); G_MMA(0, 1, At, B1); BAR; SCHED;
.Lrj_3679_1:
	s_waitcnt lgkmcnt(0)
	s_barrier
	s_setprio 1
	s_waitcnt lgkmcnt(0)
	v_mfma_f32_16x16x32_bf16 v[60:63], v[144:147], v[176:179], 0
	v_mfma_f32_16x16x32_bf16 v[56:59], v[152:155], v[176:179], 0
	v_mfma_f32_16x16x32_bf16 v[44:47], v[144:147], v[184:187], 0
	v_mfma_f32_16x16x32_bf16 v[40:43], v[152:155], v[184:187], 0
	v_mfma_f32_16x16x32_bf16 v[28:31], v[144:147], v[192:195], 0
	v_mfma_f32_16x16x32_bf16 v[24:27], v[152:155], v[192:195], 0
	v_mfma_f32_16x16x32_bf16 v[12:15], v[144:147], v[200:203], 0
	v_mfma_f32_16x16x32_bf16 v[8:11], v[152:155], v[200:203], 0
	v_mfma_f32_16x16x32_bf16 v[60:63], v[148:151], v[180:183], v[60:63]
	v_mfma_f32_16x16x32_bf16 v[56:59], v[156:159], v[180:183], v[56:59]
	v_mfma_f32_16x16x32_bf16 v[44:47], v[148:151], v[188:191], v[44:47]
	v_mfma_f32_16x16x32_bf16 v[40:43], v[156:159], v[188:191], v[40:43]
	v_mfma_f32_16x16x32_bf16 v[28:31], v[148:151], v[196:199], v[28:31]
	v_mfma_f32_16x16x32_bf16 v[24:27], v[156:159], v[196:199], v[24:27]
	v_mfma_f32_16x16x32_bf16 v[12:15], v[148:151], v[204:207], v[12:15]
	v_mfma_f32_16x16x32_bf16 v[8:11], v[156:159], v[204:207], v[8:11]
	s_setprio 0
	s_setprio 1
	v_mfma_f32_16x16x32_bf16 v[52:55], v[160:163], v[176:179], 0
	v_mfma_f32_16x16x32_bf16 v[48:51], v[168:171], v[176:179], 0
	v_mfma_f32_16x16x32_bf16 v[36:39], v[160:163], v[184:187], 0
	v_mfma_f32_16x16x32_bf16 v[32:35], v[168:171], v[184:187], 0
	v_mfma_f32_16x16x32_bf16 v[20:23], v[160:163], v[192:195], 0
	v_mfma_f32_16x16x32_bf16 v[16:19], v[168:171], v[192:195], 0
	v_mfma_f32_16x16x32_bf16 v[4:7], v[160:163], v[200:203], 0
	v_mfma_f32_16x16x32_bf16 v[0:3], v[168:171], v[200:203], 0
	v_mfma_f32_16x16x32_bf16 v[52:55], v[164:167], v[180:183], v[52:55]
	v_mfma_f32_16x16x32_bf16 v[48:51], v[172:175], v[180:183], v[48:51]
	v_mfma_f32_16x16x32_bf16 v[36:39], v[164:167], v[188:191], v[36:39]
	v_mfma_f32_16x16x32_bf16 v[32:35], v[172:175], v[188:191], v[32:35]
	v_mfma_f32_16x16x32_bf16 v[20:23], v[164:167], v[196:199], v[20:23]
	v_mfma_f32_16x16x32_bf16 v[16:19], v[172:175], v[196:199], v[16:19]
	v_mfma_f32_16x16x32_bf16 v[4:7], v[164:167], v[204:207], v[4:7]
	v_mfma_f32_16x16x32_bf16 v[0:3], v[172:175], v[204:207], v[0:3]
	s_setprio 0
	s_barrier
	s_add_i32 s54, 0, 0x18000
	s_add_i32 s55, 0, 0x1c000
	v_add_u32_e32 v156, s54, v140
	v_add_u32_e32 v172, s55, v140
	ds_read_b128 v[144:147], v156
	ds_read_b128 v[148:151], v156 offset:1024
	ds_read_b128 v[152:155], v156 offset:2048
	ds_read_b128 v[156:159], v156 offset:3072
	ds_read_b128 v[160:163], v172
	ds_read_b128 v[164:167], v172 offset:1024
	ds_read_b128 v[168:171], v172 offset:2048
	ds_read_b128 v[172:175], v172 offset:3072
	s_add_u32 s36, s36, 0x40000
	s_addc_u32 s37, s37, 0
	s_mov_b32 m0, s40
	v_lshl_add_u64 v[216:217], s[36:37], 0, v[134:135]
	ds_read_b128 v[176:179], v143 offset:32768
	ds_read_b128 v[180:183], v143 offset:33792
	ds_read_b128 v[184:187], v143 offset:34816
	ds_read_b128 v[188:191], v143 offset:35840
	ds_read_b128 v[192:195], v143 offset:36864
	ds_read_b128 v[196:199], v143 offset:37888
	ds_read_b128 v[200:203], v143 offset:38912
	ds_read_b128 v[204:207], v143 offset:39936
	global_load_lds_dwordx4 v[216:217], off
	v_lshl_add_u64 v[216:217], s[36:37], 0, v[130:131]
	s_mov_b32 m0, s41
	s_nop 0
	global_load_lds_dwordx4 v[216:217], off
	s_waitcnt vmcnt(8)
	s_waitcnt lgkmcnt(0)
	s_barrier
	s_setprio 1
	s_waitcnt lgkmcnt(0)
	v_mfma_f32_16x16x32_bf16 v[124:127], v[144:147], v[176:179], v[124:127]
	v_mfma_f32_16x16x32_bf16 v[120:123], v[152:155], v[176:179], v[120:123]
	v_mfma_f32_16x16x32_bf16 v[108:111], v[144:147], v[184:187], v[108:111]
	v_mfma_f32_16x16x32_bf16 v[104:107], v[152:155], v[184:187], v[104:107]
	v_mfma_f32_16x16x32_bf16 v[92:95], v[144:147], v[192:195], v[92:95]
	v_mfma_f32_16x16x32_bf16 v[88:91], v[152:155], v[192:195], v[88:91]
	v_mfma_f32_16x16x32_bf16 v[76:79], v[144:147], v[200:203], v[76:79]
	v_mfma_f32_16x16x32_bf16 v[72:75], v[152:155], v[200:203], v[72:75]
	v_mfma_f32_16x16x32_bf16 v[124:127], v[148:151], v[180:183], v[124:127]
	v_mfma_f32_16x16x32_bf16 v[120:123], v[156:159], v[180:183], v[120:123]
	v_mfma_f32_16x16x32_bf16 v[108:111], v[148:151], v[188:191], v[108:111]
	v_mfma_f32_16x16x32_bf16 v[104:107], v[156:159], v[188:191], v[104:107]
	v_mfma_f32_16x16x32_bf16 v[92:95], v[148:151], v[196:199], v[92:95]
	v_mfma_f32_16x16x32_bf16 v[88:91], v[156:159], v[196:199], v[88:91]
	v_mfma_f32_16x16x32_bf16 v[76:79], v[148:151], v[204:207], v[76:79]
	v_mfma_f32_16x16x32_bf16 v[72:75], v[156:159], v[204:207], v[72:75]
	s_setprio 0
	s_setprio 1
	v_mfma_f32_16x16x32_bf16 v[116:119], v[160:163], v[176:179], v[116:119]
	v_mfma_f32_16x16x32_bf16 v[112:115], v[168:171], v[176:179], v[112:115]
	v_mfma_f32_16x16x32_bf16 v[100:103], v[160:163], v[184:187], v[100:103]
	v_mfma_f32_16x16x32_bf16 v[96:99], v[168:171], v[184:187], v[96:99]
	v_mfma_f32_16x16x32_bf16 v[84:87], v[160:163], v[192:195], v[84:87]
	v_mfma_f32_16x16x32_bf16 v[80:83], v[168:171], v[192:195], v[80:83]
	v_mfma_f32_16x16x32_bf16 v[68:71], v[160:163], v[200:203], v[68:71]
	v_mfma_f32_16x16x32_bf16 v[64:67], v[168:171], v[200:203], v[64:67]
	v_mfma_f32_16x16x32_bf16 v[116:119], v[164:167], v[180:183], v[116:119]
	v_mfma_f32_16x16x32_bf16 v[112:115], v[172:175], v[180:183], v[112:115]
	v_mfma_f32_16x16x32_bf16 v[100:103], v[164:167], v[188:191], v[100:103]
	v_mfma_f32_16x16x32_bf16 v[96:99], v[172:175], v[188:191], v[96:99]
	v_mfma_f32_16x16x32_bf16 v[84:87], v[164:167], v[196:199], v[84:87]
	v_mfma_f32_16x16x32_bf16 v[80:83], v[172:175], v[196:199], v[80:83]
	v_mfma_f32_16x16x32_bf16 v[68:71], v[164:167], v[204:207], v[68:71]
	v_mfma_f32_16x16x32_bf16 v[64:67], v[172:175], v[204:207], v[64:67]
	s_setprio 0
	s_barrier
; #define G_STAGE(bufoff, gbase, voff) do { _Pragma("unroll") for (int _i = 0; _i < 2; ++_i) \
;         __builtin_amdgcn_global_load_lds((const unsigned*)((const char*)(gbase) + voff[_i]), (LAS unsigned*)(lds + (bufoff) + ldsw + _i * 8192), 16, 0, 0); } while (0)
; #define G_LDA(dst, b, h) do { _Pragma("unroll") for (int m = 0; m < 4; ++m) _Pragma("unroll") for (int k = 0; k < 2; ++k) dst[m][k] = *(const LAS bf16x8*)(lds + G_SA(b, h) + aoff + m * 2048 + k * 1024); } while (0)
; #define G_MMA(ai, bj, At_, Bt_) do { __builtin_amdgcn_s_setprio(1); _Pragma("unroll") for (int m = 0; m < 4; ++m) _Pragma("unroll") for (int n = 0; n < 2; ++n) _Pragma("unroll") for (int k = 0; k < 2; ++k) \
;         acc[ai][bj][m][n] = __builtin_amdgcn_mfma_f32_16x16x32_bf16(Bt_[n][k], At_[m][k], acc[ai][bj][m][n], 0, 0, 0); __builtin_amdgcn_s_setprio(0); } while (0)
; #define WAIT_V(n) asm volatile("s_waitcnt vmcnt(" #n ")" ::: "memory")
; #define WAIT_L(n) asm volatile("s_waitcnt lgkmcnt(" #n ")" ::: "memory")
; #define BAR __builtin_amdgcn_s_barrier()
; #define SCHED __builtin_amdgcn_sched_barrier(0)
; template <class Get, class Epi>
; DI void gemm_loop(int ntiles, int ld, char* shm, const Get& get, const Epi& epi) {
;     ...
;             G_LDA(At, 1, 1); G_STAGE(G_SB(1, 0), b3, voffB); G_STAGE(G_SB(1, 1), b3 + hstep, voffB); G_STAGE(G_SA(1, 0), a3, voffA);
;             WAIT_V(8); WAIT_L(0); BAR; G_MMA(1, 0, At, B0); G_MMA(1, 1, At, B1); BAR; SCHED;
;         }
	s_add_i32 s36, s54, s38
	v_lshl_add_u64 v[208:209], v[208:209], 0, s[2:3]
	s_mov_b32 m0, s36
	ds_read_b128 v[176:179], v143 offset:49152
	ds_read_b128 v[180:183], v143 offset:50176
	ds_read_b128 v[184:187], v143 offset:51200
	ds_read_b128 v[188:191], v143 offset:52224
	ds_read_b128 v[192:195], v143 offset:53248
	ds_read_b128 v[196:199], v143 offset:54272
	ds_read_b128 v[200:203], v143 offset:55296
	ds_read_b128 v[204:207], v143 offset:56320
	global_load_lds_dwordx4 v[208:209], off
	s_add_i32 m0, s36, 0x2000
	s_add_u32 s14, s14, 0x40080
	v_lshl_add_u64 v[208:209], v[210:211], 0, s[2:3]
	s_addc_u32 s15, s15, 0
	s_add_i32 s36, s55, s38
	global_load_lds_dwordx4 v[208:209], off
	v_lshl_add_u64 v[208:209], s[14:15], 0, v[132:133]
	s_mov_b32 m0, s36
	s_nop 0
	global_load_lds_dwordx4 v[208:209], off
	v_lshl_add_u64 v[208:209], s[14:15], 0, v[128:129]
	s_add_i32 m0, s36, 0x2000
	s_nop 0
	global_load_lds_dwordx4 v[208:209], off
	v_lshl_add_u64 v[208:209], v[212:213], 0, s[2:3]
	s_mov_b32 m0, s42
	s_nop 0
	global_load_lds_dwordx4 v[208:209], off
	v_lshl_add_u64 v[208:209], v[214:215], 0, s[2:3]
	s_mov_b32 m0, s43
	s_nop 0
	global_load_lds_dwordx4 v[208:209], off
	s_waitcnt vmcnt(8)
	s_waitcnt lgkmcnt(0)
	s_barrier
	s_setprio 1
	s_waitcnt lgkmcnt(0)
	v_mfma_f32_16x16x32_bf16 v[60:63], v[144:147], v[176:179], v[60:63]
	v_mfma_f32_16x16x32_bf16 v[56:59], v[152:155], v[176:179], v[56:59]
	v_mfma_f32_16x16x32_bf16 v[44:47], v[144:147], v[184:187], v[44:47]
	v_mfma_f32_16x16x32_bf16 v[40:43], v[152:155], v[184:187], v[40:43]
	v_mfma_f32_16x16x32_bf16 v[28:31], v[144:147], v[192:195], v[28:31]
	v_mfma_f32_16x16x32_bf16 v[24:27], v[152:155], v[192:195], v[24:27]
	v_mfma_f32_16x16x32_bf16 v[12:15], v[144:147], v[200:203], v[12:15]
	v_mfma_f32_16x16x32_bf16 v[8:11], v[152:155], v[200:203], v[8:11]
	v_mfma_f32_16x16x32_bf16 v[60:63], v[148:151], v[180:183], v[60:63]
	v_mfma_f32_16x16x32_bf16 v[56:59], v[156:159], v[180:183], v[56:59]
	v_mfma_f32_16x16x32_bf16 v[44:47], v[148:151], v[188:191], v[44:47]
	v_mfma_f32_16x16x32_bf16 v[40:43], v[156:159], v[188:191], v[40:43]
	v_mfma_f32_16x16x32_bf16 v[28:31], v[148:151], v[196:199], v[28:31]
	v_mfma_f32_16x16x32_bf16 v[24:27], v[156:159], v[196:199], v[24:27]
	v_mfma_f32_16x16x32_bf16 v[12:15], v[148:151], v[204:207], v[12:15]
	v_mfma_f32_16x16x32_bf16 v[8:11], v[156:159], v[204:207], v[8:11]
	s_setprio 0
	s_setprio 1
	v_mfma_f32_16x16x32_bf16 v[52:55], v[160:163], v[176:179], v[52:55]
	v_mfma_f32_16x16x32_bf16 v[48:51], v[168:171], v[176:179], v[48:51]
	v_mfma_f32_16x16x32_bf16 v[36:39], v[160:163], v[184:187], v[36:39]
	v_mfma_f32_16x16x32_bf16 v[32:35], v[168:171], v[184:187], v[32:35]
	v_mfma_f32_16x16x32_bf16 v[20:23], v[160:163], v[192:195], v[20:23]
	v_mfma_f32_16x16x32_bf16 v[16:19], v[168:171], v[192:195], v[16:19]
	v_mfma_f32_16x16x32_bf16 v[4:7], v[160:163], v[200:203], v[4:7]
	v_mfma_f32_16x16x32_bf16 v[0:3], v[168:171], v[200:203], v[0:3]
	v_mfma_f32_16x16x32_bf16 v[52:55], v[164:167], v[180:183], v[52:55]
	v_mfma_f32_16x16x32_bf16 v[48:51], v[172:175], v[180:183], v[48:51]
	v_mfma_f32_16x16x32_bf16 v[36:39], v[164:167], v[188:191], v[36:39]
	v_mfma_f32_16x16x32_bf16 v[32:35], v[172:175], v[188:191], v[32:35]
	v_mfma_f32_16x16x32_bf16 v[20:23], v[164:167], v[196:199], v[20:23]
	v_mfma_f32_16x16x32_bf16 v[16:19], v[172:175], v[196:199], v[16:19]
	v_mfma_f32_16x16x32_bf16 v[4:7], v[164:167], v[204:207], v[4:7]
	v_mfma_f32_16x16x32_bf16 v[0:3], v[172:175], v[204:207], v[0:3]
	s_setprio 0
	s_barrier
	s_add_i32 s53, s53, 2
	s_add_u32 s34, s34, 0x100
	s_addc_u32 s35, s35, 0
	s_add_u32 s51, s51, 0x100
	s_addc_u32 s52, s52, 0
	s_cmp_gt_u32 s53, 13
	s_cbranch_scc0 .LBB0_3679
	s_branch .Lpost_3679

; #define G_STAGE(bufoff, gbase, voff) do { _Pragma("unroll") for (int _i = 0; _i < 2; ++_i) \
;         __builtin_amdgcn_global_load_lds((const unsigned*)((const char*)(gbase) + voff[_i]), (LAS unsigned*)(lds + (bufoff) + ldsw + _i * 8192), 16, 0, 0); } while (0)
; #define WAIT_V(n) asm volatile("s_waitcnt vmcnt(" #n ")" ::: "memory")
; #define BAR __builtin_amdgcn_s_barrier()
; template <class Get, class Epi>
; DI void gemm_loop(int ntiles, int ld, char* shm, const Get& get, const Epi& epi) {
;     ...
;     for (int i = 0; i < 2; ++i) { int R, C; stage_rc(tid * 16 + i * 8192, R, C); const int rho = R & 31, Rb = (R & ~31) + 8 * ((rho & 15) >> 2) + 4 * (rho >> 4) + (rho & 3);
;         voffA[i] = (unsigned)(R * ld + C) * 2u; voffB[i] = (unsigned)(Rb * ld + C) * 2u; }
;     const size_t kstep = (size_t)(BK * 2), hstep = (size_t)HALF * ld * 2;
;     const unsigned ldsw = (unsigned)wid * 1024u;
;     const int aoff = lds_byte(wr * 64 + fr, fq * 8), boff = lds_byte(wc * 32 + fr, fq * 8);
;     ...
;     int L = bx; if (L >= ntiles) return;
;     Tile cur = get(L), nxt = cur;
;     AccT acc;
;     ...
;     G_ZERO;
;     bf16x8 At[4][2], B0[2][2], B1[2][2];
;     const char* cA = (const char*)cur.A + (size_t)cur.brow * ld * 2; const char* cB = (const char*)cur.Bt + (size_t)cur.bcol * ld * 2;
;     G_STAGE(G_SB(0, 0), cB, voffB); G_STAGE(G_SB(0, 1), cB + hstep, voffB); G_STAGE(G_SA(0, 0), cA, voffA); G_STAGE(G_SA(0, 1), cA + hstep, voffA);
;     if (wr == 1) BAR;
;     WAIT_V(2); BAR;
;     G_STAGE(G_SB(1, 0), cB + kstep, voffB); G_STAGE(G_SA(1, 0), cA + kstep, voffA); G_STAGE(G_SB(1, 1), cB + hstep + kstep, voffB);
;     WAIT_V(6); BAR;
.LBB0_3745:
	s_lshl_b32 s51, s7, 8
	s_add_u32 s40, s68, 0x8a7000
	s_addc_u32 s41, s69, 0
	s_lshl_b32 s6, s6, 12
	s_and_b32 s9, s6, 0x3000
	s_mov_b64 s[6:7], 0x80
	s_add_i32 m0, s36, 0x18000
	v_lshl_add_u64 v[6:7], v[6:7], 0, s[6:7]
	s_lshl_b32 s1, s1, 13
	s_waitcnt vmcnt(2)
	s_barrier
	global_load_lds_dwordx4 v[6:7], off
	v_lshl_add_u64 v[4:5], v[4:5], 0, s[6:7]
	s_add_i32 m0, s36, 0x1a000
	s_add_i32 s42, s36, 0x8000
	s_add_i32 s43, s36, 0xa000
	global_load_lds_dwordx4 v[4:5], off
	v_lshl_add_u64 v[0:1], v[0:1], 0, s[6:7]
	s_mov_b32 m0, s42
	s_add_u32 s10, s24, 0xb0080
	global_load_lds_dwordx4 v[0:1], off
	v_lshl_add_u64 v[0:1], v[2:3], 0, s[6:7]
	s_mov_b32 m0, s43
	s_addc_u32 s11, s25, 0
	global_load_lds_dwordx4 v[0:1], off
	s_add_i32 m0, s36, 0x1c000
	v_lshl_add_u64 v[0:1], s[10:11], 0, v[148:149]
	global_load_lds_dwordx4 v[0:1], off
	v_lshl_add_u64 v[0:1], s[10:11], 0, v[152:153]
	s_add_i32 m0, s36, 0x1e000
	v_lshlrev_b32_e32 v3, 2, v8
	global_load_lds_dwordx4 v[0:1], off
	v_and_b32_e32 v0, 15, v8
	v_and_b32_e32 v1, 48, v8
	v_lshlrev_b32_e32 v0, 6, v0
	v_and_b32_e32 v3, 32, v3
	v_or_b32_e32 v2, v0, v1
	v_bitop3_b32 v0, v0, v3, v1 bitop3:0x36
	v_bitop3_b32 v2, v2, s1, v3 bitop3:0xde
	v_or_b32_e32 v168, s9, v0
	v_lshrrev_b32_e32 v1, 1, v9
	v_mul_lo_u32 v0, v11, s0
	s_mov_b32 s1, 0xb000
	v_mad_u64_u32 v[0:1], s[14:15], v1, s1, v[0:1]
	v_or_b32_e32 v0, v0, v10
	s_mov_b64 s[12:13], 0xb0080
	v_add_lshl_u32 v0, v0, v12, 1
	v_mov_b32_e32 v1, v149
	v_lshl_add_u64 v[154:155], v[0:1], 0, s[12:13]
	v_lshrrev_b32_e32 v1, 1, v13
	v_mul_lo_u32 v0, v14, s0
	s_cmpk_lt_u32 s8, 0x100
	v_mad_u64_u32 v[0:1], s[0:1], v1, s1, v[0:1]
	s_waitcnt vmcnt(6)
	s_mov_b32 s100, 0
	s_cselect_b64 s[8:9], -1, 0
	s_add_u32 s10, s68, 0x8d7000
	v_or_b32_e32 v0, v0, v15
	s_addc_u32 s11, s69, 0
	v_add_lshl_u32 v0, v0, v16, 1
	v_mov_b32_e32 v1, v149
	s_add_i32 s44, 0, 0x10000
	s_add_i32 s45, 0, 0x14000
	v_lshl_add_u64 v[156:157], v[0:1], 0, s[12:13]
	v_add_u32_e32 v169, s44, v168
	v_add_u32_e32 v170, s45, v168
	v_add_u32_e32 v171, 0, v2
	s_movk_i32 s46, 0xffc0
	s_mov_b64 s[12:13], 0x80000
	s_mov_b64 s[14:15], 0x90000
	s_mov_b64 s[18:19], 0xa0000
	s_mov_b32 s49, s51
	s_mov_b32 s48, s50
	s_barrier
	s_branch .LBB0_3748

; #define G_STAGE(bufoff, gbase, voff) do { _Pragma("unroll") for (int _i = 0; _i < 2; ++_i) \
;         __builtin_amdgcn_global_load_lds((const unsigned*)((const char*)(gbase) + voff[_i]), (LAS unsigned*)(lds + (bufoff) + ldsw + _i * 8192), 16, 0, 0); } while (0)
; #define G_LDA(dst, b, h) do { _Pragma("unroll") for (int m = 0; m < 4; ++m) _Pragma("unroll") for (int k = 0; k < 2; ++k) dst[m][k] = *(const LAS bf16x8*)(lds + G_SA(b, h) + aoff + m * 2048 + k * 1024); } while (0)
; #define G_LDB(dst, b, h) do { _Pragma("unroll") for (int n = 0; n < 2; ++n) _Pragma("unroll") for (int k = 0; k < 2; ++k) dst[n][k] = *(const LAS bf16x8*)(lds + G_SB(b, h) + boff + n * 2048 + k * 1024); } while (0)
; #define G_MMA(ai, bj, At_, Bt_) do { __builtin_amdgcn_s_setprio(1); _Pragma("unroll") for (int m = 0; m < 4; ++m) _Pragma("unroll") for (int n = 0; n < 2; ++n) _Pragma("unroll") for (int k = 0; k < 2; ++k) \
;         acc[ai][bj][m][n] = __builtin_amdgcn_mfma_f32_16x16x32_bf16(Bt_[n][k], At_[m][k], acc[ai][bj][m][n], 0, 0, 0); __builtin_amdgcn_s_setprio(0); } while (0)
; #define WAIT_V(n) asm volatile("s_waitcnt vmcnt(" #n ")" ::: "memory")
; #define WAIT_L(n) asm volatile("s_waitcnt lgkmcnt(" #n ")" ::: "memory")
; #define BAR __builtin_amdgcn_s_barrier()
; #define SCHED __builtin_amdgcn_sched_barrier(0)
; template <class Get, class Epi>
; DI void gemm_loop(int ntiles, int ld, char* shm, const Get& get, const Epi& epi) {
;     ...
;             G_LDB(B0, 0, 0); G_LDB(B1, 0, 1); SCHED; G_LDA(At, 0, 0); G_STAGE(G_SA(1, 1), a1 + hstep, voffA);
;             WAIT_V(8); WAIT_L(0); BAR; G_MMA(0, 0, At, B0); G_MMA(0, 1, At, B1); BAR; SCHED;
.Lpeel_3759:
	ds_read_b128 v[128:131], v169
	ds_read_b128 v[132:135], v169 offset:1024
	ds_read_b128 v[136:139], v169 offset:2048
	ds_read_b128 v[140:143], v169 offset:3072
	ds_read_b128 v[158:161], v170
	ds_read_b128 v[162:165], v170 offset:1024
	ds_read_b128 v[172:175], v170 offset:2048
	ds_read_b128 v[176:179], v170 offset:3072
	s_add_u32 s24, s2, 0x100
	s_addc_u32 s25, s3, 0
	s_cmp_eq_u32 s54, 40
	s_cselect_b32 s35, s21, s25
	s_cselect_b32 s34, s20, s24
	s_cselect_b32 s31, s23, s53
	s_cselect_b32 s30, s22, s52
	v_lshl_add_u64 v[144:145], s[2:3], 0, v[154:155]
	s_add_i32 m0, s36, 0xc000
	ds_read_b128 v[180:183], v171
	ds_read_b128 v[184:187], v171 offset:1024
	ds_read_b128 v[188:191], v171 offset:2048
	ds_read_b128 v[192:195], v171 offset:3072
	ds_read_b128 v[196:199], v171 offset:4096
	ds_read_b128 v[200:203], v171 offset:5120
	ds_read_b128 v[204:207], v171 offset:6144
	ds_read_b128 v[208:211], v171 offset:7168
	global_load_lds_dwordx4 v[144:145], off
	v_lshl_add_u64 v[144:145], s[2:3], 0, v[156:157]
	s_add_i32 m0, s36, 0xe000
	s_nop 0
	global_load_lds_dwordx4 v[144:145], off
	s_cmp_lg_u32 s100, 0
	s_cbranch_scc0 .Lrf_3759_0
	s_waitcnt vmcnt(16)
	s_branch .Lrj_3759_0

; #define G_STAGE(bufoff, gbase, voff) do { _Pragma("unroll") for (int _i = 0; _i < 2; ++_i) \
;         __builtin_amdgcn_global_load_lds((const unsigned*)((const char*)(gbase) + voff[_i]), (LAS unsigned*)(lds + (bufoff) + ldsw + _i * 8192), 16, 0, 0); } while (0)
; #define G_LDA(dst, b, h) do { _Pragma("unroll") for (int m = 0; m < 4; ++m) _Pragma("unroll") for (int k = 0; k < 2; ++k) dst[m][k] = *(const LAS bf16x8*)(lds + G_SA(b, h) + aoff + m * 2048 + k * 1024); } while (0)
; #define G_MMA(ai, bj, At_, Bt_) do { __builtin_amdgcn_s_setprio(1); _Pragma("unroll") for (int m = 0; m < 4; ++m) _Pragma("unroll") for (int n = 0; n < 2; ++n) _Pragma("unroll") for (int k = 0; k < 2; ++k) \
;         acc[ai][bj][m][n] = __builtin_amdgcn_mfma_f32_16x16x32_bf16(Bt_[n][k], At_[m][k], acc[ai][bj][m][n], 0, 0, 0); __builtin_amdgcn_s_setprio(0); } while (0)
; #define WAIT_V(n) asm volatile("s_waitcnt vmcnt(" #n ")" ::: "memory")
; #define WAIT_L(n) asm volatile("s_waitcnt lgkmcnt(" #n ")" ::: "memory")
; #define BAR __builtin_amdgcn_s_barrier()
; #define SCHED __builtin_amdgcn_sched_barrier(0)
; template <class Get, class Epi>
; DI void gemm_loop(int ntiles, int ld, char* shm, const Get& get, const Epi& epi) {
;     ...
;             WAIT_V(8); WAIT_L(0); BAR; G_MMA(0, 0, At, B0); G_MMA(0, 1, At, B1); BAR; SCHED;
;             G_LDA(At, 0, 1); G_STAGE(G_SB(0, 0), b2, voffB); G_STAGE(G_SB(0, 1), b2 + hstep, voffB); G_STAGE(G_SA(0, 0), a2, voffA);
;             WAIT_V(8); WAIT_L(0); BAR; G_MMA(1, 0, At, B0); G_MMA(1, 1, At, B1); BAR; SCHED;
.Lrj_3759_0:
	s_waitcnt lgkmcnt(0)
	s_barrier
	s_setprio 1
	s_waitcnt lgkmcnt(0)
	v_mfma_f32_16x16x32_bf16 v[124:127], v[128:131], v[180:183], 0
	v_mfma_f32_16x16x32_bf16 v[120:123], v[136:139], v[180:183], 0
	v_mfma_f32_16x16x32_bf16 v[116:119], v[128:131], v[188:191], 0
	v_mfma_f32_16x16x32_bf16 v[112:115], v[136:139], v[188:191], 0
	v_mfma_f32_16x16x32_bf16 v[108:111], v[128:131], v[196:199], 0
	v_mfma_f32_16x16x32_bf16 v[104:107], v[136:139], v[196:199], 0
	v_mfma_f32_16x16x32_bf16 v[100:103], v[128:131], v[204:207], 0
	v_mfma_f32_16x16x32_bf16 v[96:99], v[136:139], v[204:207], 0
	v_mfma_f32_16x16x32_bf16 v[124:127], v[132:135], v[184:187], v[124:127]
	v_mfma_f32_16x16x32_bf16 v[120:123], v[140:143], v[184:187], v[120:123]
	v_mfma_f32_16x16x32_bf16 v[116:119], v[132:135], v[192:195], v[116:119]
	v_mfma_f32_16x16x32_bf16 v[112:115], v[140:143], v[192:195], v[112:115]
	v_mfma_f32_16x16x32_bf16 v[108:111], v[132:135], v[200:203], v[108:111]
	v_mfma_f32_16x16x32_bf16 v[104:107], v[140:143], v[200:203], v[104:107]
	v_mfma_f32_16x16x32_bf16 v[100:103], v[132:135], v[208:211], v[100:103]
	v_mfma_f32_16x16x32_bf16 v[96:99], v[140:143], v[208:211], v[96:99]
	s_setprio 0
	s_setprio 1
	v_mfma_f32_16x16x32_bf16 v[60:63], v[158:161], v[180:183], 0
	v_mfma_f32_16x16x32_bf16 v[56:59], v[172:175], v[180:183], 0
	v_mfma_f32_16x16x32_bf16 v[52:55], v[158:161], v[188:191], 0
	v_mfma_f32_16x16x32_bf16 v[48:51], v[172:175], v[188:191], 0
	v_mfma_f32_16x16x32_bf16 v[44:47], v[158:161], v[196:199], 0
	v_mfma_f32_16x16x32_bf16 v[40:43], v[172:175], v[196:199], 0
	v_mfma_f32_16x16x32_bf16 v[36:39], v[158:161], v[204:207], 0
	v_mfma_f32_16x16x32_bf16 v[32:35], v[172:175], v[204:207], 0
	v_mfma_f32_16x16x32_bf16 v[60:63], v[162:165], v[184:187], v[60:63]
	v_mfma_f32_16x16x32_bf16 v[56:59], v[176:179], v[184:187], v[56:59]
	v_mfma_f32_16x16x32_bf16 v[52:55], v[162:165], v[192:195], v[52:55]
	v_mfma_f32_16x16x32_bf16 v[48:51], v[176:179], v[192:195], v[48:51]
	v_mfma_f32_16x16x32_bf16 v[44:47], v[162:165], v[200:203], v[44:47]
	v_mfma_f32_16x16x32_bf16 v[40:43], v[176:179], v[200:203], v[40:43]
	v_mfma_f32_16x16x32_bf16 v[36:39], v[162:165], v[208:211], v[36:39]
	v_mfma_f32_16x16x32_bf16 v[32:35], v[176:179], v[208:211], v[32:35]
	s_setprio 0
	s_barrier
	s_add_i32 s2, s44, s33
	v_lshl_add_u64 v[144:145], s[30:31], 0, v[148:149]
	s_mov_b32 m0, s2
	ds_read_b128 v[180:183], v171 offset:16384
	ds_read_b128 v[184:187], v171 offset:17408
	ds_read_b128 v[188:191], v171 offset:18432
	ds_read_b128 v[192:195], v171 offset:19456
	ds_read_b128 v[196:199], v171 offset:20480
	ds_read_b128 v[200:203], v171 offset:21504
	ds_read_b128 v[204:207], v171 offset:22528
	ds_read_b128 v[208:211], v171 offset:23552
	global_load_lds_dwordx4 v[144:145], off
	s_add_i32 m0, s2, 0x2000
	s_add_u32 s2, s30, 0xb0000
	v_lshl_add_u64 v[166:167], s[30:31], 0, v[152:153]
	s_addc_u32 s3, s31, 0
	s_add_i32 s55, s45, s33
	global_load_lds_dwordx4 v[166:167], off
	v_lshl_add_u64 v[212:213], s[2:3], 0, v[148:149]
	s_mov_b32 m0, s55
	v_lshl_add_u64 v[214:215], s[34:35], 0, v[150:151]
	global_load_lds_dwordx4 v[212:213], off
	v_lshl_add_u64 v[212:213], s[2:3], 0, v[152:153]
	s_add_i32 m0, s55, 0x2000
	s_nop 0
	global_load_lds_dwordx4 v[212:213], off
	v_lshl_add_u64 v[212:213], s[34:35], 0, v[146:147]
	s_mov_b32 m0, s36
	s_nop 0
	global_load_lds_dwordx4 v[212:213], off
	s_mov_b32 m0, s37
	s_nop 0
	global_load_lds_dwordx4 v[214:215], off
	s_cmp_lg_u32 s100, 0
	s_cbranch_scc0 .Lrf_3759_1
	s_waitcnt vmcnt(16)
	s_branch .Lrj_3759_1

; #define G_STAGE(bufoff, gbase, voff) do { _Pragma("unroll") for (int _i = 0; _i < 2; ++_i) \
;         __builtin_amdgcn_global_load_lds((const unsigned*)((const char*)(gbase) + voff[_i]), (LAS unsigned*)(lds + (bufoff) + ldsw + _i * 8192), 16, 0, 0); } while (0)
; #define G_LDA(dst, b, h) do { _Pragma("unroll") for (int m = 0; m < 4; ++m) _Pragma("unroll") for (int k = 0; k < 2; ++k) dst[m][k] = *(const LAS bf16x8*)(lds + G_SA(b, h) + aoff + m * 2048 + k * 1024); } while (0)
; #define G_LDB(dst, b, h) do { _Pragma("unroll") for (int n = 0; n < 2; ++n) _Pragma("unroll") for (int k = 0; k < 2; ++k) dst[n][k] = *(const LAS bf16x8*)(lds + G_SB(b, h) + boff + n * 2048 + k * 1024); } while (0)
; #define G_MMA(ai, bj, At_, Bt_) do { __builtin_amdgcn_s_setprio(1); _Pragma("unroll") for (int m = 0; m < 4; ++m) _Pragma("unroll") for (int n = 0; n < 2; ++n) _Pragma("unroll") for (int k = 0; k < 2; ++k) \
;         acc[ai][bj][m][n] = __builtin_amdgcn_mfma_f32_16x16x32_bf16(Bt_[n][k], At_[m][k], acc[ai][bj][m][n], 0, 0, 0); __builtin_amdgcn_s_setprio(0); } while (0)
; #define WAIT_V(n) asm volatile("s_waitcnt vmcnt(" #n ")" ::: "memory")
; #define WAIT_L(n) asm volatile("s_waitcnt lgkmcnt(" #n ")" ::: "memory")
; #define BAR __builtin_amdgcn_s_barrier()
; #define SCHED __builtin_amdgcn_sched_barrier(0)
; template <class Get, class Epi>
; DI void gemm_loop(int ntiles, int ld, char* shm, const Get& get, const Epi& epi) {
;     ...
;             WAIT_V(8); WAIT_L(0); BAR; G_MMA(1, 0, At, B0); G_MMA(1, 1, At, B1); BAR; SCHED;
;             G_LDB(B0, 1, 0); G_LDB(B1, 1, 1); SCHED; G_LDA(At, 1, 0); G_STAGE(G_SA(0, 1), a2 + hstep, voffA);
;             WAIT_V(8); WAIT_L(0); BAR; G_MMA(0, 0, At, B0); G_MMA(0, 1, At, B1); BAR; SCHED;
.Lrj_3759_1:
	s_waitcnt lgkmcnt(0)
	s_barrier
	s_setprio 1
	s_waitcnt lgkmcnt(0)
	v_mfma_f32_16x16x32_bf16 v[92:95], v[128:131], v[180:183], 0
	v_mfma_f32_16x16x32_bf16 v[88:91], v[136:139], v[180:183], 0
	v_mfma_f32_16x16x32_bf16 v[84:87], v[128:131], v[188:191], 0
	v_mfma_f32_16x16x32_bf16 v[80:83], v[136:139], v[188:191], 0
	v_mfma_f32_16x16x32_bf16 v[76:79], v[128:131], v[196:199], 0
	v_mfma_f32_16x16x32_bf16 v[72:75], v[136:139], v[196:199], 0
	v_mfma_f32_16x16x32_bf16 v[68:71], v[128:131], v[204:207], 0
	v_mfma_f32_16x16x32_bf16 v[64:67], v[136:139], v[204:207], 0
	v_mfma_f32_16x16x32_bf16 v[92:95], v[132:135], v[184:187], v[92:95]
	v_mfma_f32_16x16x32_bf16 v[88:91], v[140:143], v[184:187], v[88:91]
	v_mfma_f32_16x16x32_bf16 v[84:87], v[132:135], v[192:195], v[84:87]
	v_mfma_f32_16x16x32_bf16 v[80:83], v[140:143], v[192:195], v[80:83]
	v_mfma_f32_16x16x32_bf16 v[76:79], v[132:135], v[200:203], v[76:79]
	v_mfma_f32_16x16x32_bf16 v[72:75], v[140:143], v[200:203], v[72:75]
	v_mfma_f32_16x16x32_bf16 v[68:71], v[132:135], v[208:211], v[68:71]
	v_mfma_f32_16x16x32_bf16 v[64:67], v[140:143], v[208:211], v[64:67]
	s_setprio 0
	s_setprio 1
	v_mfma_f32_16x16x32_bf16 v[28:31], v[158:161], v[180:183], 0
	v_mfma_f32_16x16x32_bf16 v[24:27], v[172:175], v[180:183], 0
	v_mfma_f32_16x16x32_bf16 v[20:23], v[158:161], v[188:191], 0
	v_mfma_f32_16x16x32_bf16 v[16:19], v[172:175], v[188:191], 0
	v_mfma_f32_16x16x32_bf16 v[12:15], v[158:161], v[196:199], 0
	v_mfma_f32_16x16x32_bf16 v[8:11], v[172:175], v[196:199], 0
	v_mfma_f32_16x16x32_bf16 v[4:7], v[158:161], v[204:207], 0
	v_mfma_f32_16x16x32_bf16 v[0:3], v[172:175], v[204:207], 0
	v_mfma_f32_16x16x32_bf16 v[28:31], v[162:165], v[184:187], v[28:31]
	v_mfma_f32_16x16x32_bf16 v[24:27], v[176:179], v[184:187], v[24:27]
	v_mfma_f32_16x16x32_bf16 v[20:23], v[162:165], v[192:195], v[20:23]
	v_mfma_f32_16x16x32_bf16 v[16:19], v[176:179], v[192:195], v[16:19]
	v_mfma_f32_16x16x32_bf16 v[12:15], v[162:165], v[200:203], v[12:15]
	v_mfma_f32_16x16x32_bf16 v[8:11], v[176:179], v[200:203], v[8:11]
	v_mfma_f32_16x16x32_bf16 v[4:7], v[162:165], v[208:211], v[4:7]
	v_mfma_f32_16x16x32_bf16 v[0:3], v[176:179], v[208:211], v[0:3]
	s_setprio 0
	s_barrier
	s_add_i32 s55, 0, 0x18000
	s_add_i32 s56, 0, 0x1c000
	v_add_u32_e32 v140, s55, v168
	v_add_u32_e32 v176, s56, v168
	ds_read_b128 v[128:131], v140
	ds_read_b128 v[132:135], v140 offset:1024
	ds_read_b128 v[136:139], v140 offset:2048
	ds_read_b128 v[140:143], v140 offset:3072
	ds_read_b128 v[158:161], v176
	ds_read_b128 v[162:165], v176 offset:1024
	ds_read_b128 v[172:175], v176 offset:2048
	ds_read_b128 v[176:179], v176 offset:3072
	s_add_u32 s2, s34, 0xb0000
	s_addc_u32 s3, s35, 0
	s_mov_b32 m0, s38
	v_lshl_add_u64 v[216:217], s[2:3], 0, v[146:147]
	ds_read_b128 v[180:183], v171 offset:32768
	ds_read_b128 v[184:187], v171 offset:33792
	ds_read_b128 v[188:191], v171 offset:34816
	ds_read_b128 v[192:195], v171 offset:35840
	ds_read_b128 v[196:199], v171 offset:36864
	ds_read_b128 v[200:203], v171 offset:37888
	ds_read_b128 v[204:207], v171 offset:38912
	ds_read_b128 v[208:211], v171 offset:39936
	global_load_lds_dwordx4 v[216:217], off
	v_lshl_add_u64 v[216:217], s[2:3], 0, v[150:151]
	s_mov_b32 m0, s39
	s_nop 0
	global_load_lds_dwordx4 v[216:217], off
	s_waitcnt vmcnt(8)
	s_waitcnt lgkmcnt(0)
	s_barrier
	s_setprio 1
	s_waitcnt lgkmcnt(0)
	v_mfma_f32_16x16x32_bf16 v[124:127], v[128:131], v[180:183], v[124:127]
	v_mfma_f32_16x16x32_bf16 v[120:123], v[136:139], v[180:183], v[120:123]
	v_mfma_f32_16x16x32_bf16 v[116:119], v[128:131], v[188:191], v[116:119]
	v_mfma_f32_16x16x32_bf16 v[112:115], v[136:139], v[188:191], v[112:115]
	v_mfma_f32_16x16x32_bf16 v[108:111], v[128:131], v[196:199], v[108:111]
	v_mfma_f32_16x16x32_bf16 v[104:107], v[136:139], v[196:199], v[104:107]
	v_mfma_f32_16x16x32_bf16 v[100:103], v[128:131], v[204:207], v[100:103]
	v_mfma_f32_16x16x32_bf16 v[96:99], v[136:139], v[204:207], v[96:99]
	v_mfma_f32_16x16x32_bf16 v[124:127], v[132:135], v[184:187], v[124:127]
	v_mfma_f32_16x16x32_bf16 v[120:123], v[140:143], v[184:187], v[120:123]
	v_mfma_f32_16x16x32_bf16 v[116:119], v[132:135], v[192:195], v[116:119]
	v_mfma_f32_16x16x32_bf16 v[112:115], v[140:143], v[192:195], v[112:115]
	v_mfma_f32_16x16x32_bf16 v[108:111], v[132:135], v[200:203], v[108:111]
	v_mfma_f32_16x16x32_bf16 v[104:107], v[140:143], v[200:203], v[104:107]
	v_mfma_f32_16x16x32_bf16 v[100:103], v[132:135], v[208:211], v[100:103]
	v_mfma_f32_16x16x32_bf16 v[96:99], v[140:143], v[208:211], v[96:99]
	s_setprio 0
	s_setprio 1
	v_mfma_f32_16x16x32_bf16 v[60:63], v[158:161], v[180:183], v[60:63]
	v_mfma_f32_16x16x32_bf16 v[56:59], v[172:175], v[180:183], v[56:59]
	v_mfma_f32_16x16x32_bf16 v[52:55], v[158:161], v[188:191], v[52:55]
	v_mfma_f32_16x16x32_bf16 v[48:51], v[172:175], v[188:191], v[48:51]
	v_mfma_f32_16x16x32_bf16 v[44:47], v[158:161], v[196:199], v[44:47]
	v_mfma_f32_16x16x32_bf16 v[40:43], v[172:175], v[196:199], v[40:43]
	v_mfma_f32_16x16x32_bf16 v[36:39], v[158:161], v[204:207], v[36:39]
	v_mfma_f32_16x16x32_bf16 v[32:35], v[172:175], v[204:207], v[32:35]
	v_mfma_f32_16x16x32_bf16 v[60:63], v[162:165], v[184:187], v[60:63]
	v_mfma_f32_16x16x32_bf16 v[56:59], v[176:179], v[184:187], v[56:59]
	v_mfma_f32_16x16x32_bf16 v[52:55], v[162:165], v[192:195], v[52:55]
	v_mfma_f32_16x16x32_bf16 v[48:51], v[176:179], v[192:195], v[48:51]
	v_mfma_f32_16x16x32_bf16 v[44:47], v[162:165], v[200:203], v[44:47]
	v_mfma_f32_16x16x32_bf16 v[40:43], v[176:179], v[200:203], v[40:43]
	v_mfma_f32_16x16x32_bf16 v[36:39], v[162:165], v[208:211], v[36:39]
	v_mfma_f32_16x16x32_bf16 v[32:35], v[176:179], v[208:211], v[32:35]
	s_setprio 0
	s_barrier
; #define G_STAGE(bufoff, gbase, voff) do { _Pragma("unroll") for (int _i = 0; _i < 2; ++_i) \
;         __builtin_amdgcn_global_load_lds((const unsigned*)((const char*)(gbase) + voff[_i]), (LAS unsigned*)(lds + (bufoff) + ldsw + _i * 8192), 16, 0, 0); } while (0)
; #define G_LDA(dst, b, h) do { _Pragma("unroll") for (int m = 0; m < 4; ++m) _Pragma("unroll") for (int k = 0; k < 2; ++k) dst[m][k] = *(const LAS bf16x8*)(lds + G_SA(b, h) + aoff + m * 2048 + k * 1024); } while (0)
; #define G_MMA(ai, bj, At_, Bt_) do { __builtin_amdgcn_s_setprio(1); _Pragma("unroll") for (int m = 0; m < 4; ++m) _Pragma("unroll") for (int n = 0; n < 2; ++n) _Pragma("unroll") for (int k = 0; k < 2; ++k) \
;         acc[ai][bj][m][n] = __builtin_amdgcn_mfma_f32_16x16x32_bf16(Bt_[n][k], At_[m][k], acc[ai][bj][m][n], 0, 0, 0); __builtin_amdgcn_s_setprio(0); } while (0)
; #define WAIT_V(n) asm volatile("s_waitcnt vmcnt(" #n ")" ::: "memory")
; #define WAIT_L(n) asm volatile("s_waitcnt lgkmcnt(" #n ")" ::: "memory")
; #define BAR __builtin_amdgcn_s_barrier()
; #define SCHED __builtin_amdgcn_sched_barrier(0)
; template <class Get, class Epi>
; DI void gemm_loop(int ntiles, int ld, char* shm, const Get& get, const Epi& epi) {
;     ...
;             G_LDA(At, 1, 1); G_STAGE(G_SB(1, 0), b3, voffB); G_STAGE(G_SB(1, 1), b3 + hstep, voffB); G_STAGE(G_SA(1, 0), a3, voffA);
;             WAIT_V(8); WAIT_L(0); BAR; G_MMA(1, 0, At, B0); G_MMA(1, 1, At, B1); BAR; SCHED;
;         }
	s_add_i32 s2, s55, s33
	v_lshl_add_u64 v[144:145], v[144:145], 0, s[6:7]
	s_mov_b32 m0, s2
	ds_read_b128 v[180:183], v171 offset:49152
	ds_read_b128 v[184:187], v171 offset:50176
	ds_read_b128 v[188:191], v171 offset:51200
	ds_read_b128 v[192:195], v171 offset:52224
	ds_read_b128 v[196:199], v171 offset:53248
	ds_read_b128 v[200:203], v171 offset:54272
	ds_read_b128 v[204:207], v171 offset:55296
	ds_read_b128 v[208:211], v171 offset:56320
	global_load_lds_dwordx4 v[144:145], off
	s_add_i32 m0, s2, 0x2000
	s_add_u32 s2, s30, 0xb0080
	v_lshl_add_u64 v[144:145], v[166:167], 0, s[6:7]
	s_addc_u32 s3, s31, 0
	s_add_i32 s30, s56, s33
	global_load_lds_dwordx4 v[144:145], off
	v_lshl_add_u64 v[144:145], s[2:3], 0, v[148:149]
	s_mov_b32 m0, s30
	s_nop 0
	global_load_lds_dwordx4 v[144:145], off
	v_lshl_add_u64 v[144:145], s[2:3], 0, v[152:153]
	s_add_i32 m0, s30, 0x2000
	s_nop 0
	global_load_lds_dwordx4 v[144:145], off
	v_lshl_add_u64 v[144:145], v[212:213], 0, s[6:7]
	s_mov_b32 m0, s42
	s_nop 0
	global_load_lds_dwordx4 v[144:145], off
	v_lshl_add_u64 v[144:145], v[214:215], 0, s[6:7]
	s_mov_b32 m0, s43
	s_nop 0
	global_load_lds_dwordx4 v[144:145], off
	s_waitcnt vmcnt(8)
	s_waitcnt lgkmcnt(0)
	s_barrier
	s_setprio 1
	s_waitcnt lgkmcnt(0)
	v_mfma_f32_16x16x32_bf16 v[92:95], v[128:131], v[180:183], v[92:95]
	v_mfma_f32_16x16x32_bf16 v[88:91], v[136:139], v[180:183], v[88:91]
	v_mfma_f32_16x16x32_bf16 v[84:87], v[128:131], v[188:191], v[84:87]
	v_mfma_f32_16x16x32_bf16 v[80:83], v[136:139], v[188:191], v[80:83]
	v_mfma_f32_16x16x32_bf16 v[76:79], v[128:131], v[196:199], v[76:79]
	v_mfma_f32_16x16x32_bf16 v[72:75], v[136:139], v[196:199], v[72:75]
	v_mfma_f32_16x16x32_bf16 v[68:71], v[128:131], v[204:207], v[68:71]
	v_mfma_f32_16x16x32_bf16 v[64:67], v[136:139], v[204:207], v[64:67]
	v_mfma_f32_16x16x32_bf16 v[92:95], v[132:135], v[184:187], v[92:95]
	v_mfma_f32_16x16x32_bf16 v[88:91], v[140:143], v[184:187], v[88:91]
	v_mfma_f32_16x16x32_bf16 v[84:87], v[132:135], v[192:195], v[84:87]
	v_mfma_f32_16x16x32_bf16 v[80:83], v[140:143], v[192:195], v[80:83]
	v_mfma_f32_16x16x32_bf16 v[76:79], v[132:135], v[200:203], v[76:79]
	v_mfma_f32_16x16x32_bf16 v[72:75], v[140:143], v[200:203], v[72:75]
	v_mfma_f32_16x16x32_bf16 v[68:71], v[132:135], v[208:211], v[68:71]
	v_mfma_f32_16x16x32_bf16 v[64:67], v[140:143], v[208:211], v[64:67]
	s_setprio 0
	s_setprio 1
	v_mfma_f32_16x16x32_bf16 v[28:31], v[158:161], v[180:183], v[28:31]
	v_mfma_f32_16x16x32_bf16 v[24:27], v[172:175], v[180:183], v[24:27]
	v_mfma_f32_16x16x32_bf16 v[20:23], v[158:161], v[188:191], v[20:23]
	v_mfma_f32_16x16x32_bf16 v[16:19], v[172:175], v[188:191], v[16:19]
	v_mfma_f32_16x16x32_bf16 v[12:15], v[158:161], v[196:199], v[12:15]
	v_mfma_f32_16x16x32_bf16 v[8:11], v[172:175], v[196:199], v[8:11]
	v_mfma_f32_16x16x32_bf16 v[4:7], v[158:161], v[204:207], v[4:7]
	v_mfma_f32_16x16x32_bf16 v[0:3], v[172:175], v[204:207], v[0:3]
	v_mfma_f32_16x16x32_bf16 v[28:31], v[162:165], v[184:187], v[28:31]
	v_mfma_f32_16x16x32_bf16 v[24:27], v[176:179], v[184:187], v[24:27]
	v_mfma_f32_16x16x32_bf16 v[20:23], v[162:165], v[192:195], v[20:23]
	v_mfma_f32_16x16x32_bf16 v[16:19], v[176:179], v[192:195], v[16:19]
	v_mfma_f32_16x16x32_bf16 v[12:15], v[162:165], v[200:203], v[12:15]
	v_mfma_f32_16x16x32_bf16 v[8:11], v[176:179], v[200:203], v[8:11]
	v_mfma_f32_16x16x32_bf16 v[4:7], v[162:165], v[208:211], v[4:7]
	v_mfma_f32_16x16x32_bf16 v[0:3], v[176:179], v[208:211], v[0:3]
	s_setprio 0
	s_barrier
	s_add_i32 s54, s54, 2
	s_add_u32 s52, s52, 0x100
	s_addc_u32 s53, s53, 0
	s_cmp_gt_u32 s54, 41
	s_mov_b64 s[2:3], s[24:25]
	s_cbranch_scc0 .LBB0_3759
	s_branch .Lpost_3759

; #define BAR __builtin_amdgcn_s_barrier()
; template <class Get, class Epi>
; DI void gemm_loop(int ntiles, int ld, char* shm, const Get& get, const Epi& epi) {
;     ...
;         if (wr == 0) BAR;
;         { int tx2 = threadIdx.x, brow2 = cur.brow, bcol2 = cur.bcol, Lo = L; asm volatile("" : "+v"(tx2), "+s"(brow2), "+s"(bcol2), "+s"(Lo));
;           const int wid2 = tx2 >> 6, lane2 = tx2 & 63; epi(Lo, acc, brow2, bcol2, wid2 >> 2, wid2 & 3, lane2 & 15, lane2 >> 4); }
;         if (!has_next) break;
;         G_ZERO;
;         cur = nxt; cA = nA; cB = nB; L = Ln;
.Lpost_3759:
	s_mov_b32 s100, 1
	s_and_b64 vcc, exec, s[8:9]
	s_cbranch_vccz .LBB0_3762
	s_barrier
